# v11
# baseline (speedup 1.0000x reference)
; #define PG8_LDA(dst, b, h) do { _Pragma("unroll") for (int m = 0; m < 4; ++m) _Pragma("unroll") for (int k = 0; k < 2; ++k) dst[m][k] = *(const PG8_LAS bf16x8*)(lds + PG8_SA(b, h) + aoff + m * 2048 + k * 1024); } while (0)
; template <class Epi, class Sched, bool ALIGN_EPI = false, bool SP2 = false>
; __device__ __forceinline__ void gemm_phase(PG8_LAS unsigned char* lds, const Gemm g, const Sched& S, const Epi& E) {
;     ...
;         const bool has_next = S.next(ui + 1, nxt);
;         const char* nA = has_next ? (const char*)g.A + (size_t)nxt.pm * tstep : cA; const char* nB = has_next ? (const char*)g.Bt + (size_t)nxt.pn * tstep : cB;
;         for (int t = 0; t < nt; t += 2) {
;             const bool last = (t == nt - 2);
;             const char* a1 = cA + (size_t)(t + 1) * kstep;
;             const char* a2 = last ? nA : cA + (size_t)(t + 2) * kstep; const char* b2 = last ? nB : cB + (size_t)(t + 2) * kstep;
;             const char* a3 = a2 + kstep; const char* b3 = b2 + kstep;
;             if (last && has_next) S.a_ready(nxt);
;             if constexpr (SP2) {
;             PG8_LDB(B0, 0, 0); PG8_LDB(B1, 0, 1); PG8_SCHED; PG8_LDA(At, 0, 0); PG8_STAGE(PG8_SA(1, 1), a1 + hstep, voffA);
;             PG8_WAIT_V(8); PG8_WAIT_L(0); PG8_BAR; PG8_MMA(0, 0, At, B0); PG8_MMA(0, 1, At, B1); PG8_BAR; PG8_SCHED;
;             PG8_LDA(At, 0, 1); PG8_STAGE(PG8_SB(0, 0), b2, voffB); PG8_STAGE(PG8_SB(0, 1), b2 + hstep, voffB); PG8_STAGE(PG8_SA(0, 0), a2, voffA);
;             PG8_WAIT_V(8); PG8_WAIT_L(0); PG8_BAR; PG8_MMA(1, 0, At, B0); PG8_MMA(1, 1, At, B1); PG8_BAR; PG8_SCHED;
;             PG8_LDB(B0, 1, 0); PG8_LDB(B1, 1, 1); PG8_SCHED; PG8_LDA(At, 1, 0); PG8_STAGE(PG8_SA(0, 1), a2 + hstep, voffA);
;             PG8_WAIT_V(8); PG8_WAIT_L(0); PG8_BAR; PG8_MMA(0, 0, At, B0); PG8_MMA(0, 1, At, B1); PG8_BAR; PG8_SCHED;
;             PG8_LDA(At, 1, 1); PG8_STAGE(PG8_SB(1, 0), b3, voffB); PG8_STAGE(PG8_SB(1, 1), b3 + hstep, voffB); PG8_STAGE(PG8_SA(1, 0), a3, voffA);
;             PG8_WAIT_V(8); PG8_WAIT_L(0); PG8_BAR; PG8_MMA(1, 0, At, B0); PG8_MMA(1, 1, At, B1); PG8_BAR; PG8_SCHED;
;     ...
; #pragma unroll
;         for (int a = 0; a < 2; ++a)
; #pragma unroll
;             for (int b = 0; b < 2; ++b)
; #pragma unroll
;                 for (int m = 0; m < 4; ++m)
; #pragma unroll
;                     for (int n = 0; n < 2; ++n) acc[a][b][m][n] = (f32x4){0.f, 0.f, 0.f, 0.f};
.LBB0_313:
	s_ashr_i32 s27, s26, 31
	s_lshl_b64 s[30:31], s[26:27], 20
	s_ashr_i32 s25, s24, 31
	v_lshl_add_u64 v[152:153], v[136:137], 0, s[30:31]
	s_lshl_b64 s[30:31], s[24:25], 20
	v_lshl_add_u64 v[154:155], v[132:133], 0, s[30:31]
	v_cndmask_b32_e64 v158, v0, v154, s[6:7]
	v_lshl_add_u64 v[162:163], v[0:1], 0, s[20:21]
	v_cndmask_b32_e64 v157, v3, v153, s[6:7]
	v_cndmask_b32_e64 v156, v2, v152, s[6:7]
	v_cndmask_b32_e64 v159, v1, v155, s[6:7]
	v_lshl_add_u64 v[160:161], v[2:3], 0, s[16:17]
	s_mov_b32 s25, -2
	ds_read_b128 v[174:177], v168
	ds_read_b128 v[178:181], v168 offset:1024
	ds_read_b128 v[182:185], v168 offset:2048
	ds_read_b128 v[186:189], v168 offset:3072
	ds_read_b128 v[190:193], v170
	ds_read_b128 v[194:197], v170 offset:1024
	ds_read_b128 v[198:201], v170 offset:2048
	ds_read_b128 v[202:205], v170 offset:3072
	s_cmp_eq_u32 s25, 28
	v_lshl_add_u64 v[206:207], v[160:161], 0, s[22:23]
	s_cselect_b64 vcc, -1, 0
	v_cndmask_b32_e32 v241, v207, v157, vcc
	v_cndmask_b32_e32 v240, v206, v156, vcc
	v_cndmask_b32_e32 v243, v163, v159, vcc
	v_cndmask_b32_e32 v242, v162, v158, vcc
	s_mov_b32 m0, s48
	v_lshl_add_u64 v[244:245], v[160:161], 0, v[146:147]
	ds_read_b128 v[206:209], v169
	ds_read_b128 v[210:213], v169 offset:1024
	ds_read_b128 v[214:217], v169 offset:2048
	ds_read_b128 v[218:221], v169 offset:3072
	ds_read_b128 v[222:225], v169 offset:4096
	ds_read_b128 v[226:229], v169 offset:5120
	ds_read_b128 v[230:233], v169 offset:6144
	ds_read_b128 v[236:239], v169 offset:7168
	global_load_lds_dwordx4 v[244:245], off
	v_lshl_add_u64 v[244:245], v[160:161], 0, v[148:149]
	s_mov_b32 m0, s49
	s_nop 0
	global_load_lds_dwordx4 v[244:245], off
	s_waitcnt vmcnt(8)
	s_waitcnt lgkmcnt(0)
	s_barrier
	s_setprio 1
	s_waitcnt lgkmcnt(0)
	v_mfma_f32_16x16x32_bf16 v[124:127], v[174:177], v[206:209], 0
	v_mfma_f32_16x16x32_bf16 v[120:123], v[182:185], v[206:209], 0
	v_mfma_f32_16x16x32_bf16 v[116:119], v[174:177], v[214:217], 0
	v_mfma_f32_16x16x32_bf16 v[108:111], v[182:185], v[214:217], 0
	v_mfma_f32_16x16x32_bf16 v[96:99], v[174:177], v[222:225], 0
	v_mfma_f32_16x16x32_bf16 v[88:91], v[182:185], v[222:225], 0
	v_mfma_f32_16x16x32_bf16 v[84:87], v[174:177], v[230:233], 0
	v_mfma_f32_16x16x32_bf16 v[76:79], v[182:185], v[230:233], 0
	v_mfma_f32_16x16x32_bf16 v[124:127], v[178:181], v[210:213], v[124:127]
	v_mfma_f32_16x16x32_bf16 v[120:123], v[186:189], v[210:213], v[120:123]
	v_mfma_f32_16x16x32_bf16 v[116:119], v[178:181], v[218:221], v[116:119]
	v_mfma_f32_16x16x32_bf16 v[108:111], v[186:189], v[218:221], v[108:111]
	v_mfma_f32_16x16x32_bf16 v[96:99], v[178:181], v[226:229], v[96:99]
	v_mfma_f32_16x16x32_bf16 v[88:91], v[186:189], v[226:229], v[88:91]
	v_mfma_f32_16x16x32_bf16 v[84:87], v[178:181], v[236:239], v[84:87]
	v_mfma_f32_16x16x32_bf16 v[76:79], v[186:189], v[236:239], v[76:79]
	s_setprio 0
	s_setprio 1
	v_mfma_f32_16x16x32_bf16 v[112:115], v[190:193], v[206:209], 0
	v_mfma_f32_16x16x32_bf16 v[104:107], v[198:201], v[206:209], 0
	v_mfma_f32_16x16x32_bf16 v[100:103], v[190:193], v[214:217], 0
	v_mfma_f32_16x16x32_bf16 v[92:95], v[198:201], v[214:217], 0
	v_mfma_f32_16x16x32_bf16 v[80:83], v[190:193], v[222:225], 0
	v_mfma_f32_16x16x32_bf16 v[72:75], v[198:201], v[222:225], 0
	v_mfma_f32_16x16x32_bf16 v[68:71], v[190:193], v[230:233], 0
	v_mfma_f32_16x16x32_bf16 v[64:67], v[198:201], v[230:233], 0
	v_mfma_f32_16x16x32_bf16 v[112:115], v[194:197], v[210:213], v[112:115]
	v_mfma_f32_16x16x32_bf16 v[104:107], v[202:205], v[210:213], v[104:107]
	v_mfma_f32_16x16x32_bf16 v[100:103], v[194:197], v[218:221], v[100:103]
	v_mfma_f32_16x16x32_bf16 v[92:95], v[202:205], v[218:221], v[92:95]
	v_mfma_f32_16x16x32_bf16 v[80:83], v[194:197], v[226:229], v[80:83]
	v_mfma_f32_16x16x32_bf16 v[72:75], v[202:205], v[226:229], v[72:75]
	v_mfma_f32_16x16x32_bf16 v[68:71], v[194:197], v[236:239], v[68:71]
	v_mfma_f32_16x16x32_bf16 v[64:67], v[202:205], v[236:239], v[64:67]
	s_setprio 0
	s_barrier
	s_mov_b32 m0, s50
	v_lshl_add_u64 v[244:245], v[242:243], 0, v[142:143]
	ds_read_b128 v[206:209], v169 offset:16384
	ds_read_b128 v[210:213], v169 offset:17408
	ds_read_b128 v[214:217], v169 offset:18432
	ds_read_b128 v[218:221], v169 offset:19456
	ds_read_b128 v[222:225], v169 offset:20480
	ds_read_b128 v[226:229], v169 offset:21504
	ds_read_b128 v[230:233], v169 offset:22528
	ds_read_b128 v[236:239], v169 offset:23552
	global_load_lds_dwordx4 v[244:245], off
	v_lshl_add_u64 v[246:247], v[242:243], 0, v[138:139]
	s_mov_b32 m0, s51
	v_lshl_add_u64 v[248:249], v[242:243], 0, s[10:11]
	global_load_lds_dwordx4 v[246:247], off
	v_lshl_add_u64 v[250:251], v[248:249], 0, v[142:143]
	s_mov_b32 m0, s52
	v_lshl_add_u64 v[248:249], v[248:249], 0, v[138:139]
	global_load_lds_dwordx4 v[250:251], off
	s_mov_b32 m0, s53
	v_lshl_add_u64 v[250:251], v[240:241], 0, v[140:141]
	global_load_lds_dwordx4 v[248:249], off
	v_lshl_add_u64 v[248:249], v[240:241], 0, v[144:145]
	s_mov_b32 m0, s29
	s_nop 0
	global_load_lds_dwordx4 v[248:249], off
	s_mov_b32 m0, s38
	s_nop 0
	global_load_lds_dwordx4 v[250:251], off
	s_waitcnt vmcnt(8)
	s_waitcnt lgkmcnt(0)
	s_barrier
; #define PG8_STAGE(bufoff, gbase, voff) do { _Pragma("unroll") for (int _i = 0; _i < 2; ++_i) \
;         __builtin_amdgcn_global_load_lds((const unsigned*)((const char*)(gbase) + (voff)[_i]), (PG8_LAS unsigned*)(lds + (bufoff) + ldsw + _i * 8192), 16, 0, 0); } while (0)
; #define PG8_LDA(dst, b, h) do { _Pragma("unroll") for (int m = 0; m < 4; ++m) _Pragma("unroll") for (int k = 0; k < 2; ++k) dst[m][k] = *(const PG8_LAS bf16x8*)(lds + PG8_SA(b, h) + aoff + m * 2048 + k * 1024); } while (0)
; #define PG8_LDB(dst, b, h) do { _Pragma("unroll") for (int n = 0; n < 2; ++n) _Pragma("unroll") for (int k = 0; k < 2; ++k) dst[n][k] = *(const PG8_LAS bf16x8*)(lds + PG8_SB(b, h) + boff + n * 2048 + k * 1024); } while (0)
; #define PG8_MMA(ai, bj, At, Bt) do { __builtin_amdgcn_s_setprio(1); _Pragma("unroll") for (int m = 0; m < 4; ++m) _Pragma("unroll") for (int n = 0; n < 2; ++n) _Pragma("unroll") for (int k = 0; k < 2; ++k) \
;         acc[ai][bj][m][n] = __builtin_amdgcn_mfma_f32_16x16x32_bf16(Bt[n][k], At[m][k], acc[ai][bj][m][n], 0, 0, 0); __builtin_amdgcn_s_setprio(0); } while (0)
; #define PG8_WAIT_V(n) asm volatile("s_waitcnt vmcnt(" #n ")" ::: "memory")
; #define PG8_WAIT_L(n) asm volatile("s_waitcnt lgkmcnt(" #n ")" ::: "memory")
; #define PG8_BAR __builtin_amdgcn_s_barrier()
; #define PG8_SCHED __builtin_amdgcn_sched_barrier(0)
; template <class Epi, class Sched, bool ALIGN_EPI = false, bool SP2 = false>
; __device__ __forceinline__ void gemm_phase(PG8_LAS unsigned char* lds, const Gemm g, const Sched& S, const Epi& E) {
;     ...
;             PG8_WAIT_V(8); PG8_WAIT_L(0); PG8_BAR; PG8_MMA(0, 0, At, B0); PG8_MMA(0, 1, At, B1); PG8_BAR; PG8_SCHED;
;             PG8_LDA(At, 0, 1); PG8_STAGE(PG8_SB(0, 0), b2, voffB); PG8_STAGE(PG8_SB(0, 1), b2 + hstep, voffB); PG8_STAGE(PG8_SA(0, 0), a2, voffA);
;             PG8_WAIT_V(8); PG8_WAIT_L(0); PG8_BAR; PG8_MMA(1, 0, At, B0); PG8_MMA(1, 1, At, B1); PG8_BAR; PG8_SCHED;
;             PG8_LDB(B0, 1, 0); PG8_LDB(B1, 1, 1); PG8_SCHED; PG8_LDA(At, 1, 0); PG8_STAGE(PG8_SA(0, 1), a2 + hstep, voffA);
;             PG8_WAIT_V(8); PG8_WAIT_L(0); PG8_BAR; PG8_MMA(0, 0, At, B0); PG8_MMA(0, 1, At, B1); PG8_BAR; PG8_SCHED;
	s_setprio 1
	s_waitcnt lgkmcnt(0)
	v_mfma_f32_16x16x32_bf16 v[60:63], v[174:177], v[206:209], 0
	v_mfma_f32_16x16x32_bf16 v[56:59], v[182:185], v[206:209], 0
	v_mfma_f32_16x16x32_bf16 v[52:55], v[174:177], v[214:217], 0
	v_mfma_f32_16x16x32_bf16 v[44:47], v[182:185], v[214:217], 0
	v_mfma_f32_16x16x32_bf16 v[32:35], v[174:177], v[222:225], 0
	v_mfma_f32_16x16x32_bf16 v[24:27], v[182:185], v[222:225], 0
	v_mfma_f32_16x16x32_bf16 v[20:23], v[174:177], v[230:233], 0
	v_mfma_f32_16x16x32_bf16 v[12:15], v[182:185], v[230:233], 0
	v_mfma_f32_16x16x32_bf16 v[60:63], v[178:181], v[210:213], v[60:63]
	v_mfma_f32_16x16x32_bf16 v[56:59], v[186:189], v[210:213], v[56:59]
	v_mfma_f32_16x16x32_bf16 v[52:55], v[178:181], v[218:221], v[52:55]
	v_mfma_f32_16x16x32_bf16 v[44:47], v[186:189], v[218:221], v[44:47]
	v_mfma_f32_16x16x32_bf16 v[32:35], v[178:181], v[226:229], v[32:35]
	v_mfma_f32_16x16x32_bf16 v[24:27], v[186:189], v[226:229], v[24:27]
	v_mfma_f32_16x16x32_bf16 v[20:23], v[178:181], v[236:239], v[20:23]
	v_mfma_f32_16x16x32_bf16 v[12:15], v[186:189], v[236:239], v[12:15]
	s_setprio 0
	s_setprio 1
	v_mfma_f32_16x16x32_bf16 v[48:51], v[190:193], v[206:209], 0
	v_mfma_f32_16x16x32_bf16 v[40:43], v[198:201], v[206:209], 0
	v_mfma_f32_16x16x32_bf16 v[36:39], v[190:193], v[214:217], 0
	v_mfma_f32_16x16x32_bf16 v[28:31], v[198:201], v[214:217], 0
	v_mfma_f32_16x16x32_bf16 v[16:19], v[190:193], v[222:225], 0
	v_mfma_f32_16x16x32_bf16 v[8:11], v[198:201], v[222:225], 0
	v_mfma_f32_16x16x32_bf16 v[4:7], v[190:193], v[230:233], 0
	v_mfma_f32_16x16x32_bf16 v[0:3], v[198:201], v[230:233], 0
	v_mfma_f32_16x16x32_bf16 v[48:51], v[194:197], v[210:213], v[48:51]
	v_mfma_f32_16x16x32_bf16 v[40:43], v[202:205], v[210:213], v[40:43]
	v_mfma_f32_16x16x32_bf16 v[36:39], v[194:197], v[218:221], v[36:39]
	v_mfma_f32_16x16x32_bf16 v[28:31], v[202:205], v[218:221], v[28:31]
	v_mfma_f32_16x16x32_bf16 v[16:19], v[194:197], v[226:229], v[16:19]
	v_mfma_f32_16x16x32_bf16 v[8:11], v[202:205], v[226:229], v[8:11]
	v_mfma_f32_16x16x32_bf16 v[4:7], v[194:197], v[236:239], v[4:7]
	v_mfma_f32_16x16x32_bf16 v[0:3], v[202:205], v[236:239], v[0:3]
	s_setprio 0
	s_barrier
	ds_read_b128 v[174:177], v171
	ds_read_b128 v[178:181], v171 offset:1024
	ds_read_b128 v[182:185], v171 offset:2048
	ds_read_b128 v[186:189], v171 offset:3072
	ds_read_b128 v[190:193], v172
	ds_read_b128 v[194:197], v172 offset:1024
	ds_read_b128 v[198:201], v172 offset:2048
	ds_read_b128 v[202:205], v172 offset:3072
	v_lshl_add_u64 v[240:241], v[240:241], 0, s[10:11]
	s_mov_b32 m0, s39
	v_lshl_add_u64 v[252:253], v[240:241], 0, v[144:145]
	ds_read_b128 v[206:209], v169 offset:32768
	ds_read_b128 v[210:213], v169 offset:33792
	ds_read_b128 v[214:217], v169 offset:34816
	ds_read_b128 v[218:221], v169 offset:35840
	ds_read_b128 v[222:225], v169 offset:36864
	ds_read_b128 v[226:229], v169 offset:37888
	ds_read_b128 v[230:233], v169 offset:38912
	ds_read_b128 v[236:239], v169 offset:39936
	global_load_lds_dwordx4 v[252:253], off
	v_lshl_add_u64 v[240:241], v[240:241], 0, v[140:141]
	s_mov_b32 m0, s40
	s_nop 0
	global_load_lds_dwordx4 v[240:241], off
	s_waitcnt vmcnt(8)
	s_waitcnt lgkmcnt(0)
	s_barrier
	s_setprio 1
	s_waitcnt lgkmcnt(0)
	v_mfma_f32_16x16x32_bf16 v[124:127], v[174:177], v[206:209], v[124:127]
	v_mfma_f32_16x16x32_bf16 v[120:123], v[182:185], v[206:209], v[120:123]
	v_mfma_f32_16x16x32_bf16 v[116:119], v[174:177], v[214:217], v[116:119]
	v_mfma_f32_16x16x32_bf16 v[108:111], v[182:185], v[214:217], v[108:111]
	v_mfma_f32_16x16x32_bf16 v[96:99], v[174:177], v[222:225], v[96:99]
	v_mfma_f32_16x16x32_bf16 v[88:91], v[182:185], v[222:225], v[88:91]
	v_mfma_f32_16x16x32_bf16 v[84:87], v[174:177], v[230:233], v[84:87]
	v_mfma_f32_16x16x32_bf16 v[76:79], v[182:185], v[230:233], v[76:79]
	v_mfma_f32_16x16x32_bf16 v[124:127], v[178:181], v[210:213], v[124:127]
	v_mfma_f32_16x16x32_bf16 v[120:123], v[186:189], v[210:213], v[120:123]
	v_mfma_f32_16x16x32_bf16 v[116:119], v[178:181], v[218:221], v[116:119]
	v_mfma_f32_16x16x32_bf16 v[108:111], v[186:189], v[218:221], v[108:111]
	v_mfma_f32_16x16x32_bf16 v[96:99], v[178:181], v[226:229], v[96:99]
	v_mfma_f32_16x16x32_bf16 v[88:91], v[186:189], v[226:229], v[88:91]
	v_mfma_f32_16x16x32_bf16 v[84:87], v[178:181], v[236:239], v[84:87]
	v_mfma_f32_16x16x32_bf16 v[76:79], v[186:189], v[236:239], v[76:79]
	s_setprio 0
	s_setprio 1
	v_mfma_f32_16x16x32_bf16 v[112:115], v[190:193], v[206:209], v[112:115]
	v_mfma_f32_16x16x32_bf16 v[104:107], v[198:201], v[206:209], v[104:107]
	v_mfma_f32_16x16x32_bf16 v[100:103], v[190:193], v[214:217], v[100:103]
	v_mfma_f32_16x16x32_bf16 v[92:95], v[198:201], v[214:217], v[92:95]
	v_mfma_f32_16x16x32_bf16 v[80:83], v[190:193], v[222:225], v[80:83]
	v_mfma_f32_16x16x32_bf16 v[72:75], v[198:201], v[222:225], v[72:75]
	v_mfma_f32_16x16x32_bf16 v[68:71], v[190:193], v[230:233], v[68:71]
	v_mfma_f32_16x16x32_bf16 v[64:67], v[198:201], v[230:233], v[64:67]
	v_mfma_f32_16x16x32_bf16 v[112:115], v[194:197], v[210:213], v[112:115]
	v_mfma_f32_16x16x32_bf16 v[104:107], v[202:205], v[210:213], v[104:107]
	v_mfma_f32_16x16x32_bf16 v[100:103], v[194:197], v[218:221], v[100:103]
	v_mfma_f32_16x16x32_bf16 v[92:95], v[202:205], v[218:221], v[92:95]
	v_mfma_f32_16x16x32_bf16 v[80:83], v[194:197], v[226:229], v[80:83]
	v_mfma_f32_16x16x32_bf16 v[72:75], v[202:205], v[226:229], v[72:75]
	v_mfma_f32_16x16x32_bf16 v[68:71], v[194:197], v[236:239], v[68:71]
	v_mfma_f32_16x16x32_bf16 v[64:67], v[202:205], v[236:239], v[64:67]
	s_setprio 0
	s_barrier
; #define PG8_STAGE(bufoff, gbase, voff) do { _Pragma("unroll") for (int _i = 0; _i < 2; ++_i) \
;         __builtin_amdgcn_global_load_lds((const unsigned*)((const char*)(gbase) + (voff)[_i]), (PG8_LAS unsigned*)(lds + (bufoff) + ldsw + _i * 8192), 16, 0, 0); } while (0)
; #define PG8_LDA(dst, b, h) do { _Pragma("unroll") for (int m = 0; m < 4; ++m) _Pragma("unroll") for (int k = 0; k < 2; ++k) dst[m][k] = *(const PG8_LAS bf16x8*)(lds + PG8_SA(b, h) + aoff + m * 2048 + k * 1024); } while (0)
; #define PG8_MMA(ai, bj, At, Bt) do { __builtin_amdgcn_s_setprio(1); _Pragma("unroll") for (int m = 0; m < 4; ++m) _Pragma("unroll") for (int n = 0; n < 2; ++n) _Pragma("unroll") for (int k = 0; k < 2; ++k) \
;         acc[ai][bj][m][n] = __builtin_amdgcn_mfma_f32_16x16x32_bf16(Bt[n][k], At[m][k], acc[ai][bj][m][n], 0, 0, 0); __builtin_amdgcn_s_setprio(0); } while (0)
; #define PG8_WAIT_V(n) asm volatile("s_waitcnt vmcnt(" #n ")" ::: "memory")
; #define PG8_WAIT_L(n) asm volatile("s_waitcnt lgkmcnt(" #n ")" ::: "memory")
; #define PG8_BAR __builtin_amdgcn_s_barrier()
; #define PG8_SCHED __builtin_amdgcn_sched_barrier(0)
; template <class Epi, class Sched, bool ALIGN_EPI = false, bool SP2 = false>
; __device__ __forceinline__ void gemm_phase(PG8_LAS unsigned char* lds, const Gemm g, const Sched& S, const Epi& E) {
;     ...
;         for (int t = 0; t < nt; t += 2) {
;             const bool last = (t == nt - 2);
;             const char* a1 = cA + (size_t)(t + 1) * kstep;
;             const char* a2 = last ? nA : cA + (size_t)(t + 2) * kstep; const char* b2 = last ? nB : cB + (size_t)(t + 2) * kstep;
;             const char* a3 = a2 + kstep; const char* b3 = b2 + kstep;
;             if (last && has_next) S.a_ready(nxt);
;     ...
;             PG8_LDA(At, 1, 1); PG8_STAGE(PG8_SB(1, 0), b3, voffB); PG8_STAGE(PG8_SB(1, 1), b3 + hstep, voffB); PG8_STAGE(PG8_SA(1, 0), a3, voffA);
;             PG8_WAIT_V(8); PG8_WAIT_L(0); PG8_BAR; PG8_MMA(1, 0, At, B0); PG8_MMA(1, 1, At, B1); PG8_BAR; PG8_SCHED;
	s_mov_b32 m0, s54
	v_lshl_add_u64 v[240:241], v[244:245], 0, s[14:15]
	ds_read_b128 v[206:209], v169 offset:49152
	ds_read_b128 v[210:213], v169 offset:50176
	ds_read_b128 v[214:217], v169 offset:51200
	ds_read_b128 v[218:221], v169 offset:52224
	ds_read_b128 v[222:225], v169 offset:53248
	ds_read_b128 v[226:229], v169 offset:54272
	ds_read_b128 v[230:233], v169 offset:55296
	ds_read_b128 v[236:239], v169 offset:56320
	global_load_lds_dwordx4 v[240:241], off
	v_lshl_add_u64 v[240:241], v[246:247], 0, s[14:15]
	s_mov_b32 m0, s55
	s_nop 0
	global_load_lds_dwordx4 v[240:241], off
	v_lshl_add_u64 v[240:241], v[242:243], 0, s[16:17]
	v_lshl_add_u64 v[242:243], v[240:241], 0, v[142:143]
	s_mov_b32 m0, s58
	v_lshl_add_u64 v[240:241], v[240:241], 0, v[138:139]
	global_load_lds_dwordx4 v[242:243], off
	s_mov_b32 m0, s59
	s_nop 0
	global_load_lds_dwordx4 v[240:241], off
	v_lshl_add_u64 v[240:241], v[248:249], 0, s[14:15]
	s_mov_b32 m0, s42
	s_nop 0
	global_load_lds_dwordx4 v[240:241], off
	v_lshl_add_u64 v[240:241], v[250:251], 0, s[14:15]
	s_mov_b32 m0, s43
	s_nop 0
	global_load_lds_dwordx4 v[240:241], off
	s_waitcnt vmcnt(8)
	s_waitcnt lgkmcnt(0)
	s_barrier
	s_setprio 1
	s_waitcnt lgkmcnt(0)
	v_mfma_f32_16x16x32_bf16 v[60:63], v[174:177], v[206:209], v[60:63]
	v_mfma_f32_16x16x32_bf16 v[56:59], v[182:185], v[206:209], v[56:59]
	v_mfma_f32_16x16x32_bf16 v[52:55], v[174:177], v[214:217], v[52:55]
	v_mfma_f32_16x16x32_bf16 v[44:47], v[182:185], v[214:217], v[44:47]
	v_mfma_f32_16x16x32_bf16 v[32:35], v[174:177], v[222:225], v[32:35]
	v_mfma_f32_16x16x32_bf16 v[24:27], v[182:185], v[222:225], v[24:27]
	v_mfma_f32_16x16x32_bf16 v[20:23], v[174:177], v[230:233], v[20:23]
	v_mfma_f32_16x16x32_bf16 v[12:15], v[182:185], v[230:233], v[12:15]
	v_mfma_f32_16x16x32_bf16 v[60:63], v[178:181], v[210:213], v[60:63]
	v_mfma_f32_16x16x32_bf16 v[56:59], v[186:189], v[210:213], v[56:59]
	v_mfma_f32_16x16x32_bf16 v[52:55], v[178:181], v[218:221], v[52:55]
	v_mfma_f32_16x16x32_bf16 v[44:47], v[186:189], v[218:221], v[44:47]
	v_mfma_f32_16x16x32_bf16 v[32:35], v[178:181], v[226:229], v[32:35]
	v_mfma_f32_16x16x32_bf16 v[24:27], v[186:189], v[226:229], v[24:27]
	v_mfma_f32_16x16x32_bf16 v[20:23], v[178:181], v[236:239], v[20:23]
	v_mfma_f32_16x16x32_bf16 v[12:15], v[186:189], v[236:239], v[12:15]
	s_setprio 0
	s_setprio 1
	v_mfma_f32_16x16x32_bf16 v[48:51], v[190:193], v[206:209], v[48:51]
	v_mfma_f32_16x16x32_bf16 v[40:43], v[198:201], v[206:209], v[40:43]
	v_mfma_f32_16x16x32_bf16 v[36:39], v[190:193], v[214:217], v[36:39]
	v_mfma_f32_16x16x32_bf16 v[28:31], v[198:201], v[214:217], v[28:31]
	v_mfma_f32_16x16x32_bf16 v[16:19], v[190:193], v[222:225], v[16:19]
	v_mfma_f32_16x16x32_bf16 v[8:11], v[198:201], v[222:225], v[8:11]
	v_mfma_f32_16x16x32_bf16 v[4:7], v[190:193], v[230:233], v[4:7]
	v_mfma_f32_16x16x32_bf16 v[0:3], v[198:201], v[230:233], v[0:3]
	v_mfma_f32_16x16x32_bf16 v[48:51], v[194:197], v[210:213], v[48:51]
	v_mfma_f32_16x16x32_bf16 v[40:43], v[202:205], v[210:213], v[40:43]
	v_mfma_f32_16x16x32_bf16 v[36:39], v[194:197], v[218:221], v[36:39]
	v_mfma_f32_16x16x32_bf16 v[28:31], v[202:205], v[218:221], v[28:31]
	v_mfma_f32_16x16x32_bf16 v[16:19], v[194:197], v[226:229], v[16:19]
	v_mfma_f32_16x16x32_bf16 v[8:11], v[202:205], v[226:229], v[8:11]
	v_mfma_f32_16x16x32_bf16 v[4:7], v[194:197], v[236:239], v[4:7]
	v_mfma_f32_16x16x32_bf16 v[0:3], v[202:205], v[236:239], v[0:3]
	s_setprio 0
	s_barrier
	s_add_i32 s25, s25, 2
	v_lshl_add_u64 v[160:161], v[160:161], 0, s[20:21]
	s_cmp_gt_u32 s25, 29
	v_lshl_add_u64 v[162:163], v[162:163], 0, s[20:21]
	s_cbranch_scc0 .LBB0_314
	s_branch .Lpeel_exit_1

; #define PG8_BAR __builtin_amdgcn_s_barrier()
; template <class Epi, class Sched, bool ALIGN_EPI = false, bool SP2 = false>
; __device__ __forceinline__ void gemm_phase(PG8_LAS unsigned char* lds, const Gemm g, const Sched& S, const Epi& E) {
;     ...
;         if constexpr (ALIGN_EPI) { if (wr == 0) PG8_BAR; }
;         if constexpr (!Epi::AFTER_DRAIN) { E(acc, cur, wr, wc, fr, fq); S.done(cur); }
.Lpeel_exit_1:
	s_and_b64 vcc, exec, s[18:19]
	s_cbranch_vccz .LBB0_317
	s_barrier

; #define PG8_LDA(dst, b, h) do { _Pragma("unroll") for (int m = 0; m < 4; ++m) _Pragma("unroll") for (int k = 0; k < 2; ++k) dst[m][k] = *(const PG8_LAS bf16x8*)(lds + PG8_SA(b, h) + aoff + m * 2048 + k * 1024); } while (0)
; template <class Epi, class Sched, bool ALIGN_EPI = false, bool SP2 = false>
; __device__ __forceinline__ void gemm_phase(PG8_LAS unsigned char* lds, const Gemm g, const Sched& S, const Epi& E) {
;     ...
;         const bool has_next = S.next(ui + 1, nxt);
;         const char* nA = has_next ? (const char*)g.A + (size_t)nxt.pm * tstep : cA; const char* nB = has_next ? (const char*)g.Bt + (size_t)nxt.pn * tstep : cB;
;         for (int t = 0; t < nt; t += 2) {
;             const bool last = (t == nt - 2);
;             const char* a1 = cA + (size_t)(t + 1) * kstep;
;             const char* a2 = last ? nA : cA + (size_t)(t + 2) * kstep; const char* b2 = last ? nB : cB + (size_t)(t + 2) * kstep;
;             const char* a3 = a2 + kstep; const char* b3 = b2 + kstep;
;             if (last && has_next) S.a_ready(nxt);
;             if constexpr (SP2) {
;             PG8_LDB(B0, 0, 0); PG8_LDB(B1, 0, 1); PG8_SCHED; PG8_LDA(At, 0, 0); PG8_STAGE(PG8_SA(1, 1), a1 + hstep, voffA);
;             PG8_WAIT_V(8); PG8_WAIT_L(0); PG8_BAR; PG8_MMA(0, 0, At, B0); PG8_MMA(0, 1, At, B1); PG8_BAR; PG8_SCHED;
;             PG8_LDA(At, 0, 1); PG8_STAGE(PG8_SB(0, 0), b2, voffB); PG8_STAGE(PG8_SB(0, 1), b2 + hstep, voffB); PG8_STAGE(PG8_SA(0, 0), a2, voffA);
;             PG8_WAIT_V(8); PG8_WAIT_L(0); PG8_BAR; PG8_MMA(1, 0, At, B0); PG8_MMA(1, 1, At, B1); PG8_BAR; PG8_SCHED;
;             PG8_LDB(B0, 1, 0); PG8_LDB(B1, 1, 1); PG8_SCHED; PG8_LDA(At, 1, 0); PG8_STAGE(PG8_SA(0, 1), a2 + hstep, voffA);
;             PG8_WAIT_V(8); PG8_WAIT_L(0); PG8_BAR; PG8_MMA(0, 0, At, B0); PG8_MMA(0, 1, At, B1); PG8_BAR; PG8_SCHED;
;             PG8_LDA(At, 1, 1); PG8_STAGE(PG8_SB(1, 0), b3, voffB); PG8_STAGE(PG8_SB(1, 1), b3 + hstep, voffB); PG8_STAGE(PG8_SA(1, 0), a3, voffA);
;             PG8_WAIT_V(8); PG8_WAIT_L(0); PG8_BAR; PG8_MMA(1, 0, At, B0); PG8_MMA(1, 1, At, B1); PG8_BAR; PG8_SCHED;
;     ...
; #pragma unroll
;         for (int a = 0; a < 2; ++a)
; #pragma unroll
;             for (int b = 0; b < 2; ++b)
; #pragma unroll
;                 for (int m = 0; m < 4; ++m)
; #pragma unroll
;                     for (int n = 0; n < 2; ++n) acc[a][b][m][n] = (f32x4){0.f, 0.f, 0.f, 0.f};
.LBB0_883:
	s_ashr_i32 s29, s28, 31
	s_lshl_b64 s[30:31], s[28:29], 20
	s_add_u32 s30, s33, s30
	s_addc_u32 s31, s52, s31
	s_and_b64 s[34:35], s[12:13], exec
	s_cselect_b32 s29, s31, s39
	s_cselect_b32 s37, s30, s38
	s_ashr_i32 s27, s26, 31
	s_lshl_b64 s[34:35], s[26:27], 20
	s_add_u32 s34, s53, s34
	s_addc_u32 s35, s54, s35
	s_and_b64 s[42:43], s[12:13], exec
	s_cselect_b32 s27, s35, s41
	s_cselect_b32 s50, s34, s40
	s_add_u32 s38, s38, 0x80080
	s_addc_u32 s39, s39, 0
	s_add_u32 s51, s40, 0x100
	s_addc_u32 s66, s41, 0
	s_mov_b32 s67, -2
	s_waitcnt lgkmcnt(0)
	ds_read_b128 v[100:103], v225
	ds_read_b128 v[108:111], v225 offset:1024
	ds_read_b128 v[124:127], v225 offset:2048
	ds_read_b128 v[132:135], v225 offset:3072
	ds_read_b128 v[144:147], v226
	ds_read_b128 v[148:151], v226 offset:1024
	ds_read_b128 v[152:155], v226 offset:2048
	ds_read_b128 v[156:159], v226 offset:3072
	s_add_u32 s40, s38, 0xfff80080
	s_addc_u32 s41, s39, -1
	s_cmp_eq_u32 s67, 28
	s_cselect_b32 s43, s29, s41
	s_cselect_b32 s42, s37, s40
	s_cselect_b32 s41, s27, s66
	s_cselect_b32 s40, s50, s51
	v_lshl_add_u64 v[208:209], s[38:39], 0, v[192:193]
	s_add_i32 m0, s56, 0xc000
	ds_read_b128 v[160:163], v227
	ds_read_b128 v[164:167], v227 offset:1024
	ds_read_b128 v[168:171], v227 offset:2048
	ds_read_b128 v[172:175], v227 offset:3072
	ds_read_b128 v[176:179], v227 offset:4096
	ds_read_b128 v[180:183], v227 offset:5120
	ds_read_b128 v[200:203], v227 offset:6144
	ds_read_b128 v[204:207], v227 offset:7168
	global_load_lds_dwordx4 v[208:209], off
	v_lshl_add_u64 v[208:209], s[38:39], 0, v[194:195]
	s_add_i32 m0, s56, 0xe000
	s_nop 0
	global_load_lds_dwordx4 v[208:209], off
	s_waitcnt vmcnt(8)
	s_waitcnt lgkmcnt(0)
	s_barrier
	s_setprio 1
	s_waitcnt lgkmcnt(0)
	v_mfma_f32_16x16x32_bf16 v[140:143], v[100:103], v[160:163], 0
	v_mfma_f32_16x16x32_bf16 v[136:139], v[124:127], v[160:163], 0
	v_mfma_f32_16x16x32_bf16 v[116:119], v[100:103], v[168:171], 0
	v_mfma_f32_16x16x32_bf16 v[112:115], v[124:127], v[168:171], 0
	v_mfma_f32_16x16x32_bf16 v[92:95], v[100:103], v[176:179], 0
	v_mfma_f32_16x16x32_bf16 v[88:91], v[124:127], v[176:179], 0
	v_mfma_f32_16x16x32_bf16 v[76:79], v[100:103], v[200:203], 0
	v_mfma_f32_16x16x32_bf16 v[72:75], v[124:127], v[200:203], 0
	v_mfma_f32_16x16x32_bf16 v[140:143], v[108:111], v[164:167], v[140:143]
	v_mfma_f32_16x16x32_bf16 v[136:139], v[132:135], v[164:167], v[136:139]
	v_mfma_f32_16x16x32_bf16 v[116:119], v[108:111], v[172:175], v[116:119]
	v_mfma_f32_16x16x32_bf16 v[112:115], v[132:135], v[172:175], v[112:115]
	v_mfma_f32_16x16x32_bf16 v[92:95], v[108:111], v[180:183], v[92:95]
	v_mfma_f32_16x16x32_bf16 v[88:91], v[132:135], v[180:183], v[88:91]
	v_mfma_f32_16x16x32_bf16 v[76:79], v[108:111], v[204:207], v[76:79]
	v_mfma_f32_16x16x32_bf16 v[72:75], v[132:135], v[204:207], v[72:75]
	s_setprio 0
	s_setprio 1
	v_mfma_f32_16x16x32_bf16 v[128:131], v[144:147], v[160:163], 0
	v_mfma_f32_16x16x32_bf16 v[120:123], v[152:155], v[160:163], 0
	v_mfma_f32_16x16x32_bf16 v[104:107], v[144:147], v[168:171], 0
	v_mfma_f32_16x16x32_bf16 v[96:99], v[152:155], v[168:171], 0
	v_mfma_f32_16x16x32_bf16 v[84:87], v[144:147], v[176:179], 0
	v_mfma_f32_16x16x32_bf16 v[80:83], v[152:155], v[176:179], 0
	v_mfma_f32_16x16x32_bf16 v[68:71], v[144:147], v[200:203], 0
	v_mfma_f32_16x16x32_bf16 v[64:67], v[152:155], v[200:203], 0
	v_mfma_f32_16x16x32_bf16 v[128:131], v[148:151], v[164:167], v[128:131]
	v_mfma_f32_16x16x32_bf16 v[120:123], v[156:159], v[164:167], v[120:123]
	v_mfma_f32_16x16x32_bf16 v[104:107], v[148:151], v[172:175], v[104:107]
	v_mfma_f32_16x16x32_bf16 v[96:99], v[156:159], v[172:175], v[96:99]
	v_mfma_f32_16x16x32_bf16 v[84:87], v[148:151], v[180:183], v[84:87]
	v_mfma_f32_16x16x32_bf16 v[80:83], v[156:159], v[180:183], v[80:83]
	v_mfma_f32_16x16x32_bf16 v[68:71], v[148:151], v[204:207], v[68:71]
	v_mfma_f32_16x16x32_bf16 v[64:67], v[156:159], v[204:207], v[64:67]
	s_setprio 0
	s_barrier
	s_add_i32 s68, s63, s55
	v_lshl_add_u64 v[208:209], s[40:41], 0, v[186:187]
	s_mov_b32 m0, s68
	ds_read_b128 v[160:163], v227 offset:16384
	ds_read_b128 v[164:167], v227 offset:17408
	ds_read_b128 v[168:171], v227 offset:18432
	ds_read_b128 v[172:175], v227 offset:19456
	ds_read_b128 v[176:179], v227 offset:20480
	ds_read_b128 v[180:183], v227 offset:21504
	ds_read_b128 v[200:203], v227 offset:22528
	ds_read_b128 v[204:207], v227 offset:23552
	global_load_lds_dwordx4 v[208:209], off
	s_add_i32 m0, s68, 0x2000
	s_add_u32 s72, s40, 0x80000
	v_lshl_add_u64 v[210:211], s[40:41], 0, v[190:191]
	s_addc_u32 s73, s41, 0
	s_add_i32 s68, s64, s55
	global_load_lds_dwordx4 v[210:211], off
	v_lshl_add_u64 v[212:213], s[72:73], 0, v[186:187]
	s_mov_b32 m0, s68
	v_lshl_add_u64 v[214:215], s[42:43], 0, v[188:189]
	global_load_lds_dwordx4 v[212:213], off
	v_lshl_add_u64 v[212:213], s[72:73], 0, v[190:191]
	s_add_i32 m0, s68, 0x2000
	s_nop 0
	global_load_lds_dwordx4 v[212:213], off
	v_lshl_add_u64 v[212:213], s[42:43], 0, v[184:185]
	s_mov_b32 m0, s56
	s_nop 0
	global_load_lds_dwordx4 v[212:213], off
	s_mov_b32 m0, s57
	s_nop 0
	global_load_lds_dwordx4 v[214:215], off
	s_waitcnt vmcnt(8)
	s_waitcnt lgkmcnt(0)
	s_barrier
; #define PG8_STAGE(bufoff, gbase, voff) do { _Pragma("unroll") for (int _i = 0; _i < 2; ++_i) \
;         __builtin_amdgcn_global_load_lds((const unsigned*)((const char*)(gbase) + (voff)[_i]), (PG8_LAS unsigned*)(lds + (bufoff) + ldsw + _i * 8192), 16, 0, 0); } while (0)
; #define PG8_LDA(dst, b, h) do { _Pragma("unroll") for (int m = 0; m < 4; ++m) _Pragma("unroll") for (int k = 0; k < 2; ++k) dst[m][k] = *(const PG8_LAS bf16x8*)(lds + PG8_SA(b, h) + aoff + m * 2048 + k * 1024); } while (0)
; #define PG8_LDB(dst, b, h) do { _Pragma("unroll") for (int n = 0; n < 2; ++n) _Pragma("unroll") for (int k = 0; k < 2; ++k) dst[n][k] = *(const PG8_LAS bf16x8*)(lds + PG8_SB(b, h) + boff + n * 2048 + k * 1024); } while (0)
; #define PG8_MMA(ai, bj, At, Bt) do { __builtin_amdgcn_s_setprio(1); _Pragma("unroll") for (int m = 0; m < 4; ++m) _Pragma("unroll") for (int n = 0; n < 2; ++n) _Pragma("unroll") for (int k = 0; k < 2; ++k) \
;         acc[ai][bj][m][n] = __builtin_amdgcn_mfma_f32_16x16x32_bf16(Bt[n][k], At[m][k], acc[ai][bj][m][n], 0, 0, 0); __builtin_amdgcn_s_setprio(0); } while (0)
; #define PG8_WAIT_V(n) asm volatile("s_waitcnt vmcnt(" #n ")" ::: "memory")
; #define PG8_WAIT_L(n) asm volatile("s_waitcnt lgkmcnt(" #n ")" ::: "memory")
; #define PG8_BAR __builtin_amdgcn_s_barrier()
; #define PG8_SCHED __builtin_amdgcn_sched_barrier(0)
; template <class Epi, class Sched, bool ALIGN_EPI = false, bool SP2 = false>
; __device__ __forceinline__ void gemm_phase(PG8_LAS unsigned char* lds, const Gemm g, const Sched& S, const Epi& E) {
;     ...
;             PG8_WAIT_V(8); PG8_WAIT_L(0); PG8_BAR; PG8_MMA(1, 0, At, B0); PG8_MMA(1, 1, At, B1); PG8_BAR; PG8_SCHED;
;             PG8_LDB(B0, 1, 0); PG8_LDB(B1, 1, 1); PG8_SCHED; PG8_LDA(At, 1, 0); PG8_STAGE(PG8_SA(0, 1), a2 + hstep, voffA);
;             PG8_WAIT_V(8); PG8_WAIT_L(0); PG8_BAR; PG8_MMA(0, 0, At, B0); PG8_MMA(0, 1, At, B1); PG8_BAR; PG8_SCHED;
	s_setprio 1
	s_waitcnt lgkmcnt(0)
	v_mfma_f32_16x16x32_bf16 v[60:63], v[100:103], v[160:163], 0
	v_mfma_f32_16x16x32_bf16 v[56:59], v[124:127], v[160:163], 0
	v_mfma_f32_16x16x32_bf16 v[44:47], v[100:103], v[168:171], 0
	v_mfma_f32_16x16x32_bf16 v[40:43], v[124:127], v[168:171], 0
	v_mfma_f32_16x16x32_bf16 v[28:31], v[100:103], v[176:179], 0
	v_mfma_f32_16x16x32_bf16 v[24:27], v[124:127], v[176:179], 0
	v_mfma_f32_16x16x32_bf16 v[12:15], v[100:103], v[200:203], 0
	v_mfma_f32_16x16x32_bf16 v[8:11], v[124:127], v[200:203], 0
	v_mfma_f32_16x16x32_bf16 v[60:63], v[108:111], v[164:167], v[60:63]
	v_mfma_f32_16x16x32_bf16 v[56:59], v[132:135], v[164:167], v[56:59]
	v_mfma_f32_16x16x32_bf16 v[44:47], v[108:111], v[172:175], v[44:47]
	v_mfma_f32_16x16x32_bf16 v[40:43], v[132:135], v[172:175], v[40:43]
	v_mfma_f32_16x16x32_bf16 v[28:31], v[108:111], v[180:183], v[28:31]
	v_mfma_f32_16x16x32_bf16 v[24:27], v[132:135], v[180:183], v[24:27]
	v_mfma_f32_16x16x32_bf16 v[12:15], v[108:111], v[204:207], v[12:15]
	v_mfma_f32_16x16x32_bf16 v[8:11], v[132:135], v[204:207], v[8:11]
	s_setprio 0
	s_setprio 1
	v_mfma_f32_16x16x32_bf16 v[52:55], v[144:147], v[160:163], 0
	v_mfma_f32_16x16x32_bf16 v[48:51], v[152:155], v[160:163], 0
	v_mfma_f32_16x16x32_bf16 v[36:39], v[144:147], v[168:171], 0
	v_mfma_f32_16x16x32_bf16 v[32:35], v[152:155], v[168:171], 0
	v_mfma_f32_16x16x32_bf16 v[20:23], v[144:147], v[176:179], 0
	v_mfma_f32_16x16x32_bf16 v[16:19], v[152:155], v[176:179], 0
	v_mfma_f32_16x16x32_bf16 v[4:7], v[144:147], v[200:203], 0
	v_mfma_f32_16x16x32_bf16 v[0:3], v[152:155], v[200:203], 0
	v_mfma_f32_16x16x32_bf16 v[52:55], v[148:151], v[164:167], v[52:55]
	v_mfma_f32_16x16x32_bf16 v[48:51], v[156:159], v[164:167], v[48:51]
	v_mfma_f32_16x16x32_bf16 v[36:39], v[148:151], v[172:175], v[36:39]
	v_mfma_f32_16x16x32_bf16 v[32:35], v[156:159], v[172:175], v[32:35]
	v_mfma_f32_16x16x32_bf16 v[20:23], v[148:151], v[180:183], v[20:23]
	v_mfma_f32_16x16x32_bf16 v[16:19], v[156:159], v[180:183], v[16:19]
	v_mfma_f32_16x16x32_bf16 v[4:7], v[148:151], v[204:207], v[4:7]
	v_mfma_f32_16x16x32_bf16 v[0:3], v[156:159], v[204:207], v[0:3]
	s_setprio 0
	s_barrier
	s_add_i32 s68, 0, 0x18000
	s_add_i32 s71, 0, 0x1c000
	v_add_u32_e32 v132, s68, v223
	v_add_u32_e32 v156, s71, v223
	ds_read_b128 v[100:103], v132
	ds_read_b128 v[108:111], v132 offset:1024
	ds_read_b128 v[124:127], v132 offset:2048
	ds_read_b128 v[132:135], v132 offset:3072
	ds_read_b128 v[144:147], v156
	ds_read_b128 v[148:151], v156 offset:1024
	ds_read_b128 v[152:155], v156 offset:2048
	ds_read_b128 v[156:159], v156 offset:3072
	s_add_u32 s42, s42, 0x80000
	s_addc_u32 s43, s43, 0
	s_mov_b32 m0, s58
	v_lshl_add_u64 v[216:217], s[42:43], 0, v[184:185]
	ds_read_b128 v[160:163], v227 offset:32768
	ds_read_b128 v[164:167], v227 offset:33792
	ds_read_b128 v[168:171], v227 offset:34816
	ds_read_b128 v[172:175], v227 offset:35840
	ds_read_b128 v[176:179], v227 offset:36864
	ds_read_b128 v[180:183], v227 offset:37888
	ds_read_b128 v[200:203], v227 offset:38912
	ds_read_b128 v[204:207], v227 offset:39936
	global_load_lds_dwordx4 v[216:217], off
	v_lshl_add_u64 v[216:217], s[42:43], 0, v[188:189]
	s_mov_b32 m0, s59
	s_nop 0
	global_load_lds_dwordx4 v[216:217], off
	s_waitcnt vmcnt(8)
	s_waitcnt lgkmcnt(0)
	s_barrier
	s_setprio 1
	s_waitcnt lgkmcnt(0)
	v_mfma_f32_16x16x32_bf16 v[140:143], v[100:103], v[160:163], v[140:143]
	v_mfma_f32_16x16x32_bf16 v[136:139], v[124:127], v[160:163], v[136:139]
	v_mfma_f32_16x16x32_bf16 v[116:119], v[100:103], v[168:171], v[116:119]
	v_mfma_f32_16x16x32_bf16 v[112:115], v[124:127], v[168:171], v[112:115]
	v_mfma_f32_16x16x32_bf16 v[92:95], v[100:103], v[176:179], v[92:95]
	v_mfma_f32_16x16x32_bf16 v[88:91], v[124:127], v[176:179], v[88:91]
	v_mfma_f32_16x16x32_bf16 v[76:79], v[100:103], v[200:203], v[76:79]
	v_mfma_f32_16x16x32_bf16 v[72:75], v[124:127], v[200:203], v[72:75]
	v_mfma_f32_16x16x32_bf16 v[140:143], v[108:111], v[164:167], v[140:143]
	v_mfma_f32_16x16x32_bf16 v[136:139], v[132:135], v[164:167], v[136:139]
	v_mfma_f32_16x16x32_bf16 v[116:119], v[108:111], v[172:175], v[116:119]
	v_mfma_f32_16x16x32_bf16 v[112:115], v[132:135], v[172:175], v[112:115]
	v_mfma_f32_16x16x32_bf16 v[92:95], v[108:111], v[180:183], v[92:95]
	v_mfma_f32_16x16x32_bf16 v[88:91], v[132:135], v[180:183], v[88:91]
	v_mfma_f32_16x16x32_bf16 v[76:79], v[108:111], v[204:207], v[76:79]
	v_mfma_f32_16x16x32_bf16 v[72:75], v[132:135], v[204:207], v[72:75]
	s_setprio 0
	s_setprio 1
	v_mfma_f32_16x16x32_bf16 v[128:131], v[144:147], v[160:163], v[128:131]
	v_mfma_f32_16x16x32_bf16 v[120:123], v[152:155], v[160:163], v[120:123]
	v_mfma_f32_16x16x32_bf16 v[104:107], v[144:147], v[168:171], v[104:107]
	v_mfma_f32_16x16x32_bf16 v[96:99], v[152:155], v[168:171], v[96:99]
	v_mfma_f32_16x16x32_bf16 v[84:87], v[144:147], v[176:179], v[84:87]
	v_mfma_f32_16x16x32_bf16 v[80:83], v[152:155], v[176:179], v[80:83]
	v_mfma_f32_16x16x32_bf16 v[68:71], v[144:147], v[200:203], v[68:71]
	v_mfma_f32_16x16x32_bf16 v[64:67], v[152:155], v[200:203], v[64:67]
	v_mfma_f32_16x16x32_bf16 v[128:131], v[148:151], v[164:167], v[128:131]
	v_mfma_f32_16x16x32_bf16 v[120:123], v[156:159], v[164:167], v[120:123]
	v_mfma_f32_16x16x32_bf16 v[104:107], v[148:151], v[172:175], v[104:107]
	v_mfma_f32_16x16x32_bf16 v[96:99], v[156:159], v[172:175], v[96:99]
	v_mfma_f32_16x16x32_bf16 v[84:87], v[148:151], v[180:183], v[84:87]
	v_mfma_f32_16x16x32_bf16 v[80:83], v[156:159], v[180:183], v[80:83]
	v_mfma_f32_16x16x32_bf16 v[68:71], v[148:151], v[204:207], v[68:71]
	v_mfma_f32_16x16x32_bf16 v[64:67], v[156:159], v[204:207], v[64:67]
	s_setprio 0
	s_barrier
; #define PG8_STAGE(bufoff, gbase, voff) do { _Pragma("unroll") for (int _i = 0; _i < 2; ++_i) \
;         __builtin_amdgcn_global_load_lds((const unsigned*)((const char*)(gbase) + (voff)[_i]), (PG8_LAS unsigned*)(lds + (bufoff) + ldsw + _i * 8192), 16, 0, 0); } while (0)
; #define PG8_LDA(dst, b, h) do { _Pragma("unroll") for (int m = 0; m < 4; ++m) _Pragma("unroll") for (int k = 0; k < 2; ++k) dst[m][k] = *(const PG8_LAS bf16x8*)(lds + PG8_SA(b, h) + aoff + m * 2048 + k * 1024); } while (0)
; #define PG8_MMA(ai, bj, At, Bt) do { __builtin_amdgcn_s_setprio(1); _Pragma("unroll") for (int m = 0; m < 4; ++m) _Pragma("unroll") for (int n = 0; n < 2; ++n) _Pragma("unroll") for (int k = 0; k < 2; ++k) \
;         acc[ai][bj][m][n] = __builtin_amdgcn_mfma_f32_16x16x32_bf16(Bt[n][k], At[m][k], acc[ai][bj][m][n], 0, 0, 0); __builtin_amdgcn_s_setprio(0); } while (0)
; #define PG8_WAIT_V(n) asm volatile("s_waitcnt vmcnt(" #n ")" ::: "memory")
; #define PG8_WAIT_L(n) asm volatile("s_waitcnt lgkmcnt(" #n ")" ::: "memory")
; #define PG8_BAR __builtin_amdgcn_s_barrier()
; #define PG8_SCHED __builtin_amdgcn_sched_barrier(0)
; template <class Epi, class Sched, bool ALIGN_EPI = false, bool SP2 = false>
; __device__ __forceinline__ void gemm_phase(PG8_LAS unsigned char* lds, const Gemm g, const Sched& S, const Epi& E) {
;     ...
;         for (int t = 0; t < nt; t += 2) {
;             const bool last = (t == nt - 2);
;             const char* a1 = cA + (size_t)(t + 1) * kstep;
;             const char* a2 = last ? nA : cA + (size_t)(t + 2) * kstep; const char* b2 = last ? nB : cB + (size_t)(t + 2) * kstep;
;             const char* a3 = a2 + kstep; const char* b3 = b2 + kstep;
;             if (last && has_next) S.a_ready(nxt);
;     ...
;             PG8_LDA(At, 1, 1); PG8_STAGE(PG8_SB(1, 0), b3, voffB); PG8_STAGE(PG8_SB(1, 1), b3 + hstep, voffB); PG8_STAGE(PG8_SA(1, 0), a3, voffA);
;             PG8_WAIT_V(8); PG8_WAIT_L(0); PG8_BAR; PG8_MMA(1, 0, At, B0); PG8_MMA(1, 1, At, B1); PG8_BAR; PG8_SCHED;
	s_add_i32 s42, s68, s55
	v_lshl_add_u64 v[208:209], v[208:209], 0, s[22:23]
	s_mov_b32 m0, s42
	ds_read_b128 v[160:163], v227 offset:49152
	ds_read_b128 v[164:167], v227 offset:50176
	ds_read_b128 v[168:171], v227 offset:51200
	ds_read_b128 v[172:175], v227 offset:52224
	ds_read_b128 v[176:179], v227 offset:53248
	ds_read_b128 v[180:183], v227 offset:54272
	ds_read_b128 v[200:203], v227 offset:55296
	ds_read_b128 v[204:207], v227 offset:56320
	global_load_lds_dwordx4 v[208:209], off
	s_add_i32 m0, s42, 0x2000
	s_add_u32 s40, s40, 0x80080
	v_lshl_add_u64 v[208:209], v[210:211], 0, s[22:23]
	s_addc_u32 s41, s41, 0
	s_add_i32 s42, s71, s55
	global_load_lds_dwordx4 v[208:209], off
	v_lshl_add_u64 v[208:209], s[40:41], 0, v[186:187]
	s_mov_b32 m0, s42
	s_nop 0
	global_load_lds_dwordx4 v[208:209], off
	v_lshl_add_u64 v[208:209], s[40:41], 0, v[190:191]
	s_add_i32 m0, s42, 0x2000
	s_nop 0
	global_load_lds_dwordx4 v[208:209], off
	v_lshl_add_u64 v[208:209], v[212:213], 0, s[22:23]
	s_mov_b32 m0, s61
	s_nop 0
	global_load_lds_dwordx4 v[208:209], off
	v_lshl_add_u64 v[208:209], v[214:215], 0, s[22:23]
	s_mov_b32 m0, s62
	s_nop 0
	global_load_lds_dwordx4 v[208:209], off
	s_waitcnt vmcnt(8)
	s_waitcnt lgkmcnt(0)
	s_barrier
	s_setprio 1
	s_waitcnt lgkmcnt(0)
	v_mfma_f32_16x16x32_bf16 v[60:63], v[100:103], v[160:163], v[60:63]
	v_mfma_f32_16x16x32_bf16 v[56:59], v[124:127], v[160:163], v[56:59]
	v_mfma_f32_16x16x32_bf16 v[44:47], v[100:103], v[168:171], v[44:47]
	v_mfma_f32_16x16x32_bf16 v[40:43], v[124:127], v[168:171], v[40:43]
	v_mfma_f32_16x16x32_bf16 v[28:31], v[100:103], v[176:179], v[28:31]
	v_mfma_f32_16x16x32_bf16 v[24:27], v[124:127], v[176:179], v[24:27]
	v_mfma_f32_16x16x32_bf16 v[12:15], v[100:103], v[200:203], v[12:15]
	v_mfma_f32_16x16x32_bf16 v[8:11], v[124:127], v[200:203], v[8:11]
	v_mfma_f32_16x16x32_bf16 v[60:63], v[108:111], v[164:167], v[60:63]
	v_mfma_f32_16x16x32_bf16 v[56:59], v[132:135], v[164:167], v[56:59]
	v_mfma_f32_16x16x32_bf16 v[44:47], v[108:111], v[172:175], v[44:47]
	v_mfma_f32_16x16x32_bf16 v[40:43], v[132:135], v[172:175], v[40:43]
	v_mfma_f32_16x16x32_bf16 v[28:31], v[108:111], v[180:183], v[28:31]
	v_mfma_f32_16x16x32_bf16 v[24:27], v[132:135], v[180:183], v[24:27]
	v_mfma_f32_16x16x32_bf16 v[12:15], v[108:111], v[204:207], v[12:15]
	v_mfma_f32_16x16x32_bf16 v[8:11], v[132:135], v[204:207], v[8:11]
	s_setprio 0
	s_setprio 1
	v_mfma_f32_16x16x32_bf16 v[52:55], v[144:147], v[160:163], v[52:55]
	v_mfma_f32_16x16x32_bf16 v[48:51], v[152:155], v[160:163], v[48:51]
	v_mfma_f32_16x16x32_bf16 v[36:39], v[144:147], v[168:171], v[36:39]
	v_mfma_f32_16x16x32_bf16 v[32:35], v[152:155], v[168:171], v[32:35]
	v_mfma_f32_16x16x32_bf16 v[20:23], v[144:147], v[176:179], v[20:23]
	v_mfma_f32_16x16x32_bf16 v[16:19], v[152:155], v[176:179], v[16:19]
	v_mfma_f32_16x16x32_bf16 v[4:7], v[144:147], v[200:203], v[4:7]
	v_mfma_f32_16x16x32_bf16 v[0:3], v[152:155], v[200:203], v[0:3]
	v_mfma_f32_16x16x32_bf16 v[52:55], v[148:151], v[164:167], v[52:55]
	v_mfma_f32_16x16x32_bf16 v[48:51], v[156:159], v[164:167], v[48:51]
	v_mfma_f32_16x16x32_bf16 v[36:39], v[148:151], v[172:175], v[36:39]
	v_mfma_f32_16x16x32_bf16 v[32:35], v[156:159], v[172:175], v[32:35]
	v_mfma_f32_16x16x32_bf16 v[20:23], v[148:151], v[180:183], v[20:23]
	v_mfma_f32_16x16x32_bf16 v[16:19], v[156:159], v[180:183], v[16:19]
	v_mfma_f32_16x16x32_bf16 v[4:7], v[148:151], v[204:207], v[4:7]
	v_mfma_f32_16x16x32_bf16 v[0:3], v[156:159], v[204:207], v[0:3]
	s_setprio 0
	s_barrier
	s_add_i32 s67, s67, 2
	s_add_u32 s38, s38, 0x100
	s_addc_u32 s39, s39, 0
	s_add_u32 s51, s51, 0x100
	s_addc_u32 s66, s66, 0
	s_cmp_gt_u32 s67, 29
	s_cbranch_scc0 .LBB0_884
	s_branch .Lpeel_exit_2

; #define PG8_BAR __builtin_amdgcn_s_barrier()
; template <class Epi, class Sched, bool ALIGN_EPI = false, bool SP2 = false>
; __device__ __forceinline__ void gemm_phase(PG8_LAS unsigned char* lds, const Gemm g, const Sched& S, const Epi& E) {
;     ...
;         if constexpr (ALIGN_EPI) { if (wr == 0) PG8_BAR; }
;         if constexpr (!Epi::AFTER_DRAIN) { E(acc, cur, wr, wc, fr, fq); S.done(cur); }
.Lpeel_exit_2:
	s_and_b64 vcc, exec, s[24:25]
	s_cbranch_vccz .LBB0_887
	s_barrier

; #define PG8_LDA(dst, b, h) do { _Pragma("unroll") for (int m = 0; m < 4; ++m) _Pragma("unroll") for (int k = 0; k < 2; ++k) dst[m][k] = *(const PG8_LAS bf16x8*)(lds + PG8_SA(b, h) + aoff + m * 2048 + k * 1024); } while (0)
; template <class Epi, class Sched, bool ALIGN_EPI = false, bool SP2 = false>
; __device__ __forceinline__ void gemm_phase(PG8_LAS unsigned char* lds, const Gemm g, const Sched& S, const Epi& E) {
;     ...
;         const bool has_next = S.next(ui + 1, nxt);
;         const char* nA = has_next ? (const char*)g.A + (size_t)nxt.pm * tstep : cA; const char* nB = has_next ? (const char*)g.Bt + (size_t)nxt.pn * tstep : cB;
;         for (int t = 0; t < nt; t += 2) {
;             const bool last = (t == nt - 2);
;             const char* a1 = cA + (size_t)(t + 1) * kstep;
;             const char* a2 = last ? nA : cA + (size_t)(t + 2) * kstep; const char* b2 = last ? nB : cB + (size_t)(t + 2) * kstep;
;             const char* a3 = a2 + kstep; const char* b3 = b2 + kstep;
;             if (last && has_next) S.a_ready(nxt);
;             if constexpr (SP2) {
;             PG8_LDB(B0, 0, 0); PG8_LDB(B1, 0, 1); PG8_SCHED; PG8_LDA(At, 0, 0); PG8_STAGE(PG8_SA(1, 1), a1 + hstep, voffA);
;             PG8_WAIT_V(8); PG8_WAIT_L(0); PG8_BAR; PG8_MMA(0, 0, At, B0); PG8_MMA(0, 1, At, B1); PG8_BAR; PG8_SCHED;
;             PG8_LDA(At, 0, 1); PG8_STAGE(PG8_SB(0, 0), b2, voffB); PG8_STAGE(PG8_SB(0, 1), b2 + hstep, voffB); PG8_STAGE(PG8_SA(0, 0), a2, voffA);
;             PG8_WAIT_V(8); PG8_WAIT_L(0); PG8_BAR; PG8_MMA(1, 0, At, B0); PG8_MMA(1, 1, At, B1); PG8_BAR; PG8_SCHED;
;             PG8_LDB(B0, 1, 0); PG8_LDB(B1, 1, 1); PG8_SCHED; PG8_LDA(At, 1, 0); PG8_STAGE(PG8_SA(0, 1), a2 + hstep, voffA);
;             PG8_WAIT_V(8); PG8_WAIT_L(0); PG8_BAR; PG8_MMA(0, 0, At, B0); PG8_MMA(0, 1, At, B1); PG8_BAR; PG8_SCHED;
;             PG8_LDA(At, 1, 1); PG8_STAGE(PG8_SB(1, 0), b3, voffB); PG8_STAGE(PG8_SB(1, 1), b3 + hstep, voffB); PG8_STAGE(PG8_SA(1, 0), a3, voffA);
;             PG8_WAIT_V(8); PG8_WAIT_L(0); PG8_BAR; PG8_MMA(1, 0, At, B0); PG8_MMA(1, 1, At, B1); PG8_BAR; PG8_SCHED;
;     ...
; #pragma unroll
;         for (int a = 0; a < 2; ++a)
; #pragma unroll
;             for (int b = 0; b < 2; ++b)
; #pragma unroll
;                 for (int m = 0; m < 4; ++m)
; #pragma unroll
;                     for (int n = 0; n < 2; ++n) acc[a][b][m][n] = (f32x4){0.f, 0.f, 0.f, 0.f};
.LBB0_988:
	s_ashr_i32 s53, s52, 31
	s_lshl_b64 s[50:51], s[52:53], 20
	s_add_u32 s54, s74, s50
	s_addc_u32 s55, s75, s51
	s_and_b64 s[50:51], s[16:17], exec
	s_cselect_b32 s50, s55, s63
	s_cselect_b32 s51, s54, s62
	s_ashr_i32 s43, s42, 31
	s_lshl_b64 s[56:57], s[42:43], 20
	s_add_u32 s56, s76, s56
	s_addc_u32 s57, s77, s57
	s_and_b64 s[66:67], s[16:17], exec
	s_cselect_b32 s43, s57, s65
	s_cselect_b32 s53, s56, s64
	s_add_u32 s62, s62, 0x80080
	s_addc_u32 s63, s63, 0
	s_add_u32 s59, s64, 0x100
	s_addc_u32 s71, s65, 0
	s_mov_b32 s90, -2
	ds_read_b128 v[128:131], v241
	ds_read_b128 v[132:135], v241 offset:1024
	ds_read_b128 v[136:139], v241 offset:2048
	ds_read_b128 v[140:143], v241 offset:3072
	ds_read_b128 v[144:147], v242
	ds_read_b128 v[148:151], v242 offset:1024
	ds_read_b128 v[170:173], v242 offset:2048
	ds_read_b128 v[174:177], v242 offset:3072
	s_add_u32 s64, s62, 0xfff80080
	s_addc_u32 s65, s63, -1
	s_cmp_eq_u32 s90, 28
	s_cselect_b32 s67, s50, s65
	s_cselect_b32 s66, s51, s64
	s_cselect_b32 s65, s43, s71
	s_cselect_b32 s64, s53, s59
	v_lshl_add_u64 v[152:153], s[62:63], 0, v[162:163]
	s_add_i32 m0, s61, 0xc000
	ds_read_b128 v[178:181], v243
	ds_read_b128 v[182:185], v243 offset:1024
	ds_read_b128 v[186:189], v243 offset:2048
	ds_read_b128 v[190:193], v243 offset:3072
	ds_read_b128 v[194:197], v243 offset:4096
	ds_read_b128 v[198:201], v243 offset:5120
	ds_read_b128 v[202:205], v243 offset:6144
	ds_read_b128 v[206:209], v243 offset:7168
	global_load_lds_dwordx4 v[152:153], off
	v_lshl_add_u64 v[152:153], s[62:63], 0, v[164:165]
	s_add_i32 m0, s61, 0xe000
	s_nop 0
	global_load_lds_dwordx4 v[152:153], off
	s_waitcnt vmcnt(8)
	s_waitcnt lgkmcnt(0)
	s_barrier
	s_setprio 1
	s_waitcnt lgkmcnt(0)
	v_mfma_f32_16x16x32_bf16 v[112:115], v[128:131], v[178:181], 0
	v_mfma_f32_16x16x32_bf16 v[80:83], v[136:139], v[178:181], 0
	v_mfma_f32_16x16x32_bf16 v[116:119], v[128:131], v[186:189], 0
	v_mfma_f32_16x16x32_bf16 v[84:87], v[136:139], v[186:189], 0
	v_mfma_f32_16x16x32_bf16 v[120:123], v[128:131], v[194:197], 0
	v_mfma_f32_16x16x32_bf16 v[88:91], v[136:139], v[194:197], 0
	v_mfma_f32_16x16x32_bf16 v[124:127], v[128:131], v[202:205], 0
	v_mfma_f32_16x16x32_bf16 v[92:95], v[136:139], v[202:205], 0
	v_mfma_f32_16x16x32_bf16 v[112:115], v[132:135], v[182:185], v[112:115]
	v_mfma_f32_16x16x32_bf16 v[80:83], v[140:143], v[182:185], v[80:83]
	v_mfma_f32_16x16x32_bf16 v[116:119], v[132:135], v[190:193], v[116:119]
	v_mfma_f32_16x16x32_bf16 v[84:87], v[140:143], v[190:193], v[84:87]
	v_mfma_f32_16x16x32_bf16 v[120:123], v[132:135], v[198:201], v[120:123]
	v_mfma_f32_16x16x32_bf16 v[88:91], v[140:143], v[198:201], v[88:91]
	v_mfma_f32_16x16x32_bf16 v[124:127], v[132:135], v[206:209], v[124:127]
	v_mfma_f32_16x16x32_bf16 v[92:95], v[140:143], v[206:209], v[92:95]
	s_setprio 0
	s_setprio 1
	v_mfma_f32_16x16x32_bf16 v[96:99], v[144:147], v[178:181], 0
	v_mfma_f32_16x16x32_bf16 v[64:67], v[170:173], v[178:181], 0
	v_mfma_f32_16x16x32_bf16 v[100:103], v[144:147], v[186:189], 0
	v_mfma_f32_16x16x32_bf16 v[68:71], v[170:173], v[186:189], 0
	v_mfma_f32_16x16x32_bf16 v[104:107], v[144:147], v[194:197], 0
	v_mfma_f32_16x16x32_bf16 v[72:75], v[170:173], v[194:197], 0
	v_mfma_f32_16x16x32_bf16 v[108:111], v[144:147], v[202:205], 0
	v_mfma_f32_16x16x32_bf16 v[76:79], v[170:173], v[202:205], 0
	v_mfma_f32_16x16x32_bf16 v[96:99], v[148:151], v[182:185], v[96:99]
	v_mfma_f32_16x16x32_bf16 v[64:67], v[174:177], v[182:185], v[64:67]
	v_mfma_f32_16x16x32_bf16 v[100:103], v[148:151], v[190:193], v[100:103]
	v_mfma_f32_16x16x32_bf16 v[68:71], v[174:177], v[190:193], v[68:71]
	v_mfma_f32_16x16x32_bf16 v[104:107], v[148:151], v[198:201], v[104:107]
	v_mfma_f32_16x16x32_bf16 v[72:75], v[174:177], v[198:201], v[72:75]
	v_mfma_f32_16x16x32_bf16 v[108:111], v[148:151], v[206:209], v[108:111]
	v_mfma_f32_16x16x32_bf16 v[76:79], v[174:177], v[206:209], v[76:79]
	s_setprio 0
	s_barrier
	s_add_i32 s91, s11, s73
	v_lshl_add_u64 v[152:153], s[64:65], 0, v[156:157]
	s_mov_b32 m0, s91
	ds_read_b128 v[178:181], v243 offset:16384
	ds_read_b128 v[182:185], v243 offset:17408
	ds_read_b128 v[186:189], v243 offset:18432
	ds_read_b128 v[190:193], v243 offset:19456
	ds_read_b128 v[194:197], v243 offset:20480
	ds_read_b128 v[198:201], v243 offset:21504
	ds_read_b128 v[202:205], v243 offset:22528
	ds_read_b128 v[206:209], v243 offset:23552
	global_load_lds_dwordx4 v[152:153], off
	s_add_i32 m0, s91, 0x2000
	s_add_u32 s92, s64, 0x80000
	v_lshl_add_u64 v[210:211], s[64:65], 0, v[160:161]
	s_addc_u32 s93, s65, 0
	s_add_i32 s91, s85, s73
	global_load_lds_dwordx4 v[210:211], off
	v_lshl_add_u64 v[212:213], s[92:93], 0, v[156:157]
	s_mov_b32 m0, s91
	v_lshl_add_u64 v[214:215], s[66:67], 0, v[158:159]
	global_load_lds_dwordx4 v[212:213], off
	v_lshl_add_u64 v[212:213], s[92:93], 0, v[160:161]
	s_add_i32 m0, s91, 0x2000
	s_nop 0
	global_load_lds_dwordx4 v[212:213], off
	v_lshl_add_u64 v[212:213], s[66:67], 0, v[154:155]
	s_mov_b32 m0, s61
	s_nop 0
	global_load_lds_dwordx4 v[212:213], off
	s_mov_b32 m0, s78
	s_nop 0
	global_load_lds_dwordx4 v[214:215], off
	s_waitcnt vmcnt(8)
	s_waitcnt lgkmcnt(0)
	s_barrier
; #define PG8_STAGE(bufoff, gbase, voff) do { _Pragma("unroll") for (int _i = 0; _i < 2; ++_i) \
;         __builtin_amdgcn_global_load_lds((const unsigned*)((const char*)(gbase) + (voff)[_i]), (PG8_LAS unsigned*)(lds + (bufoff) + ldsw + _i * 8192), 16, 0, 0); } while (0)
; #define PG8_LDA(dst, b, h) do { _Pragma("unroll") for (int m = 0; m < 4; ++m) _Pragma("unroll") for (int k = 0; k < 2; ++k) dst[m][k] = *(const PG8_LAS bf16x8*)(lds + PG8_SA(b, h) + aoff + m * 2048 + k * 1024); } while (0)
; #define PG8_LDB(dst, b, h) do { _Pragma("unroll") for (int n = 0; n < 2; ++n) _Pragma("unroll") for (int k = 0; k < 2; ++k) dst[n][k] = *(const PG8_LAS bf16x8*)(lds + PG8_SB(b, h) + boff + n * 2048 + k * 1024); } while (0)
; #define PG8_MMA(ai, bj, At, Bt) do { __builtin_amdgcn_s_setprio(1); _Pragma("unroll") for (int m = 0; m < 4; ++m) _Pragma("unroll") for (int n = 0; n < 2; ++n) _Pragma("unroll") for (int k = 0; k < 2; ++k) \
;         acc[ai][bj][m][n] = __builtin_amdgcn_mfma_f32_16x16x32_bf16(Bt[n][k], At[m][k], acc[ai][bj][m][n], 0, 0, 0); __builtin_amdgcn_s_setprio(0); } while (0)
; #define PG8_WAIT_V(n) asm volatile("s_waitcnt vmcnt(" #n ")" ::: "memory")
; #define PG8_WAIT_L(n) asm volatile("s_waitcnt lgkmcnt(" #n ")" ::: "memory")
; #define PG8_BAR __builtin_amdgcn_s_barrier()
; #define PG8_SCHED __builtin_amdgcn_sched_barrier(0)
; template <class Epi, class Sched, bool ALIGN_EPI = false, bool SP2 = false>
; __device__ __forceinline__ void gemm_phase(PG8_LAS unsigned char* lds, const Gemm g, const Sched& S, const Epi& E) {
;     ...
;             PG8_WAIT_V(8); PG8_WAIT_L(0); PG8_BAR; PG8_MMA(1, 0, At, B0); PG8_MMA(1, 1, At, B1); PG8_BAR; PG8_SCHED;
;             PG8_LDB(B0, 1, 0); PG8_LDB(B1, 1, 1); PG8_SCHED; PG8_LDA(At, 1, 0); PG8_STAGE(PG8_SA(0, 1), a2 + hstep, voffA);
;             PG8_WAIT_V(8); PG8_WAIT_L(0); PG8_BAR; PG8_MMA(0, 0, At, B0); PG8_MMA(0, 1, At, B1); PG8_BAR; PG8_SCHED;
	s_setprio 1
	s_waitcnt lgkmcnt(0)
	v_mfma_f32_16x16x32_bf16 v[48:51], v[128:131], v[178:181], 0
	v_mfma_f32_16x16x32_bf16 v[16:19], v[136:139], v[178:181], 0
	v_mfma_f32_16x16x32_bf16 v[52:55], v[128:131], v[186:189], 0
	v_mfma_f32_16x16x32_bf16 v[20:23], v[136:139], v[186:189], 0
	v_mfma_f32_16x16x32_bf16 v[56:59], v[128:131], v[194:197], 0
	v_mfma_f32_16x16x32_bf16 v[24:27], v[136:139], v[194:197], 0
	v_mfma_f32_16x16x32_bf16 v[60:63], v[128:131], v[202:205], 0
	v_mfma_f32_16x16x32_bf16 v[28:31], v[136:139], v[202:205], 0
	v_mfma_f32_16x16x32_bf16 v[48:51], v[132:135], v[182:185], v[48:51]
	v_mfma_f32_16x16x32_bf16 v[16:19], v[140:143], v[182:185], v[16:19]
	v_mfma_f32_16x16x32_bf16 v[52:55], v[132:135], v[190:193], v[52:55]
	v_mfma_f32_16x16x32_bf16 v[20:23], v[140:143], v[190:193], v[20:23]
	v_mfma_f32_16x16x32_bf16 v[56:59], v[132:135], v[198:201], v[56:59]
	v_mfma_f32_16x16x32_bf16 v[24:27], v[140:143], v[198:201], v[24:27]
	v_mfma_f32_16x16x32_bf16 v[60:63], v[132:135], v[206:209], v[60:63]
	v_mfma_f32_16x16x32_bf16 v[28:31], v[140:143], v[206:209], v[28:31]
	s_setprio 0
	s_setprio 1
	v_mfma_f32_16x16x32_bf16 v[32:35], v[144:147], v[178:181], 0
	v_mfma_f32_16x16x32_bf16 v[0:3], v[170:173], v[178:181], 0
	v_mfma_f32_16x16x32_bf16 v[36:39], v[144:147], v[186:189], 0
	v_mfma_f32_16x16x32_bf16 v[4:7], v[170:173], v[186:189], 0
	v_mfma_f32_16x16x32_bf16 v[40:43], v[144:147], v[194:197], 0
	v_mfma_f32_16x16x32_bf16 v[8:11], v[170:173], v[194:197], 0
	v_mfma_f32_16x16x32_bf16 v[44:47], v[144:147], v[202:205], 0
	v_mfma_f32_16x16x32_bf16 v[12:15], v[170:173], v[202:205], 0
	v_mfma_f32_16x16x32_bf16 v[32:35], v[148:151], v[182:185], v[32:35]
	v_mfma_f32_16x16x32_bf16 v[0:3], v[174:177], v[182:185], v[0:3]
	v_mfma_f32_16x16x32_bf16 v[36:39], v[148:151], v[190:193], v[36:39]
	v_mfma_f32_16x16x32_bf16 v[4:7], v[174:177], v[190:193], v[4:7]
	v_mfma_f32_16x16x32_bf16 v[40:43], v[148:151], v[198:201], v[40:43]
	v_mfma_f32_16x16x32_bf16 v[8:11], v[174:177], v[198:201], v[8:11]
	v_mfma_f32_16x16x32_bf16 v[44:47], v[148:151], v[206:209], v[44:47]
	v_mfma_f32_16x16x32_bf16 v[12:15], v[174:177], v[206:209], v[12:15]
	s_setprio 0
	s_barrier
	s_add_i32 s91, 0, 0x18000
	s_add_i32 s92, 0, 0x1c000
	v_add_u32_e32 v140, s91, v237
	v_add_u32_e32 v174, s92, v237
	ds_read_b128 v[128:131], v140
	ds_read_b128 v[132:135], v140 offset:1024
	ds_read_b128 v[136:139], v140 offset:2048
	ds_read_b128 v[140:143], v140 offset:3072
	ds_read_b128 v[144:147], v174
	ds_read_b128 v[148:151], v174 offset:1024
	ds_read_b128 v[170:173], v174 offset:2048
	ds_read_b128 v[174:177], v174 offset:3072
	s_add_u32 s66, s66, 0x80000
	s_addc_u32 s67, s67, 0
	s_mov_b32 m0, s79
	v_lshl_add_u64 v[216:217], s[66:67], 0, v[154:155]
	ds_read_b128 v[178:181], v243 offset:32768
	ds_read_b128 v[182:185], v243 offset:33792
	ds_read_b128 v[186:189], v243 offset:34816
	ds_read_b128 v[190:193], v243 offset:35840
	ds_read_b128 v[194:197], v243 offset:36864
	ds_read_b128 v[198:201], v243 offset:37888
	ds_read_b128 v[202:205], v243 offset:38912
	ds_read_b128 v[206:209], v243 offset:39936
	global_load_lds_dwordx4 v[216:217], off
	v_lshl_add_u64 v[216:217], s[66:67], 0, v[158:159]
	s_mov_b32 m0, s80
	s_nop 0
	global_load_lds_dwordx4 v[216:217], off
	s_waitcnt vmcnt(8)
	s_waitcnt lgkmcnt(0)
	s_barrier
	s_setprio 1
	s_waitcnt lgkmcnt(0)
	v_mfma_f32_16x16x32_bf16 v[112:115], v[128:131], v[178:181], v[112:115]
	v_mfma_f32_16x16x32_bf16 v[80:83], v[136:139], v[178:181], v[80:83]
	v_mfma_f32_16x16x32_bf16 v[116:119], v[128:131], v[186:189], v[116:119]
	v_mfma_f32_16x16x32_bf16 v[84:87], v[136:139], v[186:189], v[84:87]
	v_mfma_f32_16x16x32_bf16 v[120:123], v[128:131], v[194:197], v[120:123]
	v_mfma_f32_16x16x32_bf16 v[88:91], v[136:139], v[194:197], v[88:91]
	v_mfma_f32_16x16x32_bf16 v[124:127], v[128:131], v[202:205], v[124:127]
	v_mfma_f32_16x16x32_bf16 v[92:95], v[136:139], v[202:205], v[92:95]
	v_mfma_f32_16x16x32_bf16 v[112:115], v[132:135], v[182:185], v[112:115]
	v_mfma_f32_16x16x32_bf16 v[80:83], v[140:143], v[182:185], v[80:83]
	v_mfma_f32_16x16x32_bf16 v[116:119], v[132:135], v[190:193], v[116:119]
	v_mfma_f32_16x16x32_bf16 v[84:87], v[140:143], v[190:193], v[84:87]
	v_mfma_f32_16x16x32_bf16 v[120:123], v[132:135], v[198:201], v[120:123]
	v_mfma_f32_16x16x32_bf16 v[88:91], v[140:143], v[198:201], v[88:91]
	v_mfma_f32_16x16x32_bf16 v[124:127], v[132:135], v[206:209], v[124:127]
	v_mfma_f32_16x16x32_bf16 v[92:95], v[140:143], v[206:209], v[92:95]
	s_setprio 0
	s_setprio 1
	v_mfma_f32_16x16x32_bf16 v[96:99], v[144:147], v[178:181], v[96:99]
	v_mfma_f32_16x16x32_bf16 v[64:67], v[170:173], v[178:181], v[64:67]
	v_mfma_f32_16x16x32_bf16 v[100:103], v[144:147], v[186:189], v[100:103]
	v_mfma_f32_16x16x32_bf16 v[68:71], v[170:173], v[186:189], v[68:71]
	v_mfma_f32_16x16x32_bf16 v[104:107], v[144:147], v[194:197], v[104:107]
	v_mfma_f32_16x16x32_bf16 v[72:75], v[170:173], v[194:197], v[72:75]
	v_mfma_f32_16x16x32_bf16 v[108:111], v[144:147], v[202:205], v[108:111]
	v_mfma_f32_16x16x32_bf16 v[76:79], v[170:173], v[202:205], v[76:79]
	v_mfma_f32_16x16x32_bf16 v[96:99], v[148:151], v[182:185], v[96:99]
	v_mfma_f32_16x16x32_bf16 v[64:67], v[174:177], v[182:185], v[64:67]
	v_mfma_f32_16x16x32_bf16 v[100:103], v[148:151], v[190:193], v[100:103]
	v_mfma_f32_16x16x32_bf16 v[68:71], v[174:177], v[190:193], v[68:71]
	v_mfma_f32_16x16x32_bf16 v[104:107], v[148:151], v[198:201], v[104:107]
	v_mfma_f32_16x16x32_bf16 v[72:75], v[174:177], v[198:201], v[72:75]
	v_mfma_f32_16x16x32_bf16 v[108:111], v[148:151], v[206:209], v[108:111]
	v_mfma_f32_16x16x32_bf16 v[76:79], v[174:177], v[206:209], v[76:79]
	s_setprio 0
	s_barrier
; #define PG8_STAGE(bufoff, gbase, voff) do { _Pragma("unroll") for (int _i = 0; _i < 2; ++_i) \
;         __builtin_amdgcn_global_load_lds((const unsigned*)((const char*)(gbase) + (voff)[_i]), (PG8_LAS unsigned*)(lds + (bufoff) + ldsw + _i * 8192), 16, 0, 0); } while (0)
; #define PG8_LDA(dst, b, h) do { _Pragma("unroll") for (int m = 0; m < 4; ++m) _Pragma("unroll") for (int k = 0; k < 2; ++k) dst[m][k] = *(const PG8_LAS bf16x8*)(lds + PG8_SA(b, h) + aoff + m * 2048 + k * 1024); } while (0)
; #define PG8_MMA(ai, bj, At, Bt) do { __builtin_amdgcn_s_setprio(1); _Pragma("unroll") for (int m = 0; m < 4; ++m) _Pragma("unroll") for (int n = 0; n < 2; ++n) _Pragma("unroll") for (int k = 0; k < 2; ++k) \
;         acc[ai][bj][m][n] = __builtin_amdgcn_mfma_f32_16x16x32_bf16(Bt[n][k], At[m][k], acc[ai][bj][m][n], 0, 0, 0); __builtin_amdgcn_s_setprio(0); } while (0)
; #define PG8_WAIT_V(n) asm volatile("s_waitcnt vmcnt(" #n ")" ::: "memory")
; #define PG8_WAIT_L(n) asm volatile("s_waitcnt lgkmcnt(" #n ")" ::: "memory")
; #define PG8_BAR __builtin_amdgcn_s_barrier()
; #define PG8_SCHED __builtin_amdgcn_sched_barrier(0)
; template <class Epi, class Sched, bool ALIGN_EPI = false, bool SP2 = false>
; __device__ __forceinline__ void gemm_phase(PG8_LAS unsigned char* lds, const Gemm g, const Sched& S, const Epi& E) {
;     ...
;         for (int t = 0; t < nt; t += 2) {
;             const bool last = (t == nt - 2);
;             const char* a1 = cA + (size_t)(t + 1) * kstep;
;             const char* a2 = last ? nA : cA + (size_t)(t + 2) * kstep; const char* b2 = last ? nB : cB + (size_t)(t + 2) * kstep;
;             const char* a3 = a2 + kstep; const char* b3 = b2 + kstep;
;             if (last && has_next) S.a_ready(nxt);
;     ...
;             PG8_LDA(At, 1, 1); PG8_STAGE(PG8_SB(1, 0), b3, voffB); PG8_STAGE(PG8_SB(1, 1), b3 + hstep, voffB); PG8_STAGE(PG8_SA(1, 0), a3, voffA);
;             PG8_WAIT_V(8); PG8_WAIT_L(0); PG8_BAR; PG8_MMA(1, 0, At, B0); PG8_MMA(1, 1, At, B1); PG8_BAR; PG8_SCHED;
	s_add_i32 s66, s91, s73
	v_lshl_add_u64 v[152:153], v[152:153], 0, s[28:29]
	s_mov_b32 m0, s66
	ds_read_b128 v[178:181], v243 offset:49152
	ds_read_b128 v[182:185], v243 offset:50176
	ds_read_b128 v[186:189], v243 offset:51200
	ds_read_b128 v[190:193], v243 offset:52224
	ds_read_b128 v[194:197], v243 offset:53248
	ds_read_b128 v[198:201], v243 offset:54272
	ds_read_b128 v[202:205], v243 offset:55296
	ds_read_b128 v[206:209], v243 offset:56320
	global_load_lds_dwordx4 v[152:153], off
	s_add_i32 m0, s66, 0x2000
	s_add_u32 s64, s64, 0x80080
	v_lshl_add_u64 v[152:153], v[210:211], 0, s[28:29]
	s_addc_u32 s65, s65, 0
	s_add_i32 s66, s92, s73
	global_load_lds_dwordx4 v[152:153], off
	v_lshl_add_u64 v[152:153], s[64:65], 0, v[156:157]
	s_mov_b32 m0, s66
	s_nop 0
	global_load_lds_dwordx4 v[152:153], off
	v_lshl_add_u64 v[152:153], s[64:65], 0, v[160:161]
	s_add_i32 m0, s66, 0x2000
	s_nop 0
	global_load_lds_dwordx4 v[152:153], off
	v_lshl_add_u64 v[152:153], v[212:213], 0, s[28:29]
	s_mov_b32 m0, s83
	s_nop 0
	global_load_lds_dwordx4 v[152:153], off
	v_lshl_add_u64 v[152:153], v[214:215], 0, s[28:29]
	s_mov_b32 m0, s84
	s_nop 0
	global_load_lds_dwordx4 v[152:153], off
	s_waitcnt vmcnt(8)
	s_waitcnt lgkmcnt(0)
	s_barrier
	s_setprio 1
	s_waitcnt lgkmcnt(0)
	v_mfma_f32_16x16x32_bf16 v[48:51], v[128:131], v[178:181], v[48:51]
	v_mfma_f32_16x16x32_bf16 v[16:19], v[136:139], v[178:181], v[16:19]
	v_mfma_f32_16x16x32_bf16 v[52:55], v[128:131], v[186:189], v[52:55]
	v_mfma_f32_16x16x32_bf16 v[20:23], v[136:139], v[186:189], v[20:23]
	v_mfma_f32_16x16x32_bf16 v[56:59], v[128:131], v[194:197], v[56:59]
	v_mfma_f32_16x16x32_bf16 v[24:27], v[136:139], v[194:197], v[24:27]
	v_mfma_f32_16x16x32_bf16 v[60:63], v[128:131], v[202:205], v[60:63]
	v_mfma_f32_16x16x32_bf16 v[28:31], v[136:139], v[202:205], v[28:31]
	v_mfma_f32_16x16x32_bf16 v[48:51], v[132:135], v[182:185], v[48:51]
	v_mfma_f32_16x16x32_bf16 v[16:19], v[140:143], v[182:185], v[16:19]
	v_mfma_f32_16x16x32_bf16 v[52:55], v[132:135], v[190:193], v[52:55]
	v_mfma_f32_16x16x32_bf16 v[20:23], v[140:143], v[190:193], v[20:23]
	v_mfma_f32_16x16x32_bf16 v[56:59], v[132:135], v[198:201], v[56:59]
	v_mfma_f32_16x16x32_bf16 v[24:27], v[140:143], v[198:201], v[24:27]
	v_mfma_f32_16x16x32_bf16 v[60:63], v[132:135], v[206:209], v[60:63]
	v_mfma_f32_16x16x32_bf16 v[28:31], v[140:143], v[206:209], v[28:31]
	s_setprio 0
	s_setprio 1
	v_mfma_f32_16x16x32_bf16 v[32:35], v[144:147], v[178:181], v[32:35]
	v_mfma_f32_16x16x32_bf16 v[0:3], v[170:173], v[178:181], v[0:3]
	v_mfma_f32_16x16x32_bf16 v[36:39], v[144:147], v[186:189], v[36:39]
	v_mfma_f32_16x16x32_bf16 v[4:7], v[170:173], v[186:189], v[4:7]
	v_mfma_f32_16x16x32_bf16 v[40:43], v[144:147], v[194:197], v[40:43]
	v_mfma_f32_16x16x32_bf16 v[8:11], v[170:173], v[194:197], v[8:11]
	v_mfma_f32_16x16x32_bf16 v[44:47], v[144:147], v[202:205], v[44:47]
	v_mfma_f32_16x16x32_bf16 v[12:15], v[170:173], v[202:205], v[12:15]
	v_mfma_f32_16x16x32_bf16 v[32:35], v[148:151], v[182:185], v[32:35]
	v_mfma_f32_16x16x32_bf16 v[0:3], v[174:177], v[182:185], v[0:3]
	v_mfma_f32_16x16x32_bf16 v[36:39], v[148:151], v[190:193], v[36:39]
	v_mfma_f32_16x16x32_bf16 v[4:7], v[174:177], v[190:193], v[4:7]
	v_mfma_f32_16x16x32_bf16 v[40:43], v[148:151], v[198:201], v[40:43]
	v_mfma_f32_16x16x32_bf16 v[8:11], v[174:177], v[198:201], v[8:11]
	v_mfma_f32_16x16x32_bf16 v[44:47], v[148:151], v[206:209], v[44:47]
	v_mfma_f32_16x16x32_bf16 v[12:15], v[174:177], v[206:209], v[12:15]
	s_setprio 0
	s_barrier
	s_add_i32 s90, s90, 2
	s_add_u32 s62, s62, 0x100
	s_addc_u32 s63, s63, 0
	s_add_u32 s59, s59, 0x100
	s_addc_u32 s71, s71, 0
	s_cmp_gt_u32 s90, 29
	s_cbranch_scc0 .LBB0_989
	s_branch .Lpeel_exit_3

; #define PG8_BAR __builtin_amdgcn_s_barrier()
; template <class Epi, class Sched, bool ALIGN_EPI = false, bool SP2 = false>
; __device__ __forceinline__ void gemm_phase(PG8_LAS unsigned char* lds, const Gemm g, const Sched& S, const Epi& E) {
;     ...
;         if constexpr (ALIGN_EPI) { if (wr == 0) PG8_BAR; }
;         if constexpr (!Epi::AFTER_DRAIN) { E(acc, cur, wr, wc, fr, fq); S.done(cur); }
.Lpeel_exit_3:
	s_and_b64 vcc, exec, s[30:31]
	s_cbranch_vccz .LBB0_992
	s_barrier

; #define PG8_STAGE(bufoff, gbase, voff) do { _Pragma("unroll") for (int _i = 0; _i < 2; ++_i) \
;         __builtin_amdgcn_global_load_lds((const unsigned*)((const char*)(gbase) + (voff)[_i]), (PG8_LAS unsigned*)(lds + (bufoff) + ldsw + _i * 8192), 16, 0, 0); } while (0)
; #define PG8_WAIT_V(n) asm volatile("s_waitcnt vmcnt(" #n ")" ::: "memory")
; #define PG8_WAIT_L(n) asm volatile("s_waitcnt lgkmcnt(" #n ")" ::: "memory")
; #define PG8_BAR __builtin_amdgcn_s_barrier()
; template <class Epi, class Sched, bool ALIGN_EPI = false, bool SP2 = false>
; __device__ __forceinline__ void gemm_phase(PG8_LAS unsigned char* lds, const Gemm g, const Sched& S, const Epi& E) {
;     ...
;         const bool has_next = S.next(ui + 1, nxt);
;         const char* nA = has_next ? (const char*)g.A + (size_t)nxt.pm * tstep : cA; const char* nB = has_next ? (const char*)g.Bt + (size_t)nxt.pn * tstep : cB;
;         for (int t = 0; t < nt; t += 2) {
;             const bool last = (t == nt - 2);
;             const char* a1 = cA + (size_t)(t + 1) * kstep;
;             const char* a2 = last ? nA : cA + (size_t)(t + 2) * kstep; const char* b2 = last ? nB : cB + (size_t)(t + 2) * kstep;
;             const char* a3 = a2 + kstep; const char* b3 = b2 + kstep;
;             if (last && has_next) S.a_ready(nxt);
;             if constexpr (SP2) {
;             PG8_LDB(B0, 0, 0); PG8_LDB(B1, 0, 1); PG8_SCHED; PG8_LDA(At, 0, 0); PG8_STAGE(PG8_SA(1, 1), a1 + hstep, voffA);
;             PG8_WAIT_V(8); PG8_WAIT_L(0); PG8_BAR; PG8_MMA(0, 0, At, B0); PG8_MMA(0, 1, At, B1); PG8_BAR; PG8_SCHED;
;             PG8_LDA(At, 0, 1); PG8_STAGE(PG8_SB(0, 0), b2, voffB); PG8_STAGE(PG8_SB(0, 1), b2 + hstep, voffB); PG8_STAGE(PG8_SA(0, 0), a2, voffA);
;             PG8_WAIT_V(8); PG8_WAIT_L(0); PG8_BAR; PG8_MMA(1, 0, At, B0); PG8_MMA(1, 1, At, B1); PG8_BAR; PG8_SCHED;
;             PG8_LDB(B0, 1, 0); PG8_LDB(B1, 1, 1); PG8_SCHED; PG8_LDA(At, 1, 0); PG8_STAGE(PG8_SA(0, 1), a2 + hstep, voffA);
;             PG8_WAIT_V(8); PG8_WAIT_L(0); PG8_BAR; PG8_MMA(0, 0, At, B0); PG8_MMA(0, 1, At, B1); PG8_BAR; PG8_SCHED;
;     ...
; #pragma unroll
;         for (int a = 0; a < 2; ++a)
; #pragma unroll
;             for (int b = 0; b < 2; ++b)
; #pragma unroll
;                 for (int m = 0; m < 4; ++m)
; #pragma unroll
;                     for (int n = 0; n < 2; ++n) acc[a][b][m][n] = (f32x4){0.f, 0.f, 0.f, 0.f};
.LBB0_1152:
	s_add_u32 s51, s36, 0x100
	s_addc_u32 s64, s37, 0
	s_mov_b32 s65, -2
	s_waitcnt lgkmcnt(0)
	ds_read_b128 v[100:103], v225
	ds_read_b128 v[108:111], v225 offset:1024
	ds_read_b128 v[124:127], v225 offset:2048
	ds_read_b128 v[132:135], v225 offset:3072
	ds_read_b128 v[144:147], v226
	ds_read_b128 v[148:151], v226 offset:1024
	ds_read_b128 v[152:155], v226 offset:2048
	ds_read_b128 v[156:159], v226 offset:3072
	s_add_u32 s36, s34, 0x100
	s_addc_u32 s37, s35, 0
	s_cmpk_eq_i32 s65, 0x54
	s_cselect_b32 s41, s17, s37
	s_cselect_b32 s40, s16, s36
	s_cselect_b32 s39, s31, s64
	s_cselect_b32 s38, s30, s51
	v_lshl_add_u64 v[208:209], s[34:35], 0, v[192:193]
	s_add_i32 m0, s52, 0xc000
	ds_read_b128 v[160:163], v227
	ds_read_b128 v[164:167], v227 offset:1024
	ds_read_b128 v[168:171], v227 offset:2048
	ds_read_b128 v[172:175], v227 offset:3072
	ds_read_b128 v[176:179], v227 offset:4096
	ds_read_b128 v[180:183], v227 offset:5120
	ds_read_b128 v[200:203], v227 offset:6144
	ds_read_b128 v[204:207], v227 offset:7168
	global_load_lds_dwordx4 v[208:209], off
	v_lshl_add_u64 v[208:209], s[34:35], 0, v[194:195]
	s_add_i32 m0, s52, 0xe000
	s_nop 0
	global_load_lds_dwordx4 v[208:209], off
	s_waitcnt vmcnt(8)
	s_waitcnt lgkmcnt(0)
	s_barrier
	s_setprio 1
	s_waitcnt lgkmcnt(0)
	v_mfma_f32_16x16x32_bf16 v[140:143], v[100:103], v[160:163], 0
	v_mfma_f32_16x16x32_bf16 v[136:139], v[124:127], v[160:163], 0
	v_mfma_f32_16x16x32_bf16 v[116:119], v[100:103], v[168:171], 0
	v_mfma_f32_16x16x32_bf16 v[112:115], v[124:127], v[168:171], 0
	v_mfma_f32_16x16x32_bf16 v[92:95], v[100:103], v[176:179], 0
	v_mfma_f32_16x16x32_bf16 v[88:91], v[124:127], v[176:179], 0
	v_mfma_f32_16x16x32_bf16 v[76:79], v[100:103], v[200:203], 0
	v_mfma_f32_16x16x32_bf16 v[72:75], v[124:127], v[200:203], 0
	v_mfma_f32_16x16x32_bf16 v[140:143], v[108:111], v[164:167], v[140:143]
	v_mfma_f32_16x16x32_bf16 v[136:139], v[132:135], v[164:167], v[136:139]
	v_mfma_f32_16x16x32_bf16 v[116:119], v[108:111], v[172:175], v[116:119]
	v_mfma_f32_16x16x32_bf16 v[112:115], v[132:135], v[172:175], v[112:115]
	v_mfma_f32_16x16x32_bf16 v[92:95], v[108:111], v[180:183], v[92:95]
	v_mfma_f32_16x16x32_bf16 v[88:91], v[132:135], v[180:183], v[88:91]
	v_mfma_f32_16x16x32_bf16 v[76:79], v[108:111], v[204:207], v[76:79]
	v_mfma_f32_16x16x32_bf16 v[72:75], v[132:135], v[204:207], v[72:75]
	s_setprio 0
	s_setprio 1
	v_mfma_f32_16x16x32_bf16 v[128:131], v[144:147], v[160:163], 0
	v_mfma_f32_16x16x32_bf16 v[120:123], v[152:155], v[160:163], 0
	v_mfma_f32_16x16x32_bf16 v[104:107], v[144:147], v[168:171], 0
	v_mfma_f32_16x16x32_bf16 v[96:99], v[152:155], v[168:171], 0
	v_mfma_f32_16x16x32_bf16 v[84:87], v[144:147], v[176:179], 0
	v_mfma_f32_16x16x32_bf16 v[80:83], v[152:155], v[176:179], 0
	v_mfma_f32_16x16x32_bf16 v[68:71], v[144:147], v[200:203], 0
	v_mfma_f32_16x16x32_bf16 v[64:67], v[152:155], v[200:203], 0
	v_mfma_f32_16x16x32_bf16 v[128:131], v[148:151], v[164:167], v[128:131]
	v_mfma_f32_16x16x32_bf16 v[120:123], v[156:159], v[164:167], v[120:123]
	v_mfma_f32_16x16x32_bf16 v[104:107], v[148:151], v[172:175], v[104:107]
	v_mfma_f32_16x16x32_bf16 v[96:99], v[156:159], v[172:175], v[96:99]
	v_mfma_f32_16x16x32_bf16 v[84:87], v[148:151], v[180:183], v[84:87]
	v_mfma_f32_16x16x32_bf16 v[80:83], v[156:159], v[180:183], v[80:83]
	v_mfma_f32_16x16x32_bf16 v[68:71], v[148:151], v[204:207], v[68:71]
	v_mfma_f32_16x16x32_bf16 v[64:67], v[156:159], v[204:207], v[64:67]
	s_setprio 0
	s_barrier
	s_add_i32 s34, s59, s43
	v_lshl_add_u64 v[208:209], s[38:39], 0, v[186:187]
	s_mov_b32 m0, s34
	ds_read_b128 v[160:163], v227 offset:16384
	ds_read_b128 v[164:167], v227 offset:17408
	ds_read_b128 v[168:171], v227 offset:18432
	ds_read_b128 v[172:175], v227 offset:19456
	ds_read_b128 v[176:179], v227 offset:20480
	ds_read_b128 v[180:183], v227 offset:21504
	ds_read_b128 v[200:203], v227 offset:22528
	ds_read_b128 v[204:207], v227 offset:23552
	global_load_lds_dwordx4 v[208:209], off
	s_add_i32 m0, s34, 0x2000
	s_add_u32 s34, s38, 0x160000
	v_lshl_add_u64 v[210:211], s[38:39], 0, v[190:191]
	s_addc_u32 s35, s39, 0
	s_add_i32 s66, s60, s43
	global_load_lds_dwordx4 v[210:211], off
	v_lshl_add_u64 v[212:213], s[34:35], 0, v[186:187]
	s_mov_b32 m0, s66
	v_lshl_add_u64 v[214:215], s[40:41], 0, v[188:189]
	global_load_lds_dwordx4 v[212:213], off
	v_lshl_add_u64 v[212:213], s[34:35], 0, v[190:191]
	s_add_i32 m0, s66, 0x2000
	s_nop 0
	global_load_lds_dwordx4 v[212:213], off
	v_lshl_add_u64 v[212:213], s[40:41], 0, v[184:185]
	s_mov_b32 m0, s52
	s_nop 0
	global_load_lds_dwordx4 v[212:213], off
	s_mov_b32 m0, s53
	s_nop 0
	global_load_lds_dwordx4 v[214:215], off
	s_waitcnt vmcnt(8)
	s_waitcnt lgkmcnt(0)
	s_barrier
; #define PG8_STAGE(bufoff, gbase, voff) do { _Pragma("unroll") for (int _i = 0; _i < 2; ++_i) \
;         __builtin_amdgcn_global_load_lds((const unsigned*)((const char*)(gbase) + (voff)[_i]), (PG8_LAS unsigned*)(lds + (bufoff) + ldsw + _i * 8192), 16, 0, 0); } while (0)
; #define PG8_LDA(dst, b, h) do { _Pragma("unroll") for (int m = 0; m < 4; ++m) _Pragma("unroll") for (int k = 0; k < 2; ++k) dst[m][k] = *(const PG8_LAS bf16x8*)(lds + PG8_SA(b, h) + aoff + m * 2048 + k * 1024); } while (0)
; #define PG8_LDB(dst, b, h) do { _Pragma("unroll") for (int n = 0; n < 2; ++n) _Pragma("unroll") for (int k = 0; k < 2; ++k) dst[n][k] = *(const PG8_LAS bf16x8*)(lds + PG8_SB(b, h) + boff + n * 2048 + k * 1024); } while (0)
; #define PG8_MMA(ai, bj, At, Bt) do { __builtin_amdgcn_s_setprio(1); _Pragma("unroll") for (int m = 0; m < 4; ++m) _Pragma("unroll") for (int n = 0; n < 2; ++n) _Pragma("unroll") for (int k = 0; k < 2; ++k) \
;         acc[ai][bj][m][n] = __builtin_amdgcn_mfma_f32_16x16x32_bf16(Bt[n][k], At[m][k], acc[ai][bj][m][n], 0, 0, 0); __builtin_amdgcn_s_setprio(0); } while (0)
; #define PG8_WAIT_V(n) asm volatile("s_waitcnt vmcnt(" #n ")" ::: "memory")
; #define PG8_WAIT_L(n) asm volatile("s_waitcnt lgkmcnt(" #n ")" ::: "memory")
; #define PG8_BAR __builtin_amdgcn_s_barrier()
; #define PG8_SCHED __builtin_amdgcn_sched_barrier(0)
; template <class Epi, class Sched, bool ALIGN_EPI = false, bool SP2 = false>
; __device__ __forceinline__ void gemm_phase(PG8_LAS unsigned char* lds, const Gemm g, const Sched& S, const Epi& E) {
;     ...
;             PG8_WAIT_V(8); PG8_WAIT_L(0); PG8_BAR; PG8_MMA(1, 0, At, B0); PG8_MMA(1, 1, At, B1); PG8_BAR; PG8_SCHED;
;             PG8_LDB(B0, 1, 0); PG8_LDB(B1, 1, 1); PG8_SCHED; PG8_LDA(At, 1, 0); PG8_STAGE(PG8_SA(0, 1), a2 + hstep, voffA);
;             PG8_WAIT_V(8); PG8_WAIT_L(0); PG8_BAR; PG8_MMA(0, 0, At, B0); PG8_MMA(0, 1, At, B1); PG8_BAR; PG8_SCHED;
	s_setprio 1
	s_waitcnt lgkmcnt(0)
	v_mfma_f32_16x16x32_bf16 v[60:63], v[100:103], v[160:163], 0
	v_mfma_f32_16x16x32_bf16 v[56:59], v[124:127], v[160:163], 0
	v_mfma_f32_16x16x32_bf16 v[44:47], v[100:103], v[168:171], 0
	v_mfma_f32_16x16x32_bf16 v[40:43], v[124:127], v[168:171], 0
	v_mfma_f32_16x16x32_bf16 v[28:31], v[100:103], v[176:179], 0
	v_mfma_f32_16x16x32_bf16 v[24:27], v[124:127], v[176:179], 0
	v_mfma_f32_16x16x32_bf16 v[12:15], v[100:103], v[200:203], 0
	v_mfma_f32_16x16x32_bf16 v[8:11], v[124:127], v[200:203], 0
	v_mfma_f32_16x16x32_bf16 v[60:63], v[108:111], v[164:167], v[60:63]
	v_mfma_f32_16x16x32_bf16 v[56:59], v[132:135], v[164:167], v[56:59]
	v_mfma_f32_16x16x32_bf16 v[44:47], v[108:111], v[172:175], v[44:47]
	v_mfma_f32_16x16x32_bf16 v[40:43], v[132:135], v[172:175], v[40:43]
	v_mfma_f32_16x16x32_bf16 v[28:31], v[108:111], v[180:183], v[28:31]
	v_mfma_f32_16x16x32_bf16 v[24:27], v[132:135], v[180:183], v[24:27]
	v_mfma_f32_16x16x32_bf16 v[12:15], v[108:111], v[204:207], v[12:15]
	v_mfma_f32_16x16x32_bf16 v[8:11], v[132:135], v[204:207], v[8:11]
	s_setprio 0
	s_setprio 1
	v_mfma_f32_16x16x32_bf16 v[52:55], v[144:147], v[160:163], 0
	v_mfma_f32_16x16x32_bf16 v[48:51], v[152:155], v[160:163], 0
	v_mfma_f32_16x16x32_bf16 v[36:39], v[144:147], v[168:171], 0
	v_mfma_f32_16x16x32_bf16 v[32:35], v[152:155], v[168:171], 0
	v_mfma_f32_16x16x32_bf16 v[20:23], v[144:147], v[176:179], 0
	v_mfma_f32_16x16x32_bf16 v[16:19], v[152:155], v[176:179], 0
	v_mfma_f32_16x16x32_bf16 v[4:7], v[144:147], v[200:203], 0
	v_mfma_f32_16x16x32_bf16 v[0:3], v[152:155], v[200:203], 0
	v_mfma_f32_16x16x32_bf16 v[52:55], v[148:151], v[164:167], v[52:55]
	v_mfma_f32_16x16x32_bf16 v[48:51], v[156:159], v[164:167], v[48:51]
	v_mfma_f32_16x16x32_bf16 v[36:39], v[148:151], v[172:175], v[36:39]
	v_mfma_f32_16x16x32_bf16 v[32:35], v[156:159], v[172:175], v[32:35]
	v_mfma_f32_16x16x32_bf16 v[20:23], v[148:151], v[180:183], v[20:23]
	v_mfma_f32_16x16x32_bf16 v[16:19], v[156:159], v[180:183], v[16:19]
	v_mfma_f32_16x16x32_bf16 v[4:7], v[148:151], v[204:207], v[4:7]
	v_mfma_f32_16x16x32_bf16 v[0:3], v[156:159], v[204:207], v[0:3]
	s_setprio 0
	s_barrier
	s_add_i32 s66, 0, 0x18000
	s_add_i32 s67, 0, 0x1c000
	v_add_u32_e32 v132, s66, v223
	v_add_u32_e32 v156, s67, v223
	ds_read_b128 v[100:103], v132
	ds_read_b128 v[108:111], v132 offset:1024
	ds_read_b128 v[124:127], v132 offset:2048
	ds_read_b128 v[132:135], v132 offset:3072
	ds_read_b128 v[144:147], v156
	ds_read_b128 v[148:151], v156 offset:1024
	ds_read_b128 v[152:155], v156 offset:2048
	ds_read_b128 v[156:159], v156 offset:3072
	s_add_u32 s34, s40, 0x160000
	s_addc_u32 s35, s41, 0
	s_mov_b32 m0, s54
	v_lshl_add_u64 v[216:217], s[34:35], 0, v[184:185]
	ds_read_b128 v[160:163], v227 offset:32768
	ds_read_b128 v[164:167], v227 offset:33792
	ds_read_b128 v[168:171], v227 offset:34816
	ds_read_b128 v[172:175], v227 offset:35840
	ds_read_b128 v[176:179], v227 offset:36864
	ds_read_b128 v[180:183], v227 offset:37888
	ds_read_b128 v[200:203], v227 offset:38912
	ds_read_b128 v[204:207], v227 offset:39936
	global_load_lds_dwordx4 v[216:217], off
	v_lshl_add_u64 v[216:217], s[34:35], 0, v[188:189]
	s_mov_b32 m0, s55
	s_nop 0
	global_load_lds_dwordx4 v[216:217], off
	s_waitcnt vmcnt(8)
	s_waitcnt lgkmcnt(0)
	s_barrier
	s_setprio 1
	s_waitcnt lgkmcnt(0)
	v_mfma_f32_16x16x32_bf16 v[140:143], v[100:103], v[160:163], v[140:143]
	v_mfma_f32_16x16x32_bf16 v[136:139], v[124:127], v[160:163], v[136:139]
	v_mfma_f32_16x16x32_bf16 v[116:119], v[100:103], v[168:171], v[116:119]
	v_mfma_f32_16x16x32_bf16 v[112:115], v[124:127], v[168:171], v[112:115]
	v_mfma_f32_16x16x32_bf16 v[92:95], v[100:103], v[176:179], v[92:95]
	v_mfma_f32_16x16x32_bf16 v[88:91], v[124:127], v[176:179], v[88:91]
	v_mfma_f32_16x16x32_bf16 v[76:79], v[100:103], v[200:203], v[76:79]
	v_mfma_f32_16x16x32_bf16 v[72:75], v[124:127], v[200:203], v[72:75]
	v_mfma_f32_16x16x32_bf16 v[140:143], v[108:111], v[164:167], v[140:143]
	v_mfma_f32_16x16x32_bf16 v[136:139], v[132:135], v[164:167], v[136:139]
	v_mfma_f32_16x16x32_bf16 v[116:119], v[108:111], v[172:175], v[116:119]
	v_mfma_f32_16x16x32_bf16 v[112:115], v[132:135], v[172:175], v[112:115]
	v_mfma_f32_16x16x32_bf16 v[92:95], v[108:111], v[180:183], v[92:95]
	v_mfma_f32_16x16x32_bf16 v[88:91], v[132:135], v[180:183], v[88:91]
	v_mfma_f32_16x16x32_bf16 v[76:79], v[108:111], v[204:207], v[76:79]
	v_mfma_f32_16x16x32_bf16 v[72:75], v[132:135], v[204:207], v[72:75]
	s_setprio 0
	s_setprio 1
	v_mfma_f32_16x16x32_bf16 v[128:131], v[144:147], v[160:163], v[128:131]
	v_mfma_f32_16x16x32_bf16 v[120:123], v[152:155], v[160:163], v[120:123]
	v_mfma_f32_16x16x32_bf16 v[104:107], v[144:147], v[168:171], v[104:107]
	v_mfma_f32_16x16x32_bf16 v[96:99], v[152:155], v[168:171], v[96:99]
	v_mfma_f32_16x16x32_bf16 v[84:87], v[144:147], v[176:179], v[84:87]
	v_mfma_f32_16x16x32_bf16 v[80:83], v[152:155], v[176:179], v[80:83]
	v_mfma_f32_16x16x32_bf16 v[68:71], v[144:147], v[200:203], v[68:71]
	v_mfma_f32_16x16x32_bf16 v[64:67], v[152:155], v[200:203], v[64:67]
	v_mfma_f32_16x16x32_bf16 v[128:131], v[148:151], v[164:167], v[128:131]
	v_mfma_f32_16x16x32_bf16 v[120:123], v[156:159], v[164:167], v[120:123]
	v_mfma_f32_16x16x32_bf16 v[104:107], v[148:151], v[172:175], v[104:107]
	v_mfma_f32_16x16x32_bf16 v[96:99], v[156:159], v[172:175], v[96:99]
	v_mfma_f32_16x16x32_bf16 v[84:87], v[148:151], v[180:183], v[84:87]
	v_mfma_f32_16x16x32_bf16 v[80:83], v[156:159], v[180:183], v[80:83]
	v_mfma_f32_16x16x32_bf16 v[68:71], v[148:151], v[204:207], v[68:71]
	v_mfma_f32_16x16x32_bf16 v[64:67], v[156:159], v[204:207], v[64:67]
	s_setprio 0
	s_barrier
; #define PG8_STAGE(bufoff, gbase, voff) do { _Pragma("unroll") for (int _i = 0; _i < 2; ++_i) \
;         __builtin_amdgcn_global_load_lds((const unsigned*)((const char*)(gbase) + (voff)[_i]), (PG8_LAS unsigned*)(lds + (bufoff) + ldsw + _i * 8192), 16, 0, 0); } while (0)
; #define PG8_LDA(dst, b, h) do { _Pragma("unroll") for (int m = 0; m < 4; ++m) _Pragma("unroll") for (int k = 0; k < 2; ++k) dst[m][k] = *(const PG8_LAS bf16x8*)(lds + PG8_SA(b, h) + aoff + m * 2048 + k * 1024); } while (0)
; #define PG8_LDB(dst, b, h) do { _Pragma("unroll") for (int n = 0; n < 2; ++n) _Pragma("unroll") for (int k = 0; k < 2; ++k) dst[n][k] = *(const PG8_LAS bf16x8*)(lds + PG8_SB(b, h) + boff + n * 2048 + k * 1024); } while (0)
; #define PG8_MMA(ai, bj, At, Bt) do { __builtin_amdgcn_s_setprio(1); _Pragma("unroll") for (int m = 0; m < 4; ++m) _Pragma("unroll") for (int n = 0; n < 2; ++n) _Pragma("unroll") for (int k = 0; k < 2; ++k) \
;         acc[ai][bj][m][n] = __builtin_amdgcn_mfma_f32_16x16x32_bf16(Bt[n][k], At[m][k], acc[ai][bj][m][n], 0, 0, 0); __builtin_amdgcn_s_setprio(0); } while (0)
; #define PG8_WAIT_V(n) asm volatile("s_waitcnt vmcnt(" #n ")" ::: "memory")
; #define PG8_BAR __builtin_amdgcn_s_barrier()
; template <class Epi, class Sched, bool ALIGN_EPI = false, bool SP2 = false>
; __device__ __forceinline__ void gemm_phase(PG8_LAS unsigned char* lds, const Gemm g, const Sched& S, const Epi& E) {
;     ...
;         for (int t = 0; t < nt; t += 2) {
;             const bool last = (t == nt - 2);
;             const char* a1 = cA + (size_t)(t + 1) * kstep;
;             const char* a2 = last ? nA : cA + (size_t)(t + 2) * kstep; const char* b2 = last ? nB : cB + (size_t)(t + 2) * kstep;
;             const char* a3 = a2 + kstep; const char* b3 = b2 + kstep;
;             if (last && has_next) S.a_ready(nxt);
;             if constexpr (SP2) {
;             PG8_LDB(B0, 0, 0); PG8_LDB(B1, 0, 1); PG8_SCHED; PG8_LDA(At, 0, 0); PG8_STAGE(PG8_SA(1, 1), a1 + hstep, voffA);
;             PG8_WAIT_V(8); PG8_WAIT_L(0); PG8_BAR; PG8_MMA(0, 0, At, B0); PG8_MMA(0, 1, At, B1); PG8_BAR; PG8_SCHED;
;     ...
;             PG8_LDA(At, 1, 1); PG8_STAGE(PG8_SB(1, 0), b3, voffB); PG8_STAGE(PG8_SB(1, 1), b3 + hstep, voffB); PG8_STAGE(PG8_SA(1, 0), a3, voffA);
;             PG8_WAIT_V(8); PG8_WAIT_L(0); PG8_BAR; PG8_MMA(1, 0, At, B0); PG8_MMA(1, 1, At, B1); PG8_BAR; PG8_SCHED;
	s_add_i32 s34, s66, s43
	v_lshl_add_u64 v[208:209], v[208:209], 0, s[26:27]
	s_mov_b32 m0, s34
	ds_read_b128 v[160:163], v227 offset:49152
	ds_read_b128 v[164:167], v227 offset:50176
	ds_read_b128 v[168:171], v227 offset:51200
	ds_read_b128 v[172:175], v227 offset:52224
	ds_read_b128 v[176:179], v227 offset:53248
	ds_read_b128 v[180:183], v227 offset:54272
	ds_read_b128 v[200:203], v227 offset:55296
	ds_read_b128 v[204:207], v227 offset:56320
	global_load_lds_dwordx4 v[208:209], off
	s_add_i32 m0, s34, 0x2000
	s_add_u32 s34, s38, 0x160080
	v_lshl_add_u64 v[208:209], v[210:211], 0, s[26:27]
	s_addc_u32 s35, s39, 0
	s_add_i32 s38, s67, s43
	global_load_lds_dwordx4 v[208:209], off
	v_lshl_add_u64 v[208:209], s[34:35], 0, v[186:187]
	s_mov_b32 m0, s38
	s_nop 0
	global_load_lds_dwordx4 v[208:209], off
	v_lshl_add_u64 v[208:209], s[34:35], 0, v[190:191]
	s_add_i32 m0, s38, 0x2000
	s_nop 0
	global_load_lds_dwordx4 v[208:209], off
	v_lshl_add_u64 v[208:209], v[212:213], 0, s[26:27]
	s_mov_b32 m0, s57
	s_nop 0
	global_load_lds_dwordx4 v[208:209], off
	v_lshl_add_u64 v[208:209], v[214:215], 0, s[26:27]
	s_mov_b32 m0, s58
	s_nop 0
	global_load_lds_dwordx4 v[208:209], off
	s_waitcnt vmcnt(8)
	s_waitcnt lgkmcnt(0)
	s_barrier
	s_setprio 1
	s_waitcnt lgkmcnt(0)
	v_mfma_f32_16x16x32_bf16 v[60:63], v[100:103], v[160:163], v[60:63]
	v_mfma_f32_16x16x32_bf16 v[56:59], v[124:127], v[160:163], v[56:59]
	v_mfma_f32_16x16x32_bf16 v[44:47], v[100:103], v[168:171], v[44:47]
	v_mfma_f32_16x16x32_bf16 v[40:43], v[124:127], v[168:171], v[40:43]
	v_mfma_f32_16x16x32_bf16 v[28:31], v[100:103], v[176:179], v[28:31]
	v_mfma_f32_16x16x32_bf16 v[24:27], v[124:127], v[176:179], v[24:27]
	v_mfma_f32_16x16x32_bf16 v[12:15], v[100:103], v[200:203], v[12:15]
	v_mfma_f32_16x16x32_bf16 v[8:11], v[124:127], v[200:203], v[8:11]
	v_mfma_f32_16x16x32_bf16 v[60:63], v[108:111], v[164:167], v[60:63]
	v_mfma_f32_16x16x32_bf16 v[56:59], v[132:135], v[164:167], v[56:59]
	v_mfma_f32_16x16x32_bf16 v[44:47], v[108:111], v[172:175], v[44:47]
	v_mfma_f32_16x16x32_bf16 v[40:43], v[132:135], v[172:175], v[40:43]
	v_mfma_f32_16x16x32_bf16 v[28:31], v[108:111], v[180:183], v[28:31]
	v_mfma_f32_16x16x32_bf16 v[24:27], v[132:135], v[180:183], v[24:27]
	v_mfma_f32_16x16x32_bf16 v[12:15], v[108:111], v[204:207], v[12:15]
	v_mfma_f32_16x16x32_bf16 v[8:11], v[132:135], v[204:207], v[8:11]
	s_setprio 0
	s_setprio 1
	v_mfma_f32_16x16x32_bf16 v[52:55], v[144:147], v[160:163], v[52:55]
	v_mfma_f32_16x16x32_bf16 v[48:51], v[152:155], v[160:163], v[48:51]
	v_mfma_f32_16x16x32_bf16 v[36:39], v[144:147], v[168:171], v[36:39]
	v_mfma_f32_16x16x32_bf16 v[32:35], v[152:155], v[168:171], v[32:35]
	v_mfma_f32_16x16x32_bf16 v[20:23], v[144:147], v[176:179], v[20:23]
	v_mfma_f32_16x16x32_bf16 v[16:19], v[152:155], v[176:179], v[16:19]
	v_mfma_f32_16x16x32_bf16 v[4:7], v[144:147], v[200:203], v[4:7]
	v_mfma_f32_16x16x32_bf16 v[0:3], v[152:155], v[200:203], v[0:3]
	v_mfma_f32_16x16x32_bf16 v[52:55], v[148:151], v[164:167], v[52:55]
	v_mfma_f32_16x16x32_bf16 v[48:51], v[156:159], v[164:167], v[48:51]
	v_mfma_f32_16x16x32_bf16 v[36:39], v[148:151], v[172:175], v[36:39]
	v_mfma_f32_16x16x32_bf16 v[32:35], v[156:159], v[172:175], v[32:35]
	v_mfma_f32_16x16x32_bf16 v[20:23], v[148:151], v[180:183], v[20:23]
	v_mfma_f32_16x16x32_bf16 v[16:19], v[156:159], v[180:183], v[16:19]
	v_mfma_f32_16x16x32_bf16 v[4:7], v[148:151], v[204:207], v[4:7]
	v_mfma_f32_16x16x32_bf16 v[0:3], v[156:159], v[204:207], v[0:3]
	s_setprio 0
	s_barrier
	s_add_i32 s65, s65, 2
	s_add_u32 s51, s51, 0x100
	s_addc_u32 s64, s64, 0
	s_cmpk_gt_u32 s65, 0x55
	s_mov_b64 s[34:35], s[36:37]
	s_cbranch_scc0 .LBB0_1153
	s_branch .Lpeel_exit_4
.LBB0_1153:
	ds_read_b128 v[100:103], v225
	ds_read_b128 v[108:111], v225 offset:1024
	ds_read_b128 v[124:127], v225 offset:2048
	ds_read_b128 v[132:135], v225 offset:3072
	ds_read_b128 v[144:147], v226
	ds_read_b128 v[148:151], v226 offset:1024
	ds_read_b128 v[152:155], v226 offset:2048
	ds_read_b128 v[156:159], v226 offset:3072
	s_add_u32 s36, s34, 0x100
	s_addc_u32 s37, s35, 0
	s_cmpk_eq_i32 s65, 0x54
	s_cselect_b32 s41, s17, s37
	s_cselect_b32 s40, s16, s36
	s_cselect_b32 s39, s31, s64
	s_cselect_b32 s38, s30, s51
	v_lshl_add_u64 v[208:209], s[34:35], 0, v[192:193]
	s_add_i32 m0, s52, 0xc000
	ds_read_b128 v[160:163], v227
	ds_read_b128 v[164:167], v227 offset:1024
	ds_read_b128 v[168:171], v227 offset:2048
	ds_read_b128 v[172:175], v227 offset:3072
	ds_read_b128 v[176:179], v227 offset:4096
	ds_read_b128 v[180:183], v227 offset:5120
	ds_read_b128 v[200:203], v227 offset:6144
	ds_read_b128 v[204:207], v227 offset:7168
	global_load_lds_dwordx4 v[208:209], off
	v_lshl_add_u64 v[208:209], s[34:35], 0, v[194:195]
	s_add_i32 m0, s52, 0xe000
	s_nop 0
	global_load_lds_dwordx4 v[208:209], off
	s_waitcnt vmcnt(8)
	s_waitcnt lgkmcnt(0)
	s_barrier
; #define PG8_STAGE(bufoff, gbase, voff) do { _Pragma("unroll") for (int _i = 0; _i < 2; ++_i) \
;         __builtin_amdgcn_global_load_lds((const unsigned*)((const char*)(gbase) + (voff)[_i]), (PG8_LAS unsigned*)(lds + (bufoff) + ldsw + _i * 8192), 16, 0, 0); } while (0)
; #define PG8_LDA(dst, b, h) do { _Pragma("unroll") for (int m = 0; m < 4; ++m) _Pragma("unroll") for (int k = 0; k < 2; ++k) dst[m][k] = *(const PG8_LAS bf16x8*)(lds + PG8_SA(b, h) + aoff + m * 2048 + k * 1024); } while (0)
; #define PG8_LDB(dst, b, h) do { _Pragma("unroll") for (int n = 0; n < 2; ++n) _Pragma("unroll") for (int k = 0; k < 2; ++k) dst[n][k] = *(const PG8_LAS bf16x8*)(lds + PG8_SB(b, h) + boff + n * 2048 + k * 1024); } while (0)
; #define PG8_MMA(ai, bj, At, Bt) do { __builtin_amdgcn_s_setprio(1); _Pragma("unroll") for (int m = 0; m < 4; ++m) _Pragma("unroll") for (int n = 0; n < 2; ++n) _Pragma("unroll") for (int k = 0; k < 2; ++k) \
;         acc[ai][bj][m][n] = __builtin_amdgcn_mfma_f32_16x16x32_bf16(Bt[n][k], At[m][k], acc[ai][bj][m][n], 0, 0, 0); __builtin_amdgcn_s_setprio(0); } while (0)
; #define PG8_WAIT_V(n) asm volatile("s_waitcnt vmcnt(" #n ")" ::: "memory")
; #define PG8_WAIT_L(n) asm volatile("s_waitcnt lgkmcnt(" #n ")" ::: "memory")
; #define PG8_BAR __builtin_amdgcn_s_barrier()
; #define PG8_SCHED __builtin_amdgcn_sched_barrier(0)
; template <class Epi, class Sched, bool ALIGN_EPI = false, bool SP2 = false>
; __device__ __forceinline__ void gemm_phase(PG8_LAS unsigned char* lds, const Gemm g, const Sched& S, const Epi& E) {
;     ...
;             PG8_WAIT_V(8); PG8_WAIT_L(0); PG8_BAR; PG8_MMA(0, 0, At, B0); PG8_MMA(0, 1, At, B1); PG8_BAR; PG8_SCHED;
;             PG8_LDA(At, 0, 1); PG8_STAGE(PG8_SB(0, 0), b2, voffB); PG8_STAGE(PG8_SB(0, 1), b2 + hstep, voffB); PG8_STAGE(PG8_SA(0, 0), a2, voffA);
;             PG8_WAIT_V(8); PG8_WAIT_L(0); PG8_BAR; PG8_MMA(1, 0, At, B0); PG8_MMA(1, 1, At, B1); PG8_BAR; PG8_SCHED;
;             PG8_LDB(B0, 1, 0); PG8_LDB(B1, 1, 1); PG8_SCHED; PG8_LDA(At, 1, 0); PG8_STAGE(PG8_SA(0, 1), a2 + hstep, voffA);
;             PG8_WAIT_V(8); PG8_WAIT_L(0); PG8_BAR; PG8_MMA(0, 0, At, B0); PG8_MMA(0, 1, At, B1); PG8_BAR; PG8_SCHED;
	s_setprio 1
	s_waitcnt lgkmcnt(0)
	v_mfma_f32_16x16x32_bf16 v[140:143], v[100:103], v[160:163], v[140:143]
	v_mfma_f32_16x16x32_bf16 v[136:139], v[124:127], v[160:163], v[136:139]
	v_mfma_f32_16x16x32_bf16 v[116:119], v[100:103], v[168:171], v[116:119]
	v_mfma_f32_16x16x32_bf16 v[112:115], v[124:127], v[168:171], v[112:115]
	v_mfma_f32_16x16x32_bf16 v[92:95], v[100:103], v[176:179], v[92:95]
	v_mfma_f32_16x16x32_bf16 v[88:91], v[124:127], v[176:179], v[88:91]
	v_mfma_f32_16x16x32_bf16 v[76:79], v[100:103], v[200:203], v[76:79]
	v_mfma_f32_16x16x32_bf16 v[72:75], v[124:127], v[200:203], v[72:75]
	v_mfma_f32_16x16x32_bf16 v[140:143], v[108:111], v[164:167], v[140:143]
	v_mfma_f32_16x16x32_bf16 v[136:139], v[132:135], v[164:167], v[136:139]
	v_mfma_f32_16x16x32_bf16 v[116:119], v[108:111], v[172:175], v[116:119]
	v_mfma_f32_16x16x32_bf16 v[112:115], v[132:135], v[172:175], v[112:115]
	v_mfma_f32_16x16x32_bf16 v[92:95], v[108:111], v[180:183], v[92:95]
	v_mfma_f32_16x16x32_bf16 v[88:91], v[132:135], v[180:183], v[88:91]
	v_mfma_f32_16x16x32_bf16 v[76:79], v[108:111], v[204:207], v[76:79]
	v_mfma_f32_16x16x32_bf16 v[72:75], v[132:135], v[204:207], v[72:75]
	s_setprio 0
	s_setprio 1
	v_mfma_f32_16x16x32_bf16 v[128:131], v[144:147], v[160:163], v[128:131]
	v_mfma_f32_16x16x32_bf16 v[120:123], v[152:155], v[160:163], v[120:123]
	v_mfma_f32_16x16x32_bf16 v[104:107], v[144:147], v[168:171], v[104:107]
	v_mfma_f32_16x16x32_bf16 v[96:99], v[152:155], v[168:171], v[96:99]
	v_mfma_f32_16x16x32_bf16 v[84:87], v[144:147], v[176:179], v[84:87]
	v_mfma_f32_16x16x32_bf16 v[80:83], v[152:155], v[176:179], v[80:83]
	v_mfma_f32_16x16x32_bf16 v[68:71], v[144:147], v[200:203], v[68:71]
	v_mfma_f32_16x16x32_bf16 v[64:67], v[152:155], v[200:203], v[64:67]
	v_mfma_f32_16x16x32_bf16 v[128:131], v[148:151], v[164:167], v[128:131]
	v_mfma_f32_16x16x32_bf16 v[120:123], v[156:159], v[164:167], v[120:123]
	v_mfma_f32_16x16x32_bf16 v[104:107], v[148:151], v[172:175], v[104:107]
	v_mfma_f32_16x16x32_bf16 v[96:99], v[156:159], v[172:175], v[96:99]
	v_mfma_f32_16x16x32_bf16 v[84:87], v[148:151], v[180:183], v[84:87]
	v_mfma_f32_16x16x32_bf16 v[80:83], v[156:159], v[180:183], v[80:83]
	v_mfma_f32_16x16x32_bf16 v[68:71], v[148:151], v[204:207], v[68:71]
	v_mfma_f32_16x16x32_bf16 v[64:67], v[156:159], v[204:207], v[64:67]
	s_setprio 0
	s_barrier
	s_add_i32 s34, s59, s43
	v_lshl_add_u64 v[208:209], s[38:39], 0, v[186:187]
	s_mov_b32 m0, s34
	ds_read_b128 v[160:163], v227 offset:16384
	ds_read_b128 v[164:167], v227 offset:17408
	ds_read_b128 v[168:171], v227 offset:18432
	ds_read_b128 v[172:175], v227 offset:19456
	ds_read_b128 v[176:179], v227 offset:20480
	ds_read_b128 v[180:183], v227 offset:21504
	ds_read_b128 v[200:203], v227 offset:22528
	ds_read_b128 v[204:207], v227 offset:23552
	global_load_lds_dwordx4 v[208:209], off
	s_add_i32 m0, s34, 0x2000
	s_add_u32 s34, s38, 0x160000
	v_lshl_add_u64 v[210:211], s[38:39], 0, v[190:191]
	s_addc_u32 s35, s39, 0
	s_add_i32 s66, s60, s43
	global_load_lds_dwordx4 v[210:211], off
	v_lshl_add_u64 v[212:213], s[34:35], 0, v[186:187]
	s_mov_b32 m0, s66
	v_lshl_add_u64 v[214:215], s[40:41], 0, v[188:189]
	global_load_lds_dwordx4 v[212:213], off
	v_lshl_add_u64 v[212:213], s[34:35], 0, v[190:191]
	s_add_i32 m0, s66, 0x2000
	s_nop 0
	global_load_lds_dwordx4 v[212:213], off
	v_lshl_add_u64 v[212:213], s[40:41], 0, v[184:185]
	s_mov_b32 m0, s52
	s_nop 0
	global_load_lds_dwordx4 v[212:213], off
	s_mov_b32 m0, s53
	s_nop 0
	global_load_lds_dwordx4 v[214:215], off
	s_waitcnt vmcnt(8)
	s_waitcnt lgkmcnt(0)
	s_barrier
	s_setprio 1
	s_waitcnt lgkmcnt(0)
	v_mfma_f32_16x16x32_bf16 v[60:63], v[100:103], v[160:163], v[60:63]
	v_mfma_f32_16x16x32_bf16 v[56:59], v[124:127], v[160:163], v[56:59]
	v_mfma_f32_16x16x32_bf16 v[44:47], v[100:103], v[168:171], v[44:47]
	v_mfma_f32_16x16x32_bf16 v[40:43], v[124:127], v[168:171], v[40:43]
	v_mfma_f32_16x16x32_bf16 v[28:31], v[100:103], v[176:179], v[28:31]
	v_mfma_f32_16x16x32_bf16 v[24:27], v[124:127], v[176:179], v[24:27]
	v_mfma_f32_16x16x32_bf16 v[12:15], v[100:103], v[200:203], v[12:15]
	v_mfma_f32_16x16x32_bf16 v[8:11], v[124:127], v[200:203], v[8:11]
	v_mfma_f32_16x16x32_bf16 v[60:63], v[108:111], v[164:167], v[60:63]
	v_mfma_f32_16x16x32_bf16 v[56:59], v[132:135], v[164:167], v[56:59]
	v_mfma_f32_16x16x32_bf16 v[44:47], v[108:111], v[172:175], v[44:47]
	v_mfma_f32_16x16x32_bf16 v[40:43], v[132:135], v[172:175], v[40:43]
	v_mfma_f32_16x16x32_bf16 v[28:31], v[108:111], v[180:183], v[28:31]
	v_mfma_f32_16x16x32_bf16 v[24:27], v[132:135], v[180:183], v[24:27]
	v_mfma_f32_16x16x32_bf16 v[12:15], v[108:111], v[204:207], v[12:15]
	v_mfma_f32_16x16x32_bf16 v[8:11], v[132:135], v[204:207], v[8:11]
	s_setprio 0
	s_setprio 1
	v_mfma_f32_16x16x32_bf16 v[52:55], v[144:147], v[160:163], v[52:55]
	v_mfma_f32_16x16x32_bf16 v[48:51], v[152:155], v[160:163], v[48:51]
	v_mfma_f32_16x16x32_bf16 v[36:39], v[144:147], v[168:171], v[36:39]
	v_mfma_f32_16x16x32_bf16 v[32:35], v[152:155], v[168:171], v[32:35]
	v_mfma_f32_16x16x32_bf16 v[20:23], v[144:147], v[176:179], v[20:23]
	v_mfma_f32_16x16x32_bf16 v[16:19], v[152:155], v[176:179], v[16:19]
	v_mfma_f32_16x16x32_bf16 v[4:7], v[144:147], v[200:203], v[4:7]
	v_mfma_f32_16x16x32_bf16 v[0:3], v[152:155], v[200:203], v[0:3]
	v_mfma_f32_16x16x32_bf16 v[52:55], v[148:151], v[164:167], v[52:55]
	v_mfma_f32_16x16x32_bf16 v[48:51], v[156:159], v[164:167], v[48:51]
	v_mfma_f32_16x16x32_bf16 v[36:39], v[148:151], v[172:175], v[36:39]
	v_mfma_f32_16x16x32_bf16 v[32:35], v[156:159], v[172:175], v[32:35]
	v_mfma_f32_16x16x32_bf16 v[20:23], v[148:151], v[180:183], v[20:23]
	v_mfma_f32_16x16x32_bf16 v[16:19], v[156:159], v[180:183], v[16:19]
	v_mfma_f32_16x16x32_bf16 v[4:7], v[148:151], v[204:207], v[4:7]
	v_mfma_f32_16x16x32_bf16 v[0:3], v[156:159], v[204:207], v[0:3]
	s_setprio 0
	s_barrier
; #define PG8_STAGE(bufoff, gbase, voff) do { _Pragma("unroll") for (int _i = 0; _i < 2; ++_i) \
;         __builtin_amdgcn_global_load_lds((const unsigned*)((const char*)(gbase) + (voff)[_i]), (PG8_LAS unsigned*)(lds + (bufoff) + ldsw + _i * 8192), 16, 0, 0); } while (0)
; #define PG8_LDA(dst, b, h) do { _Pragma("unroll") for (int m = 0; m < 4; ++m) _Pragma("unroll") for (int k = 0; k < 2; ++k) dst[m][k] = *(const PG8_LAS bf16x8*)(lds + PG8_SA(b, h) + aoff + m * 2048 + k * 1024); } while (0)
; #define PG8_LDB(dst, b, h) do { _Pragma("unroll") for (int n = 0; n < 2; ++n) _Pragma("unroll") for (int k = 0; k < 2; ++k) dst[n][k] = *(const PG8_LAS bf16x8*)(lds + PG8_SB(b, h) + boff + n * 2048 + k * 1024); } while (0)
; #define PG8_MMA(ai, bj, At, Bt) do { __builtin_amdgcn_s_setprio(1); _Pragma("unroll") for (int m = 0; m < 4; ++m) _Pragma("unroll") for (int n = 0; n < 2; ++n) _Pragma("unroll") for (int k = 0; k < 2; ++k) \
;         acc[ai][bj][m][n] = __builtin_amdgcn_mfma_f32_16x16x32_bf16(Bt[n][k], At[m][k], acc[ai][bj][m][n], 0, 0, 0); __builtin_amdgcn_s_setprio(0); } while (0)
; #define PG8_WAIT_V(n) asm volatile("s_waitcnt vmcnt(" #n ")" ::: "memory")
; #define PG8_WAIT_L(n) asm volatile("s_waitcnt lgkmcnt(" #n ")" ::: "memory")
; #define PG8_BAR __builtin_amdgcn_s_barrier()
; #define PG8_SCHED __builtin_amdgcn_sched_barrier(0)
; template <class Epi, class Sched, bool ALIGN_EPI = false, bool SP2 = false>
; __device__ __forceinline__ void gemm_phase(PG8_LAS unsigned char* lds, const Gemm g, const Sched& S, const Epi& E) {
;     ...
;             PG8_LDB(B0, 1, 0); PG8_LDB(B1, 1, 1); PG8_SCHED; PG8_LDA(At, 1, 0); PG8_STAGE(PG8_SA(0, 1), a2 + hstep, voffA);
;             PG8_WAIT_V(8); PG8_WAIT_L(0); PG8_BAR; PG8_MMA(0, 0, At, B0); PG8_MMA(0, 1, At, B1); PG8_BAR; PG8_SCHED;
;             PG8_LDA(At, 1, 1); PG8_STAGE(PG8_SB(1, 0), b3, voffB); PG8_STAGE(PG8_SB(1, 1), b3 + hstep, voffB); PG8_STAGE(PG8_SA(1, 0), a3, voffA);
;             PG8_WAIT_V(8); PG8_WAIT_L(0); PG8_BAR; PG8_MMA(1, 0, At, B0); PG8_MMA(1, 1, At, B1); PG8_BAR; PG8_SCHED;
	s_add_i32 s66, 0, 0x18000
	s_add_i32 s67, 0, 0x1c000
	v_add_u32_e32 v132, s66, v223
	v_add_u32_e32 v156, s67, v223
	ds_read_b128 v[100:103], v132
	ds_read_b128 v[108:111], v132 offset:1024
	ds_read_b128 v[124:127], v132 offset:2048
	ds_read_b128 v[132:135], v132 offset:3072
	ds_read_b128 v[144:147], v156
	ds_read_b128 v[148:151], v156 offset:1024
	ds_read_b128 v[152:155], v156 offset:2048
	ds_read_b128 v[156:159], v156 offset:3072
	s_add_u32 s34, s40, 0x160000
	s_addc_u32 s35, s41, 0
	s_mov_b32 m0, s54
	v_lshl_add_u64 v[216:217], s[34:35], 0, v[184:185]
	ds_read_b128 v[160:163], v227 offset:32768
	ds_read_b128 v[164:167], v227 offset:33792
	ds_read_b128 v[168:171], v227 offset:34816
	ds_read_b128 v[172:175], v227 offset:35840
	ds_read_b128 v[176:179], v227 offset:36864
	ds_read_b128 v[180:183], v227 offset:37888
	ds_read_b128 v[200:203], v227 offset:38912
	ds_read_b128 v[204:207], v227 offset:39936
	global_load_lds_dwordx4 v[216:217], off
	v_lshl_add_u64 v[216:217], s[34:35], 0, v[188:189]
	s_mov_b32 m0, s55
	s_nop 0
	global_load_lds_dwordx4 v[216:217], off
	s_waitcnt vmcnt(8)
	s_waitcnt lgkmcnt(0)
	s_barrier
	s_setprio 1
	s_waitcnt lgkmcnt(0)
	v_mfma_f32_16x16x32_bf16 v[140:143], v[100:103], v[160:163], v[140:143]
	v_mfma_f32_16x16x32_bf16 v[136:139], v[124:127], v[160:163], v[136:139]
	v_mfma_f32_16x16x32_bf16 v[116:119], v[100:103], v[168:171], v[116:119]
	v_mfma_f32_16x16x32_bf16 v[112:115], v[124:127], v[168:171], v[112:115]
	v_mfma_f32_16x16x32_bf16 v[92:95], v[100:103], v[176:179], v[92:95]
	v_mfma_f32_16x16x32_bf16 v[88:91], v[124:127], v[176:179], v[88:91]
	v_mfma_f32_16x16x32_bf16 v[76:79], v[100:103], v[200:203], v[76:79]
	v_mfma_f32_16x16x32_bf16 v[72:75], v[124:127], v[200:203], v[72:75]
	v_mfma_f32_16x16x32_bf16 v[140:143], v[108:111], v[164:167], v[140:143]
	v_mfma_f32_16x16x32_bf16 v[136:139], v[132:135], v[164:167], v[136:139]
	v_mfma_f32_16x16x32_bf16 v[116:119], v[108:111], v[172:175], v[116:119]
	v_mfma_f32_16x16x32_bf16 v[112:115], v[132:135], v[172:175], v[112:115]
	v_mfma_f32_16x16x32_bf16 v[92:95], v[108:111], v[180:183], v[92:95]
	v_mfma_f32_16x16x32_bf16 v[88:91], v[132:135], v[180:183], v[88:91]
	v_mfma_f32_16x16x32_bf16 v[76:79], v[108:111], v[204:207], v[76:79]
	v_mfma_f32_16x16x32_bf16 v[72:75], v[132:135], v[204:207], v[72:75]
	s_setprio 0
	s_setprio 1
	v_mfma_f32_16x16x32_bf16 v[128:131], v[144:147], v[160:163], v[128:131]
	v_mfma_f32_16x16x32_bf16 v[120:123], v[152:155], v[160:163], v[120:123]
	v_mfma_f32_16x16x32_bf16 v[104:107], v[144:147], v[168:171], v[104:107]
	v_mfma_f32_16x16x32_bf16 v[96:99], v[152:155], v[168:171], v[96:99]
	v_mfma_f32_16x16x32_bf16 v[84:87], v[144:147], v[176:179], v[84:87]
	v_mfma_f32_16x16x32_bf16 v[80:83], v[152:155], v[176:179], v[80:83]
	v_mfma_f32_16x16x32_bf16 v[68:71], v[144:147], v[200:203], v[68:71]
	v_mfma_f32_16x16x32_bf16 v[64:67], v[152:155], v[200:203], v[64:67]
	v_mfma_f32_16x16x32_bf16 v[128:131], v[148:151], v[164:167], v[128:131]
	v_mfma_f32_16x16x32_bf16 v[120:123], v[156:159], v[164:167], v[120:123]
	v_mfma_f32_16x16x32_bf16 v[104:107], v[148:151], v[172:175], v[104:107]
	v_mfma_f32_16x16x32_bf16 v[96:99], v[156:159], v[172:175], v[96:99]
	v_mfma_f32_16x16x32_bf16 v[84:87], v[148:151], v[180:183], v[84:87]
	v_mfma_f32_16x16x32_bf16 v[80:83], v[156:159], v[180:183], v[80:83]
	v_mfma_f32_16x16x32_bf16 v[68:71], v[148:151], v[204:207], v[68:71]
	v_mfma_f32_16x16x32_bf16 v[64:67], v[156:159], v[204:207], v[64:67]
	s_setprio 0
	s_barrier
	s_add_i32 s34, s66, s43
	v_lshl_add_u64 v[208:209], v[208:209], 0, s[26:27]
	s_mov_b32 m0, s34
	ds_read_b128 v[160:163], v227 offset:49152
	ds_read_b128 v[164:167], v227 offset:50176
	ds_read_b128 v[168:171], v227 offset:51200
	ds_read_b128 v[172:175], v227 offset:52224
	ds_read_b128 v[176:179], v227 offset:53248
	ds_read_b128 v[180:183], v227 offset:54272
	ds_read_b128 v[200:203], v227 offset:55296
	ds_read_b128 v[204:207], v227 offset:56320
	global_load_lds_dwordx4 v[208:209], off
	s_add_i32 m0, s34, 0x2000
	s_add_u32 s34, s38, 0x160080
	v_lshl_add_u64 v[208:209], v[210:211], 0, s[26:27]
	s_addc_u32 s35, s39, 0
	s_add_i32 s38, s67, s43
	global_load_lds_dwordx4 v[208:209], off
	v_lshl_add_u64 v[208:209], s[34:35], 0, v[186:187]
	s_mov_b32 m0, s38
	s_nop 0
	global_load_lds_dwordx4 v[208:209], off
	v_lshl_add_u64 v[208:209], s[34:35], 0, v[190:191]
	s_add_i32 m0, s38, 0x2000
	s_nop 0
	global_load_lds_dwordx4 v[208:209], off
	v_lshl_add_u64 v[208:209], v[212:213], 0, s[26:27]
	s_mov_b32 m0, s57
	s_nop 0
	global_load_lds_dwordx4 v[208:209], off
	v_lshl_add_u64 v[208:209], v[214:215], 0, s[26:27]
	s_mov_b32 m0, s58
	s_nop 0
	global_load_lds_dwordx4 v[208:209], off
	s_waitcnt vmcnt(8)
	s_waitcnt lgkmcnt(0)
	s_barrier
; #define PG8_MMA(ai, bj, At, Bt) do { __builtin_amdgcn_s_setprio(1); _Pragma("unroll") for (int m = 0; m < 4; ++m) _Pragma("unroll") for (int n = 0; n < 2; ++n) _Pragma("unroll") for (int k = 0; k < 2; ++k) \
;         acc[ai][bj][m][n] = __builtin_amdgcn_mfma_f32_16x16x32_bf16(Bt[n][k], At[m][k], acc[ai][bj][m][n], 0, 0, 0); __builtin_amdgcn_s_setprio(0); } while (0)
; #define PG8_WAIT_V(n) asm volatile("s_waitcnt vmcnt(" #n ")" ::: "memory")
; #define PG8_WAIT_L(n) asm volatile("s_waitcnt lgkmcnt(" #n ")" ::: "memory")
; #define PG8_BAR __builtin_amdgcn_s_barrier()
; #define PG8_SCHED __builtin_amdgcn_sched_barrier(0)
; template <class Epi, class Sched, bool ALIGN_EPI = false, bool SP2 = false>
; __device__ __forceinline__ void gemm_phase(PG8_LAS unsigned char* lds, const Gemm g, const Sched& S, const Epi& E) {
;     ...
;         for (int t = 0; t < nt; t += 2) {
;     ...
;             PG8_WAIT_V(8); PG8_WAIT_L(0); PG8_BAR; PG8_MMA(1, 0, At, B0); PG8_MMA(1, 1, At, B1); PG8_BAR; PG8_SCHED;
;     ...
;         if constexpr (ALIGN_EPI) { if (wr == 0) PG8_BAR; }
	s_setprio 1
	s_waitcnt lgkmcnt(0)
	v_mfma_f32_16x16x32_bf16 v[60:63], v[100:103], v[160:163], v[60:63]
	v_mfma_f32_16x16x32_bf16 v[56:59], v[124:127], v[160:163], v[56:59]
	v_mfma_f32_16x16x32_bf16 v[44:47], v[100:103], v[168:171], v[44:47]
	v_mfma_f32_16x16x32_bf16 v[40:43], v[124:127], v[168:171], v[40:43]
	v_mfma_f32_16x16x32_bf16 v[28:31], v[100:103], v[176:179], v[28:31]
	v_mfma_f32_16x16x32_bf16 v[24:27], v[124:127], v[176:179], v[24:27]
	v_mfma_f32_16x16x32_bf16 v[12:15], v[100:103], v[200:203], v[12:15]
	v_mfma_f32_16x16x32_bf16 v[8:11], v[124:127], v[200:203], v[8:11]
	v_mfma_f32_16x16x32_bf16 v[60:63], v[108:111], v[164:167], v[60:63]
	v_mfma_f32_16x16x32_bf16 v[56:59], v[132:135], v[164:167], v[56:59]
	v_mfma_f32_16x16x32_bf16 v[44:47], v[108:111], v[172:175], v[44:47]
	v_mfma_f32_16x16x32_bf16 v[40:43], v[132:135], v[172:175], v[40:43]
	v_mfma_f32_16x16x32_bf16 v[28:31], v[108:111], v[180:183], v[28:31]
	v_mfma_f32_16x16x32_bf16 v[24:27], v[132:135], v[180:183], v[24:27]
	v_mfma_f32_16x16x32_bf16 v[12:15], v[108:111], v[204:207], v[12:15]
	v_mfma_f32_16x16x32_bf16 v[8:11], v[132:135], v[204:207], v[8:11]
	s_setprio 0
	s_setprio 1
	v_mfma_f32_16x16x32_bf16 v[52:55], v[144:147], v[160:163], v[52:55]
	v_mfma_f32_16x16x32_bf16 v[48:51], v[152:155], v[160:163], v[48:51]
	v_mfma_f32_16x16x32_bf16 v[36:39], v[144:147], v[168:171], v[36:39]
	v_mfma_f32_16x16x32_bf16 v[32:35], v[152:155], v[168:171], v[32:35]
	v_mfma_f32_16x16x32_bf16 v[20:23], v[144:147], v[176:179], v[20:23]
	v_mfma_f32_16x16x32_bf16 v[16:19], v[152:155], v[176:179], v[16:19]
	v_mfma_f32_16x16x32_bf16 v[4:7], v[144:147], v[200:203], v[4:7]
	v_mfma_f32_16x16x32_bf16 v[0:3], v[152:155], v[200:203], v[0:3]
	v_mfma_f32_16x16x32_bf16 v[52:55], v[148:151], v[164:167], v[52:55]
	v_mfma_f32_16x16x32_bf16 v[48:51], v[156:159], v[164:167], v[48:51]
	v_mfma_f32_16x16x32_bf16 v[36:39], v[148:151], v[172:175], v[36:39]
	v_mfma_f32_16x16x32_bf16 v[32:35], v[156:159], v[172:175], v[32:35]
	v_mfma_f32_16x16x32_bf16 v[20:23], v[148:151], v[180:183], v[20:23]
	v_mfma_f32_16x16x32_bf16 v[16:19], v[156:159], v[180:183], v[16:19]
	v_mfma_f32_16x16x32_bf16 v[4:7], v[148:151], v[204:207], v[4:7]
	v_mfma_f32_16x16x32_bf16 v[0:3], v[156:159], v[204:207], v[0:3]
	s_setprio 0
	s_barrier
	s_add_i32 s65, s65, 2
	s_add_u32 s51, s51, 0x100
	s_addc_u32 s64, s64, 0
	s_cmpk_gt_u32 s65, 0x55
	s_mov_b64 s[34:35], s[36:37]
	s_cbranch_scc0 .LBB0_1153
.Lpeel_exit_4:
	s_and_b64 vcc, exec, s[28:29]
	s_cbranch_vccz .LBB0_1156
	s_barrier
; __device__ __forceinline__ unsigned cvt_pk_bf16(float lo, float hi) { f32x2_cv v = {lo, hi}; bf16x2_cv b = __builtin_convertvector(v, bf16x2_cv); return __builtin_bit_cast(unsigned, b); }
;     __device__ __forceinline__ void operator()(const f32x4 (&acc)[2][2][4][2], const Unit& u, int wr, int wc, int fr, int fq) const {
;         const int col0 = u.pn * BM + wc * 32 + 8 * fq;
;         const int row0 = u.pm * BM + wr * 64 + fr;
;         u32x4 b[2][4][2];
; #pragma unroll
;         for (int ai = 0; ai < 2; ++ai)
; #pragma unroll
;             for (int m = 0; m < 4; ++m)
; #pragma unroll
;                 for (int bj = 0; bj < 2; ++bj) b[ai][m][bj] = *(const u32x4*)(X + (size_t)(row0 + ai * HALF + m * 16) * ldc + col0 + bj * HALF);
; #pragma unroll
;         for (int ai = 0; ai < 2; ++ai)
; #pragma unroll
;             for (int m = 0; m < 4; ++m) { const int row = row0 + ai * HALF + m * 16; const size_t off = (size_t)row * ldc + col0; float ss = 0.f;
; #pragma unroll
;                 for (int bj = 0; bj < 2; ++bj) { const u32x4 bb = b[ai][m][bj]; const unsigned xw[4] = {bb.x, bb.y, bb.z, bb.w}; unsigned ow[4];
; #pragma unroll
;                     for (int q = 0; q < 4; ++q) { const f32x4 a = acc[ai][bj][m][q >> 1];
;                         ow[q] = cvt_pk_bf16(__uint_as_float(xw[q] << 16) + a[(q & 1) * 2], __uint_as_float(xw[q] & 0xffff0000u) + a[(q & 1) * 2 + 1]);
;                         const float y0 = __uint_as_float(ow[q] << 16), y1 = __uint_as_float(ow[q] & 0xffff0000u); ss += y0 * y0 + y1 * y1; }
;                     *(u32x4*)(X + off + bj * HALF) = (u32x4){ow[0], ow[1], ow[2], ow[3]}; }
;                 ss += __shfl_xor(ss, 16); ss += __shfl_xor(ss, 32);
;                 if (fq == 0) SS[(size_t)row * 32 + u.pn * 4 + wc] = ss; }
.LBB0_1156:
	v_lshl_or_b32 v200, s18, 8, v224
	v_lshl_add_u32 v216, s50, 8, v222
	v_ashrrev_i32_e32 v201, 31, v200
	v_lshlrev_b64 v[218:219], 1, v[200:201]
	v_ashrrev_i32_e32 v217, 31, v216
	v_lshl_add_u64 v[100:101], s[22:23], 0, v[218:219]
	v_lshlrev_b64 v[220:221], 12, v[216:217]
	v_lshl_add_u64 v[102:103], v[100:101], 0, v[220:221]
	global_load_dwordx4 v[230:233], v[102:103], off
	global_load_dwordx4 v[236:239], v[102:103], off offset:256
	v_and_b32_e32 v109, 64, v228
	v_xor_b32_e32 v108, 16, v228
	v_or_b32_e32 v214, 16, v216
	v_or_b32_e32 v212, 32, v216
	v_or_b32_e32 v210, 48, v216
	v_add_u32_e32 v208, 0x80, v216
	v_add_u32_e32 v206, 0x90, v216
	v_add_u32_e32 v204, 0xa0, v216
	v_add_u32_e32 v202, 0xb0, v216
	v_add_u32_e32 v245, 64, v109
	v_ashrrev_i32_e32 v215, 31, v214
	v_ashrrev_i32_e32 v213, 31, v212
	v_ashrrev_i32_e32 v211, 31, v210
	v_ashrrev_i32_e32 v209, 31, v208
	v_ashrrev_i32_e32 v207, 31, v206
	v_ashrrev_i32_e32 v205, 31, v204
	v_ashrrev_i32_e32 v203, 31, v202
	v_cmp_lt_i32_e32 vcc, v108, v245
	v_lshlrev_b64 v[102:103], 12, v[214:215]
	v_lshlrev_b64 v[110:111], 12, v[210:211]
	v_cndmask_b32_e32 v144, v228, v108, vcc
	v_lshlrev_b64 v[108:109], 12, v[212:213]
	v_lshlrev_b64 v[124:125], 12, v[208:209]
	v_lshlrev_b64 v[126:127], 12, v[206:207]
	v_lshlrev_b64 v[132:133], 12, v[204:205]
	v_lshlrev_b64 v[134:135], 12, v[202:203]
	v_lshl_add_u64 v[102:103], v[100:101], 0, v[102:103]
	v_lshl_add_u64 v[108:109], v[100:101], 0, v[108:109]
	v_lshl_add_u64 v[110:111], v[100:101], 0, v[110:111]
	v_lshl_add_u64 v[124:125], v[100:101], 0, v[124:125]
	v_lshl_add_u64 v[126:127], v[100:101], 0, v[126:127]
	v_lshl_add_u64 v[240:241], v[100:101], 0, v[132:133]
	v_lshl_add_u64 v[100:101], v[100:101], 0, v[134:135]
	v_lshlrev_b32_e32 v229, 2, v144
	global_load_dwordx4 v[180:183], v[102:103], off
	global_load_dwordx4 v[176:179], v[102:103], off offset:256
	global_load_dwordx4 v[172:175], v[108:109], off
	global_load_dwordx4 v[168:171], v[108:109], off offset:256
	global_load_dwordx4 v[164:167], v[110:111], off
	global_load_dwordx4 v[160:163], v[110:111], off offset:256
	global_load_dwordx4 v[156:159], v[124:125], off
	global_load_dwordx4 v[152:155], v[124:125], off offset:256
	global_load_dwordx4 v[148:151], v[126:127], off
	global_load_dwordx4 v[144:147], v[126:127], off offset:256
	global_load_dwordx4 v[132:135], v[240:241], off
	s_nop 0
	global_load_dwordx4 v[124:127], v[240:241], off offset:256
	global_load_dwordx4 v[108:111], v[100:101], off
	s_nop 0
	global_load_dwordx4 v[100:103], v[100:101], off offset:256
	v_xor_b32_e32 v244, 32, v228
	v_cmp_lt_i32_e32 vcc, v244, v245
	s_lshl_b32 s34, s18, 2
	s_ashr_i32 s35, s34, 31
	s_waitcnt vmcnt(0)
	v_lshlrev_b32_e32 v240, 16, v230
	v_and_b32_e32 v241, 0xffff0000, v230
	v_lshlrev_b32_e32 v230, 16, v231
	v_and_b32_e32 v231, 0xffff0000, v231
	v_lshlrev_b32_e32 v242, 16, v232
	v_and_b32_e32 v243, 0xffff0000, v232
	v_pk_add_f32 v[140:141], v[140:141], v[240:241]
	v_pk_add_f32 v[142:143], v[142:143], v[230:231]
	v_lshlrev_b32_e32 v232, 16, v233
	v_and_b32_e32 v233, 0xffff0000, v233
	v_pk_add_f32 v[230:231], v[136:137], v[242:243]
	v_cvt_pk_bf16_f32 v136, v140, v141
	v_cvt_pk_bf16_f32 v137, v142, v143
	v_pk_add_f32 v[232:233], v[138:139], v[232:233]
	v_cvt_pk_bf16_f32 v138, v230, v231
	v_and_b32_e32 v141, 0xffff0000, v136
	v_and_b32_e32 v143, 0xffff0000, v137
	v_cvt_pk_bf16_f32 v139, v232, v233
	v_lshlrev_b32_e32 v140, 16, v136
	v_lshlrev_b32_e32 v142, 16, v137
	v_and_b32_e32 v231, 0xffff0000, v138
	v_mul_f32_e32 v141, v141, v141
	v_mul_f32_e32 v143, v143, v143
	v_lshlrev_b32_e32 v230, 16, v138
	v_and_b32_e32 v233, 0xffff0000, v139
	v_mul_f32_e32 v231, v231, v231
	v_fmac_f32_e32 v141, v140, v140
	v_fmac_f32_e32 v143, v142, v142
	v_lshlrev_b32_e32 v232, 16, v139
	v_mul_f32_e32 v233, v233, v233
	v_fmac_f32_e32 v231, v230, v230
	v_add_f32_e32 v140, v141, v143
	v_fmac_f32_e32 v233, v232, v232
	v_add_f32_e32 v140, v231, v140
	v_add_f32_e32 v142, v233, v140
	v_lshlrev_b32_e32 v140, 16, v236
	v_and_b32_e32 v141, 0xffff0000, v236
	v_pk_add_f32 v[128:129], v[128:129], v[140:141]
	v_and_b32_e32 v141, 0xffff0000, v237
	v_cvt_pk_bf16_f32 v128, v128, v129
	v_and_b32_e32 v140, 0xffff0000, v128
	v_lshlrev_b32_e32 v129, 16, v128
	v_mul_f32_e32 v140, v140, v140
	v_fmac_f32_e32 v140, v129, v129
	v_add_f32_e32 v142, v140, v142
	v_lshlrev_b32_e32 v140, 16, v237
	v_pk_add_f32 v[130:131], v[130:131], v[140:141]
	s_nop 0
	v_cvt_pk_bf16_f32 v129, v130, v131
	v_and_b32_e32 v131, 0xffff0000, v129
	v_lshlrev_b32_e32 v130, 16, v129
	v_mul_f32_e32 v131, v131, v131
	v_fmac_f32_e32 v131, v130, v130
	v_add_f32_e32 v140, v131, v142
	v_lshlrev_b32_e32 v130, 16, v238
	v_and_b32_e32 v131, 0xffff0000, v238
	v_pk_add_f32 v[120:121], v[120:121], v[130:131]
	s_nop 0
	v_cvt_pk_bf16_f32 v130, v120, v121
	v_and_b32_e32 v121, 0xffff0000, v130
	v_lshlrev_b32_e32 v120, 16, v130
	v_mul_f32_e32 v121, v121, v121
	v_fmac_f32_e32 v121, v120, v120
	v_add_f32_e32 v140, v121, v140
	v_lshlrev_b32_e32 v120, 16, v239
	v_and_b32_e32 v121, 0xffff0000, v239
	v_pk_add_f32 v[120:121], v[122:123], v[120:121]
	s_nop 0
	v_cvt_pk_bf16_f32 v131, v120, v121
	v_and_b32_e32 v121, 0xffff0000, v131
	v_lshlrev_b32_e32 v120, 16, v131
	v_mul_f32_e32 v121, v121, v121
	v_fmac_f32_e32 v121, v120, v120
	v_add_f32_e32 v121, v121, v140
	ds_bpermute_b32 v122, v229, v121
	v_cndmask_b32_e32 v120, v228, v244, vcc
	v_lshlrev_b32_e32 v120, 2, v120
	v_lshl_add_u64 v[140:141], s[22:23], 0, v[220:221]
	v_lshl_add_u64 v[140:141], v[140:141], 0, v[218:219]
	s_waitcnt lgkmcnt(0)
	v_add_f32_e32 v121, v121, v122
	ds_bpermute_b32 v122, v120, v121
	global_store_dwordx4 v[140:141], v[136:139], off
	global_store_dwordx4 v[140:141], v[128:131], off offset:256
	s_and_saveexec_b64 s[36:37], s[12:13]
	s_cbranch_execz .LBB0_1158
	v_lshlrev_b64 v[128:129], 7, v[216:217]
	v_lshl_add_u64 v[128:129], s[24:25], 0, v[128:129]
	v_lshl_add_u64 v[128:129], s[34:35], 2, v[128:129]
	s_lshl_b32 s18, s56, 2
	v_lshl_add_u64 v[128:129], v[128:129], 0, s[18:19]
	s_waitcnt lgkmcnt(0)
	v_add_f32_e32 v121, v121, v122
	global_store_dword v[128:129], v121, off

; #define PG8_LDA(dst, b, h) do { _Pragma("unroll") for (int m = 0; m < 4; ++m) _Pragma("unroll") for (int k = 0; k < 2; ++k) dst[m][k] = *(const PG8_LAS bf16x8*)(lds + PG8_SA(b, h) + aoff + m * 2048 + k * 1024); } while (0)
; template <class Epi, class Sched, bool ALIGN_EPI = false, bool SP2 = false>
; __device__ __forceinline__ void gemm_phase(PG8_LAS unsigned char* lds, const Gemm g, const Sched& S, const Epi& E) {
;     ...
;         const bool has_next = S.next(ui + 1, nxt);
;         const char* nA = has_next ? (const char*)g.A + (size_t)nxt.pm * tstep : cA; const char* nB = has_next ? (const char*)g.Bt + (size_t)nxt.pn * tstep : cB;
;         for (int t = 0; t < nt; t += 2) {
;             const bool last = (t == nt - 2);
;             const char* a1 = cA + (size_t)(t + 1) * kstep;
;             const char* a2 = last ? nA : cA + (size_t)(t + 2) * kstep; const char* b2 = last ? nB : cB + (size_t)(t + 2) * kstep;
;             const char* a3 = a2 + kstep; const char* b3 = b2 + kstep;
;             if (last && has_next) S.a_ready(nxt);
;             if constexpr (SP2) {
;             PG8_LDB(B0, 0, 0); PG8_LDB(B1, 0, 1); PG8_SCHED; PG8_LDA(At, 0, 0); PG8_STAGE(PG8_SA(1, 1), a1 + hstep, voffA);
;             PG8_WAIT_V(8); PG8_WAIT_L(0); PG8_BAR; PG8_MMA(0, 0, At, B0); PG8_MMA(0, 1, At, B1); PG8_BAR; PG8_SCHED;
;             PG8_LDA(At, 0, 1); PG8_STAGE(PG8_SB(0, 0), b2, voffB); PG8_STAGE(PG8_SB(0, 1), b2 + hstep, voffB); PG8_STAGE(PG8_SA(0, 0), a2, voffA);
;             PG8_WAIT_V(8); PG8_WAIT_L(0); PG8_BAR; PG8_MMA(1, 0, At, B0); PG8_MMA(1, 1, At, B1); PG8_BAR; PG8_SCHED;
;             PG8_LDB(B0, 1, 0); PG8_LDB(B1, 1, 1); PG8_SCHED; PG8_LDA(At, 1, 0); PG8_STAGE(PG8_SA(0, 1), a2 + hstep, voffA);
;             PG8_WAIT_V(8); PG8_WAIT_L(0); PG8_BAR; PG8_MMA(0, 0, At, B0); PG8_MMA(0, 1, At, B1); PG8_BAR; PG8_SCHED;
;             PG8_LDA(At, 1, 1); PG8_STAGE(PG8_SB(1, 0), b3, voffB); PG8_STAGE(PG8_SB(1, 1), b3 + hstep, voffB); PG8_STAGE(PG8_SA(1, 0), a3, voffA);
;             PG8_WAIT_V(8); PG8_WAIT_L(0); PG8_BAR; PG8_MMA(1, 0, At, B0); PG8_MMA(1, 1, At, B1); PG8_BAR; PG8_SCHED;
;     ...
; #pragma unroll
;         for (int a = 0; a < 2; ++a)
; #pragma unroll
;             for (int b = 0; b < 2; ++b)
; #pragma unroll
;                 for (int m = 0; m < 4; ++m)
; #pragma unroll
;                     for (int n = 0; n < 2; ++n) acc[a][b][m][n] = (f32x4){0.f, 0.f, 0.f, 0.f};
.LBB0_1267:
	s_ashr_i32 s35, s34, 31
	s_lshl_b64 s[36:37], s[34:35], 20
	s_add_u32 s36, s57, s36
	s_addc_u32 s37, s58, s37
	s_and_b64 s[38:39], s[12:13], exec
	s_cselect_b32 s35, s37, s43
	s_cselect_b32 s51, s36, s42
	s_ashr_i32 s31, s30, 31
	s_lshl_b64 s[38:39], s[30:31], 20
	s_add_u32 s38, s59, s38
	s_addc_u32 s39, s60, s39
	s_and_b64 s[54:55], s[12:13], exec
	s_cselect_b32 s31, s39, s53
	s_cselect_b32 s71, s38, s52
	s_add_u32 s42, s42, 0x80080
	s_addc_u32 s43, s43, 0
	s_add_u32 s77, s52, 0x100
	s_addc_u32 s78, s53, 0
	s_mov_b32 s79, -2
	ds_read_b128 v[144:147], v154
	ds_read_b128 v[158:161], v154 offset:1024
	ds_read_b128 v[162:165], v154 offset:2048
	ds_read_b128 v[166:169], v154 offset:3072
	ds_read_b128 v[170:173], v155
	ds_read_b128 v[174:177], v155 offset:1024
	ds_read_b128 v[178:181], v155 offset:2048
	ds_read_b128 v[182:185], v155 offset:3072
	s_add_u32 s52, s42, 0xfff80080
	s_addc_u32 s53, s43, -1
	s_cmp_eq_u32 s79, 28
	s_cselect_b32 s55, s35, s53
	s_cselect_b32 s54, s51, s52
	s_cselect_b32 s53, s31, s78
	s_cselect_b32 s52, s71, s77
	v_lshl_add_u64 v[148:149], s[42:43], 0, v[136:137]
	s_add_i32 m0, s41, 0xc000
	ds_read_b128 v[186:189], v156
	ds_read_b128 v[190:193], v156 offset:1024
	ds_read_b128 v[194:197], v156 offset:2048
	ds_read_b128 v[198:201], v156 offset:3072
	ds_read_b128 v[202:205], v156 offset:4096
	ds_read_b128 v[206:209], v156 offset:5120
	ds_read_b128 v[210:213], v156 offset:6144
	ds_read_b128 v[214:217], v156 offset:7168
	global_load_lds_dwordx4 v[148:149], off
	v_lshl_add_u64 v[148:149], s[42:43], 0, v[138:139]
	s_add_i32 m0, s41, 0xe000
	s_nop 0
	global_load_lds_dwordx4 v[148:149], off
	s_waitcnt vmcnt(8)
	s_waitcnt lgkmcnt(0)
	s_barrier
	s_setprio 1
	s_waitcnt lgkmcnt(0)
	v_mfma_f32_16x16x32_bf16 v[124:127], v[144:147], v[186:189], 0
	v_mfma_f32_16x16x32_bf16 v[120:123], v[162:165], v[186:189], 0
	v_mfma_f32_16x16x32_bf16 v[108:111], v[144:147], v[194:197], 0
	v_mfma_f32_16x16x32_bf16 v[104:107], v[162:165], v[194:197], 0
	v_mfma_f32_16x16x32_bf16 v[92:95], v[144:147], v[202:205], 0
	v_mfma_f32_16x16x32_bf16 v[88:91], v[162:165], v[202:205], 0
	v_mfma_f32_16x16x32_bf16 v[76:79], v[144:147], v[210:213], 0
	v_mfma_f32_16x16x32_bf16 v[72:75], v[162:165], v[210:213], 0
	v_mfma_f32_16x16x32_bf16 v[124:127], v[158:161], v[190:193], v[124:127]
	v_mfma_f32_16x16x32_bf16 v[120:123], v[166:169], v[190:193], v[120:123]
	v_mfma_f32_16x16x32_bf16 v[108:111], v[158:161], v[198:201], v[108:111]
	v_mfma_f32_16x16x32_bf16 v[104:107], v[166:169], v[198:201], v[104:107]
	v_mfma_f32_16x16x32_bf16 v[92:95], v[158:161], v[206:209], v[92:95]
	v_mfma_f32_16x16x32_bf16 v[88:91], v[166:169], v[206:209], v[88:91]
	v_mfma_f32_16x16x32_bf16 v[76:79], v[158:161], v[214:217], v[76:79]
	v_mfma_f32_16x16x32_bf16 v[72:75], v[166:169], v[214:217], v[72:75]
	s_setprio 0
	s_setprio 1
	v_mfma_f32_16x16x32_bf16 v[116:119], v[170:173], v[186:189], 0
	v_mfma_f32_16x16x32_bf16 v[112:115], v[178:181], v[186:189], 0
	v_mfma_f32_16x16x32_bf16 v[100:103], v[170:173], v[194:197], 0
	v_mfma_f32_16x16x32_bf16 v[96:99], v[178:181], v[194:197], 0
	v_mfma_f32_16x16x32_bf16 v[84:87], v[170:173], v[202:205], 0
	v_mfma_f32_16x16x32_bf16 v[80:83], v[178:181], v[202:205], 0
	v_mfma_f32_16x16x32_bf16 v[68:71], v[170:173], v[210:213], 0
	v_mfma_f32_16x16x32_bf16 v[64:67], v[178:181], v[210:213], 0
	v_mfma_f32_16x16x32_bf16 v[116:119], v[174:177], v[190:193], v[116:119]
	v_mfma_f32_16x16x32_bf16 v[112:115], v[182:185], v[190:193], v[112:115]
	v_mfma_f32_16x16x32_bf16 v[100:103], v[174:177], v[198:201], v[100:103]
	v_mfma_f32_16x16x32_bf16 v[96:99], v[182:185], v[198:201], v[96:99]
	v_mfma_f32_16x16x32_bf16 v[84:87], v[174:177], v[206:209], v[84:87]
	v_mfma_f32_16x16x32_bf16 v[80:83], v[182:185], v[206:209], v[80:83]
	v_mfma_f32_16x16x32_bf16 v[68:71], v[174:177], v[214:217], v[68:71]
	v_mfma_f32_16x16x32_bf16 v[64:67], v[182:185], v[214:217], v[64:67]
	s_setprio 0
	s_barrier
	s_add_i32 s80, s67, s56
	v_lshl_add_u64 v[148:149], s[52:53], 0, v[130:131]
	s_mov_b32 m0, s80
	ds_read_b128 v[186:189], v156 offset:16384
	ds_read_b128 v[190:193], v156 offset:17408
	ds_read_b128 v[194:197], v156 offset:18432
	ds_read_b128 v[198:201], v156 offset:19456
	ds_read_b128 v[202:205], v156 offset:20480
	ds_read_b128 v[206:209], v156 offset:21504
	ds_read_b128 v[210:213], v156 offset:22528
	ds_read_b128 v[214:217], v156 offset:23552
	global_load_lds_dwordx4 v[148:149], off
	s_add_i32 m0, s80, 0x2000
	s_add_u32 s80, s52, 0x80000
	v_lshl_add_u64 v[218:219], s[52:53], 0, v[134:135]
	s_addc_u32 s81, s53, 0
	s_add_i32 s82, s68, s56
	global_load_lds_dwordx4 v[218:219], off
	v_lshl_add_u64 v[220:221], s[80:81], 0, v[130:131]
	s_mov_b32 m0, s82
	v_lshl_add_u64 v[222:223], s[54:55], 0, v[132:133]
	global_load_lds_dwordx4 v[220:221], off
	v_lshl_add_u64 v[220:221], s[80:81], 0, v[134:135]
	s_add_i32 m0, s82, 0x2000
	s_nop 0
	global_load_lds_dwordx4 v[220:221], off
	v_lshl_add_u64 v[220:221], s[54:55], 0, v[128:129]
	s_mov_b32 m0, s41
	s_nop 0
	global_load_lds_dwordx4 v[220:221], off
	s_mov_b32 m0, s61
	s_nop 0
	global_load_lds_dwordx4 v[222:223], off
	s_waitcnt vmcnt(8)
	s_waitcnt lgkmcnt(0)
	s_barrier
; #define PG8_STAGE(bufoff, gbase, voff) do { _Pragma("unroll") for (int _i = 0; _i < 2; ++_i) \
;         __builtin_amdgcn_global_load_lds((const unsigned*)((const char*)(gbase) + (voff)[_i]), (PG8_LAS unsigned*)(lds + (bufoff) + ldsw + _i * 8192), 16, 0, 0); } while (0)
; #define PG8_LDA(dst, b, h) do { _Pragma("unroll") for (int m = 0; m < 4; ++m) _Pragma("unroll") for (int k = 0; k < 2; ++k) dst[m][k] = *(const PG8_LAS bf16x8*)(lds + PG8_SA(b, h) + aoff + m * 2048 + k * 1024); } while (0)
; #define PG8_LDB(dst, b, h) do { _Pragma("unroll") for (int n = 0; n < 2; ++n) _Pragma("unroll") for (int k = 0; k < 2; ++k) dst[n][k] = *(const PG8_LAS bf16x8*)(lds + PG8_SB(b, h) + boff + n * 2048 + k * 1024); } while (0)
; #define PG8_MMA(ai, bj, At, Bt) do { __builtin_amdgcn_s_setprio(1); _Pragma("unroll") for (int m = 0; m < 4; ++m) _Pragma("unroll") for (int n = 0; n < 2; ++n) _Pragma("unroll") for (int k = 0; k < 2; ++k) \
;         acc[ai][bj][m][n] = __builtin_amdgcn_mfma_f32_16x16x32_bf16(Bt[n][k], At[m][k], acc[ai][bj][m][n], 0, 0, 0); __builtin_amdgcn_s_setprio(0); } while (0)
; #define PG8_WAIT_V(n) asm volatile("s_waitcnt vmcnt(" #n ")" ::: "memory")
; #define PG8_WAIT_L(n) asm volatile("s_waitcnt lgkmcnt(" #n ")" ::: "memory")
; #define PG8_BAR __builtin_amdgcn_s_barrier()
; #define PG8_SCHED __builtin_amdgcn_sched_barrier(0)
; template <class Epi, class Sched, bool ALIGN_EPI = false, bool SP2 = false>
; __device__ __forceinline__ void gemm_phase(PG8_LAS unsigned char* lds, const Gemm g, const Sched& S, const Epi& E) {
;     ...
;             PG8_WAIT_V(8); PG8_WAIT_L(0); PG8_BAR; PG8_MMA(1, 0, At, B0); PG8_MMA(1, 1, At, B1); PG8_BAR; PG8_SCHED;
;             PG8_LDB(B0, 1, 0); PG8_LDB(B1, 1, 1); PG8_SCHED; PG8_LDA(At, 1, 0); PG8_STAGE(PG8_SA(0, 1), a2 + hstep, voffA);
;             PG8_WAIT_V(8); PG8_WAIT_L(0); PG8_BAR; PG8_MMA(0, 0, At, B0); PG8_MMA(0, 1, At, B1); PG8_BAR; PG8_SCHED;
	s_setprio 1
	s_waitcnt lgkmcnt(0)
	v_mfma_f32_16x16x32_bf16 v[60:63], v[144:147], v[186:189], 0
	v_mfma_f32_16x16x32_bf16 v[56:59], v[162:165], v[186:189], 0
	v_mfma_f32_16x16x32_bf16 v[44:47], v[144:147], v[194:197], 0
	v_mfma_f32_16x16x32_bf16 v[40:43], v[162:165], v[194:197], 0
	v_mfma_f32_16x16x32_bf16 v[28:31], v[144:147], v[202:205], 0
	v_mfma_f32_16x16x32_bf16 v[24:27], v[162:165], v[202:205], 0
	v_mfma_f32_16x16x32_bf16 v[12:15], v[144:147], v[210:213], 0
	v_mfma_f32_16x16x32_bf16 v[8:11], v[162:165], v[210:213], 0
	v_mfma_f32_16x16x32_bf16 v[60:63], v[158:161], v[190:193], v[60:63]
	v_mfma_f32_16x16x32_bf16 v[56:59], v[166:169], v[190:193], v[56:59]
	v_mfma_f32_16x16x32_bf16 v[44:47], v[158:161], v[198:201], v[44:47]
	v_mfma_f32_16x16x32_bf16 v[40:43], v[166:169], v[198:201], v[40:43]
	v_mfma_f32_16x16x32_bf16 v[28:31], v[158:161], v[206:209], v[28:31]
	v_mfma_f32_16x16x32_bf16 v[24:27], v[166:169], v[206:209], v[24:27]
	v_mfma_f32_16x16x32_bf16 v[12:15], v[158:161], v[214:217], v[12:15]
	v_mfma_f32_16x16x32_bf16 v[8:11], v[166:169], v[214:217], v[8:11]
	s_setprio 0
	s_setprio 1
	v_mfma_f32_16x16x32_bf16 v[52:55], v[170:173], v[186:189], 0
	v_mfma_f32_16x16x32_bf16 v[48:51], v[178:181], v[186:189], 0
	v_mfma_f32_16x16x32_bf16 v[36:39], v[170:173], v[194:197], 0
	v_mfma_f32_16x16x32_bf16 v[32:35], v[178:181], v[194:197], 0
	v_mfma_f32_16x16x32_bf16 v[20:23], v[170:173], v[202:205], 0
	v_mfma_f32_16x16x32_bf16 v[16:19], v[178:181], v[202:205], 0
	v_mfma_f32_16x16x32_bf16 v[4:7], v[170:173], v[210:213], 0
	v_mfma_f32_16x16x32_bf16 v[0:3], v[178:181], v[210:213], 0
	v_mfma_f32_16x16x32_bf16 v[52:55], v[174:177], v[190:193], v[52:55]
	v_mfma_f32_16x16x32_bf16 v[48:51], v[182:185], v[190:193], v[48:51]
	v_mfma_f32_16x16x32_bf16 v[36:39], v[174:177], v[198:201], v[36:39]
	v_mfma_f32_16x16x32_bf16 v[32:35], v[182:185], v[198:201], v[32:35]
	v_mfma_f32_16x16x32_bf16 v[20:23], v[174:177], v[206:209], v[20:23]
	v_mfma_f32_16x16x32_bf16 v[16:19], v[182:185], v[206:209], v[16:19]
	v_mfma_f32_16x16x32_bf16 v[4:7], v[174:177], v[214:217], v[4:7]
	v_mfma_f32_16x16x32_bf16 v[0:3], v[182:185], v[214:217], v[0:3]
	s_setprio 0
	s_barrier
	s_add_i32 s80, 0, 0x18000
	v_add_u32_e32 v157, s80, v151
	s_add_i32 s81, 0, 0x1c000
	ds_read_b128 v[144:147], v157
	ds_read_b128 v[158:161], v157 offset:1024
	ds_read_b128 v[162:165], v157 offset:2048
	ds_read_b128 v[166:169], v157 offset:3072
	v_add_u32_e32 v157, s81, v151
	ds_read_b128 v[170:173], v157
	ds_read_b128 v[174:177], v157 offset:1024
	ds_read_b128 v[178:181], v157 offset:2048
	ds_read_b128 v[182:185], v157 offset:3072
	s_add_u32 s54, s54, 0x80000
	s_addc_u32 s55, s55, 0
	s_mov_b32 m0, s62
	v_lshl_add_u64 v[224:225], s[54:55], 0, v[128:129]
	ds_read_b128 v[186:189], v156 offset:32768
	ds_read_b128 v[190:193], v156 offset:33792
	ds_read_b128 v[194:197], v156 offset:34816
	ds_read_b128 v[198:201], v156 offset:35840
	ds_read_b128 v[202:205], v156 offset:36864
	ds_read_b128 v[206:209], v156 offset:37888
	ds_read_b128 v[210:213], v156 offset:38912
	ds_read_b128 v[214:217], v156 offset:39936
	global_load_lds_dwordx4 v[224:225], off
	v_lshl_add_u64 v[224:225], s[54:55], 0, v[132:133]
	s_mov_b32 m0, s63
	s_nop 0
	global_load_lds_dwordx4 v[224:225], off
	s_waitcnt vmcnt(8)
	s_waitcnt lgkmcnt(0)
	s_barrier
	s_setprio 1
	s_waitcnt lgkmcnt(0)
	v_mfma_f32_16x16x32_bf16 v[124:127], v[144:147], v[186:189], v[124:127]
	v_mfma_f32_16x16x32_bf16 v[120:123], v[162:165], v[186:189], v[120:123]
	v_mfma_f32_16x16x32_bf16 v[108:111], v[144:147], v[194:197], v[108:111]
	v_mfma_f32_16x16x32_bf16 v[104:107], v[162:165], v[194:197], v[104:107]
	v_mfma_f32_16x16x32_bf16 v[92:95], v[144:147], v[202:205], v[92:95]
	v_mfma_f32_16x16x32_bf16 v[88:91], v[162:165], v[202:205], v[88:91]
	v_mfma_f32_16x16x32_bf16 v[76:79], v[144:147], v[210:213], v[76:79]
	v_mfma_f32_16x16x32_bf16 v[72:75], v[162:165], v[210:213], v[72:75]
	v_mfma_f32_16x16x32_bf16 v[124:127], v[158:161], v[190:193], v[124:127]
	v_mfma_f32_16x16x32_bf16 v[120:123], v[166:169], v[190:193], v[120:123]
	v_mfma_f32_16x16x32_bf16 v[108:111], v[158:161], v[198:201], v[108:111]
	v_mfma_f32_16x16x32_bf16 v[104:107], v[166:169], v[198:201], v[104:107]
	v_mfma_f32_16x16x32_bf16 v[92:95], v[158:161], v[206:209], v[92:95]
	v_mfma_f32_16x16x32_bf16 v[88:91], v[166:169], v[206:209], v[88:91]
	v_mfma_f32_16x16x32_bf16 v[76:79], v[158:161], v[214:217], v[76:79]
	v_mfma_f32_16x16x32_bf16 v[72:75], v[166:169], v[214:217], v[72:75]
	s_setprio 0
	s_setprio 1
	v_mfma_f32_16x16x32_bf16 v[116:119], v[170:173], v[186:189], v[116:119]
	v_mfma_f32_16x16x32_bf16 v[112:115], v[178:181], v[186:189], v[112:115]
	v_mfma_f32_16x16x32_bf16 v[100:103], v[170:173], v[194:197], v[100:103]
	v_mfma_f32_16x16x32_bf16 v[96:99], v[178:181], v[194:197], v[96:99]
	v_mfma_f32_16x16x32_bf16 v[84:87], v[170:173], v[202:205], v[84:87]
	v_mfma_f32_16x16x32_bf16 v[80:83], v[178:181], v[202:205], v[80:83]
	v_mfma_f32_16x16x32_bf16 v[68:71], v[170:173], v[210:213], v[68:71]
	v_mfma_f32_16x16x32_bf16 v[64:67], v[178:181], v[210:213], v[64:67]
	v_mfma_f32_16x16x32_bf16 v[116:119], v[174:177], v[190:193], v[116:119]
	v_mfma_f32_16x16x32_bf16 v[112:115], v[182:185], v[190:193], v[112:115]
	v_mfma_f32_16x16x32_bf16 v[100:103], v[174:177], v[198:201], v[100:103]
	v_mfma_f32_16x16x32_bf16 v[96:99], v[182:185], v[198:201], v[96:99]
	v_mfma_f32_16x16x32_bf16 v[84:87], v[174:177], v[206:209], v[84:87]
	v_mfma_f32_16x16x32_bf16 v[80:83], v[182:185], v[206:209], v[80:83]
	v_mfma_f32_16x16x32_bf16 v[68:71], v[174:177], v[214:217], v[68:71]
	v_mfma_f32_16x16x32_bf16 v[64:67], v[182:185], v[214:217], v[64:67]
	s_setprio 0
	s_barrier
; #define PG8_STAGE(bufoff, gbase, voff) do { _Pragma("unroll") for (int _i = 0; _i < 2; ++_i) \
;         __builtin_amdgcn_global_load_lds((const unsigned*)((const char*)(gbase) + (voff)[_i]), (PG8_LAS unsigned*)(lds + (bufoff) + ldsw + _i * 8192), 16, 0, 0); } while (0)
; #define PG8_LDA(dst, b, h) do { _Pragma("unroll") for (int m = 0; m < 4; ++m) _Pragma("unroll") for (int k = 0; k < 2; ++k) dst[m][k] = *(const PG8_LAS bf16x8*)(lds + PG8_SA(b, h) + aoff + m * 2048 + k * 1024); } while (0)
; #define PG8_MMA(ai, bj, At, Bt) do { __builtin_amdgcn_s_setprio(1); _Pragma("unroll") for (int m = 0; m < 4; ++m) _Pragma("unroll") for (int n = 0; n < 2; ++n) _Pragma("unroll") for (int k = 0; k < 2; ++k) \
;         acc[ai][bj][m][n] = __builtin_amdgcn_mfma_f32_16x16x32_bf16(Bt[n][k], At[m][k], acc[ai][bj][m][n], 0, 0, 0); __builtin_amdgcn_s_setprio(0); } while (0)
; #define PG8_WAIT_V(n) asm volatile("s_waitcnt vmcnt(" #n ")" ::: "memory")
; #define PG8_WAIT_L(n) asm volatile("s_waitcnt lgkmcnt(" #n ")" ::: "memory")
; #define PG8_BAR __builtin_amdgcn_s_barrier()
; #define PG8_SCHED __builtin_amdgcn_sched_barrier(0)
; template <class Epi, class Sched, bool ALIGN_EPI = false, bool SP2 = false>
; __device__ __forceinline__ void gemm_phase(PG8_LAS unsigned char* lds, const Gemm g, const Sched& S, const Epi& E) {
;     ...
;         for (int t = 0; t < nt; t += 2) {
;             const bool last = (t == nt - 2);
;             const char* a1 = cA + (size_t)(t + 1) * kstep;
;             const char* a2 = last ? nA : cA + (size_t)(t + 2) * kstep; const char* b2 = last ? nB : cB + (size_t)(t + 2) * kstep;
;             const char* a3 = a2 + kstep; const char* b3 = b2 + kstep;
;             if (last && has_next) S.a_ready(nxt);
;     ...
;             PG8_LDA(At, 1, 1); PG8_STAGE(PG8_SB(1, 0), b3, voffB); PG8_STAGE(PG8_SB(1, 1), b3 + hstep, voffB); PG8_STAGE(PG8_SA(1, 0), a3, voffA);
;             PG8_WAIT_V(8); PG8_WAIT_L(0); PG8_BAR; PG8_MMA(1, 0, At, B0); PG8_MMA(1, 1, At, B1); PG8_BAR; PG8_SCHED;
	s_add_i32 s54, s80, s56
	v_lshl_add_u64 v[148:149], v[148:149], 0, s[20:21]
	s_mov_b32 m0, s54
	ds_read_b128 v[186:189], v156 offset:49152
	ds_read_b128 v[190:193], v156 offset:50176
	ds_read_b128 v[194:197], v156 offset:51200
	ds_read_b128 v[198:201], v156 offset:52224
	ds_read_b128 v[202:205], v156 offset:53248
	ds_read_b128 v[206:209], v156 offset:54272
	ds_read_b128 v[210:213], v156 offset:55296
	ds_read_b128 v[214:217], v156 offset:56320
	global_load_lds_dwordx4 v[148:149], off
	s_add_i32 m0, s54, 0x2000
	s_add_u32 s52, s52, 0x80080
	v_lshl_add_u64 v[148:149], v[218:219], 0, s[20:21]
	s_addc_u32 s53, s53, 0
	s_add_i32 s54, s81, s56
	global_load_lds_dwordx4 v[148:149], off
	v_lshl_add_u64 v[148:149], s[52:53], 0, v[130:131]
	s_mov_b32 m0, s54
	s_nop 0
	global_load_lds_dwordx4 v[148:149], off
	v_lshl_add_u64 v[148:149], s[52:53], 0, v[134:135]
	s_add_i32 m0, s54, 0x2000
	s_nop 0
	global_load_lds_dwordx4 v[148:149], off
	v_lshl_add_u64 v[148:149], v[220:221], 0, s[20:21]
	s_mov_b32 m0, s65
	s_nop 0
	global_load_lds_dwordx4 v[148:149], off
	v_lshl_add_u64 v[148:149], v[222:223], 0, s[20:21]
	s_mov_b32 m0, s66
	s_nop 0
	global_load_lds_dwordx4 v[148:149], off
	s_waitcnt vmcnt(8)
	s_waitcnt lgkmcnt(0)
	s_barrier
	s_setprio 1
	s_waitcnt lgkmcnt(0)
	v_mfma_f32_16x16x32_bf16 v[60:63], v[144:147], v[186:189], v[60:63]
	v_mfma_f32_16x16x32_bf16 v[56:59], v[162:165], v[186:189], v[56:59]
	v_mfma_f32_16x16x32_bf16 v[44:47], v[144:147], v[194:197], v[44:47]
	v_mfma_f32_16x16x32_bf16 v[40:43], v[162:165], v[194:197], v[40:43]
	v_mfma_f32_16x16x32_bf16 v[28:31], v[144:147], v[202:205], v[28:31]
	v_mfma_f32_16x16x32_bf16 v[24:27], v[162:165], v[202:205], v[24:27]
	v_mfma_f32_16x16x32_bf16 v[12:15], v[144:147], v[210:213], v[12:15]
	v_mfma_f32_16x16x32_bf16 v[8:11], v[162:165], v[210:213], v[8:11]
	v_mfma_f32_16x16x32_bf16 v[60:63], v[158:161], v[190:193], v[60:63]
	v_mfma_f32_16x16x32_bf16 v[56:59], v[166:169], v[190:193], v[56:59]
	v_mfma_f32_16x16x32_bf16 v[44:47], v[158:161], v[198:201], v[44:47]
	v_mfma_f32_16x16x32_bf16 v[40:43], v[166:169], v[198:201], v[40:43]
	v_mfma_f32_16x16x32_bf16 v[28:31], v[158:161], v[206:209], v[28:31]
	v_mfma_f32_16x16x32_bf16 v[24:27], v[166:169], v[206:209], v[24:27]
	v_mfma_f32_16x16x32_bf16 v[12:15], v[158:161], v[214:217], v[12:15]
	v_mfma_f32_16x16x32_bf16 v[8:11], v[166:169], v[214:217], v[8:11]
	s_setprio 0
	s_setprio 1
	v_mfma_f32_16x16x32_bf16 v[52:55], v[170:173], v[186:189], v[52:55]
	v_mfma_f32_16x16x32_bf16 v[48:51], v[178:181], v[186:189], v[48:51]
	v_mfma_f32_16x16x32_bf16 v[36:39], v[170:173], v[194:197], v[36:39]
	v_mfma_f32_16x16x32_bf16 v[32:35], v[178:181], v[194:197], v[32:35]
	v_mfma_f32_16x16x32_bf16 v[20:23], v[170:173], v[202:205], v[20:23]
	v_mfma_f32_16x16x32_bf16 v[16:19], v[178:181], v[202:205], v[16:19]
	v_mfma_f32_16x16x32_bf16 v[4:7], v[170:173], v[210:213], v[4:7]
	v_mfma_f32_16x16x32_bf16 v[0:3], v[178:181], v[210:213], v[0:3]
	v_mfma_f32_16x16x32_bf16 v[52:55], v[174:177], v[190:193], v[52:55]
	v_mfma_f32_16x16x32_bf16 v[48:51], v[182:185], v[190:193], v[48:51]
	v_mfma_f32_16x16x32_bf16 v[36:39], v[174:177], v[198:201], v[36:39]
	v_mfma_f32_16x16x32_bf16 v[32:35], v[182:185], v[198:201], v[32:35]
	v_mfma_f32_16x16x32_bf16 v[20:23], v[174:177], v[206:209], v[20:23]
	v_mfma_f32_16x16x32_bf16 v[16:19], v[182:185], v[206:209], v[16:19]
	v_mfma_f32_16x16x32_bf16 v[4:7], v[174:177], v[214:217], v[4:7]
	v_mfma_f32_16x16x32_bf16 v[0:3], v[182:185], v[214:217], v[0:3]
	s_setprio 0
	s_barrier
	s_add_i32 s79, s79, 2
	s_add_u32 s42, s42, 0x100
	s_addc_u32 s43, s43, 0
	s_add_u32 s77, s77, 0x100
	s_addc_u32 s78, s78, 0
	s_cmp_gt_u32 s79, 29
	s_cbranch_scc0 .LBB0_1268
	s_branch .Lpeel_exit_5

; #define PG8_BAR __builtin_amdgcn_s_barrier()
; template <class Epi, class Sched, bool ALIGN_EPI = false, bool SP2 = false>
; __device__ __forceinline__ void gemm_phase(PG8_LAS unsigned char* lds, const Gemm g, const Sched& S, const Epi& E) {
;     ...
;         if constexpr (ALIGN_EPI) { if (wr == 0) PG8_BAR; }
;         if constexpr (!Epi::AFTER_DRAIN) { E(acc, cur, wr, wc, fr, fq); S.done(cur); }
.Lpeel_exit_5:
	s_and_b64 vcc, exec, s[22:23]
	s_cbranch_vccz .LBB0_1271
	s_barrier

; #define PG8_STAGE(bufoff, gbase, voff) do { _Pragma("unroll") for (int _i = 0; _i < 2; ++_i) \
;         __builtin_amdgcn_global_load_lds((const unsigned*)((const char*)(gbase) + (voff)[_i]), (PG8_LAS unsigned*)(lds + (bufoff) + ldsw + _i * 8192), 16, 0, 0); } while (0)
; #define PG8_LDA(dst, b, h) do { _Pragma("unroll") for (int m = 0; m < 4; ++m) _Pragma("unroll") for (int k = 0; k < 2; ++k) dst[m][k] = *(const PG8_LAS bf16x8*)(lds + PG8_SA(b, h) + aoff + m * 2048 + k * 1024); } while (0)
; #define PG8_LDB(dst, b, h) do { _Pragma("unroll") for (int n = 0; n < 2; ++n) _Pragma("unroll") for (int k = 0; k < 2; ++k) dst[n][k] = *(const PG8_LAS bf16x8*)(lds + PG8_SB(b, h) + boff + n * 2048 + k * 1024); } while (0)
; #define PG8_WAIT_V(n) asm volatile("s_waitcnt vmcnt(" #n ")" ::: "memory")
; #define PG8_WAIT_L(n) asm volatile("s_waitcnt lgkmcnt(" #n ")" ::: "memory")
; #define PG8_BAR __builtin_amdgcn_s_barrier()
; template <class Epi, class Sched, bool ALIGN_EPI = false, bool SP2 = false>
; __device__ __forceinline__ void gemm_phase(PG8_LAS unsigned char* lds, const Gemm g, const Sched& S, const Epi& E) {
;     ...
;     f32x4 acc[2][2][4][2];
; #pragma unroll
;     for (int a = 0; a < 2; ++a)
; #pragma unroll
;         for (int b = 0; b < 2; ++b)
; #pragma unroll
;             for (int m = 0; m < 4; ++m)
; #pragma unroll
;                 for (int n = 0; n < 2; ++n) acc[a][b][m][n] = (f32x4){0.f, 0.f, 0.f, 0.f};
;     ...
;         for (int t = 0; t < nt; t += 2) {
;             const bool last = (t == nt - 2);
;             const char* a1 = cA + (size_t)(t + 1) * kstep;
;             const char* a2 = last ? nA : cA + (size_t)(t + 2) * kstep; const char* b2 = last ? nB : cB + (size_t)(t + 2) * kstep;
;             const char* a3 = a2 + kstep; const char* b3 = b2 + kstep;
;             if (last && has_next) S.a_ready(nxt);
;             if constexpr (SP2) {
;             PG8_LDB(B0, 0, 0); PG8_LDB(B1, 0, 1); PG8_SCHED; PG8_LDA(At, 0, 0); PG8_STAGE(PG8_SA(1, 1), a1 + hstep, voffA);
;             PG8_WAIT_V(8); PG8_WAIT_L(0); PG8_BAR; PG8_MMA(0, 0, At, B0); PG8_MMA(0, 1, At, B1); PG8_BAR; PG8_SCHED;
;             PG8_LDA(At, 0, 1); PG8_STAGE(PG8_SB(0, 0), b2, voffB); PG8_STAGE(PG8_SB(0, 1), b2 + hstep, voffB); PG8_STAGE(PG8_SA(0, 0), a2, voffA);
;             PG8_WAIT_V(8); PG8_WAIT_L(0); PG8_BAR; PG8_MMA(1, 0, At, B0); PG8_MMA(1, 1, At, B1); PG8_BAR; PG8_SCHED;
.LBB0_1297:
	v_mov_b32_e32 v127, 0
	s_andn2_b64 vcc, exec, s[38:39]
	v_mov_b32_e32 v126, v127
	v_mov_b32_e32 v125, v127
	v_mov_b32_e32 v124, v127
	v_mov_b32_e32 v123, v127
	v_mov_b32_e32 v122, v127
	v_mov_b32_e32 v121, v127
	v_mov_b32_e32 v120, v127
	v_mov_b32_e32 v111, v127
	v_mov_b32_e32 v110, v127
	v_mov_b32_e32 v109, v127
	v_mov_b32_e32 v108, v127
	v_mov_b32_e32 v107, v127
	v_mov_b32_e32 v106, v127
	v_mov_b32_e32 v105, v127
	v_mov_b32_e32 v104, v127
	v_mov_b32_e32 v95, v127
	v_mov_b32_e32 v94, v127
	v_mov_b32_e32 v93, v127
	v_mov_b32_e32 v92, v127
	v_mov_b32_e32 v91, v127
	v_mov_b32_e32 v90, v127
	v_mov_b32_e32 v89, v127
	v_mov_b32_e32 v88, v127
	v_mov_b32_e32 v79, v127
	v_mov_b32_e32 v78, v127
	v_mov_b32_e32 v77, v127
	v_mov_b32_e32 v76, v127
	v_mov_b32_e32 v75, v127
	v_mov_b32_e32 v74, v127
	v_mov_b32_e32 v73, v127
	v_mov_b32_e32 v72, v127
	v_mov_b32_e32 v119, v127
	v_mov_b32_e32 v118, v127
	v_mov_b32_e32 v117, v127
	v_mov_b32_e32 v116, v127
	v_mov_b32_e32 v115, v127
	v_mov_b32_e32 v114, v127
	v_mov_b32_e32 v113, v127
	v_mov_b32_e32 v112, v127
	v_mov_b32_e32 v103, v127
	v_mov_b32_e32 v102, v127
	v_mov_b32_e32 v101, v127
	v_mov_b32_e32 v100, v127
	v_mov_b32_e32 v99, v127
	v_mov_b32_e32 v98, v127
	v_mov_b32_e32 v97, v127
	v_mov_b32_e32 v96, v127
	v_mov_b32_e32 v87, v127
	v_mov_b32_e32 v86, v127
	v_mov_b32_e32 v85, v127
	v_mov_b32_e32 v84, v127
	v_mov_b32_e32 v83, v127
	v_mov_b32_e32 v82, v127
	v_mov_b32_e32 v81, v127
	v_mov_b32_e32 v80, v127
	v_mov_b32_e32 v71, v127
	v_mov_b32_e32 v70, v127
	v_mov_b32_e32 v69, v127
	v_mov_b32_e32 v68, v127
	v_mov_b32_e32 v67, v127
	v_mov_b32_e32 v66, v127
	v_mov_b32_e32 v65, v127
	v_mov_b32_e32 v64, v127
	v_mov_b32_e32 v63, v127
	v_mov_b32_e32 v62, v127
	v_mov_b32_e32 v61, v127
	v_mov_b32_e32 v60, v127
	v_mov_b32_e32 v59, v127
	v_mov_b32_e32 v58, v127
	v_mov_b32_e32 v57, v127
	v_mov_b32_e32 v56, v127
	v_mov_b32_e32 v47, v127
	v_mov_b32_e32 v46, v127
	v_mov_b32_e32 v45, v127
	v_mov_b32_e32 v44, v127
	v_mov_b32_e32 v43, v127
	v_mov_b32_e32 v42, v127
	v_mov_b32_e32 v41, v127
	v_mov_b32_e32 v40, v127
	v_mov_b32_e32 v31, v127
	v_mov_b32_e32 v30, v127
	v_mov_b32_e32 v29, v127
	v_mov_b32_e32 v28, v127
	v_mov_b32_e32 v27, v127
	v_mov_b32_e32 v26, v127
	v_mov_b32_e32 v25, v127
	v_mov_b32_e32 v24, v127
	v_mov_b32_e32 v15, v127
	v_mov_b32_e32 v14, v127
	v_mov_b32_e32 v13, v127
	v_mov_b32_e32 v12, v127
	v_mov_b32_e32 v11, v127
	v_mov_b32_e32 v10, v127
	v_mov_b32_e32 v9, v127
	v_mov_b32_e32 v8, v127
	v_mov_b32_e32 v55, v127
	v_mov_b32_e32 v54, v127
	v_mov_b32_e32 v53, v127
	v_mov_b32_e32 v52, v127
	v_mov_b32_e32 v51, v127
	v_mov_b32_e32 v50, v127
	v_mov_b32_e32 v49, v127
	v_mov_b32_e32 v48, v127
	v_mov_b32_e32 v39, v127
	v_mov_b32_e32 v38, v127
	v_mov_b32_e32 v37, v127
	v_mov_b32_e32 v36, v127
	v_mov_b32_e32 v35, v127
	v_mov_b32_e32 v34, v127
	v_mov_b32_e32 v33, v127
	v_mov_b32_e32 v32, v127
	v_mov_b32_e32 v23, v127
	v_mov_b32_e32 v22, v127
	v_mov_b32_e32 v21, v127
	v_mov_b32_e32 v20, v127
	v_mov_b32_e32 v19, v127
	v_mov_b32_e32 v18, v127
	v_mov_b32_e32 v17, v127
	v_mov_b32_e32 v16, v127
	v_mov_b32_e32 v7, v127
	v_mov_b32_e32 v6, v127
	v_mov_b32_e32 v5, v127
	v_mov_b32_e32 v4, v127
	v_mov_b32_e32 v3, v127
	v_mov_b32_e32 v2, v127
	s_waitcnt lgkmcnt(0)
	v_mov_b32_e32 v1, v127
	v_mov_b32_e32 v0, v127
	s_cbranch_vccnz .LBB0_1300
	s_add_u32 s52, s52, 0x80
	s_addc_u32 s53, s53, 0
	s_add_u32 s51, s54, 0x100
	s_addc_u32 s71, s55, 0
	s_mov_b32 s54, 0
	ds_read_b128 v[128:131], v211
	ds_read_b128 v[132:135], v211 offset:1024
	ds_read_b128 v[136:139], v211 offset:2048
	ds_read_b128 v[140:143], v211 offset:3072
	ds_read_b128 v[144:147], v212
	ds_read_b128 v[148:151], v212 offset:1024
	ds_read_b128 v[152:155], v212 offset:2048
	ds_read_b128 v[156:159], v212 offset:3072
	s_add_i32 s75, s54, 2
	s_add_u32 s76, s52, 0x80
	s_addc_u32 s55, s53, 0
	s_cmp_eq_u32 s66, s54
	s_cselect_b32 s54, s16, s76
	s_cselect_b32 s55, s17, s55
	s_cselect_b32 s77, s43, s71
	s_cselect_b32 s76, s42, s51
	v_lshl_add_u64 v[216:217], s[52:53], 0, v[184:185]
	s_add_i32 m0, s58, 0xc000
	ds_read_b128 v[160:163], v213
	ds_read_b128 v[164:167], v213 offset:1024
	ds_read_b128 v[168:171], v213 offset:2048
	ds_read_b128 v[172:175], v213 offset:3072
	ds_read_b128 v[192:195], v213 offset:4096
	ds_read_b128 v[196:199], v213 offset:5120
	ds_read_b128 v[200:203], v213 offset:6144
	ds_read_b128 v[204:207], v213 offset:7168
	global_load_lds_dwordx4 v[216:217], off
	v_lshl_add_u64 v[216:217], s[52:53], 0, v[186:187]
	s_add_i32 m0, s58, 0xe000
	s_nop 0
	global_load_lds_dwordx4 v[216:217], off
	s_waitcnt vmcnt(8)
	s_waitcnt lgkmcnt(0)
	s_barrier
; #define PG8_STAGE(bufoff, gbase, voff) do { _Pragma("unroll") for (int _i = 0; _i < 2; ++_i) \
;         __builtin_amdgcn_global_load_lds((const unsigned*)((const char*)(gbase) + (voff)[_i]), (PG8_LAS unsigned*)(lds + (bufoff) + ldsw + _i * 8192), 16, 0, 0); } while (0)
; #define PG8_LDA(dst, b, h) do { _Pragma("unroll") for (int m = 0; m < 4; ++m) _Pragma("unroll") for (int k = 0; k < 2; ++k) dst[m][k] = *(const PG8_LAS bf16x8*)(lds + PG8_SA(b, h) + aoff + m * 2048 + k * 1024); } while (0)
; #define PG8_MMA(ai, bj, At, Bt) do { __builtin_amdgcn_s_setprio(1); _Pragma("unroll") for (int m = 0; m < 4; ++m) _Pragma("unroll") for (int n = 0; n < 2; ++n) _Pragma("unroll") for (int k = 0; k < 2; ++k) \
;         acc[ai][bj][m][n] = __builtin_amdgcn_mfma_f32_16x16x32_bf16(Bt[n][k], At[m][k], acc[ai][bj][m][n], 0, 0, 0); __builtin_amdgcn_s_setprio(0); } while (0)
; #define PG8_WAIT_V(n) asm volatile("s_waitcnt vmcnt(" #n ")" ::: "memory")
; #define PG8_WAIT_L(n) asm volatile("s_waitcnt lgkmcnt(" #n ")" ::: "memory")
; #define PG8_BAR __builtin_amdgcn_s_barrier()
; #define PG8_SCHED __builtin_amdgcn_sched_barrier(0)
; template <class Epi, class Sched, bool ALIGN_EPI = false, bool SP2 = false>
; __device__ __forceinline__ void gemm_phase(PG8_LAS unsigned char* lds, const Gemm g, const Sched& S, const Epi& E) {
;     ...
;             PG8_WAIT_V(8); PG8_WAIT_L(0); PG8_BAR; PG8_MMA(0, 0, At, B0); PG8_MMA(0, 1, At, B1); PG8_BAR; PG8_SCHED;
;             PG8_LDA(At, 0, 1); PG8_STAGE(PG8_SB(0, 0), b2, voffB); PG8_STAGE(PG8_SB(0, 1), b2 + hstep, voffB); PG8_STAGE(PG8_SA(0, 0), a2, voffA);
;             PG8_WAIT_V(8); PG8_WAIT_L(0); PG8_BAR; PG8_MMA(1, 0, At, B0); PG8_MMA(1, 1, At, B1); PG8_BAR; PG8_SCHED;
	s_setprio 1
	s_waitcnt lgkmcnt(0)
	v_mfma_f32_16x16x32_bf16 v[124:127], v[128:131], v[160:163], 0
	v_mfma_f32_16x16x32_bf16 v[120:123], v[136:139], v[160:163], 0
	v_mfma_f32_16x16x32_bf16 v[108:111], v[128:131], v[168:171], 0
	v_mfma_f32_16x16x32_bf16 v[104:107], v[136:139], v[168:171], 0
	v_mfma_f32_16x16x32_bf16 v[92:95], v[128:131], v[192:195], 0
	v_mfma_f32_16x16x32_bf16 v[88:91], v[136:139], v[192:195], 0
	v_mfma_f32_16x16x32_bf16 v[76:79], v[128:131], v[200:203], 0
	v_mfma_f32_16x16x32_bf16 v[72:75], v[136:139], v[200:203], 0
	v_mfma_f32_16x16x32_bf16 v[124:127], v[132:135], v[164:167], v[124:127]
	v_mfma_f32_16x16x32_bf16 v[120:123], v[140:143], v[164:167], v[120:123]
	v_mfma_f32_16x16x32_bf16 v[108:111], v[132:135], v[172:175], v[108:111]
	v_mfma_f32_16x16x32_bf16 v[104:107], v[140:143], v[172:175], v[104:107]
	v_mfma_f32_16x16x32_bf16 v[92:95], v[132:135], v[196:199], v[92:95]
	v_mfma_f32_16x16x32_bf16 v[88:91], v[140:143], v[196:199], v[88:91]
	v_mfma_f32_16x16x32_bf16 v[76:79], v[132:135], v[204:207], v[76:79]
	v_mfma_f32_16x16x32_bf16 v[72:75], v[140:143], v[204:207], v[72:75]
	s_setprio 0
	s_setprio 1
	v_mfma_f32_16x16x32_bf16 v[116:119], v[144:147], v[160:163], 0
	v_mfma_f32_16x16x32_bf16 v[112:115], v[152:155], v[160:163], 0
	v_mfma_f32_16x16x32_bf16 v[100:103], v[144:147], v[168:171], 0
	v_mfma_f32_16x16x32_bf16 v[96:99], v[152:155], v[168:171], 0
	v_mfma_f32_16x16x32_bf16 v[84:87], v[144:147], v[192:195], 0
	v_mfma_f32_16x16x32_bf16 v[80:83], v[152:155], v[192:195], 0
	v_mfma_f32_16x16x32_bf16 v[68:71], v[144:147], v[200:203], 0
	v_mfma_f32_16x16x32_bf16 v[64:67], v[152:155], v[200:203], 0
	v_mfma_f32_16x16x32_bf16 v[116:119], v[148:151], v[164:167], v[116:119]
	v_mfma_f32_16x16x32_bf16 v[112:115], v[156:159], v[164:167], v[112:115]
	v_mfma_f32_16x16x32_bf16 v[100:103], v[148:151], v[172:175], v[100:103]
	v_mfma_f32_16x16x32_bf16 v[96:99], v[156:159], v[172:175], v[96:99]
	v_mfma_f32_16x16x32_bf16 v[84:87], v[148:151], v[196:199], v[84:87]
	v_mfma_f32_16x16x32_bf16 v[80:83], v[156:159], v[196:199], v[80:83]
	v_mfma_f32_16x16x32_bf16 v[68:71], v[148:151], v[204:207], v[68:71]
	v_mfma_f32_16x16x32_bf16 v[64:67], v[156:159], v[204:207], v[64:67]
	s_setprio 0
	s_barrier
	s_add_i32 s78, s67, s57
	v_lshl_add_u64 v[216:217], s[76:77], 0, v[178:179]
	s_mov_b32 m0, s78
	ds_read_b128 v[160:163], v213 offset:16384
	ds_read_b128 v[164:167], v213 offset:17408
	ds_read_b128 v[168:171], v213 offset:18432
	ds_read_b128 v[172:175], v213 offset:19456
	ds_read_b128 v[192:195], v213 offset:20480
	ds_read_b128 v[196:199], v213 offset:21504
	ds_read_b128 v[200:203], v213 offset:22528
	ds_read_b128 v[204:207], v213 offset:23552
	global_load_lds_dwordx4 v[216:217], off
	s_add_i32 m0, s78, 0x2000
	v_lshl_add_u64 v[218:219], s[76:77], 0, v[182:183]
	s_add_u32 s76, s76, s18
	s_addc_u32 s77, s77, s19
	s_add_i32 s78, s68, s57
	global_load_lds_dwordx4 v[218:219], off
	v_lshl_add_u64 v[220:221], s[76:77], 0, v[178:179]
	s_mov_b32 m0, s78
	v_lshl_add_u64 v[222:223], s[76:77], 0, v[182:183]
	global_load_lds_dwordx4 v[220:221], off
	s_add_i32 m0, s78, 0x2000
	v_lshl_add_u64 v[224:225], s[54:55], 0, v[176:177]
	global_load_lds_dwordx4 v[222:223], off
	s_mov_b32 m0, s58
	v_lshl_add_u64 v[226:227], s[54:55], 0, v[180:181]
	global_load_lds_dwordx4 v[224:225], off
	s_mov_b32 m0, s59
	s_nop 0
	global_load_lds_dwordx4 v[226:227], off
	s_waitcnt vmcnt(8)
	s_waitcnt lgkmcnt(0)
	s_barrier
	s_setprio 1
	s_waitcnt lgkmcnt(0)
	v_mfma_f32_16x16x32_bf16 v[60:63], v[128:131], v[160:163], 0
	v_mfma_f32_16x16x32_bf16 v[56:59], v[136:139], v[160:163], 0
	v_mfma_f32_16x16x32_bf16 v[44:47], v[128:131], v[168:171], 0
	v_mfma_f32_16x16x32_bf16 v[40:43], v[136:139], v[168:171], 0
	v_mfma_f32_16x16x32_bf16 v[28:31], v[128:131], v[192:195], 0
	v_mfma_f32_16x16x32_bf16 v[24:27], v[136:139], v[192:195], 0
	v_mfma_f32_16x16x32_bf16 v[12:15], v[128:131], v[200:203], 0
	v_mfma_f32_16x16x32_bf16 v[8:11], v[136:139], v[200:203], 0
	v_mfma_f32_16x16x32_bf16 v[60:63], v[132:135], v[164:167], v[60:63]
	v_mfma_f32_16x16x32_bf16 v[56:59], v[140:143], v[164:167], v[56:59]
	v_mfma_f32_16x16x32_bf16 v[44:47], v[132:135], v[172:175], v[44:47]
	v_mfma_f32_16x16x32_bf16 v[40:43], v[140:143], v[172:175], v[40:43]
	v_mfma_f32_16x16x32_bf16 v[28:31], v[132:135], v[196:199], v[28:31]
	v_mfma_f32_16x16x32_bf16 v[24:27], v[140:143], v[196:199], v[24:27]
	v_mfma_f32_16x16x32_bf16 v[12:15], v[132:135], v[204:207], v[12:15]
	v_mfma_f32_16x16x32_bf16 v[8:11], v[140:143], v[204:207], v[8:11]
	s_setprio 0
	s_setprio 1
	v_mfma_f32_16x16x32_bf16 v[52:55], v[144:147], v[160:163], 0
	v_mfma_f32_16x16x32_bf16 v[48:51], v[152:155], v[160:163], 0
	v_mfma_f32_16x16x32_bf16 v[36:39], v[144:147], v[168:171], 0
	v_mfma_f32_16x16x32_bf16 v[32:35], v[152:155], v[168:171], 0
	v_mfma_f32_16x16x32_bf16 v[20:23], v[144:147], v[192:195], 0
	v_mfma_f32_16x16x32_bf16 v[16:19], v[152:155], v[192:195], 0
	v_mfma_f32_16x16x32_bf16 v[4:7], v[144:147], v[200:203], 0
	v_mfma_f32_16x16x32_bf16 v[0:3], v[152:155], v[200:203], 0
	v_mfma_f32_16x16x32_bf16 v[52:55], v[148:151], v[164:167], v[52:55]
	v_mfma_f32_16x16x32_bf16 v[48:51], v[156:159], v[164:167], v[48:51]
	v_mfma_f32_16x16x32_bf16 v[36:39], v[148:151], v[172:175], v[36:39]
	v_mfma_f32_16x16x32_bf16 v[32:35], v[156:159], v[172:175], v[32:35]
	v_mfma_f32_16x16x32_bf16 v[20:23], v[148:151], v[196:199], v[20:23]
	v_mfma_f32_16x16x32_bf16 v[16:19], v[156:159], v[196:199], v[16:19]
	v_mfma_f32_16x16x32_bf16 v[4:7], v[148:151], v[204:207], v[4:7]
	v_mfma_f32_16x16x32_bf16 v[0:3], v[156:159], v[204:207], v[0:3]
	s_setprio 0
	s_barrier
; #define PG8_STAGE(bufoff, gbase, voff) do { _Pragma("unroll") for (int _i = 0; _i < 2; ++_i) \
;         __builtin_amdgcn_global_load_lds((const unsigned*)((const char*)(gbase) + (voff)[_i]), (PG8_LAS unsigned*)(lds + (bufoff) + ldsw + _i * 8192), 16, 0, 0); } while (0)
; #define PG8_LDA(dst, b, h) do { _Pragma("unroll") for (int m = 0; m < 4; ++m) _Pragma("unroll") for (int k = 0; k < 2; ++k) dst[m][k] = *(const PG8_LAS bf16x8*)(lds + PG8_SA(b, h) + aoff + m * 2048 + k * 1024); } while (0)
; #define PG8_LDB(dst, b, h) do { _Pragma("unroll") for (int n = 0; n < 2; ++n) _Pragma("unroll") for (int k = 0; k < 2; ++k) dst[n][k] = *(const PG8_LAS bf16x8*)(lds + PG8_SB(b, h) + boff + n * 2048 + k * 1024); } while (0)
; #define PG8_MMA(ai, bj, At, Bt) do { __builtin_amdgcn_s_setprio(1); _Pragma("unroll") for (int m = 0; m < 4; ++m) _Pragma("unroll") for (int n = 0; n < 2; ++n) _Pragma("unroll") for (int k = 0; k < 2; ++k) \
;         acc[ai][bj][m][n] = __builtin_amdgcn_mfma_f32_16x16x32_bf16(Bt[n][k], At[m][k], acc[ai][bj][m][n], 0, 0, 0); __builtin_amdgcn_s_setprio(0); } while (0)
; #define PG8_WAIT_V(n) asm volatile("s_waitcnt vmcnt(" #n ")" ::: "memory")
; #define PG8_WAIT_L(n) asm volatile("s_waitcnt lgkmcnt(" #n ")" ::: "memory")
; #define PG8_BAR __builtin_amdgcn_s_barrier()
; #define PG8_SCHED __builtin_amdgcn_sched_barrier(0)
; template <class Epi, class Sched, bool ALIGN_EPI = false, bool SP2 = false>
; __device__ __forceinline__ void gemm_phase(PG8_LAS unsigned char* lds, const Gemm g, const Sched& S, const Epi& E) {
;     ...
;             PG8_LDB(B0, 1, 0); PG8_LDB(B1, 1, 1); PG8_SCHED; PG8_LDA(At, 1, 0); PG8_STAGE(PG8_SA(0, 1), a2 + hstep, voffA);
;             PG8_WAIT_V(8); PG8_WAIT_L(0); PG8_BAR; PG8_MMA(0, 0, At, B0); PG8_MMA(0, 1, At, B1); PG8_BAR; PG8_SCHED;
	s_add_i32 s76, 0, 0x18000
	s_add_i32 s77, 0, 0x1c000
	v_add_u32_e32 v140, s76, v209
	v_add_u32_e32 v156, s77, v209
	ds_read_b128 v[128:131], v140
	ds_read_b128 v[132:135], v140 offset:1024
	ds_read_b128 v[136:139], v140 offset:2048
	ds_read_b128 v[140:143], v140 offset:3072
	ds_read_b128 v[144:147], v156
	ds_read_b128 v[148:151], v156 offset:1024
	ds_read_b128 v[152:155], v156 offset:2048
	ds_read_b128 v[156:159], v156 offset:3072
	s_add_u32 s54, s54, s18
	s_addc_u32 s55, s55, s19
	s_mov_b32 m0, s60
	v_lshl_add_u64 v[228:229], s[54:55], 0, v[176:177]
	ds_read_b128 v[160:163], v213 offset:32768
	ds_read_b128 v[164:167], v213 offset:33792
	ds_read_b128 v[168:171], v213 offset:34816
	ds_read_b128 v[172:175], v213 offset:35840
	ds_read_b128 v[192:195], v213 offset:36864
	ds_read_b128 v[196:199], v213 offset:37888
	ds_read_b128 v[200:203], v213 offset:38912
	ds_read_b128 v[204:207], v213 offset:39936
	global_load_lds_dwordx4 v[228:229], off
	v_lshl_add_u64 v[228:229], s[54:55], 0, v[180:181]
	s_mov_b32 m0, s61
	s_nop 0
	global_load_lds_dwordx4 v[228:229], off
	s_waitcnt vmcnt(8)
	s_waitcnt lgkmcnt(0)
	s_barrier
	s_setprio 1
	s_waitcnt lgkmcnt(0)
	v_mfma_f32_16x16x32_bf16 v[124:127], v[128:131], v[160:163], v[124:127]
	v_mfma_f32_16x16x32_bf16 v[120:123], v[136:139], v[160:163], v[120:123]
	v_mfma_f32_16x16x32_bf16 v[108:111], v[128:131], v[168:171], v[108:111]
	v_mfma_f32_16x16x32_bf16 v[104:107], v[136:139], v[168:171], v[104:107]
	v_mfma_f32_16x16x32_bf16 v[92:95], v[128:131], v[192:195], v[92:95]
	v_mfma_f32_16x16x32_bf16 v[88:91], v[136:139], v[192:195], v[88:91]
	v_mfma_f32_16x16x32_bf16 v[76:79], v[128:131], v[200:203], v[76:79]
	v_mfma_f32_16x16x32_bf16 v[72:75], v[136:139], v[200:203], v[72:75]
	v_mfma_f32_16x16x32_bf16 v[124:127], v[132:135], v[164:167], v[124:127]
	v_mfma_f32_16x16x32_bf16 v[120:123], v[140:143], v[164:167], v[120:123]
	v_mfma_f32_16x16x32_bf16 v[108:111], v[132:135], v[172:175], v[108:111]
	v_mfma_f32_16x16x32_bf16 v[104:107], v[140:143], v[172:175], v[104:107]
	v_mfma_f32_16x16x32_bf16 v[92:95], v[132:135], v[196:199], v[92:95]
	v_mfma_f32_16x16x32_bf16 v[88:91], v[140:143], v[196:199], v[88:91]
	v_mfma_f32_16x16x32_bf16 v[76:79], v[132:135], v[204:207], v[76:79]
	v_mfma_f32_16x16x32_bf16 v[72:75], v[140:143], v[204:207], v[72:75]
	s_setprio 0
	s_setprio 1
	v_mfma_f32_16x16x32_bf16 v[116:119], v[144:147], v[160:163], v[116:119]
	v_mfma_f32_16x16x32_bf16 v[112:115], v[152:155], v[160:163], v[112:115]
	v_mfma_f32_16x16x32_bf16 v[100:103], v[144:147], v[168:171], v[100:103]
	v_mfma_f32_16x16x32_bf16 v[96:99], v[152:155], v[168:171], v[96:99]
	v_mfma_f32_16x16x32_bf16 v[84:87], v[144:147], v[192:195], v[84:87]
	v_mfma_f32_16x16x32_bf16 v[80:83], v[152:155], v[192:195], v[80:83]
	v_mfma_f32_16x16x32_bf16 v[68:71], v[144:147], v[200:203], v[68:71]
	v_mfma_f32_16x16x32_bf16 v[64:67], v[152:155], v[200:203], v[64:67]
	v_mfma_f32_16x16x32_bf16 v[116:119], v[148:151], v[164:167], v[116:119]
	v_mfma_f32_16x16x32_bf16 v[112:115], v[156:159], v[164:167], v[112:115]
	v_mfma_f32_16x16x32_bf16 v[100:103], v[148:151], v[172:175], v[100:103]
	v_mfma_f32_16x16x32_bf16 v[96:99], v[156:159], v[172:175], v[96:99]
	v_mfma_f32_16x16x32_bf16 v[84:87], v[148:151], v[196:199], v[84:87]
	v_mfma_f32_16x16x32_bf16 v[80:83], v[156:159], v[196:199], v[80:83]
	v_mfma_f32_16x16x32_bf16 v[68:71], v[148:151], v[204:207], v[68:71]
	v_mfma_f32_16x16x32_bf16 v[64:67], v[156:159], v[204:207], v[64:67]
	s_setprio 0
	s_barrier
; #define PG8_STAGE(bufoff, gbase, voff) do { _Pragma("unroll") for (int _i = 0; _i < 2; ++_i) \
;         __builtin_amdgcn_global_load_lds((const unsigned*)((const char*)(gbase) + (voff)[_i]), (PG8_LAS unsigned*)(lds + (bufoff) + ldsw + _i * 8192), 16, 0, 0); } while (0)
; #define PG8_LDA(dst, b, h) do { _Pragma("unroll") for (int m = 0; m < 4; ++m) _Pragma("unroll") for (int k = 0; k < 2; ++k) dst[m][k] = *(const PG8_LAS bf16x8*)(lds + PG8_SA(b, h) + aoff + m * 2048 + k * 1024); } while (0)
; #define PG8_MMA(ai, bj, At, Bt) do { __builtin_amdgcn_s_setprio(1); _Pragma("unroll") for (int m = 0; m < 4; ++m) _Pragma("unroll") for (int n = 0; n < 2; ++n) _Pragma("unroll") for (int k = 0; k < 2; ++k) \
;         acc[ai][bj][m][n] = __builtin_amdgcn_mfma_f32_16x16x32_bf16(Bt[n][k], At[m][k], acc[ai][bj][m][n], 0, 0, 0); __builtin_amdgcn_s_setprio(0); } while (0)
; #define PG8_WAIT_V(n) asm volatile("s_waitcnt vmcnt(" #n ")" ::: "memory")
; #define PG8_WAIT_L(n) asm volatile("s_waitcnt lgkmcnt(" #n ")" ::: "memory")
; #define PG8_BAR __builtin_amdgcn_s_barrier()
; #define PG8_SCHED __builtin_amdgcn_sched_barrier(0)
; template <class Epi, class Sched, bool ALIGN_EPI = false, bool SP2 = false>
; __device__ __forceinline__ void gemm_phase(PG8_LAS unsigned char* lds, const Gemm g, const Sched& S, const Epi& E) {
;     ...
;         for (int t = 0; t < nt; t += 2) {
;     ...
;             PG8_LDA(At, 1, 1); PG8_STAGE(PG8_SB(1, 0), b3, voffB); PG8_STAGE(PG8_SB(1, 1), b3 + hstep, voffB); PG8_STAGE(PG8_SA(1, 0), a3, voffA);
;             PG8_WAIT_V(8); PG8_WAIT_L(0); PG8_BAR; PG8_MMA(1, 0, At, B0); PG8_MMA(1, 1, At, B1); PG8_BAR; PG8_SCHED;
	s_add_i32 s54, s76, s57
	v_lshl_add_u64 v[216:217], v[216:217], 0, s[36:37]
	s_mov_b32 m0, s54
	ds_read_b128 v[160:163], v213 offset:49152
	ds_read_b128 v[164:167], v213 offset:50176
	ds_read_b128 v[168:171], v213 offset:51200
	ds_read_b128 v[172:175], v213 offset:52224
	ds_read_b128 v[192:195], v213 offset:53248
	ds_read_b128 v[196:199], v213 offset:54272
	ds_read_b128 v[200:203], v213 offset:55296
	ds_read_b128 v[204:207], v213 offset:56320
	global_load_lds_dwordx4 v[216:217], off
	v_lshl_add_u64 v[216:217], v[218:219], 0, s[36:37]
	s_add_i32 m0, s54, 0x2000
	s_add_i32 s54, s77, s57
	global_load_lds_dwordx4 v[216:217], off
	v_lshl_add_u64 v[216:217], v[220:221], 0, s[36:37]
	s_mov_b32 m0, s54
	s_nop 0
	global_load_lds_dwordx4 v[216:217], off
	v_lshl_add_u64 v[216:217], v[222:223], 0, s[36:37]
	s_add_i32 m0, s54, 0x2000
	s_nop 0
	global_load_lds_dwordx4 v[216:217], off
	v_lshl_add_u64 v[216:217], v[224:225], 0, s[36:37]
	s_mov_b32 m0, s62
	s_nop 0
	global_load_lds_dwordx4 v[216:217], off
	v_lshl_add_u64 v[216:217], v[226:227], 0, s[36:37]
	s_mov_b32 m0, s63
	s_nop 0
	global_load_lds_dwordx4 v[216:217], off
	s_waitcnt vmcnt(8)
	s_waitcnt lgkmcnt(0)
	s_barrier
	s_setprio 1
	s_waitcnt lgkmcnt(0)
	v_mfma_f32_16x16x32_bf16 v[60:63], v[128:131], v[160:163], v[60:63]
	v_mfma_f32_16x16x32_bf16 v[56:59], v[136:139], v[160:163], v[56:59]
	v_mfma_f32_16x16x32_bf16 v[44:47], v[128:131], v[168:171], v[44:47]
	v_mfma_f32_16x16x32_bf16 v[40:43], v[136:139], v[168:171], v[40:43]
	v_mfma_f32_16x16x32_bf16 v[28:31], v[128:131], v[192:195], v[28:31]
	v_mfma_f32_16x16x32_bf16 v[24:27], v[136:139], v[192:195], v[24:27]
	v_mfma_f32_16x16x32_bf16 v[12:15], v[128:131], v[200:203], v[12:15]
	v_mfma_f32_16x16x32_bf16 v[8:11], v[136:139], v[200:203], v[8:11]
	v_mfma_f32_16x16x32_bf16 v[60:63], v[132:135], v[164:167], v[60:63]
	v_mfma_f32_16x16x32_bf16 v[56:59], v[140:143], v[164:167], v[56:59]
	v_mfma_f32_16x16x32_bf16 v[44:47], v[132:135], v[172:175], v[44:47]
	v_mfma_f32_16x16x32_bf16 v[40:43], v[140:143], v[172:175], v[40:43]
	v_mfma_f32_16x16x32_bf16 v[28:31], v[132:135], v[196:199], v[28:31]
	v_mfma_f32_16x16x32_bf16 v[24:27], v[140:143], v[196:199], v[24:27]
	v_mfma_f32_16x16x32_bf16 v[12:15], v[132:135], v[204:207], v[12:15]
	v_mfma_f32_16x16x32_bf16 v[8:11], v[140:143], v[204:207], v[8:11]
	s_setprio 0
	s_setprio 1
	v_mfma_f32_16x16x32_bf16 v[52:55], v[144:147], v[160:163], v[52:55]
	v_mfma_f32_16x16x32_bf16 v[48:51], v[152:155], v[160:163], v[48:51]
	v_mfma_f32_16x16x32_bf16 v[36:39], v[144:147], v[168:171], v[36:39]
	v_mfma_f32_16x16x32_bf16 v[32:35], v[152:155], v[168:171], v[32:35]
	v_mfma_f32_16x16x32_bf16 v[20:23], v[144:147], v[192:195], v[20:23]
	v_mfma_f32_16x16x32_bf16 v[16:19], v[152:155], v[192:195], v[16:19]
	v_mfma_f32_16x16x32_bf16 v[4:7], v[144:147], v[200:203], v[4:7]
	v_mfma_f32_16x16x32_bf16 v[0:3], v[152:155], v[200:203], v[0:3]
	v_mfma_f32_16x16x32_bf16 v[52:55], v[148:151], v[164:167], v[52:55]
	v_mfma_f32_16x16x32_bf16 v[48:51], v[156:159], v[164:167], v[48:51]
	v_mfma_f32_16x16x32_bf16 v[36:39], v[148:151], v[172:175], v[36:39]
	v_mfma_f32_16x16x32_bf16 v[32:35], v[156:159], v[172:175], v[32:35]
	v_mfma_f32_16x16x32_bf16 v[20:23], v[148:151], v[196:199], v[20:23]
	v_mfma_f32_16x16x32_bf16 v[16:19], v[156:159], v[196:199], v[16:19]
	v_mfma_f32_16x16x32_bf16 v[4:7], v[148:151], v[204:207], v[4:7]
	v_mfma_f32_16x16x32_bf16 v[0:3], v[156:159], v[204:207], v[0:3]
	s_setprio 0
	s_barrier
	s_add_u32 s52, s52, 0x100
	s_addc_u32 s53, s53, 0
	s_add_u32 s51, s51, 0x100
	s_addc_u32 s71, s71, 0
	s_cmp_ge_i32 s75, s65
	s_mov_b32 s54, s75
	s_cbranch_scc0 .LBB0_1299
	s_branch .Lpeel_exit_6

; #define PG8_BAR __builtin_amdgcn_s_barrier()
; template <class Epi, class Sched, bool ALIGN_EPI = false, bool SP2 = false>
; __device__ __forceinline__ void gemm_phase(PG8_LAS unsigned char* lds, const Gemm g, const Sched& S, const Epi& E) {
;     ...
;         if constexpr (ALIGN_EPI) { if (wr == 0) PG8_BAR; }
;         if constexpr (!Epi::AFTER_DRAIN) { E(acc, cur, wr, wc, fr, fq); S.done(cur); }
.Lpeel_exit_6:
.LBB0_1300:
	s_and_b64 vcc, exec, s[40:41]
	s_cbranch_vccz .LBB0_1302
	s_barrier

; #define PG8_STAGE(bufoff, gbase, voff) do { _Pragma("unroll") for (int _i = 0; _i < 2; ++_i) \
;         __builtin_amdgcn_global_load_lds((const unsigned*)((const char*)(gbase) + (voff)[_i]), (PG8_LAS unsigned*)(lds + (bufoff) + ldsw + _i * 8192), 16, 0, 0); } while (0)
; #define PG8_WAIT_V(n) asm volatile("s_waitcnt vmcnt(" #n ")" ::: "memory")
; #define PG8_WAIT_L(n) asm volatile("s_waitcnt lgkmcnt(" #n ")" ::: "memory")
; #define PG8_BAR __builtin_amdgcn_s_barrier()
; template <class Epi, class Sched, bool ALIGN_EPI = false, bool SP2 = false>
; __device__ __forceinline__ void gemm_phase(PG8_LAS unsigned char* lds, const Gemm g, const Sched& S, const Epi& E) {
;     ...
;         const bool has_next = S.next(ui + 1, nxt);
;         const char* nA = has_next ? (const char*)g.A + (size_t)nxt.pm * tstep : cA; const char* nB = has_next ? (const char*)g.Bt + (size_t)nxt.pn * tstep : cB;
;         for (int t = 0; t < nt; t += 2) {
;             const bool last = (t == nt - 2);
;             const char* a1 = cA + (size_t)(t + 1) * kstep;
;             const char* a2 = last ? nA : cA + (size_t)(t + 2) * kstep; const char* b2 = last ? nB : cB + (size_t)(t + 2) * kstep;
;             const char* a3 = a2 + kstep; const char* b3 = b2 + kstep;
;             if (last && has_next) S.a_ready(nxt);
;             if constexpr (SP2) {
;             PG8_LDB(B0, 0, 0); PG8_LDB(B1, 0, 1); PG8_SCHED; PG8_LDA(At, 0, 0); PG8_STAGE(PG8_SA(1, 1), a1 + hstep, voffA);
;             PG8_WAIT_V(8); PG8_WAIT_L(0); PG8_BAR; PG8_MMA(0, 0, At, B0); PG8_MMA(0, 1, At, B1); PG8_BAR; PG8_SCHED;
;             PG8_LDA(At, 0, 1); PG8_STAGE(PG8_SB(0, 0), b2, voffB); PG8_STAGE(PG8_SB(0, 1), b2 + hstep, voffB); PG8_STAGE(PG8_SA(0, 0), a2, voffA);
;             PG8_WAIT_V(8); PG8_WAIT_L(0); PG8_BAR; PG8_MMA(1, 0, At, B0); PG8_MMA(1, 1, At, B1); PG8_BAR; PG8_SCHED;
;             PG8_LDB(B0, 1, 0); PG8_LDB(B1, 1, 1); PG8_SCHED; PG8_LDA(At, 1, 0); PG8_STAGE(PG8_SA(0, 1), a2 + hstep, voffA);
;             PG8_WAIT_V(8); PG8_WAIT_L(0); PG8_BAR; PG8_MMA(0, 0, At, B0); PG8_MMA(0, 1, At, B1); PG8_BAR; PG8_SCHED;
;     ...
; #pragma unroll
;         for (int a = 0; a < 2; ++a)
; #pragma unroll
;             for (int b = 0; b < 2; ++b)
; #pragma unroll
;                 for (int m = 0; m < 4; ++m)
; #pragma unroll
;                     for (int n = 0; n < 2; ++n) acc[a][b][m][n] = (f32x4){0.f, 0.f, 0.f, 0.f};
.LBB0_1401:
	s_ashr_i32 s35, s34, 31
	s_lshl_b64 s[36:37], s[34:35], 20
	s_add_u32 s36, s22, s36
	s_addc_u32 s37, s23, s37
	s_and_b64 s[38:39], s[12:13], exec
	s_cselect_b32 s35, s37, s43
	s_cselect_b32 s72, s36, s42
	s_ashr_i32 s31, s30, 31
	s_lshl_b64 s[38:39], s[30:31], 20
	s_add_u32 s38, s56, s38
	s_addc_u32 s39, s57, s39
	s_and_b64 s[52:53], s[12:13], exec
	s_cselect_b32 s31, s39, s51
	s_cselect_b32 s73, s38, s50
	s_add_u32 s42, s42, 0x80080
	s_addc_u32 s43, s43, 0
	s_add_u32 s74, s50, 0x100
	s_addc_u32 s75, s51, 0
	s_mov_b32 s76, -2
	ds_read_b128 v[144:147], v153
	ds_read_b128 v[156:159], v153 offset:1024
	ds_read_b128 v[160:163], v153 offset:2048
	ds_read_b128 v[164:167], v153 offset:3072
	ds_read_b128 v[168:171], v154
	ds_read_b128 v[172:175], v154 offset:1024
	ds_read_b128 v[176:179], v154 offset:2048
	ds_read_b128 v[180:183], v154 offset:3072
	s_add_u32 s50, s42, 0xfff80080
	s_addc_u32 s51, s43, -1
	s_cmp_eq_u32 s76, 28
	s_cselect_b32 s53, s35, s51
	s_cselect_b32 s52, s72, s50
	s_cselect_b32 s51, s31, s75
	s_cselect_b32 s50, s73, s74
	v_lshl_add_u64 v[216:217], s[42:43], 0, v[136:137]
	s_add_i32 m0, s41, 0xc000
	ds_read_b128 v[184:187], v155
	ds_read_b128 v[188:191], v155 offset:1024
	ds_read_b128 v[192:195], v155 offset:2048
	ds_read_b128 v[196:199], v155 offset:3072
	ds_read_b128 v[200:203], v155 offset:4096
	ds_read_b128 v[204:207], v155 offset:5120
	ds_read_b128 v[208:211], v155 offset:6144
	ds_read_b128 v[212:215], v155 offset:7168
	global_load_lds_dwordx4 v[216:217], off
	v_lshl_add_u64 v[216:217], s[42:43], 0, v[138:139]
	s_add_i32 m0, s41, 0xe000
	s_nop 0
	global_load_lds_dwordx4 v[216:217], off
	s_waitcnt vmcnt(8)
	s_waitcnt lgkmcnt(0)
	s_barrier
	s_setprio 1
	s_waitcnt lgkmcnt(0)
	v_mfma_f32_16x16x32_bf16 v[124:127], v[144:147], v[184:187], 0
	v_mfma_f32_16x16x32_bf16 v[120:123], v[160:163], v[184:187], 0
	v_mfma_f32_16x16x32_bf16 v[116:119], v[144:147], v[192:195], 0
	v_mfma_f32_16x16x32_bf16 v[108:111], v[160:163], v[192:195], 0
	v_mfma_f32_16x16x32_bf16 v[96:99], v[144:147], v[200:203], 0
	v_mfma_f32_16x16x32_bf16 v[88:91], v[160:163], v[200:203], 0
	v_mfma_f32_16x16x32_bf16 v[84:87], v[144:147], v[208:211], 0
	v_mfma_f32_16x16x32_bf16 v[76:79], v[160:163], v[208:211], 0
	v_mfma_f32_16x16x32_bf16 v[124:127], v[156:159], v[188:191], v[124:127]
	v_mfma_f32_16x16x32_bf16 v[120:123], v[164:167], v[188:191], v[120:123]
	v_mfma_f32_16x16x32_bf16 v[116:119], v[156:159], v[196:199], v[116:119]
	v_mfma_f32_16x16x32_bf16 v[108:111], v[164:167], v[196:199], v[108:111]
	v_mfma_f32_16x16x32_bf16 v[96:99], v[156:159], v[204:207], v[96:99]
	v_mfma_f32_16x16x32_bf16 v[88:91], v[164:167], v[204:207], v[88:91]
	v_mfma_f32_16x16x32_bf16 v[84:87], v[156:159], v[212:215], v[84:87]
	v_mfma_f32_16x16x32_bf16 v[76:79], v[164:167], v[212:215], v[76:79]
	s_setprio 0
	s_setprio 1
	v_mfma_f32_16x16x32_bf16 v[112:115], v[168:171], v[184:187], 0
	v_mfma_f32_16x16x32_bf16 v[104:107], v[176:179], v[184:187], 0
	v_mfma_f32_16x16x32_bf16 v[100:103], v[168:171], v[192:195], 0
	v_mfma_f32_16x16x32_bf16 v[92:95], v[176:179], v[192:195], 0
	v_mfma_f32_16x16x32_bf16 v[80:83], v[168:171], v[200:203], 0
	v_mfma_f32_16x16x32_bf16 v[72:75], v[176:179], v[200:203], 0
	v_mfma_f32_16x16x32_bf16 v[68:71], v[168:171], v[208:211], 0
	v_mfma_f32_16x16x32_bf16 v[64:67], v[176:179], v[208:211], 0
	v_mfma_f32_16x16x32_bf16 v[112:115], v[172:175], v[188:191], v[112:115]
	v_mfma_f32_16x16x32_bf16 v[104:107], v[180:183], v[188:191], v[104:107]
	v_mfma_f32_16x16x32_bf16 v[100:103], v[172:175], v[196:199], v[100:103]
	v_mfma_f32_16x16x32_bf16 v[92:95], v[180:183], v[196:199], v[92:95]
	v_mfma_f32_16x16x32_bf16 v[80:83], v[172:175], v[204:207], v[80:83]
	v_mfma_f32_16x16x32_bf16 v[72:75], v[180:183], v[204:207], v[72:75]
	v_mfma_f32_16x16x32_bf16 v[68:71], v[172:175], v[212:215], v[68:71]
	v_mfma_f32_16x16x32_bf16 v[64:67], v[180:183], v[212:215], v[64:67]
	s_setprio 0
	s_barrier
	s_add_i32 s77, s65, s55
	v_lshl_add_u64 v[216:217], s[50:51], 0, v[132:133]
	s_mov_b32 m0, s77
	ds_read_b128 v[184:187], v155 offset:16384
	ds_read_b128 v[188:191], v155 offset:17408
	ds_read_b128 v[192:195], v155 offset:18432
	ds_read_b128 v[196:199], v155 offset:19456
	ds_read_b128 v[200:203], v155 offset:20480
	ds_read_b128 v[204:207], v155 offset:21504
	ds_read_b128 v[208:211], v155 offset:22528
	ds_read_b128 v[212:215], v155 offset:23552
	global_load_lds_dwordx4 v[216:217], off
	s_add_i32 m0, s77, 0x2000
	s_add_u32 s78, s50, 0x80000
	v_lshl_add_u64 v[218:219], s[50:51], 0, v[128:129]
	s_addc_u32 s79, s51, 0
	s_add_i32 s77, s66, s55
	global_load_lds_dwordx4 v[218:219], off
	v_lshl_add_u64 v[220:221], s[78:79], 0, v[132:133]
	s_mov_b32 m0, s77
	v_lshl_add_u64 v[222:223], s[52:53], 0, v[130:131]
	global_load_lds_dwordx4 v[220:221], off
	v_lshl_add_u64 v[220:221], s[78:79], 0, v[128:129]
	s_add_i32 m0, s77, 0x2000
	s_nop 0
	global_load_lds_dwordx4 v[220:221], off
	v_lshl_add_u64 v[220:221], s[52:53], 0, v[134:135]
	s_mov_b32 m0, s41
	s_nop 0
	global_load_lds_dwordx4 v[220:221], off
	s_mov_b32 m0, s59
	s_nop 0
	global_load_lds_dwordx4 v[222:223], off
	s_waitcnt vmcnt(8)
	s_waitcnt lgkmcnt(0)
	s_barrier
; #define PG8_STAGE(bufoff, gbase, voff) do { _Pragma("unroll") for (int _i = 0; _i < 2; ++_i) \
;         __builtin_amdgcn_global_load_lds((const unsigned*)((const char*)(gbase) + (voff)[_i]), (PG8_LAS unsigned*)(lds + (bufoff) + ldsw + _i * 8192), 16, 0, 0); } while (0)
; #define PG8_LDA(dst, b, h) do { _Pragma("unroll") for (int m = 0; m < 4; ++m) _Pragma("unroll") for (int k = 0; k < 2; ++k) dst[m][k] = *(const PG8_LAS bf16x8*)(lds + PG8_SA(b, h) + aoff + m * 2048 + k * 1024); } while (0)
; #define PG8_LDB(dst, b, h) do { _Pragma("unroll") for (int n = 0; n < 2; ++n) _Pragma("unroll") for (int k = 0; k < 2; ++k) dst[n][k] = *(const PG8_LAS bf16x8*)(lds + PG8_SB(b, h) + boff + n * 2048 + k * 1024); } while (0)
; #define PG8_MMA(ai, bj, At, Bt) do { __builtin_amdgcn_s_setprio(1); _Pragma("unroll") for (int m = 0; m < 4; ++m) _Pragma("unroll") for (int n = 0; n < 2; ++n) _Pragma("unroll") for (int k = 0; k < 2; ++k) \
;         acc[ai][bj][m][n] = __builtin_amdgcn_mfma_f32_16x16x32_bf16(Bt[n][k], At[m][k], acc[ai][bj][m][n], 0, 0, 0); __builtin_amdgcn_s_setprio(0); } while (0)
; #define PG8_WAIT_V(n) asm volatile("s_waitcnt vmcnt(" #n ")" ::: "memory")
; #define PG8_WAIT_L(n) asm volatile("s_waitcnt lgkmcnt(" #n ")" ::: "memory")
; #define PG8_BAR __builtin_amdgcn_s_barrier()
; #define PG8_SCHED __builtin_amdgcn_sched_barrier(0)
; template <class Epi, class Sched, bool ALIGN_EPI = false, bool SP2 = false>
; __device__ __forceinline__ void gemm_phase(PG8_LAS unsigned char* lds, const Gemm g, const Sched& S, const Epi& E) {
;     ...
;             PG8_WAIT_V(8); PG8_WAIT_L(0); PG8_BAR; PG8_MMA(1, 0, At, B0); PG8_MMA(1, 1, At, B1); PG8_BAR; PG8_SCHED;
;             PG8_LDB(B0, 1, 0); PG8_LDB(B1, 1, 1); PG8_SCHED; PG8_LDA(At, 1, 0); PG8_STAGE(PG8_SA(0, 1), a2 + hstep, voffA);
;             PG8_WAIT_V(8); PG8_WAIT_L(0); PG8_BAR; PG8_MMA(0, 0, At, B0); PG8_MMA(0, 1, At, B1); PG8_BAR; PG8_SCHED;
;             PG8_LDA(At, 1, 1); PG8_STAGE(PG8_SB(1, 0), b3, voffB); PG8_STAGE(PG8_SB(1, 1), b3 + hstep, voffB); PG8_STAGE(PG8_SA(1, 0), a3, voffA);
	s_setprio 1
	s_waitcnt lgkmcnt(0)
	v_mfma_f32_16x16x32_bf16 v[60:63], v[144:147], v[184:187], 0
	v_mfma_f32_16x16x32_bf16 v[56:59], v[160:163], v[184:187], 0
	v_mfma_f32_16x16x32_bf16 v[52:55], v[144:147], v[192:195], 0
	v_mfma_f32_16x16x32_bf16 v[44:47], v[160:163], v[192:195], 0
	v_mfma_f32_16x16x32_bf16 v[32:35], v[144:147], v[200:203], 0
	v_mfma_f32_16x16x32_bf16 v[24:27], v[160:163], v[200:203], 0
	v_mfma_f32_16x16x32_bf16 v[20:23], v[144:147], v[208:211], 0
	v_mfma_f32_16x16x32_bf16 v[12:15], v[160:163], v[208:211], 0
	v_mfma_f32_16x16x32_bf16 v[60:63], v[156:159], v[188:191], v[60:63]
	v_mfma_f32_16x16x32_bf16 v[56:59], v[164:167], v[188:191], v[56:59]
	v_mfma_f32_16x16x32_bf16 v[52:55], v[156:159], v[196:199], v[52:55]
	v_mfma_f32_16x16x32_bf16 v[44:47], v[164:167], v[196:199], v[44:47]
	v_mfma_f32_16x16x32_bf16 v[32:35], v[156:159], v[204:207], v[32:35]
	v_mfma_f32_16x16x32_bf16 v[24:27], v[164:167], v[204:207], v[24:27]
	v_mfma_f32_16x16x32_bf16 v[20:23], v[156:159], v[212:215], v[20:23]
	v_mfma_f32_16x16x32_bf16 v[12:15], v[164:167], v[212:215], v[12:15]
	s_setprio 0
	s_setprio 1
	v_mfma_f32_16x16x32_bf16 v[48:51], v[168:171], v[184:187], 0
	v_mfma_f32_16x16x32_bf16 v[40:43], v[176:179], v[184:187], 0
	v_mfma_f32_16x16x32_bf16 v[36:39], v[168:171], v[192:195], 0
	v_mfma_f32_16x16x32_bf16 v[28:31], v[176:179], v[192:195], 0
	v_mfma_f32_16x16x32_bf16 v[16:19], v[168:171], v[200:203], 0
	v_mfma_f32_16x16x32_bf16 v[8:11], v[176:179], v[200:203], 0
	v_mfma_f32_16x16x32_bf16 v[4:7], v[168:171], v[208:211], 0
	v_mfma_f32_16x16x32_bf16 v[0:3], v[176:179], v[208:211], 0
	v_mfma_f32_16x16x32_bf16 v[48:51], v[172:175], v[188:191], v[48:51]
	v_mfma_f32_16x16x32_bf16 v[40:43], v[180:183], v[188:191], v[40:43]
	v_mfma_f32_16x16x32_bf16 v[36:39], v[172:175], v[196:199], v[36:39]
	v_mfma_f32_16x16x32_bf16 v[28:31], v[180:183], v[196:199], v[28:31]
	v_mfma_f32_16x16x32_bf16 v[16:19], v[172:175], v[204:207], v[16:19]
	v_mfma_f32_16x16x32_bf16 v[8:11], v[180:183], v[204:207], v[8:11]
	v_mfma_f32_16x16x32_bf16 v[4:7], v[172:175], v[212:215], v[4:7]
	v_mfma_f32_16x16x32_bf16 v[0:3], v[180:183], v[212:215], v[0:3]
	s_setprio 0
	s_barrier
	s_add_i32 s77, 0, 0x18000
	s_add_i32 s78, 0, 0x1c000
	v_add_u32_e32 v164, s77, v150
	v_add_u32_e32 v180, s78, v150
	ds_read_b128 v[144:147], v164
	ds_read_b128 v[156:159], v164 offset:1024
	ds_read_b128 v[160:163], v164 offset:2048
	ds_read_b128 v[164:167], v164 offset:3072
	ds_read_b128 v[168:171], v180
	ds_read_b128 v[172:175], v180 offset:1024
	ds_read_b128 v[176:179], v180 offset:2048
	ds_read_b128 v[180:183], v180 offset:3072
	s_add_u32 s52, s52, 0x80000
	s_addc_u32 s53, s53, 0
	s_mov_b32 m0, s60
	v_lshl_add_u64 v[224:225], s[52:53], 0, v[134:135]
	ds_read_b128 v[184:187], v155 offset:32768
	ds_read_b128 v[188:191], v155 offset:33792
	ds_read_b128 v[192:195], v155 offset:34816
	ds_read_b128 v[196:199], v155 offset:35840
	ds_read_b128 v[200:203], v155 offset:36864
	ds_read_b128 v[204:207], v155 offset:37888
	ds_read_b128 v[208:211], v155 offset:38912
	ds_read_b128 v[212:215], v155 offset:39936
	global_load_lds_dwordx4 v[224:225], off
	v_lshl_add_u64 v[224:225], s[52:53], 0, v[130:131]
	s_mov_b32 m0, s61
	s_nop 0
	global_load_lds_dwordx4 v[224:225], off
	s_waitcnt vmcnt(8)
	s_waitcnt lgkmcnt(0)
	s_barrier
	s_setprio 1
	s_waitcnt lgkmcnt(0)
	v_mfma_f32_16x16x32_bf16 v[124:127], v[144:147], v[184:187], v[124:127]
	v_mfma_f32_16x16x32_bf16 v[120:123], v[160:163], v[184:187], v[120:123]
	v_mfma_f32_16x16x32_bf16 v[116:119], v[144:147], v[192:195], v[116:119]
	v_mfma_f32_16x16x32_bf16 v[108:111], v[160:163], v[192:195], v[108:111]
	v_mfma_f32_16x16x32_bf16 v[96:99], v[144:147], v[200:203], v[96:99]
	v_mfma_f32_16x16x32_bf16 v[88:91], v[160:163], v[200:203], v[88:91]
	v_mfma_f32_16x16x32_bf16 v[84:87], v[144:147], v[208:211], v[84:87]
	v_mfma_f32_16x16x32_bf16 v[76:79], v[160:163], v[208:211], v[76:79]
	v_mfma_f32_16x16x32_bf16 v[124:127], v[156:159], v[188:191], v[124:127]
	v_mfma_f32_16x16x32_bf16 v[120:123], v[164:167], v[188:191], v[120:123]
	v_mfma_f32_16x16x32_bf16 v[116:119], v[156:159], v[196:199], v[116:119]
	v_mfma_f32_16x16x32_bf16 v[108:111], v[164:167], v[196:199], v[108:111]
	v_mfma_f32_16x16x32_bf16 v[96:99], v[156:159], v[204:207], v[96:99]
	v_mfma_f32_16x16x32_bf16 v[88:91], v[164:167], v[204:207], v[88:91]
	v_mfma_f32_16x16x32_bf16 v[84:87], v[156:159], v[212:215], v[84:87]
	v_mfma_f32_16x16x32_bf16 v[76:79], v[164:167], v[212:215], v[76:79]
	s_setprio 0
	s_setprio 1
	v_mfma_f32_16x16x32_bf16 v[112:115], v[168:171], v[184:187], v[112:115]
	v_mfma_f32_16x16x32_bf16 v[104:107], v[176:179], v[184:187], v[104:107]
	v_mfma_f32_16x16x32_bf16 v[100:103], v[168:171], v[192:195], v[100:103]
	v_mfma_f32_16x16x32_bf16 v[92:95], v[176:179], v[192:195], v[92:95]
	v_mfma_f32_16x16x32_bf16 v[80:83], v[168:171], v[200:203], v[80:83]
	v_mfma_f32_16x16x32_bf16 v[72:75], v[176:179], v[200:203], v[72:75]
	v_mfma_f32_16x16x32_bf16 v[68:71], v[168:171], v[208:211], v[68:71]
	v_mfma_f32_16x16x32_bf16 v[64:67], v[176:179], v[208:211], v[64:67]
	v_mfma_f32_16x16x32_bf16 v[112:115], v[172:175], v[188:191], v[112:115]
	v_mfma_f32_16x16x32_bf16 v[104:107], v[180:183], v[188:191], v[104:107]
	v_mfma_f32_16x16x32_bf16 v[100:103], v[172:175], v[196:199], v[100:103]
	v_mfma_f32_16x16x32_bf16 v[92:95], v[180:183], v[196:199], v[92:95]
	v_mfma_f32_16x16x32_bf16 v[80:83], v[172:175], v[204:207], v[80:83]
	v_mfma_f32_16x16x32_bf16 v[72:75], v[180:183], v[204:207], v[72:75]
	v_mfma_f32_16x16x32_bf16 v[68:71], v[172:175], v[212:215], v[68:71]
	v_mfma_f32_16x16x32_bf16 v[64:67], v[180:183], v[212:215], v[64:67]
	s_setprio 0
	s_barrier
; #define PG8_STAGE(bufoff, gbase, voff) do { _Pragma("unroll") for (int _i = 0; _i < 2; ++_i) \
;         __builtin_amdgcn_global_load_lds((const unsigned*)((const char*)(gbase) + (voff)[_i]), (PG8_LAS unsigned*)(lds + (bufoff) + ldsw + _i * 8192), 16, 0, 0); } while (0)
; #define PG8_LDA(dst, b, h) do { _Pragma("unroll") for (int m = 0; m < 4; ++m) _Pragma("unroll") for (int k = 0; k < 2; ++k) dst[m][k] = *(const PG8_LAS bf16x8*)(lds + PG8_SA(b, h) + aoff + m * 2048 + k * 1024); } while (0)
; #define PG8_LDB(dst, b, h) do { _Pragma("unroll") for (int n = 0; n < 2; ++n) _Pragma("unroll") for (int k = 0; k < 2; ++k) dst[n][k] = *(const PG8_LAS bf16x8*)(lds + PG8_SB(b, h) + boff + n * 2048 + k * 1024); } while (0)
; template <class Epi, class Sched, bool ALIGN_EPI = false, bool SP2 = false>
; __device__ __forceinline__ void gemm_phase(PG8_LAS unsigned char* lds, const Gemm g, const Sched& S, const Epi& E) {
;     ...
;         for (int t = 0; t < nt; t += 2) {
;             const bool last = (t == nt - 2);
;             const char* a1 = cA + (size_t)(t + 1) * kstep;
;             const char* a2 = last ? nA : cA + (size_t)(t + 2) * kstep; const char* b2 = last ? nB : cB + (size_t)(t + 2) * kstep;
;             const char* a3 = a2 + kstep; const char* b3 = b2 + kstep;
;             if (last && has_next) S.a_ready(nxt);
;             if constexpr (SP2) {
;             PG8_LDB(B0, 0, 0); PG8_LDB(B1, 0, 1); PG8_SCHED; PG8_LDA(At, 0, 0); PG8_STAGE(PG8_SA(1, 1), a1 + hstep, voffA);
;             PG8_WAIT_V(8); PG8_WAIT_L(0); PG8_BAR; PG8_MMA(0, 0, At, B0); PG8_MMA(0, 1, At, B1); PG8_BAR; PG8_SCHED;
;             PG8_LDA(At, 0, 1); PG8_STAGE(PG8_SB(0, 0), b2, voffB); PG8_STAGE(PG8_SB(0, 1), b2 + hstep, voffB); PG8_STAGE(PG8_SA(0, 0), a2, voffA);
;             PG8_WAIT_V(8); PG8_WAIT_L(0); PG8_BAR; PG8_MMA(1, 0, At, B0); PG8_MMA(1, 1, At, B1); PG8_BAR; PG8_SCHED;
;             PG8_LDB(B0, 1, 0); PG8_LDB(B1, 1, 1); PG8_SCHED; PG8_LDA(At, 1, 0); PG8_STAGE(PG8_SA(0, 1), a2 + hstep, voffA);
;             PG8_WAIT_V(8); PG8_WAIT_L(0); PG8_BAR; PG8_MMA(0, 0, At, B0); PG8_MMA(0, 1, At, B1); PG8_BAR; PG8_SCHED;
;             PG8_LDA(At, 1, 1); PG8_STAGE(PG8_SB(1, 0), b3, voffB); PG8_STAGE(PG8_SB(1, 1), b3 + hstep, voffB); PG8_STAGE(PG8_SA(1, 0), a3, voffA);
;             PG8_WAIT_V(8); PG8_WAIT_L(0); PG8_BAR; PG8_MMA(1, 0, At, B0); PG8_MMA(1, 1, At, B1); PG8_BAR; PG8_SCHED;
	s_add_i32 s52, s77, s55
	v_lshl_add_u64 v[216:217], v[216:217], 0, s[26:27]
	s_mov_b32 m0, s52
	ds_read_b128 v[184:187], v155 offset:49152
	ds_read_b128 v[188:191], v155 offset:50176
	ds_read_b128 v[192:195], v155 offset:51200
	ds_read_b128 v[196:199], v155 offset:52224
	ds_read_b128 v[200:203], v155 offset:53248
	ds_read_b128 v[204:207], v155 offset:54272
	ds_read_b128 v[208:211], v155 offset:55296
	ds_read_b128 v[212:215], v155 offset:56320
	global_load_lds_dwordx4 v[216:217], off
	s_add_i32 m0, s52, 0x2000
	s_add_u32 s50, s50, 0x80080
	v_lshl_add_u64 v[216:217], v[218:219], 0, s[26:27]
	s_addc_u32 s51, s51, 0
	s_add_i32 s52, s78, s55
	global_load_lds_dwordx4 v[216:217], off
	v_lshl_add_u64 v[216:217], s[50:51], 0, v[132:133]
	s_mov_b32 m0, s52
	s_nop 0
	global_load_lds_dwordx4 v[216:217], off
	v_lshl_add_u64 v[216:217], s[50:51], 0, v[128:129]
	s_add_i32 m0, s52, 0x2000
	s_nop 0
	global_load_lds_dwordx4 v[216:217], off
	v_lshl_add_u64 v[216:217], v[220:221], 0, s[26:27]
	s_mov_b32 m0, s63
	s_nop 0
	global_load_lds_dwordx4 v[216:217], off
	v_lshl_add_u64 v[216:217], v[222:223], 0, s[26:27]
	s_mov_b32 m0, s64
	s_nop 0
	global_load_lds_dwordx4 v[216:217], off
	s_waitcnt vmcnt(8)
	s_waitcnt lgkmcnt(0)
	s_barrier
	s_setprio 1
	s_waitcnt lgkmcnt(0)
	v_mfma_f32_16x16x32_bf16 v[60:63], v[144:147], v[184:187], v[60:63]
	v_mfma_f32_16x16x32_bf16 v[56:59], v[160:163], v[184:187], v[56:59]
	v_mfma_f32_16x16x32_bf16 v[52:55], v[144:147], v[192:195], v[52:55]
	v_mfma_f32_16x16x32_bf16 v[44:47], v[160:163], v[192:195], v[44:47]
	v_mfma_f32_16x16x32_bf16 v[32:35], v[144:147], v[200:203], v[32:35]
	v_mfma_f32_16x16x32_bf16 v[24:27], v[160:163], v[200:203], v[24:27]
	v_mfma_f32_16x16x32_bf16 v[20:23], v[144:147], v[208:211], v[20:23]
	v_mfma_f32_16x16x32_bf16 v[12:15], v[160:163], v[208:211], v[12:15]
	v_mfma_f32_16x16x32_bf16 v[60:63], v[156:159], v[188:191], v[60:63]
	v_mfma_f32_16x16x32_bf16 v[56:59], v[164:167], v[188:191], v[56:59]
	v_mfma_f32_16x16x32_bf16 v[52:55], v[156:159], v[196:199], v[52:55]
	v_mfma_f32_16x16x32_bf16 v[44:47], v[164:167], v[196:199], v[44:47]
	v_mfma_f32_16x16x32_bf16 v[32:35], v[156:159], v[204:207], v[32:35]
	v_mfma_f32_16x16x32_bf16 v[24:27], v[164:167], v[204:207], v[24:27]
	v_mfma_f32_16x16x32_bf16 v[20:23], v[156:159], v[212:215], v[20:23]
	v_mfma_f32_16x16x32_bf16 v[12:15], v[164:167], v[212:215], v[12:15]
	s_setprio 0
	s_setprio 1
	v_mfma_f32_16x16x32_bf16 v[48:51], v[168:171], v[184:187], v[48:51]
	v_mfma_f32_16x16x32_bf16 v[40:43], v[176:179], v[184:187], v[40:43]
	v_mfma_f32_16x16x32_bf16 v[36:39], v[168:171], v[192:195], v[36:39]
	v_mfma_f32_16x16x32_bf16 v[28:31], v[176:179], v[192:195], v[28:31]
	v_mfma_f32_16x16x32_bf16 v[16:19], v[168:171], v[200:203], v[16:19]
	v_mfma_f32_16x16x32_bf16 v[8:11], v[176:179], v[200:203], v[8:11]
	v_mfma_f32_16x16x32_bf16 v[4:7], v[168:171], v[208:211], v[4:7]
	v_mfma_f32_16x16x32_bf16 v[0:3], v[176:179], v[208:211], v[0:3]
	v_mfma_f32_16x16x32_bf16 v[48:51], v[172:175], v[188:191], v[48:51]
	v_mfma_f32_16x16x32_bf16 v[40:43], v[180:183], v[188:191], v[40:43]
	v_mfma_f32_16x16x32_bf16 v[36:39], v[172:175], v[196:199], v[36:39]
	v_mfma_f32_16x16x32_bf16 v[28:31], v[180:183], v[196:199], v[28:31]
	v_mfma_f32_16x16x32_bf16 v[16:19], v[172:175], v[204:207], v[16:19]
	v_mfma_f32_16x16x32_bf16 v[8:11], v[180:183], v[204:207], v[8:11]
	v_mfma_f32_16x16x32_bf16 v[4:7], v[172:175], v[212:215], v[4:7]
	v_mfma_f32_16x16x32_bf16 v[0:3], v[180:183], v[212:215], v[0:3]
	s_setprio 0
	s_barrier
	s_add_i32 s76, s76, 2
	s_add_u32 s42, s42, 0x100
	s_addc_u32 s43, s43, 0
	s_add_u32 s74, s74, 0x100
	s_addc_u32 s75, s75, 0
	s_cmp_gt_u32 s76, 29
	s_cbranch_scc0 .LBB0_1402
	s_branch .Lpeel_exit_7
.LBB0_1402:
	ds_read_b128 v[144:147], v153
	ds_read_b128 v[156:159], v153 offset:1024
	ds_read_b128 v[160:163], v153 offset:2048
	ds_read_b128 v[164:167], v153 offset:3072
	ds_read_b128 v[168:171], v154
	ds_read_b128 v[172:175], v154 offset:1024
	ds_read_b128 v[176:179], v154 offset:2048
	ds_read_b128 v[180:183], v154 offset:3072
	s_add_u32 s50, s42, 0xfff80080
	s_addc_u32 s51, s43, -1
	s_cmp_eq_u32 s76, 28
	s_cselect_b32 s53, s35, s51
	s_cselect_b32 s52, s72, s50
	s_cselect_b32 s51, s31, s75
	s_cselect_b32 s50, s73, s74
	v_lshl_add_u64 v[216:217], s[42:43], 0, v[136:137]
	s_add_i32 m0, s41, 0xc000
	ds_read_b128 v[184:187], v155
	ds_read_b128 v[188:191], v155 offset:1024
	ds_read_b128 v[192:195], v155 offset:2048
	ds_read_b128 v[196:199], v155 offset:3072
	ds_read_b128 v[200:203], v155 offset:4096
	ds_read_b128 v[204:207], v155 offset:5120
	ds_read_b128 v[208:211], v155 offset:6144
	ds_read_b128 v[212:215], v155 offset:7168
	global_load_lds_dwordx4 v[216:217], off
	v_lshl_add_u64 v[216:217], s[42:43], 0, v[138:139]
	s_add_i32 m0, s41, 0xe000
	s_nop 0
	global_load_lds_dwordx4 v[216:217], off
	s_waitcnt vmcnt(8)
	s_waitcnt lgkmcnt(0)
	s_barrier
; #define PG8_STAGE(bufoff, gbase, voff) do { _Pragma("unroll") for (int _i = 0; _i < 2; ++_i) \
;         __builtin_amdgcn_global_load_lds((const unsigned*)((const char*)(gbase) + (voff)[_i]), (PG8_LAS unsigned*)(lds + (bufoff) + ldsw + _i * 8192), 16, 0, 0); } while (0)
; #define PG8_LDA(dst, b, h) do { _Pragma("unroll") for (int m = 0; m < 4; ++m) _Pragma("unroll") for (int k = 0; k < 2; ++k) dst[m][k] = *(const PG8_LAS bf16x8*)(lds + PG8_SA(b, h) + aoff + m * 2048 + k * 1024); } while (0)
; #define PG8_LDB(dst, b, h) do { _Pragma("unroll") for (int n = 0; n < 2; ++n) _Pragma("unroll") for (int k = 0; k < 2; ++k) dst[n][k] = *(const PG8_LAS bf16x8*)(lds + PG8_SB(b, h) + boff + n * 2048 + k * 1024); } while (0)
; #define PG8_MMA(ai, bj, At, Bt) do { __builtin_amdgcn_s_setprio(1); _Pragma("unroll") for (int m = 0; m < 4; ++m) _Pragma("unroll") for (int n = 0; n < 2; ++n) _Pragma("unroll") for (int k = 0; k < 2; ++k) \
;         acc[ai][bj][m][n] = __builtin_amdgcn_mfma_f32_16x16x32_bf16(Bt[n][k], At[m][k], acc[ai][bj][m][n], 0, 0, 0); __builtin_amdgcn_s_setprio(0); } while (0)
; #define PG8_WAIT_V(n) asm volatile("s_waitcnt vmcnt(" #n ")" ::: "memory")
; #define PG8_WAIT_L(n) asm volatile("s_waitcnt lgkmcnt(" #n ")" ::: "memory")
; #define PG8_BAR __builtin_amdgcn_s_barrier()
; #define PG8_SCHED __builtin_amdgcn_sched_barrier(0)
; template <class Epi, class Sched, bool ALIGN_EPI = false, bool SP2 = false>
; __device__ __forceinline__ void gemm_phase(PG8_LAS unsigned char* lds, const Gemm g, const Sched& S, const Epi& E) {
;     ...
;             PG8_LDB(B0, 0, 0); PG8_LDB(B1, 0, 1); PG8_SCHED; PG8_LDA(At, 0, 0); PG8_STAGE(PG8_SA(1, 1), a1 + hstep, voffA);
;             PG8_WAIT_V(8); PG8_WAIT_L(0); PG8_BAR; PG8_MMA(0, 0, At, B0); PG8_MMA(0, 1, At, B1); PG8_BAR; PG8_SCHED;
;             PG8_LDA(At, 0, 1); PG8_STAGE(PG8_SB(0, 0), b2, voffB); PG8_STAGE(PG8_SB(0, 1), b2 + hstep, voffB); PG8_STAGE(PG8_SA(0, 0), a2, voffA);
;             PG8_WAIT_V(8); PG8_WAIT_L(0); PG8_BAR; PG8_MMA(1, 0, At, B0); PG8_MMA(1, 1, At, B1); PG8_BAR; PG8_SCHED;
	s_setprio 1
	s_waitcnt lgkmcnt(0)
	v_mfma_f32_16x16x32_bf16 v[124:127], v[144:147], v[184:187], v[124:127]
	v_mfma_f32_16x16x32_bf16 v[120:123], v[160:163], v[184:187], v[120:123]
	v_mfma_f32_16x16x32_bf16 v[116:119], v[144:147], v[192:195], v[116:119]
	v_mfma_f32_16x16x32_bf16 v[108:111], v[160:163], v[192:195], v[108:111]
	v_mfma_f32_16x16x32_bf16 v[96:99], v[144:147], v[200:203], v[96:99]
	v_mfma_f32_16x16x32_bf16 v[88:91], v[160:163], v[200:203], v[88:91]
	v_mfma_f32_16x16x32_bf16 v[84:87], v[144:147], v[208:211], v[84:87]
	v_mfma_f32_16x16x32_bf16 v[76:79], v[160:163], v[208:211], v[76:79]
	v_mfma_f32_16x16x32_bf16 v[124:127], v[156:159], v[188:191], v[124:127]
	v_mfma_f32_16x16x32_bf16 v[120:123], v[164:167], v[188:191], v[120:123]
	v_mfma_f32_16x16x32_bf16 v[116:119], v[156:159], v[196:199], v[116:119]
	v_mfma_f32_16x16x32_bf16 v[108:111], v[164:167], v[196:199], v[108:111]
	v_mfma_f32_16x16x32_bf16 v[96:99], v[156:159], v[204:207], v[96:99]
	v_mfma_f32_16x16x32_bf16 v[88:91], v[164:167], v[204:207], v[88:91]
	v_mfma_f32_16x16x32_bf16 v[84:87], v[156:159], v[212:215], v[84:87]
	v_mfma_f32_16x16x32_bf16 v[76:79], v[164:167], v[212:215], v[76:79]
	s_setprio 0
	s_setprio 1
	v_mfma_f32_16x16x32_bf16 v[112:115], v[168:171], v[184:187], v[112:115]
	v_mfma_f32_16x16x32_bf16 v[104:107], v[176:179], v[184:187], v[104:107]
	v_mfma_f32_16x16x32_bf16 v[100:103], v[168:171], v[192:195], v[100:103]
	v_mfma_f32_16x16x32_bf16 v[92:95], v[176:179], v[192:195], v[92:95]
	v_mfma_f32_16x16x32_bf16 v[80:83], v[168:171], v[200:203], v[80:83]
	v_mfma_f32_16x16x32_bf16 v[72:75], v[176:179], v[200:203], v[72:75]
	v_mfma_f32_16x16x32_bf16 v[68:71], v[168:171], v[208:211], v[68:71]
	v_mfma_f32_16x16x32_bf16 v[64:67], v[176:179], v[208:211], v[64:67]
	v_mfma_f32_16x16x32_bf16 v[112:115], v[172:175], v[188:191], v[112:115]
	v_mfma_f32_16x16x32_bf16 v[104:107], v[180:183], v[188:191], v[104:107]
	v_mfma_f32_16x16x32_bf16 v[100:103], v[172:175], v[196:199], v[100:103]
	v_mfma_f32_16x16x32_bf16 v[92:95], v[180:183], v[196:199], v[92:95]
	v_mfma_f32_16x16x32_bf16 v[80:83], v[172:175], v[204:207], v[80:83]
	v_mfma_f32_16x16x32_bf16 v[72:75], v[180:183], v[204:207], v[72:75]
	v_mfma_f32_16x16x32_bf16 v[68:71], v[172:175], v[212:215], v[68:71]
	v_mfma_f32_16x16x32_bf16 v[64:67], v[180:183], v[212:215], v[64:67]
	s_setprio 0
	s_barrier
	s_add_i32 s77, s65, s55
	v_lshl_add_u64 v[216:217], s[50:51], 0, v[132:133]
	s_mov_b32 m0, s77
	ds_read_b128 v[184:187], v155 offset:16384
	ds_read_b128 v[188:191], v155 offset:17408
	ds_read_b128 v[192:195], v155 offset:18432
	ds_read_b128 v[196:199], v155 offset:19456
	ds_read_b128 v[200:203], v155 offset:20480
	ds_read_b128 v[204:207], v155 offset:21504
	ds_read_b128 v[208:211], v155 offset:22528
	ds_read_b128 v[212:215], v155 offset:23552
	global_load_lds_dwordx4 v[216:217], off
	s_add_i32 m0, s77, 0x2000
	s_add_u32 s78, s50, 0x80000
	v_lshl_add_u64 v[218:219], s[50:51], 0, v[128:129]
	s_addc_u32 s79, s51, 0
	s_add_i32 s77, s66, s55
	global_load_lds_dwordx4 v[218:219], off
	v_lshl_add_u64 v[220:221], s[78:79], 0, v[132:133]
	s_mov_b32 m0, s77
	v_lshl_add_u64 v[222:223], s[52:53], 0, v[130:131]
	global_load_lds_dwordx4 v[220:221], off
	v_lshl_add_u64 v[220:221], s[78:79], 0, v[128:129]
	s_add_i32 m0, s77, 0x2000
	s_nop 0
	global_load_lds_dwordx4 v[220:221], off
	v_lshl_add_u64 v[220:221], s[52:53], 0, v[134:135]
	s_mov_b32 m0, s41
	s_nop 0
	global_load_lds_dwordx4 v[220:221], off
	s_mov_b32 m0, s59
	s_nop 0
	global_load_lds_dwordx4 v[222:223], off
	s_waitcnt vmcnt(8)
	s_waitcnt lgkmcnt(0)
	s_barrier
	s_setprio 1
	s_waitcnt lgkmcnt(0)
	v_mfma_f32_16x16x32_bf16 v[60:63], v[144:147], v[184:187], v[60:63]
	v_mfma_f32_16x16x32_bf16 v[56:59], v[160:163], v[184:187], v[56:59]
	v_mfma_f32_16x16x32_bf16 v[52:55], v[144:147], v[192:195], v[52:55]
	v_mfma_f32_16x16x32_bf16 v[44:47], v[160:163], v[192:195], v[44:47]
	v_mfma_f32_16x16x32_bf16 v[32:35], v[144:147], v[200:203], v[32:35]
	v_mfma_f32_16x16x32_bf16 v[24:27], v[160:163], v[200:203], v[24:27]
	v_mfma_f32_16x16x32_bf16 v[20:23], v[144:147], v[208:211], v[20:23]
	v_mfma_f32_16x16x32_bf16 v[12:15], v[160:163], v[208:211], v[12:15]
	v_mfma_f32_16x16x32_bf16 v[60:63], v[156:159], v[188:191], v[60:63]
	v_mfma_f32_16x16x32_bf16 v[56:59], v[164:167], v[188:191], v[56:59]
	v_mfma_f32_16x16x32_bf16 v[52:55], v[156:159], v[196:199], v[52:55]
	v_mfma_f32_16x16x32_bf16 v[44:47], v[164:167], v[196:199], v[44:47]
	v_mfma_f32_16x16x32_bf16 v[32:35], v[156:159], v[204:207], v[32:35]
	v_mfma_f32_16x16x32_bf16 v[24:27], v[164:167], v[204:207], v[24:27]
	v_mfma_f32_16x16x32_bf16 v[20:23], v[156:159], v[212:215], v[20:23]
	v_mfma_f32_16x16x32_bf16 v[12:15], v[164:167], v[212:215], v[12:15]
	s_setprio 0
	s_setprio 1
	v_mfma_f32_16x16x32_bf16 v[48:51], v[168:171], v[184:187], v[48:51]
	v_mfma_f32_16x16x32_bf16 v[40:43], v[176:179], v[184:187], v[40:43]
	v_mfma_f32_16x16x32_bf16 v[36:39], v[168:171], v[192:195], v[36:39]
	v_mfma_f32_16x16x32_bf16 v[28:31], v[176:179], v[192:195], v[28:31]
	v_mfma_f32_16x16x32_bf16 v[16:19], v[168:171], v[200:203], v[16:19]
	v_mfma_f32_16x16x32_bf16 v[8:11], v[176:179], v[200:203], v[8:11]
	v_mfma_f32_16x16x32_bf16 v[4:7], v[168:171], v[208:211], v[4:7]
	v_mfma_f32_16x16x32_bf16 v[0:3], v[176:179], v[208:211], v[0:3]
	v_mfma_f32_16x16x32_bf16 v[48:51], v[172:175], v[188:191], v[48:51]
	v_mfma_f32_16x16x32_bf16 v[40:43], v[180:183], v[188:191], v[40:43]
	v_mfma_f32_16x16x32_bf16 v[36:39], v[172:175], v[196:199], v[36:39]
	v_mfma_f32_16x16x32_bf16 v[28:31], v[180:183], v[196:199], v[28:31]
	v_mfma_f32_16x16x32_bf16 v[16:19], v[172:175], v[204:207], v[16:19]
	v_mfma_f32_16x16x32_bf16 v[8:11], v[180:183], v[204:207], v[8:11]
	v_mfma_f32_16x16x32_bf16 v[4:7], v[172:175], v[212:215], v[4:7]
	v_mfma_f32_16x16x32_bf16 v[0:3], v[180:183], v[212:215], v[0:3]
	s_setprio 0
	s_barrier
; #define PG8_STAGE(bufoff, gbase, voff) do { _Pragma("unroll") for (int _i = 0; _i < 2; ++_i) \
;         __builtin_amdgcn_global_load_lds((const unsigned*)((const char*)(gbase) + (voff)[_i]), (PG8_LAS unsigned*)(lds + (bufoff) + ldsw + _i * 8192), 16, 0, 0); } while (0)
; #define PG8_LDA(dst, b, h) do { _Pragma("unroll") for (int m = 0; m < 4; ++m) _Pragma("unroll") for (int k = 0; k < 2; ++k) dst[m][k] = *(const PG8_LAS bf16x8*)(lds + PG8_SA(b, h) + aoff + m * 2048 + k * 1024); } while (0)
; #define PG8_LDB(dst, b, h) do { _Pragma("unroll") for (int n = 0; n < 2; ++n) _Pragma("unroll") for (int k = 0; k < 2; ++k) dst[n][k] = *(const PG8_LAS bf16x8*)(lds + PG8_SB(b, h) + boff + n * 2048 + k * 1024); } while (0)
; #define PG8_MMA(ai, bj, At, Bt) do { __builtin_amdgcn_s_setprio(1); _Pragma("unroll") for (int m = 0; m < 4; ++m) _Pragma("unroll") for (int n = 0; n < 2; ++n) _Pragma("unroll") for (int k = 0; k < 2; ++k) \
;         acc[ai][bj][m][n] = __builtin_amdgcn_mfma_f32_16x16x32_bf16(Bt[n][k], At[m][k], acc[ai][bj][m][n], 0, 0, 0); __builtin_amdgcn_s_setprio(0); } while (0)
; #define PG8_WAIT_V(n) asm volatile("s_waitcnt vmcnt(" #n ")" ::: "memory")
; #define PG8_WAIT_L(n) asm volatile("s_waitcnt lgkmcnt(" #n ")" ::: "memory")
; #define PG8_BAR __builtin_amdgcn_s_barrier()
; #define PG8_SCHED __builtin_amdgcn_sched_barrier(0)
; template <class Epi, class Sched, bool ALIGN_EPI = false, bool SP2 = false>
; __device__ __forceinline__ void gemm_phase(PG8_LAS unsigned char* lds, const Gemm g, const Sched& S, const Epi& E) {
;     ...
;             PG8_LDB(B0, 1, 0); PG8_LDB(B1, 1, 1); PG8_SCHED; PG8_LDA(At, 1, 0); PG8_STAGE(PG8_SA(0, 1), a2 + hstep, voffA);
;             PG8_WAIT_V(8); PG8_WAIT_L(0); PG8_BAR; PG8_MMA(0, 0, At, B0); PG8_MMA(0, 1, At, B1); PG8_BAR; PG8_SCHED;
;             PG8_LDA(At, 1, 1); PG8_STAGE(PG8_SB(1, 0), b3, voffB); PG8_STAGE(PG8_SB(1, 1), b3 + hstep, voffB); PG8_STAGE(PG8_SA(1, 0), a3, voffA);
	s_add_i32 s77, 0, 0x18000
	s_add_i32 s78, 0, 0x1c000
	v_add_u32_e32 v164, s77, v150
	v_add_u32_e32 v180, s78, v150
	ds_read_b128 v[144:147], v164
	ds_read_b128 v[156:159], v164 offset:1024
	ds_read_b128 v[160:163], v164 offset:2048
	ds_read_b128 v[164:167], v164 offset:3072
	ds_read_b128 v[168:171], v180
	ds_read_b128 v[172:175], v180 offset:1024
	ds_read_b128 v[176:179], v180 offset:2048
	ds_read_b128 v[180:183], v180 offset:3072
	s_add_u32 s52, s52, 0x80000
	s_addc_u32 s53, s53, 0
	s_mov_b32 m0, s60
	v_lshl_add_u64 v[224:225], s[52:53], 0, v[134:135]
	ds_read_b128 v[184:187], v155 offset:32768
	ds_read_b128 v[188:191], v155 offset:33792
	ds_read_b128 v[192:195], v155 offset:34816
	ds_read_b128 v[196:199], v155 offset:35840
	ds_read_b128 v[200:203], v155 offset:36864
	ds_read_b128 v[204:207], v155 offset:37888
	ds_read_b128 v[208:211], v155 offset:38912
	ds_read_b128 v[212:215], v155 offset:39936
	global_load_lds_dwordx4 v[224:225], off
	v_lshl_add_u64 v[224:225], s[52:53], 0, v[130:131]
	s_mov_b32 m0, s61
	s_nop 0
	global_load_lds_dwordx4 v[224:225], off
	s_waitcnt vmcnt(8)
	s_waitcnt lgkmcnt(0)
	s_barrier
	s_setprio 1
	s_waitcnt lgkmcnt(0)
	v_mfma_f32_16x16x32_bf16 v[124:127], v[144:147], v[184:187], v[124:127]
	v_mfma_f32_16x16x32_bf16 v[120:123], v[160:163], v[184:187], v[120:123]
	v_mfma_f32_16x16x32_bf16 v[116:119], v[144:147], v[192:195], v[116:119]
	v_mfma_f32_16x16x32_bf16 v[108:111], v[160:163], v[192:195], v[108:111]
	v_mfma_f32_16x16x32_bf16 v[96:99], v[144:147], v[200:203], v[96:99]
	v_mfma_f32_16x16x32_bf16 v[88:91], v[160:163], v[200:203], v[88:91]
	v_mfma_f32_16x16x32_bf16 v[84:87], v[144:147], v[208:211], v[84:87]
	v_mfma_f32_16x16x32_bf16 v[76:79], v[160:163], v[208:211], v[76:79]
	v_mfma_f32_16x16x32_bf16 v[124:127], v[156:159], v[188:191], v[124:127]
	v_mfma_f32_16x16x32_bf16 v[120:123], v[164:167], v[188:191], v[120:123]
	v_mfma_f32_16x16x32_bf16 v[116:119], v[156:159], v[196:199], v[116:119]
	v_mfma_f32_16x16x32_bf16 v[108:111], v[164:167], v[196:199], v[108:111]
	v_mfma_f32_16x16x32_bf16 v[96:99], v[156:159], v[204:207], v[96:99]
	v_mfma_f32_16x16x32_bf16 v[88:91], v[164:167], v[204:207], v[88:91]
	v_mfma_f32_16x16x32_bf16 v[84:87], v[156:159], v[212:215], v[84:87]
	v_mfma_f32_16x16x32_bf16 v[76:79], v[164:167], v[212:215], v[76:79]
	s_setprio 0
	s_setprio 1
	v_mfma_f32_16x16x32_bf16 v[112:115], v[168:171], v[184:187], v[112:115]
	v_mfma_f32_16x16x32_bf16 v[104:107], v[176:179], v[184:187], v[104:107]
	v_mfma_f32_16x16x32_bf16 v[100:103], v[168:171], v[192:195], v[100:103]
	v_mfma_f32_16x16x32_bf16 v[92:95], v[176:179], v[192:195], v[92:95]
	v_mfma_f32_16x16x32_bf16 v[80:83], v[168:171], v[200:203], v[80:83]
	v_mfma_f32_16x16x32_bf16 v[72:75], v[176:179], v[200:203], v[72:75]
	v_mfma_f32_16x16x32_bf16 v[68:71], v[168:171], v[208:211], v[68:71]
	v_mfma_f32_16x16x32_bf16 v[64:67], v[176:179], v[208:211], v[64:67]
	v_mfma_f32_16x16x32_bf16 v[112:115], v[172:175], v[188:191], v[112:115]
	v_mfma_f32_16x16x32_bf16 v[104:107], v[180:183], v[188:191], v[104:107]
	v_mfma_f32_16x16x32_bf16 v[100:103], v[172:175], v[196:199], v[100:103]
	v_mfma_f32_16x16x32_bf16 v[92:95], v[180:183], v[196:199], v[92:95]
	v_mfma_f32_16x16x32_bf16 v[80:83], v[172:175], v[204:207], v[80:83]
	v_mfma_f32_16x16x32_bf16 v[72:75], v[180:183], v[204:207], v[72:75]
	v_mfma_f32_16x16x32_bf16 v[68:71], v[172:175], v[212:215], v[68:71]
	v_mfma_f32_16x16x32_bf16 v[64:67], v[180:183], v[212:215], v[64:67]
	s_setprio 0
	s_barrier
	s_add_i32 s52, s77, s55
	v_lshl_add_u64 v[216:217], v[216:217], 0, s[26:27]
	s_mov_b32 m0, s52
	ds_read_b128 v[184:187], v155 offset:49152
	ds_read_b128 v[188:191], v155 offset:50176
	ds_read_b128 v[192:195], v155 offset:51200
	ds_read_b128 v[196:199], v155 offset:52224
	ds_read_b128 v[200:203], v155 offset:53248
	ds_read_b128 v[204:207], v155 offset:54272
	ds_read_b128 v[208:211], v155 offset:55296
	ds_read_b128 v[212:215], v155 offset:56320
	global_load_lds_dwordx4 v[216:217], off
	s_add_i32 m0, s52, 0x2000
	s_add_u32 s50, s50, 0x80080
	v_lshl_add_u64 v[216:217], v[218:219], 0, s[26:27]
	s_addc_u32 s51, s51, 0
	s_add_i32 s52, s78, s55
	global_load_lds_dwordx4 v[216:217], off
	v_lshl_add_u64 v[216:217], s[50:51], 0, v[132:133]
	s_mov_b32 m0, s52
	s_nop 0
	global_load_lds_dwordx4 v[216:217], off
	v_lshl_add_u64 v[216:217], s[50:51], 0, v[128:129]
	s_add_i32 m0, s52, 0x2000
	s_nop 0
	global_load_lds_dwordx4 v[216:217], off
	v_lshl_add_u64 v[216:217], v[220:221], 0, s[26:27]
	s_mov_b32 m0, s63
	s_nop 0
	global_load_lds_dwordx4 v[216:217], off
	v_lshl_add_u64 v[216:217], v[222:223], 0, s[26:27]
	s_mov_b32 m0, s64
	s_nop 0
	global_load_lds_dwordx4 v[216:217], off
	s_waitcnt vmcnt(8)
	s_waitcnt lgkmcnt(0)
	s_barrier
;     __device__ __forceinline__ void operator()(const f32x4 (&acc)[2][2][4][2], const Unit& u, int wr, int wc, int fr, int fq) const {
;         const int row0 = u.pm * BM + wr * 64 + fr; const int col0 = u.pn * BM + wc * 32 + 8 * fq;
;         const PG8_LAS float* rt = rtab + (u.pm == pm0 ? 0 : u.pm == pm1 ? 256 : u.pm == pm2 ? 512 : 768) + wr * 64 + fr;
; #pragma unroll
;         for (int ai = 0; ai < 2; ++ai)
; #pragma unroll
;             for (int m = 0; m < 4; ++m) { bf16_t* rowp = O + (size_t)(row0 + ai * HALF + m * 16) * ldc + col0; const float rs = rt[ai * HALF + m * 16];
; #pragma unroll
;                 for (int bj = 0; bj < 2; ++bj) { f32x4 v0 = acc[ai][bj][m][0] * rs, v1 = acc[ai][bj][m][1] * rs;
; template <class Epi, class Sched, bool ALIGN_EPI = false, bool SP2 = false>
; __device__ __forceinline__ void gemm_phase(PG8_LAS unsigned char* lds, const Gemm g, const Sched& S, const Epi& E) {
;     ...
;             PG8_WAIT_V(8); PG8_WAIT_L(0); PG8_BAR; PG8_MMA(1, 0, At, B0); PG8_MMA(1, 1, At, B1); PG8_BAR; PG8_SCHED;
;             } else {
;             PG8_LDB(B0, 0, 0); PG8_SCHED; PG8_LDA(At, 0, 0); PG8_STAGE(PG8_SA(1, 1), a1 + hstep, voffA);
;             PG8_WAIT_L(8); PG8_BAR; PG8_WAIT_L(0); PG8_MMA(0, 0, At, B0); PG8_BAR; PG8_SCHED;
;             PG8_LDB(B1, 0, 1); PG8_STAGE(PG8_SB(0, 0), b2, voffB);
;             PG8_BAR; PG8_WAIT_L(0); PG8_MMA(0, 1, At, B1); PG8_BAR;
;             PG8_LDA(At, 0, 1); PG8_STAGE(PG8_SA(0, 0), a2, voffA);
;             PG8_BAR; PG8_WAIT_L(0); PG8_MMA(1, 0, At, B0); PG8_BAR; PG8_SCHED;
;             PG8_STAGE(PG8_SB(0, 1), b2 + hstep, voffB);
;             PG8_WAIT_V(6); PG8_BAR; PG8_MMA(1, 1, At, B1); PG8_BAR;
;             PG8_LDB(B0, 1, 0); PG8_SCHED; PG8_LDA(At, 1, 0); PG8_STAGE(PG8_SA(0, 1), a2 + hstep, voffA);
;             PG8_WAIT_L(8); PG8_BAR; PG8_WAIT_L(0); PG8_MMA(0, 0, At, B0); PG8_BAR; PG8_SCHED;
;             PG8_LDB(B1, 1, 1); PG8_STAGE(PG8_SB(1, 0), b3, voffB);
;             PG8_BAR; PG8_WAIT_L(0); PG8_MMA(0, 1, At, B1); PG8_BAR;
;             PG8_LDA(At, 1, 1); PG8_STAGE(PG8_SA(1, 0), a3, voffA);
;             PG8_BAR; PG8_WAIT_L(0); PG8_MMA(1, 0, At, B0); PG8_BAR; PG8_SCHED;
;             PG8_STAGE(PG8_SB(1, 1), b3 + hstep, voffB);
;             PG8_WAIT_V(6); PG8_BAR; PG8_MMA(1, 1, At, B1); PG8_BAR;
;             }
;         }
;         if constexpr (ALIGN_EPI) { if (wr == 0) PG8_BAR; }
	s_setprio 1
	s_waitcnt lgkmcnt(0)
	v_mfma_f32_16x16x32_bf16 v[60:63], v[144:147], v[184:187], v[60:63]
	v_mfma_f32_16x16x32_bf16 v[56:59], v[160:163], v[184:187], v[56:59]
	v_mfma_f32_16x16x32_bf16 v[52:55], v[144:147], v[192:195], v[52:55]
	v_mfma_f32_16x16x32_bf16 v[44:47], v[160:163], v[192:195], v[44:47]
	v_mfma_f32_16x16x32_bf16 v[32:35], v[144:147], v[200:203], v[32:35]
	v_mfma_f32_16x16x32_bf16 v[24:27], v[160:163], v[200:203], v[24:27]
	v_mfma_f32_16x16x32_bf16 v[20:23], v[144:147], v[208:211], v[20:23]
	v_mfma_f32_16x16x32_bf16 v[12:15], v[160:163], v[208:211], v[12:15]
	v_mfma_f32_16x16x32_bf16 v[60:63], v[156:159], v[188:191], v[60:63]
	v_mfma_f32_16x16x32_bf16 v[56:59], v[164:167], v[188:191], v[56:59]
	v_mfma_f32_16x16x32_bf16 v[52:55], v[156:159], v[196:199], v[52:55]
	v_mfma_f32_16x16x32_bf16 v[44:47], v[164:167], v[196:199], v[44:47]
	v_mfma_f32_16x16x32_bf16 v[32:35], v[156:159], v[204:207], v[32:35]
	v_mfma_f32_16x16x32_bf16 v[24:27], v[164:167], v[204:207], v[24:27]
	v_mfma_f32_16x16x32_bf16 v[20:23], v[156:159], v[212:215], v[20:23]
	v_mfma_f32_16x16x32_bf16 v[12:15], v[164:167], v[212:215], v[12:15]
	s_setprio 0
	s_setprio 1
	v_mfma_f32_16x16x32_bf16 v[48:51], v[168:171], v[184:187], v[48:51]
	v_mfma_f32_16x16x32_bf16 v[40:43], v[176:179], v[184:187], v[40:43]
	v_mfma_f32_16x16x32_bf16 v[36:39], v[168:171], v[192:195], v[36:39]
	v_mfma_f32_16x16x32_bf16 v[28:31], v[176:179], v[192:195], v[28:31]
	v_mfma_f32_16x16x32_bf16 v[16:19], v[168:171], v[200:203], v[16:19]
	v_mfma_f32_16x16x32_bf16 v[8:11], v[176:179], v[200:203], v[8:11]
	v_mfma_f32_16x16x32_bf16 v[4:7], v[168:171], v[208:211], v[4:7]
	v_mfma_f32_16x16x32_bf16 v[0:3], v[176:179], v[208:211], v[0:3]
	v_mfma_f32_16x16x32_bf16 v[48:51], v[172:175], v[188:191], v[48:51]
	v_mfma_f32_16x16x32_bf16 v[40:43], v[180:183], v[188:191], v[40:43]
	v_mfma_f32_16x16x32_bf16 v[36:39], v[172:175], v[196:199], v[36:39]
	v_mfma_f32_16x16x32_bf16 v[28:31], v[180:183], v[196:199], v[28:31]
	v_mfma_f32_16x16x32_bf16 v[16:19], v[172:175], v[204:207], v[16:19]
	v_mfma_f32_16x16x32_bf16 v[8:11], v[180:183], v[204:207], v[8:11]
	v_mfma_f32_16x16x32_bf16 v[4:7], v[172:175], v[212:215], v[4:7]
	v_mfma_f32_16x16x32_bf16 v[0:3], v[180:183], v[212:215], v[0:3]
	s_setprio 0
	s_barrier
	s_add_i32 s76, s76, 2
	s_add_u32 s42, s42, 0x100
	s_addc_u32 s43, s43, 0
	s_add_u32 s74, s74, 0x100
	s_addc_u32 s75, s75, 0
	s_cmp_gt_u32 s76, 29
	s_cbranch_scc0 .LBB0_1402
.Lpeel_exit_7:
	s_and_b64 vcc, exec, s[28:29]
	s_cbranch_vccz .LBB0_1405
	s_barrier
.LBB0_1405:
	s_cmp_eq_u32 s40, s33
	s_cselect_b32 s31, s67, 0x300
	s_cmp_lg_u32 s40, s11
	s_cselect_b32 s31, s31, 0x100
	s_cmp_lg_u32 s40, s10
	s_cselect_b32 s31, s31, 0
	v_lshl_add_u32 v163, s31, 2, v151
	ds_read2_b32 v[156:157], v163 offset1:16
	v_lshl_or_b32 v146, s71, 8, v152
	v_lshl_add_u32 v162, s40, 8, v149
	v_ashrrev_i32_e32 v147, 31, v146
	v_mov_b64_e32 v[144:145], s[16:17]
	v_mad_i64_i32 v[158:159], s[42:43], v162, s68, v[144:145]
	v_lshlrev_b64 v[146:147], 1, v[146:147]
	s_waitcnt lgkmcnt(0)
	v_pk_mul_f32 v[126:127], v[126:127], v[156:157] op_sel_hi:[1,0]
	v_pk_mul_f32 v[124:125], v[124:125], v[156:157] op_sel_hi:[1,0]
	v_pk_mul_f32 v[160:161], v[122:123], v[156:157] op_sel_hi:[1,0]
	v_pk_mul_f32 v[122:123], v[120:121], v[156:157] op_sel_hi:[1,0]
	v_lshl_add_u64 v[158:159], v[158:159], 0, v[146:147]
	v_cvt_pk_bf16_f32 v120, v124, v125
	v_cvt_pk_bf16_f32 v121, v126, v127
	v_cvt_pk_bf16_f32 v122, v122, v123
	v_cvt_pk_bf16_f32 v123, v160, v161
	global_store_dwordx4 v[158:159], v[120:123], off
	v_pk_mul_f32 v[114:115], v[114:115], v[156:157] op_sel_hi:[1,0]
	v_pk_mul_f32 v[112:113], v[112:113], v[156:157] op_sel_hi:[1,0]
	v_pk_mul_f32 v[120:121], v[106:107], v[156:157] op_sel_hi:[1,0]
	v_pk_mul_f32 v[106:107], v[104:105], v[156:157] op_sel_hi:[1,0]
	v_cvt_pk_bf16_f32 v104, v112, v113
	v_cvt_pk_bf16_f32 v105, v114, v115
	v_cvt_pk_bf16_f32 v106, v106, v107
	v_cvt_pk_bf16_f32 v107, v120, v121
	global_store_dwordx4 v[158:159], v[104:107], off offset:256
	v_mov_b32_e32 v114, v157
	v_pk_mul_f32 v[110:111], v[110:111], v[114:115] op_sel_hi:[1,0]
	v_or_b32_e32 v104, 16, v162
	v_mad_i64_i32 v[104:105], s[42:43], v104, s68, v[144:145]
	v_lshl_add_u64 v[112:113], v[104:105], 0, v[146:147]
	v_pk_mul_f32 v[106:107], v[118:119], v[114:115] op_sel_hi:[1,0]
	v_pk_mul_f32 v[104:105], v[116:117], v[114:115] op_sel_hi:[1,0]
	v_pk_mul_f32 v[108:109], v[108:109], v[114:115] op_sel_hi:[1,0]
	v_cvt_pk_bf16_f32 v104, v104, v105
	v_cvt_pk_bf16_f32 v105, v106, v107
	v_cvt_pk_bf16_f32 v106, v108, v109
	v_cvt_pk_bf16_f32 v107, v110, v111
	global_store_dwordx4 v[112:113], v[104:107], off
	v_pk_mul_f32 v[102:103], v[102:103], v[114:115] op_sel_hi:[1,0]
	v_pk_mul_f32 v[100:101], v[100:101], v[114:115] op_sel_hi:[1,0]
	v_pk_mul_f32 v[104:105], v[94:95], v[114:115] op_sel_hi:[1,0]
	v_pk_mul_f32 v[94:95], v[92:93], v[114:115] op_sel_hi:[1,0]
	v_cvt_pk_bf16_f32 v92, v100, v101
	v_cvt_pk_bf16_f32 v93, v102, v103
	v_cvt_pk_bf16_f32 v94, v94, v95
	v_cvt_pk_bf16_f32 v95, v104, v105
	global_store_dwordx4 v[112:113], v[92:95], off offset:256
	ds_read2_b32 v[92:93], v163 offset0:32 offset1:48
	s_andn2_b64 vcc, exec, s[12:13]
	v_or_b32_e32 v94, 32, v162
	v_mad_i64_i32 v[94:95], s[42:43], v94, s68, v[144:145]
	s_waitcnt lgkmcnt(0)
; #define PG8_LAS __attribute__((address_space(3)))
; __device__ __forceinline__ unsigned cvt_pk_bf16(float lo, float hi) { f32x2_cv v = {lo, hi}; bf16x2_cv b = __builtin_convertvector(v, bf16x2_cv); return __builtin_bit_cast(unsigned, b); }
; __device__ __forceinline__ float sigmoidf_(float x) { return __builtin_amdgcn_rcpf(1.0f + __expf(-x)); }
;     __device__ __forceinline__ void operator()(const f32x4 (&acc)[2][2][4][2], const Unit& u, int wr, int wc, int fr, int fq) const {
;         const int row0 = u.pm * BM + wr * 64 + fr; const int col0 = u.pn * BM + wc * 32 + 8 * fq;
;         const PG8_LAS float* rt = rtab + (u.pm == pm0 ? 0 : u.pm == pm1 ? 256 : u.pm == pm2 ? 512 : 768) + wr * 64 + fr;
; #pragma unroll
;         for (int ai = 0; ai < 2; ++ai)
; #pragma unroll
;             for (int m = 0; m < 4; ++m) { bf16_t* rowp = O + (size_t)(row0 + ai * HALF + m * 16) * ldc + col0; const float rs = rt[ai * HALF + m * 16];
; #pragma unroll
;                 for (int bj = 0; bj < 2; ++bj) { f32x4 v0 = acc[ai][bj][m][0] * rs, v1 = acc[ai][bj][m][1] * rs;
;                     if (ACT == 2) {
; #pragma unroll
;                         for (int i = 0; i < 4; ++i) { v0[i] = sigmoidf_(v0[i]); v1[i] = sigmoidf_(v1[i]); } }
;                     u32x4 w; w.x = cvt_pk_bf16(v0[0], v0[1]); w.y = cvt_pk_bf16(v0[2], v0[3]); w.z = cvt_pk_bf16(v1[0], v1[1]); w.w = cvt_pk_bf16(v1[2], v1[3]);
;                     *(u32x4*)(rowp + bj * HALF) = w; } }
	v_pk_mul_f32 v[98:99], v[98:99], v[92:93] op_sel_hi:[1,0]
	v_pk_mul_f32 v[96:97], v[96:97], v[92:93] op_sel_hi:[1,0]
	v_pk_mul_f32 v[100:101], v[90:91], v[92:93] op_sel_hi:[1,0]
	v_pk_mul_f32 v[90:91], v[88:89], v[92:93] op_sel_hi:[1,0]
	v_lshl_add_u64 v[94:95], v[94:95], 0, v[146:147]
	v_cvt_pk_bf16_f32 v88, v96, v97
	v_cvt_pk_bf16_f32 v89, v98, v99
	v_cvt_pk_bf16_f32 v90, v90, v91
	v_cvt_pk_bf16_f32 v91, v100, v101
	global_store_dwordx4 v[94:95], v[88:91], off
	v_pk_mul_f32 v[82:83], v[82:83], v[92:93] op_sel_hi:[1,0]
	v_pk_mul_f32 v[80:81], v[80:81], v[92:93] op_sel_hi:[1,0]
	v_pk_mul_f32 v[88:89], v[74:75], v[92:93] op_sel_hi:[1,0]
	v_pk_mul_f32 v[74:75], v[72:73], v[92:93] op_sel_hi:[1,0]
	v_cvt_pk_bf16_f32 v72, v80, v81
	v_cvt_pk_bf16_f32 v73, v82, v83
	v_cvt_pk_bf16_f32 v74, v74, v75
	v_cvt_pk_bf16_f32 v75, v88, v89
	global_store_dwordx4 v[94:95], v[72:75], off offset:256
	v_mov_b32_e32 v82, v93
	v_pk_mul_f32 v[78:79], v[78:79], v[82:83] op_sel_hi:[1,0]
	v_or_b32_e32 v72, 48, v162
	v_mad_i64_i32 v[72:73], s[42:43], v72, s68, v[144:145]
	v_lshl_add_u64 v[80:81], v[72:73], 0, v[146:147]
	v_pk_mul_f32 v[74:75], v[86:87], v[82:83] op_sel_hi:[1,0]
	v_pk_mul_f32 v[72:73], v[84:85], v[82:83] op_sel_hi:[1,0]
	v_pk_mul_f32 v[76:77], v[76:77], v[82:83] op_sel_hi:[1,0]
	v_cvt_pk_bf16_f32 v72, v72, v73
	v_cvt_pk_bf16_f32 v73, v74, v75
	v_cvt_pk_bf16_f32 v74, v76, v77
	v_cvt_pk_bf16_f32 v75, v78, v79
	global_store_dwordx4 v[80:81], v[72:75], off
	v_pk_mul_f32 v[70:71], v[70:71], v[82:83] op_sel_hi:[1,0]
	v_pk_mul_f32 v[68:69], v[68:69], v[82:83] op_sel_hi:[1,0]
	v_pk_mul_f32 v[72:73], v[66:67], v[82:83] op_sel_hi:[1,0]
	v_pk_mul_f32 v[66:67], v[64:65], v[82:83] op_sel_hi:[1,0]
	v_cvt_pk_bf16_f32 v64, v68, v69
	v_cvt_pk_bf16_f32 v65, v70, v71
	v_cvt_pk_bf16_f32 v66, v66, v67
	v_cvt_pk_bf16_f32 v67, v72, v73
	global_store_dwordx4 v[80:81], v[64:67], off offset:256
	ds_read2_b32 v[64:65], v163 offset0:128 offset1:144
	s_mov_b64 s[12:13], -1
	v_add_u32_e32 v66, 0x80, v162
	v_mad_i64_i32 v[66:67], s[42:43], v66, s68, v[144:145]
	s_waitcnt lgkmcnt(0)
	v_pk_mul_f32 v[62:63], v[62:63], v[64:65] op_sel_hi:[1,0]
	v_pk_mul_f32 v[60:61], v[60:61], v[64:65] op_sel_hi:[1,0]
	v_pk_mul_f32 v[68:69], v[58:59], v[64:65] op_sel_hi:[1,0]
	v_pk_mul_f32 v[58:59], v[56:57], v[64:65] op_sel_hi:[1,0]
	v_lshl_add_u64 v[66:67], v[66:67], 0, v[146:147]
	v_cvt_pk_bf16_f32 v56, v60, v61
	v_cvt_pk_bf16_f32 v57, v62, v63
	v_cvt_pk_bf16_f32 v58, v58, v59
	v_cvt_pk_bf16_f32 v59, v68, v69
	global_store_dwordx4 v[66:67], v[56:59], off
	v_pk_mul_f32 v[50:51], v[50:51], v[64:65] op_sel_hi:[1,0]
	v_pk_mul_f32 v[48:49], v[48:49], v[64:65] op_sel_hi:[1,0]
	v_pk_mul_f32 v[56:57], v[42:43], v[64:65] op_sel_hi:[1,0]
	v_pk_mul_f32 v[42:43], v[40:41], v[64:65] op_sel_hi:[1,0]
	v_cvt_pk_bf16_f32 v40, v48, v49
	v_cvt_pk_bf16_f32 v41, v50, v51
	v_cvt_pk_bf16_f32 v42, v42, v43
	v_cvt_pk_bf16_f32 v43, v56, v57
	global_store_dwordx4 v[66:67], v[40:43], off offset:256
	v_mov_b32_e32 v50, v65
	v_pk_mul_f32 v[46:47], v[46:47], v[50:51] op_sel_hi:[1,0]
	v_add_u32_e32 v40, 0x90, v162
	v_mad_i64_i32 v[40:41], s[42:43], v40, s68, v[144:145]
	v_lshl_add_u64 v[48:49], v[40:41], 0, v[146:147]
	v_pk_mul_f32 v[42:43], v[54:55], v[50:51] op_sel_hi:[1,0]
	v_pk_mul_f32 v[40:41], v[52:53], v[50:51] op_sel_hi:[1,0]
	v_pk_mul_f32 v[44:45], v[44:45], v[50:51] op_sel_hi:[1,0]
	v_cvt_pk_bf16_f32 v40, v40, v41
	v_cvt_pk_bf16_f32 v41, v42, v43
	v_cvt_pk_bf16_f32 v42, v44, v45
	v_cvt_pk_bf16_f32 v43, v46, v47
	global_store_dwordx4 v[48:49], v[40:43], off
	v_pk_mul_f32 v[38:39], v[38:39], v[50:51] op_sel_hi:[1,0]
	v_pk_mul_f32 v[36:37], v[36:37], v[50:51] op_sel_hi:[1,0]
	v_pk_mul_f32 v[40:41], v[30:31], v[50:51] op_sel_hi:[1,0]
	v_pk_mul_f32 v[30:31], v[28:29], v[50:51] op_sel_hi:[1,0]
	v_cvt_pk_bf16_f32 v28, v36, v37
	v_cvt_pk_bf16_f32 v29, v38, v39
	v_cvt_pk_bf16_f32 v30, v30, v31
	v_cvt_pk_bf16_f32 v31, v40, v41
	global_store_dwordx4 v[48:49], v[28:31], off offset:256
	ds_read2_b32 v[28:29], v163 offset0:160 offset1:176
	s_waitcnt lgkmcnt(0)
	v_pk_mul_f32 v[34:35], v[34:35], v[28:29] op_sel_hi:[1,0]
	v_add_u32_e32 v30, 0xa0, v162
	v_mad_i64_i32 v[30:31], s[42:43], v30, s68, v[144:145]
	v_pk_mul_f32 v[32:33], v[32:33], v[28:29] op_sel_hi:[1,0]
	v_pk_mul_f32 v[36:37], v[26:27], v[28:29] op_sel_hi:[1,0]
	v_pk_mul_f32 v[26:27], v[24:25], v[28:29] op_sel_hi:[1,0]
	v_lshl_add_u64 v[30:31], v[30:31], 0, v[146:147]
	v_cvt_pk_bf16_f32 v24, v32, v33
	v_cvt_pk_bf16_f32 v25, v34, v35
	v_cvt_pk_bf16_f32 v26, v26, v27
	v_cvt_pk_bf16_f32 v27, v36, v37
	global_store_dwordx4 v[30:31], v[24:27], off
	v_pk_mul_f32 v[18:19], v[18:19], v[28:29] op_sel_hi:[1,0]
	v_pk_mul_f32 v[16:17], v[16:17], v[28:29] op_sel_hi:[1,0]
	v_pk_mul_f32 v[24:25], v[10:11], v[28:29] op_sel_hi:[1,0]
	v_pk_mul_f32 v[10:11], v[8:9], v[28:29] op_sel_hi:[1,0]
	v_cvt_pk_bf16_f32 v8, v16, v17
	v_cvt_pk_bf16_f32 v9, v18, v19
	v_cvt_pk_bf16_f32 v10, v10, v11
	v_cvt_pk_bf16_f32 v11, v24, v25
	global_store_dwordx4 v[30:31], v[8:11], off offset:256
	v_mov_b32_e32 v18, v29
	v_pk_mul_f32 v[14:15], v[14:15], v[18:19] op_sel_hi:[1,0]
	v_add_u32_e32 v8, 0xb0, v162
	v_mad_i64_i32 v[8:9], s[42:43], v8, s68, v[144:145]
	v_lshl_add_u64 v[16:17], v[8:9], 0, v[146:147]
	v_pk_mul_f32 v[10:11], v[22:23], v[18:19] op_sel_hi:[1,0]
	v_pk_mul_f32 v[8:9], v[20:21], v[18:19] op_sel_hi:[1,0]
	v_pk_mul_f32 v[12:13], v[12:13], v[18:19] op_sel_hi:[1,0]
	v_cvt_pk_bf16_f32 v8, v8, v9
	v_cvt_pk_bf16_f32 v9, v10, v11
	v_cvt_pk_bf16_f32 v10, v12, v13
	v_cvt_pk_bf16_f32 v11, v14, v15
	global_store_dwordx4 v[16:17], v[8:11], off
	v_pk_mul_f32 v[6:7], v[6:7], v[18:19] op_sel_hi:[1,0]
	v_pk_mul_f32 v[4:5], v[4:5], v[18:19] op_sel_hi:[1,0]
	v_pk_mul_f32 v[8:9], v[2:3], v[18:19] op_sel_hi:[1,0]
	v_pk_mul_f32 v[2:3], v[0:1], v[18:19] op_sel_hi:[1,0]
	v_cvt_pk_bf16_f32 v0, v4, v5
	v_cvt_pk_bf16_f32 v1, v6, v7
	v_cvt_pk_bf16_f32 v2, v2, v3
	v_cvt_pk_bf16_f32 v3, v8, v9
	global_store_dwordx4 v[16:17], v[0:3], off offset:256
	s_cbranch_vccnz .LBB0_1398
	s_andn2_b64 vcc, exec, s[24:25]
	s_cbranch_vccnz .LBB0_1397
	s_barrier
	s_branch .LBB0_1397

; #define PG8_STAGE(bufoff, gbase, voff) do { _Pragma("unroll") for (int _i = 0; _i < 2; ++_i) \
;         __builtin_amdgcn_global_load_lds((const unsigned*)((const char*)(gbase) + (voff)[_i]), (PG8_LAS unsigned*)(lds + (bufoff) + ldsw + _i * 8192), 16, 0, 0); } while (0)
; #define PG8_LDA(dst, b, h) do { _Pragma("unroll") for (int m = 0; m < 4; ++m) _Pragma("unroll") for (int k = 0; k < 2; ++k) dst[m][k] = *(const PG8_LAS bf16x8*)(lds + PG8_SA(b, h) + aoff + m * 2048 + k * 1024); } while (0)
; #define PG8_LDB(dst, b, h) do { _Pragma("unroll") for (int n = 0; n < 2; ++n) _Pragma("unroll") for (int k = 0; k < 2; ++k) dst[n][k] = *(const PG8_LAS bf16x8*)(lds + PG8_SB(b, h) + boff + n * 2048 + k * 1024); } while (0)
; #define PG8_MMA(ai, bj, At, Bt) do { __builtin_amdgcn_s_setprio(1); _Pragma("unroll") for (int m = 0; m < 4; ++m) _Pragma("unroll") for (int n = 0; n < 2; ++n) _Pragma("unroll") for (int k = 0; k < 2; ++k) \
;         acc[ai][bj][m][n] = __builtin_amdgcn_mfma_f32_16x16x32_bf16(Bt[n][k], At[m][k], acc[ai][bj][m][n], 0, 0, 0); __builtin_amdgcn_s_setprio(0); } while (0)
; #define PG8_BAR __builtin_amdgcn_s_barrier()
; template <class Epi, class Sched, bool ALIGN_EPI = false, bool SP2 = false>
; __device__ __forceinline__ void gemm_phase(PG8_LAS unsigned char* lds, const Gemm g, const Sched& S, const Epi& E) {
;     ...
;         const bool has_next = S.next(ui + 1, nxt);
;         const char* nA = has_next ? (const char*)g.A + (size_t)nxt.pm * tstep : cA; const char* nB = has_next ? (const char*)g.Bt + (size_t)nxt.pn * tstep : cB;
;         for (int t = 0; t < nt; t += 2) {
;             const bool last = (t == nt - 2);
;             const char* a1 = cA + (size_t)(t + 1) * kstep;
;             const char* a2 = last ? nA : cA + (size_t)(t + 2) * kstep; const char* b2 = last ? nB : cB + (size_t)(t + 2) * kstep;
;             const char* a3 = a2 + kstep; const char* b3 = b2 + kstep;
;             if (last && has_next) S.a_ready(nxt);
;             if constexpr (SP2) {
;             PG8_LDB(B0, 0, 0); PG8_LDB(B1, 0, 1); PG8_SCHED; PG8_LDA(At, 0, 0); PG8_STAGE(PG8_SA(1, 1), a1 + hstep, voffA);
;             PG8_WAIT_V(8); PG8_WAIT_L(0); PG8_BAR; PG8_MMA(0, 0, At, B0); PG8_MMA(0, 1, At, B1); PG8_BAR; PG8_SCHED;
;             PG8_LDA(At, 0, 1); PG8_STAGE(PG8_SB(0, 0), b2, voffB); PG8_STAGE(PG8_SB(0, 1), b2 + hstep, voffB); PG8_STAGE(PG8_SA(0, 0), a2, voffA);
.LBB0_1971:
	s_ashr_i32 s29, s28, 31
	s_lshl_b64 s[30:31], s[28:29], 20
	s_add_u32 s30, s10, s30
	s_addc_u32 s31, s11, s31
	s_and_b64 s[34:35], s[12:13], exec
	s_cselect_b32 s14, s31, s41
	s_cselect_b32 s29, s30, s40
	s_ashr_i32 s27, s26, 31
	s_lshl_b64 s[34:35], s[26:27], 20
	s_add_u32 s34, s33, s34
	s_addc_u32 s35, s50, s35
	s_and_b64 s[48:49], s[12:13], exec
	s_cselect_b32 s27, s35, s43
	s_cselect_b32 s37, s34, s42
	s_add_u32 s40, s40, 0x80080
	s_addc_u32 s41, s41, 0
	s_add_u32 s39, s42, 0x100
	s_addc_u32 s62, s43, 0
	s_mov_b32 s63, -2
	s_waitcnt lgkmcnt(0)
	ds_read_b128 v[100:103], v225
	ds_read_b128 v[108:111], v225 offset:1024
	ds_read_b128 v[124:127], v225 offset:2048
	ds_read_b128 v[132:135], v225 offset:3072
	ds_read_b128 v[144:147], v226
	ds_read_b128 v[148:151], v226 offset:1024
	ds_read_b128 v[152:155], v226 offset:2048
	ds_read_b128 v[156:159], v226 offset:3072
	s_add_u32 s42, s40, 0xfff80080
	s_addc_u32 s43, s41, -1
	s_cmp_eq_u32 s63, 28
	s_cselect_b32 s49, s14, s43
	s_cselect_b32 s48, s29, s42
	s_cselect_b32 s43, s27, s62
	s_cselect_b32 s42, s37, s39
	v_lshl_add_u64 v[208:209], s[40:41], 0, v[192:193]
	s_add_i32 m0, s52, 0xc000
	ds_read_b128 v[160:163], v227
	ds_read_b128 v[164:167], v227 offset:1024
	ds_read_b128 v[168:171], v227 offset:2048
	ds_read_b128 v[172:175], v227 offset:3072
	ds_read_b128 v[176:179], v227 offset:4096
	ds_read_b128 v[180:183], v227 offset:5120
	ds_read_b128 v[200:203], v227 offset:6144
	ds_read_b128 v[204:207], v227 offset:7168
	global_load_lds_dwordx4 v[208:209], off
	v_lshl_add_u64 v[208:209], s[40:41], 0, v[194:195]
	s_add_i32 m0, s52, 0xe000
	s_nop 0
	global_load_lds_dwordx4 v[208:209], off
	s_waitcnt vmcnt(8)
	s_waitcnt lgkmcnt(0)
	s_barrier
	s_setprio 1
	s_waitcnt lgkmcnt(0)
	v_mfma_f32_16x16x32_bf16 v[140:143], v[100:103], v[160:163], 0
	v_mfma_f32_16x16x32_bf16 v[136:139], v[124:127], v[160:163], 0
	v_mfma_f32_16x16x32_bf16 v[116:119], v[100:103], v[168:171], 0
	v_mfma_f32_16x16x32_bf16 v[112:115], v[124:127], v[168:171], 0
	v_mfma_f32_16x16x32_bf16 v[92:95], v[100:103], v[176:179], 0
	v_mfma_f32_16x16x32_bf16 v[88:91], v[124:127], v[176:179], 0
	v_mfma_f32_16x16x32_bf16 v[76:79], v[100:103], v[200:203], 0
	v_mfma_f32_16x16x32_bf16 v[72:75], v[124:127], v[200:203], 0
	v_mfma_f32_16x16x32_bf16 v[140:143], v[108:111], v[164:167], v[140:143]
	v_mfma_f32_16x16x32_bf16 v[136:139], v[132:135], v[164:167], v[136:139]
	v_mfma_f32_16x16x32_bf16 v[116:119], v[108:111], v[172:175], v[116:119]
	v_mfma_f32_16x16x32_bf16 v[112:115], v[132:135], v[172:175], v[112:115]
	v_mfma_f32_16x16x32_bf16 v[92:95], v[108:111], v[180:183], v[92:95]
	v_mfma_f32_16x16x32_bf16 v[88:91], v[132:135], v[180:183], v[88:91]
	v_mfma_f32_16x16x32_bf16 v[76:79], v[108:111], v[204:207], v[76:79]
	v_mfma_f32_16x16x32_bf16 v[72:75], v[132:135], v[204:207], v[72:75]
	s_setprio 0
	s_setprio 1
	v_mfma_f32_16x16x32_bf16 v[128:131], v[144:147], v[160:163], 0
	v_mfma_f32_16x16x32_bf16 v[120:123], v[152:155], v[160:163], 0
	v_mfma_f32_16x16x32_bf16 v[104:107], v[144:147], v[168:171], 0
	v_mfma_f32_16x16x32_bf16 v[96:99], v[152:155], v[168:171], 0
	v_mfma_f32_16x16x32_bf16 v[84:87], v[144:147], v[176:179], 0
	v_mfma_f32_16x16x32_bf16 v[80:83], v[152:155], v[176:179], 0
	v_mfma_f32_16x16x32_bf16 v[68:71], v[144:147], v[200:203], 0
	v_mfma_f32_16x16x32_bf16 v[64:67], v[152:155], v[200:203], 0
	v_mfma_f32_16x16x32_bf16 v[128:131], v[148:151], v[164:167], v[128:131]
	v_mfma_f32_16x16x32_bf16 v[120:123], v[156:159], v[164:167], v[120:123]
	v_mfma_f32_16x16x32_bf16 v[104:107], v[148:151], v[172:175], v[104:107]
	v_mfma_f32_16x16x32_bf16 v[96:99], v[156:159], v[172:175], v[96:99]
	v_mfma_f32_16x16x32_bf16 v[84:87], v[148:151], v[180:183], v[84:87]
	v_mfma_f32_16x16x32_bf16 v[80:83], v[156:159], v[180:183], v[80:83]
	v_mfma_f32_16x16x32_bf16 v[68:71], v[148:151], v[204:207], v[68:71]
	v_mfma_f32_16x16x32_bf16 v[64:67], v[156:159], v[204:207], v[64:67]
	s_setprio 0
	s_barrier
	s_add_i32 s64, s59, s51
	v_lshl_add_u64 v[208:209], s[42:43], 0, v[186:187]
	s_mov_b32 m0, s64
	ds_read_b128 v[160:163], v227 offset:16384
	ds_read_b128 v[164:167], v227 offset:17408
	ds_read_b128 v[168:171], v227 offset:18432
	ds_read_b128 v[172:175], v227 offset:19456
	ds_read_b128 v[176:179], v227 offset:20480
	ds_read_b128 v[180:183], v227 offset:21504
	ds_read_b128 v[200:203], v227 offset:22528
	ds_read_b128 v[204:207], v227 offset:23552
	global_load_lds_dwordx4 v[208:209], off
	s_add_i32 m0, s64, 0x2000
	s_add_u32 s64, s42, 0x80000
	v_lshl_add_u64 v[210:211], s[42:43], 0, v[190:191]
	s_addc_u32 s65, s43, 0
	s_add_i32 s66, s60, s51
	global_load_lds_dwordx4 v[210:211], off
	v_lshl_add_u64 v[212:213], s[64:65], 0, v[186:187]
	s_mov_b32 m0, s66
	v_lshl_add_u64 v[214:215], s[48:49], 0, v[188:189]
	global_load_lds_dwordx4 v[212:213], off
	v_lshl_add_u64 v[212:213], s[64:65], 0, v[190:191]
	s_add_i32 m0, s66, 0x2000
	s_nop 0
	global_load_lds_dwordx4 v[212:213], off
	v_lshl_add_u64 v[212:213], s[48:49], 0, v[184:185]
	s_mov_b32 m0, s52
	s_nop 0
	global_load_lds_dwordx4 v[212:213], off
	s_mov_b32 m0, s53
	s_nop 0
	global_load_lds_dwordx4 v[214:215], off
	s_waitcnt vmcnt(8)
	s_waitcnt lgkmcnt(0)
	s_barrier
; #define PG8_STAGE(bufoff, gbase, voff) do { _Pragma("unroll") for (int _i = 0; _i < 2; ++_i) \
;         __builtin_amdgcn_global_load_lds((const unsigned*)((const char*)(gbase) + (voff)[_i]), (PG8_LAS unsigned*)(lds + (bufoff) + ldsw + _i * 8192), 16, 0, 0); } while (0)
; #define PG8_LDA(dst, b, h) do { _Pragma("unroll") for (int m = 0; m < 4; ++m) _Pragma("unroll") for (int k = 0; k < 2; ++k) dst[m][k] = *(const PG8_LAS bf16x8*)(lds + PG8_SA(b, h) + aoff + m * 2048 + k * 1024); } while (0)
; #define PG8_LDB(dst, b, h) do { _Pragma("unroll") for (int n = 0; n < 2; ++n) _Pragma("unroll") for (int k = 0; k < 2; ++k) dst[n][k] = *(const PG8_LAS bf16x8*)(lds + PG8_SB(b, h) + boff + n * 2048 + k * 1024); } while (0)
; #define PG8_MMA(ai, bj, At, Bt) do { __builtin_amdgcn_s_setprio(1); _Pragma("unroll") for (int m = 0; m < 4; ++m) _Pragma("unroll") for (int n = 0; n < 2; ++n) _Pragma("unroll") for (int k = 0; k < 2; ++k) \
;         acc[ai][bj][m][n] = __builtin_amdgcn_mfma_f32_16x16x32_bf16(Bt[n][k], At[m][k], acc[ai][bj][m][n], 0, 0, 0); __builtin_amdgcn_s_setprio(0); } while (0)
; #define PG8_WAIT_V(n) asm volatile("s_waitcnt vmcnt(" #n ")" ::: "memory")
; #define PG8_WAIT_L(n) asm volatile("s_waitcnt lgkmcnt(" #n ")" ::: "memory")
; #define PG8_BAR __builtin_amdgcn_s_barrier()
; #define PG8_SCHED __builtin_amdgcn_sched_barrier(0)
; template <class Epi, class Sched, bool ALIGN_EPI = false, bool SP2 = false>
; __device__ __forceinline__ void gemm_phase(PG8_LAS unsigned char* lds, const Gemm g, const Sched& S, const Epi& E) {
;     ...
;             PG8_WAIT_V(8); PG8_WAIT_L(0); PG8_BAR; PG8_MMA(1, 0, At, B0); PG8_MMA(1, 1, At, B1); PG8_BAR; PG8_SCHED;
;             PG8_LDB(B0, 1, 0); PG8_LDB(B1, 1, 1); PG8_SCHED; PG8_LDA(At, 1, 0); PG8_STAGE(PG8_SA(0, 1), a2 + hstep, voffA);
;             PG8_WAIT_V(8); PG8_WAIT_L(0); PG8_BAR; PG8_MMA(0, 0, At, B0); PG8_MMA(0, 1, At, B1); PG8_BAR; PG8_SCHED;
	s_setprio 1
	s_waitcnt lgkmcnt(0)
	v_mfma_f32_16x16x32_bf16 v[60:63], v[100:103], v[160:163], 0
	v_mfma_f32_16x16x32_bf16 v[56:59], v[124:127], v[160:163], 0
	v_mfma_f32_16x16x32_bf16 v[44:47], v[100:103], v[168:171], 0
	v_mfma_f32_16x16x32_bf16 v[40:43], v[124:127], v[168:171], 0
	v_mfma_f32_16x16x32_bf16 v[28:31], v[100:103], v[176:179], 0
	v_mfma_f32_16x16x32_bf16 v[24:27], v[124:127], v[176:179], 0
	v_mfma_f32_16x16x32_bf16 v[12:15], v[100:103], v[200:203], 0
	v_mfma_f32_16x16x32_bf16 v[8:11], v[124:127], v[200:203], 0
	v_mfma_f32_16x16x32_bf16 v[60:63], v[108:111], v[164:167], v[60:63]
	v_mfma_f32_16x16x32_bf16 v[56:59], v[132:135], v[164:167], v[56:59]
	v_mfma_f32_16x16x32_bf16 v[44:47], v[108:111], v[172:175], v[44:47]
	v_mfma_f32_16x16x32_bf16 v[40:43], v[132:135], v[172:175], v[40:43]
	v_mfma_f32_16x16x32_bf16 v[28:31], v[108:111], v[180:183], v[28:31]
	v_mfma_f32_16x16x32_bf16 v[24:27], v[132:135], v[180:183], v[24:27]
	v_mfma_f32_16x16x32_bf16 v[12:15], v[108:111], v[204:207], v[12:15]
	v_mfma_f32_16x16x32_bf16 v[8:11], v[132:135], v[204:207], v[8:11]
	s_setprio 0
	s_setprio 1
	v_mfma_f32_16x16x32_bf16 v[52:55], v[144:147], v[160:163], 0
	v_mfma_f32_16x16x32_bf16 v[48:51], v[152:155], v[160:163], 0
	v_mfma_f32_16x16x32_bf16 v[36:39], v[144:147], v[168:171], 0
	v_mfma_f32_16x16x32_bf16 v[32:35], v[152:155], v[168:171], 0
	v_mfma_f32_16x16x32_bf16 v[20:23], v[144:147], v[176:179], 0
	v_mfma_f32_16x16x32_bf16 v[16:19], v[152:155], v[176:179], 0
	v_mfma_f32_16x16x32_bf16 v[4:7], v[144:147], v[200:203], 0
	v_mfma_f32_16x16x32_bf16 v[0:3], v[152:155], v[200:203], 0
	v_mfma_f32_16x16x32_bf16 v[52:55], v[148:151], v[164:167], v[52:55]
	v_mfma_f32_16x16x32_bf16 v[48:51], v[156:159], v[164:167], v[48:51]
	v_mfma_f32_16x16x32_bf16 v[36:39], v[148:151], v[172:175], v[36:39]
	v_mfma_f32_16x16x32_bf16 v[32:35], v[156:159], v[172:175], v[32:35]
	v_mfma_f32_16x16x32_bf16 v[20:23], v[148:151], v[180:183], v[20:23]
	v_mfma_f32_16x16x32_bf16 v[16:19], v[156:159], v[180:183], v[16:19]
	v_mfma_f32_16x16x32_bf16 v[4:7], v[148:151], v[204:207], v[4:7]
	v_mfma_f32_16x16x32_bf16 v[0:3], v[156:159], v[204:207], v[0:3]
	s_setprio 0
	s_barrier
	s_add_i32 s64, 0, 0x18000
	s_add_i32 s65, 0, 0x1c000
	v_add_u32_e32 v132, s64, v223
	v_add_u32_e32 v156, s65, v223
	ds_read_b128 v[100:103], v132
	ds_read_b128 v[108:111], v132 offset:1024
	ds_read_b128 v[124:127], v132 offset:2048
	ds_read_b128 v[132:135], v132 offset:3072
	ds_read_b128 v[144:147], v156
	ds_read_b128 v[148:151], v156 offset:1024
	ds_read_b128 v[152:155], v156 offset:2048
	ds_read_b128 v[156:159], v156 offset:3072
	s_add_u32 s48, s48, 0x80000
	s_addc_u32 s49, s49, 0
	s_mov_b32 m0, s54
	v_lshl_add_u64 v[216:217], s[48:49], 0, v[184:185]
	ds_read_b128 v[160:163], v227 offset:32768
	ds_read_b128 v[164:167], v227 offset:33792
	ds_read_b128 v[168:171], v227 offset:34816
	ds_read_b128 v[172:175], v227 offset:35840
	ds_read_b128 v[176:179], v227 offset:36864
	ds_read_b128 v[180:183], v227 offset:37888
	ds_read_b128 v[200:203], v227 offset:38912
	ds_read_b128 v[204:207], v227 offset:39936
	global_load_lds_dwordx4 v[216:217], off
	v_lshl_add_u64 v[216:217], s[48:49], 0, v[188:189]
	s_mov_b32 m0, s55
	s_nop 0
	global_load_lds_dwordx4 v[216:217], off
	s_waitcnt vmcnt(8)
	s_waitcnt lgkmcnt(0)
	s_barrier
	s_setprio 1
	s_waitcnt lgkmcnt(0)
	v_mfma_f32_16x16x32_bf16 v[140:143], v[100:103], v[160:163], v[140:143]
	v_mfma_f32_16x16x32_bf16 v[136:139], v[124:127], v[160:163], v[136:139]
	v_mfma_f32_16x16x32_bf16 v[116:119], v[100:103], v[168:171], v[116:119]
	v_mfma_f32_16x16x32_bf16 v[112:115], v[124:127], v[168:171], v[112:115]
	v_mfma_f32_16x16x32_bf16 v[92:95], v[100:103], v[176:179], v[92:95]
	v_mfma_f32_16x16x32_bf16 v[88:91], v[124:127], v[176:179], v[88:91]
	v_mfma_f32_16x16x32_bf16 v[76:79], v[100:103], v[200:203], v[76:79]
	v_mfma_f32_16x16x32_bf16 v[72:75], v[124:127], v[200:203], v[72:75]
	v_mfma_f32_16x16x32_bf16 v[140:143], v[108:111], v[164:167], v[140:143]
	v_mfma_f32_16x16x32_bf16 v[136:139], v[132:135], v[164:167], v[136:139]
	v_mfma_f32_16x16x32_bf16 v[116:119], v[108:111], v[172:175], v[116:119]
	v_mfma_f32_16x16x32_bf16 v[112:115], v[132:135], v[172:175], v[112:115]
	v_mfma_f32_16x16x32_bf16 v[92:95], v[108:111], v[180:183], v[92:95]
	v_mfma_f32_16x16x32_bf16 v[88:91], v[132:135], v[180:183], v[88:91]
	v_mfma_f32_16x16x32_bf16 v[76:79], v[108:111], v[204:207], v[76:79]
	v_mfma_f32_16x16x32_bf16 v[72:75], v[132:135], v[204:207], v[72:75]
	s_setprio 0
	s_setprio 1
	v_mfma_f32_16x16x32_bf16 v[128:131], v[144:147], v[160:163], v[128:131]
	v_mfma_f32_16x16x32_bf16 v[120:123], v[152:155], v[160:163], v[120:123]
	v_mfma_f32_16x16x32_bf16 v[104:107], v[144:147], v[168:171], v[104:107]
	v_mfma_f32_16x16x32_bf16 v[96:99], v[152:155], v[168:171], v[96:99]
	v_mfma_f32_16x16x32_bf16 v[84:87], v[144:147], v[176:179], v[84:87]
	v_mfma_f32_16x16x32_bf16 v[80:83], v[152:155], v[176:179], v[80:83]
	v_mfma_f32_16x16x32_bf16 v[68:71], v[144:147], v[200:203], v[68:71]
	v_mfma_f32_16x16x32_bf16 v[64:67], v[152:155], v[200:203], v[64:67]
	v_mfma_f32_16x16x32_bf16 v[128:131], v[148:151], v[164:167], v[128:131]
	v_mfma_f32_16x16x32_bf16 v[120:123], v[156:159], v[164:167], v[120:123]
	v_mfma_f32_16x16x32_bf16 v[104:107], v[148:151], v[172:175], v[104:107]
	v_mfma_f32_16x16x32_bf16 v[96:99], v[156:159], v[172:175], v[96:99]
	v_mfma_f32_16x16x32_bf16 v[84:87], v[148:151], v[180:183], v[84:87]
	v_mfma_f32_16x16x32_bf16 v[80:83], v[156:159], v[180:183], v[80:83]
	v_mfma_f32_16x16x32_bf16 v[68:71], v[148:151], v[204:207], v[68:71]
	v_mfma_f32_16x16x32_bf16 v[64:67], v[156:159], v[204:207], v[64:67]
	s_setprio 0
	s_barrier
; #define PG8_STAGE(bufoff, gbase, voff) do { _Pragma("unroll") for (int _i = 0; _i < 2; ++_i) \
;         __builtin_amdgcn_global_load_lds((const unsigned*)((const char*)(gbase) + (voff)[_i]), (PG8_LAS unsigned*)(lds + (bufoff) + ldsw + _i * 8192), 16, 0, 0); } while (0)
; #define PG8_LDA(dst, b, h) do { _Pragma("unroll") for (int m = 0; m < 4; ++m) _Pragma("unroll") for (int k = 0; k < 2; ++k) dst[m][k] = *(const PG8_LAS bf16x8*)(lds + PG8_SA(b, h) + aoff + m * 2048 + k * 1024); } while (0)
; #define PG8_MMA(ai, bj, At, Bt) do { __builtin_amdgcn_s_setprio(1); _Pragma("unroll") for (int m = 0; m < 4; ++m) _Pragma("unroll") for (int n = 0; n < 2; ++n) _Pragma("unroll") for (int k = 0; k < 2; ++k) \
;         acc[ai][bj][m][n] = __builtin_amdgcn_mfma_f32_16x16x32_bf16(Bt[n][k], At[m][k], acc[ai][bj][m][n], 0, 0, 0); __builtin_amdgcn_s_setprio(0); } while (0)
; #define PG8_WAIT_V(n) asm volatile("s_waitcnt vmcnt(" #n ")" ::: "memory")
; #define PG8_WAIT_L(n) asm volatile("s_waitcnt lgkmcnt(" #n ")" ::: "memory")
; #define PG8_BAR __builtin_amdgcn_s_barrier()
; #define PG8_SCHED __builtin_amdgcn_sched_barrier(0)
; template <class Epi, class Sched, bool ALIGN_EPI = false, bool SP2 = false>
; __device__ __forceinline__ void gemm_phase(PG8_LAS unsigned char* lds, const Gemm g, const Sched& S, const Epi& E) {
;     ...
;         for (int t = 0; t < nt; t += 2) {
;     ...
;             PG8_LDA(At, 1, 1); PG8_STAGE(PG8_SB(1, 0), b3, voffB); PG8_STAGE(PG8_SB(1, 1), b3 + hstep, voffB); PG8_STAGE(PG8_SA(1, 0), a3, voffA);
;             PG8_WAIT_V(8); PG8_WAIT_L(0); PG8_BAR; PG8_MMA(1, 0, At, B0); PG8_MMA(1, 1, At, B1); PG8_BAR; PG8_SCHED;
	s_add_i32 s48, s64, s51
	v_lshl_add_u64 v[208:209], v[208:209], 0, s[22:23]
	s_mov_b32 m0, s48
	ds_read_b128 v[160:163], v227 offset:49152
	ds_read_b128 v[164:167], v227 offset:50176
	ds_read_b128 v[168:171], v227 offset:51200
	ds_read_b128 v[172:175], v227 offset:52224
	ds_read_b128 v[176:179], v227 offset:53248
	ds_read_b128 v[180:183], v227 offset:54272
	ds_read_b128 v[200:203], v227 offset:55296
	ds_read_b128 v[204:207], v227 offset:56320
	global_load_lds_dwordx4 v[208:209], off
	s_add_i32 m0, s48, 0x2000
	s_add_u32 s42, s42, 0x80080
	v_lshl_add_u64 v[208:209], v[210:211], 0, s[22:23]
	s_addc_u32 s43, s43, 0
	s_add_i32 s48, s65, s51
	global_load_lds_dwordx4 v[208:209], off
	v_lshl_add_u64 v[208:209], s[42:43], 0, v[186:187]
	s_mov_b32 m0, s48
	s_nop 0
	global_load_lds_dwordx4 v[208:209], off
	v_lshl_add_u64 v[208:209], s[42:43], 0, v[190:191]
	s_add_i32 m0, s48, 0x2000
	s_nop 0
	global_load_lds_dwordx4 v[208:209], off
	v_lshl_add_u64 v[208:209], v[212:213], 0, s[22:23]
	s_mov_b32 m0, s57
	s_nop 0
	global_load_lds_dwordx4 v[208:209], off
	v_lshl_add_u64 v[208:209], v[214:215], 0, s[22:23]
	s_mov_b32 m0, s58
	s_nop 0
	global_load_lds_dwordx4 v[208:209], off
	s_waitcnt vmcnt(8)
	s_waitcnt lgkmcnt(0)
	s_barrier
	s_setprio 1
	s_waitcnt lgkmcnt(0)
	v_mfma_f32_16x16x32_bf16 v[60:63], v[100:103], v[160:163], v[60:63]
	v_mfma_f32_16x16x32_bf16 v[56:59], v[124:127], v[160:163], v[56:59]
	v_mfma_f32_16x16x32_bf16 v[44:47], v[100:103], v[168:171], v[44:47]
	v_mfma_f32_16x16x32_bf16 v[40:43], v[124:127], v[168:171], v[40:43]
	v_mfma_f32_16x16x32_bf16 v[28:31], v[100:103], v[176:179], v[28:31]
	v_mfma_f32_16x16x32_bf16 v[24:27], v[124:127], v[176:179], v[24:27]
	v_mfma_f32_16x16x32_bf16 v[12:15], v[100:103], v[200:203], v[12:15]
	v_mfma_f32_16x16x32_bf16 v[8:11], v[124:127], v[200:203], v[8:11]
	v_mfma_f32_16x16x32_bf16 v[60:63], v[108:111], v[164:167], v[60:63]
	v_mfma_f32_16x16x32_bf16 v[56:59], v[132:135], v[164:167], v[56:59]
	v_mfma_f32_16x16x32_bf16 v[44:47], v[108:111], v[172:175], v[44:47]
	v_mfma_f32_16x16x32_bf16 v[40:43], v[132:135], v[172:175], v[40:43]
	v_mfma_f32_16x16x32_bf16 v[28:31], v[108:111], v[180:183], v[28:31]
	v_mfma_f32_16x16x32_bf16 v[24:27], v[132:135], v[180:183], v[24:27]
	v_mfma_f32_16x16x32_bf16 v[12:15], v[108:111], v[204:207], v[12:15]
	v_mfma_f32_16x16x32_bf16 v[8:11], v[132:135], v[204:207], v[8:11]
	s_setprio 0
	s_setprio 1
	v_mfma_f32_16x16x32_bf16 v[52:55], v[144:147], v[160:163], v[52:55]
	v_mfma_f32_16x16x32_bf16 v[48:51], v[152:155], v[160:163], v[48:51]
	v_mfma_f32_16x16x32_bf16 v[36:39], v[144:147], v[168:171], v[36:39]
	v_mfma_f32_16x16x32_bf16 v[32:35], v[152:155], v[168:171], v[32:35]
	v_mfma_f32_16x16x32_bf16 v[20:23], v[144:147], v[176:179], v[20:23]
	v_mfma_f32_16x16x32_bf16 v[16:19], v[152:155], v[176:179], v[16:19]
	v_mfma_f32_16x16x32_bf16 v[4:7], v[144:147], v[200:203], v[4:7]
	v_mfma_f32_16x16x32_bf16 v[0:3], v[152:155], v[200:203], v[0:3]
	v_mfma_f32_16x16x32_bf16 v[52:55], v[148:151], v[164:167], v[52:55]
	v_mfma_f32_16x16x32_bf16 v[48:51], v[156:159], v[164:167], v[48:51]
	v_mfma_f32_16x16x32_bf16 v[36:39], v[148:151], v[172:175], v[36:39]
	v_mfma_f32_16x16x32_bf16 v[32:35], v[156:159], v[172:175], v[32:35]
	v_mfma_f32_16x16x32_bf16 v[20:23], v[148:151], v[180:183], v[20:23]
	v_mfma_f32_16x16x32_bf16 v[16:19], v[156:159], v[180:183], v[16:19]
	v_mfma_f32_16x16x32_bf16 v[4:7], v[148:151], v[204:207], v[4:7]
	v_mfma_f32_16x16x32_bf16 v[0:3], v[156:159], v[204:207], v[0:3]
	s_setprio 0
	s_barrier
	s_add_i32 s63, s63, 2
	s_add_u32 s40, s40, 0x100
	s_addc_u32 s41, s41, 0
	s_add_u32 s39, s39, 0x100
	s_addc_u32 s62, s62, 0
	s_cmp_gt_u32 s63, 29
	s_cbranch_scc0 .LBB0_1972
	s_branch .Lpeel_exit_8

; #define PG8_STAGE(bufoff, gbase, voff) do { _Pragma("unroll") for (int _i = 0; _i < 2; ++_i) \
;         __builtin_amdgcn_global_load_lds((const unsigned*)((const char*)(gbase) + (voff)[_i]), (PG8_LAS unsigned*)(lds + (bufoff) + ldsw + _i * 8192), 16, 0, 0); } while (0)
; #define PG8_LDA(dst, b, h) do { _Pragma("unroll") for (int m = 0; m < 4; ++m) _Pragma("unroll") for (int k = 0; k < 2; ++k) dst[m][k] = *(const PG8_LAS bf16x8*)(lds + PG8_SA(b, h) + aoff + m * 2048 + k * 1024); } while (0)
; #define PG8_LDB(dst, b, h) do { _Pragma("unroll") for (int n = 0; n < 2; ++n) _Pragma("unroll") for (int k = 0; k < 2; ++k) dst[n][k] = *(const PG8_LAS bf16x8*)(lds + PG8_SB(b, h) + boff + n * 2048 + k * 1024); } while (0)
; #define PG8_MMA(ai, bj, At, Bt) do { __builtin_amdgcn_s_setprio(1); _Pragma("unroll") for (int m = 0; m < 4; ++m) _Pragma("unroll") for (int n = 0; n < 2; ++n) _Pragma("unroll") for (int k = 0; k < 2; ++k) \
;         acc[ai][bj][m][n] = __builtin_amdgcn_mfma_f32_16x16x32_bf16(Bt[n][k], At[m][k], acc[ai][bj][m][n], 0, 0, 0); __builtin_amdgcn_s_setprio(0); } while (0)
; #define PG8_BAR __builtin_amdgcn_s_barrier()
; template <class Epi, class Sched, bool ALIGN_EPI = false, bool SP2 = false>
; __device__ __forceinline__ void gemm_phase(PG8_LAS unsigned char* lds, const Gemm g, const Sched& S, const Epi& E) {
;     ...
;         const bool has_next = S.next(ui + 1, nxt);
;         const char* nA = has_next ? (const char*)g.A + (size_t)nxt.pm * tstep : cA; const char* nB = has_next ? (const char*)g.Bt + (size_t)nxt.pn * tstep : cB;
;         for (int t = 0; t < nt; t += 2) {
;             const bool last = (t == nt - 2);
;             const char* a1 = cA + (size_t)(t + 1) * kstep;
;             const char* a2 = last ? nA : cA + (size_t)(t + 2) * kstep; const char* b2 = last ? nB : cB + (size_t)(t + 2) * kstep;
;             const char* a3 = a2 + kstep; const char* b3 = b2 + kstep;
;             if (last && has_next) S.a_ready(nxt);
;             if constexpr (SP2) {
;             PG8_LDB(B0, 0, 0); PG8_LDB(B1, 0, 1); PG8_SCHED; PG8_LDA(At, 0, 0); PG8_STAGE(PG8_SA(1, 1), a1 + hstep, voffA);
;             PG8_WAIT_V(8); PG8_WAIT_L(0); PG8_BAR; PG8_MMA(0, 0, At, B0); PG8_MMA(0, 1, At, B1); PG8_BAR; PG8_SCHED;
;             PG8_LDA(At, 0, 1); PG8_STAGE(PG8_SB(0, 0), b2, voffB); PG8_STAGE(PG8_SB(0, 1), b2 + hstep, voffB); PG8_STAGE(PG8_SA(0, 0), a2, voffA);
.LBB0_2076:
	s_ashr_i32 s41, s40, 31
	s_lshl_b64 s[42:43], s[40:41], 20
	s_add_u32 s42, s63, s42
	s_addc_u32 s43, s64, s43
	s_and_b64 s[48:49], s[12:13], exec
	s_cselect_b32 s41, s43, s55
	s_cselect_b32 s51, s42, s54
	s_ashr_i32 s39, s38, 31
	s_lshl_b64 s[48:49], s[38:39], 20
	s_add_u32 s48, s65, s48
	s_addc_u32 s49, s66, s49
	s_and_b64 s[58:59], s[12:13], exec
	s_cselect_b32 s39, s49, s57
	s_cselect_b32 s71, s48, s56
	s_add_u32 s54, s54, 0x80080
	s_addc_u32 s55, s55, 0
	s_add_u32 s84, s56, 0x100
	s_addc_u32 s85, s57, 0
	s_mov_b32 s86, -2
	ds_read_b128 v[128:131], v241
	ds_read_b128 v[132:135], v241 offset:1024
	ds_read_b128 v[136:139], v241 offset:2048
	ds_read_b128 v[140:143], v241 offset:3072
	ds_read_b128 v[144:147], v242
	ds_read_b128 v[148:151], v242 offset:1024
	ds_read_b128 v[170:173], v242 offset:2048
	ds_read_b128 v[174:177], v242 offset:3072
	s_add_u32 s56, s54, 0xfff80080
	s_addc_u32 s57, s55, -1
	s_cmp_eq_u32 s86, 28
	s_cselect_b32 s59, s41, s57
	s_cselect_b32 s58, s51, s56
	s_cselect_b32 s57, s39, s85
	s_cselect_b32 s56, s71, s84
	v_lshl_add_u64 v[152:153], s[54:55], 0, v[162:163]
	s_add_i32 m0, s53, 0xc000
	ds_read_b128 v[178:181], v243
	ds_read_b128 v[182:185], v243 offset:1024
	ds_read_b128 v[186:189], v243 offset:2048
	ds_read_b128 v[190:193], v243 offset:3072
	ds_read_b128 v[194:197], v243 offset:4096
	ds_read_b128 v[198:201], v243 offset:5120
	ds_read_b128 v[202:205], v243 offset:6144
	ds_read_b128 v[206:209], v243 offset:7168
	global_load_lds_dwordx4 v[152:153], off
	v_lshl_add_u64 v[152:153], s[54:55], 0, v[164:165]
	s_add_i32 m0, s53, 0xe000
	s_nop 0
	global_load_lds_dwordx4 v[152:153], off
	s_waitcnt vmcnt(8)
	s_waitcnt lgkmcnt(0)
	s_barrier
	s_setprio 1
	s_waitcnt lgkmcnt(0)
	v_mfma_f32_16x16x32_bf16 v[112:115], v[128:131], v[178:181], 0
	v_mfma_f32_16x16x32_bf16 v[80:83], v[136:139], v[178:181], 0
	v_mfma_f32_16x16x32_bf16 v[116:119], v[128:131], v[186:189], 0
	v_mfma_f32_16x16x32_bf16 v[84:87], v[136:139], v[186:189], 0
	v_mfma_f32_16x16x32_bf16 v[120:123], v[128:131], v[194:197], 0
	v_mfma_f32_16x16x32_bf16 v[88:91], v[136:139], v[194:197], 0
	v_mfma_f32_16x16x32_bf16 v[124:127], v[128:131], v[202:205], 0
	v_mfma_f32_16x16x32_bf16 v[92:95], v[136:139], v[202:205], 0
	v_mfma_f32_16x16x32_bf16 v[112:115], v[132:135], v[182:185], v[112:115]
	v_mfma_f32_16x16x32_bf16 v[80:83], v[140:143], v[182:185], v[80:83]
	v_mfma_f32_16x16x32_bf16 v[116:119], v[132:135], v[190:193], v[116:119]
	v_mfma_f32_16x16x32_bf16 v[84:87], v[140:143], v[190:193], v[84:87]
	v_mfma_f32_16x16x32_bf16 v[120:123], v[132:135], v[198:201], v[120:123]
	v_mfma_f32_16x16x32_bf16 v[88:91], v[140:143], v[198:201], v[88:91]
	v_mfma_f32_16x16x32_bf16 v[124:127], v[132:135], v[206:209], v[124:127]
	v_mfma_f32_16x16x32_bf16 v[92:95], v[140:143], v[206:209], v[92:95]
	s_setprio 0
	s_setprio 1
	v_mfma_f32_16x16x32_bf16 v[96:99], v[144:147], v[178:181], 0
	v_mfma_f32_16x16x32_bf16 v[64:67], v[170:173], v[178:181], 0
	v_mfma_f32_16x16x32_bf16 v[100:103], v[144:147], v[186:189], 0
	v_mfma_f32_16x16x32_bf16 v[68:71], v[170:173], v[186:189], 0
	v_mfma_f32_16x16x32_bf16 v[104:107], v[144:147], v[194:197], 0
	v_mfma_f32_16x16x32_bf16 v[72:75], v[170:173], v[194:197], 0
	v_mfma_f32_16x16x32_bf16 v[108:111], v[144:147], v[202:205], 0
	v_mfma_f32_16x16x32_bf16 v[76:79], v[170:173], v[202:205], 0
	v_mfma_f32_16x16x32_bf16 v[96:99], v[148:151], v[182:185], v[96:99]
	v_mfma_f32_16x16x32_bf16 v[64:67], v[174:177], v[182:185], v[64:67]
	v_mfma_f32_16x16x32_bf16 v[100:103], v[148:151], v[190:193], v[100:103]
	v_mfma_f32_16x16x32_bf16 v[68:71], v[174:177], v[190:193], v[68:71]
	v_mfma_f32_16x16x32_bf16 v[104:107], v[148:151], v[198:201], v[104:107]
	v_mfma_f32_16x16x32_bf16 v[72:75], v[174:177], v[198:201], v[72:75]
	v_mfma_f32_16x16x32_bf16 v[108:111], v[148:151], v[206:209], v[108:111]
	v_mfma_f32_16x16x32_bf16 v[76:79], v[174:177], v[206:209], v[76:79]
	s_setprio 0
	s_barrier
	s_add_i32 s87, s78, s62
	v_lshl_add_u64 v[152:153], s[56:57], 0, v[156:157]
	s_mov_b32 m0, s87
	ds_read_b128 v[178:181], v243 offset:16384
	ds_read_b128 v[182:185], v243 offset:17408
	ds_read_b128 v[186:189], v243 offset:18432
	ds_read_b128 v[190:193], v243 offset:19456
	ds_read_b128 v[194:197], v243 offset:20480
	ds_read_b128 v[198:201], v243 offset:21504
	ds_read_b128 v[202:205], v243 offset:22528
	ds_read_b128 v[206:209], v243 offset:23552
	global_load_lds_dwordx4 v[152:153], off
	s_add_i32 m0, s87, 0x2000
	s_add_u32 s88, s56, 0x80000
	v_lshl_add_u64 v[210:211], s[56:57], 0, v[160:161]
	s_addc_u32 s89, s57, 0
	s_add_i32 s87, s79, s62
	global_load_lds_dwordx4 v[210:211], off
	v_lshl_add_u64 v[212:213], s[88:89], 0, v[156:157]
	s_mov_b32 m0, s87
	v_lshl_add_u64 v[214:215], s[58:59], 0, v[158:159]
	global_load_lds_dwordx4 v[212:213], off
	v_lshl_add_u64 v[212:213], s[88:89], 0, v[160:161]
	s_add_i32 m0, s87, 0x2000
	s_nop 0
	global_load_lds_dwordx4 v[212:213], off
	v_lshl_add_u64 v[212:213], s[58:59], 0, v[154:155]
	s_mov_b32 m0, s53
	s_nop 0
	global_load_lds_dwordx4 v[212:213], off
	s_mov_b32 m0, s67
	s_nop 0
	global_load_lds_dwordx4 v[214:215], off
	s_waitcnt vmcnt(8)
	s_waitcnt lgkmcnt(0)
	s_barrier
; #define PG8_STAGE(bufoff, gbase, voff) do { _Pragma("unroll") for (int _i = 0; _i < 2; ++_i) \
;         __builtin_amdgcn_global_load_lds((const unsigned*)((const char*)(gbase) + (voff)[_i]), (PG8_LAS unsigned*)(lds + (bufoff) + ldsw + _i * 8192), 16, 0, 0); } while (0)
; #define PG8_LDA(dst, b, h) do { _Pragma("unroll") for (int m = 0; m < 4; ++m) _Pragma("unroll") for (int k = 0; k < 2; ++k) dst[m][k] = *(const PG8_LAS bf16x8*)(lds + PG8_SA(b, h) + aoff + m * 2048 + k * 1024); } while (0)
; #define PG8_LDB(dst, b, h) do { _Pragma("unroll") for (int n = 0; n < 2; ++n) _Pragma("unroll") for (int k = 0; k < 2; ++k) dst[n][k] = *(const PG8_LAS bf16x8*)(lds + PG8_SB(b, h) + boff + n * 2048 + k * 1024); } while (0)
; #define PG8_MMA(ai, bj, At, Bt) do { __builtin_amdgcn_s_setprio(1); _Pragma("unroll") for (int m = 0; m < 4; ++m) _Pragma("unroll") for (int n = 0; n < 2; ++n) _Pragma("unroll") for (int k = 0; k < 2; ++k) \
;         acc[ai][bj][m][n] = __builtin_amdgcn_mfma_f32_16x16x32_bf16(Bt[n][k], At[m][k], acc[ai][bj][m][n], 0, 0, 0); __builtin_amdgcn_s_setprio(0); } while (0)
; #define PG8_WAIT_V(n) asm volatile("s_waitcnt vmcnt(" #n ")" ::: "memory")
; #define PG8_WAIT_L(n) asm volatile("s_waitcnt lgkmcnt(" #n ")" ::: "memory")
; #define PG8_BAR __builtin_amdgcn_s_barrier()
; #define PG8_SCHED __builtin_amdgcn_sched_barrier(0)
; template <class Epi, class Sched, bool ALIGN_EPI = false, bool SP2 = false>
; __device__ __forceinline__ void gemm_phase(PG8_LAS unsigned char* lds, const Gemm g, const Sched& S, const Epi& E) {
;     ...
;             PG8_WAIT_V(8); PG8_WAIT_L(0); PG8_BAR; PG8_MMA(1, 0, At, B0); PG8_MMA(1, 1, At, B1); PG8_BAR; PG8_SCHED;
;             PG8_LDB(B0, 1, 0); PG8_LDB(B1, 1, 1); PG8_SCHED; PG8_LDA(At, 1, 0); PG8_STAGE(PG8_SA(0, 1), a2 + hstep, voffA);
;             PG8_WAIT_V(8); PG8_WAIT_L(0); PG8_BAR; PG8_MMA(0, 0, At, B0); PG8_MMA(0, 1, At, B1); PG8_BAR; PG8_SCHED;
	s_setprio 1
	s_waitcnt lgkmcnt(0)
	v_mfma_f32_16x16x32_bf16 v[48:51], v[128:131], v[178:181], 0
	v_mfma_f32_16x16x32_bf16 v[16:19], v[136:139], v[178:181], 0
	v_mfma_f32_16x16x32_bf16 v[52:55], v[128:131], v[186:189], 0
	v_mfma_f32_16x16x32_bf16 v[20:23], v[136:139], v[186:189], 0
	v_mfma_f32_16x16x32_bf16 v[56:59], v[128:131], v[194:197], 0
	v_mfma_f32_16x16x32_bf16 v[24:27], v[136:139], v[194:197], 0
	v_mfma_f32_16x16x32_bf16 v[60:63], v[128:131], v[202:205], 0
	v_mfma_f32_16x16x32_bf16 v[28:31], v[136:139], v[202:205], 0
	v_mfma_f32_16x16x32_bf16 v[48:51], v[132:135], v[182:185], v[48:51]
	v_mfma_f32_16x16x32_bf16 v[16:19], v[140:143], v[182:185], v[16:19]
	v_mfma_f32_16x16x32_bf16 v[52:55], v[132:135], v[190:193], v[52:55]
	v_mfma_f32_16x16x32_bf16 v[20:23], v[140:143], v[190:193], v[20:23]
	v_mfma_f32_16x16x32_bf16 v[56:59], v[132:135], v[198:201], v[56:59]
	v_mfma_f32_16x16x32_bf16 v[24:27], v[140:143], v[198:201], v[24:27]
	v_mfma_f32_16x16x32_bf16 v[60:63], v[132:135], v[206:209], v[60:63]
	v_mfma_f32_16x16x32_bf16 v[28:31], v[140:143], v[206:209], v[28:31]
	s_setprio 0
	s_setprio 1
	v_mfma_f32_16x16x32_bf16 v[32:35], v[144:147], v[178:181], 0
	v_mfma_f32_16x16x32_bf16 v[0:3], v[170:173], v[178:181], 0
	v_mfma_f32_16x16x32_bf16 v[36:39], v[144:147], v[186:189], 0
	v_mfma_f32_16x16x32_bf16 v[4:7], v[170:173], v[186:189], 0
	v_mfma_f32_16x16x32_bf16 v[40:43], v[144:147], v[194:197], 0
	v_mfma_f32_16x16x32_bf16 v[8:11], v[170:173], v[194:197], 0
	v_mfma_f32_16x16x32_bf16 v[44:47], v[144:147], v[202:205], 0
	v_mfma_f32_16x16x32_bf16 v[12:15], v[170:173], v[202:205], 0
	v_mfma_f32_16x16x32_bf16 v[32:35], v[148:151], v[182:185], v[32:35]
	v_mfma_f32_16x16x32_bf16 v[0:3], v[174:177], v[182:185], v[0:3]
	v_mfma_f32_16x16x32_bf16 v[36:39], v[148:151], v[190:193], v[36:39]
	v_mfma_f32_16x16x32_bf16 v[4:7], v[174:177], v[190:193], v[4:7]
	v_mfma_f32_16x16x32_bf16 v[40:43], v[148:151], v[198:201], v[40:43]
	v_mfma_f32_16x16x32_bf16 v[8:11], v[174:177], v[198:201], v[8:11]
	v_mfma_f32_16x16x32_bf16 v[44:47], v[148:151], v[206:209], v[44:47]
	v_mfma_f32_16x16x32_bf16 v[12:15], v[174:177], v[206:209], v[12:15]
	s_setprio 0
	s_barrier
	s_add_i32 s87, 0, 0x18000
	s_add_i32 s88, 0, 0x1c000
	v_add_u32_e32 v140, s87, v237
	v_add_u32_e32 v174, s88, v237
	ds_read_b128 v[128:131], v140
	ds_read_b128 v[132:135], v140 offset:1024
	ds_read_b128 v[136:139], v140 offset:2048
	ds_read_b128 v[140:143], v140 offset:3072
	ds_read_b128 v[144:147], v174
	ds_read_b128 v[148:151], v174 offset:1024
	ds_read_b128 v[170:173], v174 offset:2048
	ds_read_b128 v[174:177], v174 offset:3072
	s_add_u32 s58, s58, 0x80000
	s_addc_u32 s59, s59, 0
	s_mov_b32 m0, s68
	v_lshl_add_u64 v[216:217], s[58:59], 0, v[154:155]
	ds_read_b128 v[178:181], v243 offset:32768
	ds_read_b128 v[182:185], v243 offset:33792
	ds_read_b128 v[186:189], v243 offset:34816
	ds_read_b128 v[190:193], v243 offset:35840
	ds_read_b128 v[194:197], v243 offset:36864
	ds_read_b128 v[198:201], v243 offset:37888
	ds_read_b128 v[202:205], v243 offset:38912
	ds_read_b128 v[206:209], v243 offset:39936
	global_load_lds_dwordx4 v[216:217], off
	v_lshl_add_u64 v[216:217], s[58:59], 0, v[158:159]
	s_mov_b32 m0, s72
	s_nop 0
	global_load_lds_dwordx4 v[216:217], off
	s_waitcnt vmcnt(8)
	s_waitcnt lgkmcnt(0)
	s_barrier
	s_setprio 1
	s_waitcnt lgkmcnt(0)
	v_mfma_f32_16x16x32_bf16 v[112:115], v[128:131], v[178:181], v[112:115]
	v_mfma_f32_16x16x32_bf16 v[80:83], v[136:139], v[178:181], v[80:83]
	v_mfma_f32_16x16x32_bf16 v[116:119], v[128:131], v[186:189], v[116:119]
	v_mfma_f32_16x16x32_bf16 v[84:87], v[136:139], v[186:189], v[84:87]
	v_mfma_f32_16x16x32_bf16 v[120:123], v[128:131], v[194:197], v[120:123]
	v_mfma_f32_16x16x32_bf16 v[88:91], v[136:139], v[194:197], v[88:91]
	v_mfma_f32_16x16x32_bf16 v[124:127], v[128:131], v[202:205], v[124:127]
	v_mfma_f32_16x16x32_bf16 v[92:95], v[136:139], v[202:205], v[92:95]
	v_mfma_f32_16x16x32_bf16 v[112:115], v[132:135], v[182:185], v[112:115]
	v_mfma_f32_16x16x32_bf16 v[80:83], v[140:143], v[182:185], v[80:83]
	v_mfma_f32_16x16x32_bf16 v[116:119], v[132:135], v[190:193], v[116:119]
	v_mfma_f32_16x16x32_bf16 v[84:87], v[140:143], v[190:193], v[84:87]
	v_mfma_f32_16x16x32_bf16 v[120:123], v[132:135], v[198:201], v[120:123]
	v_mfma_f32_16x16x32_bf16 v[88:91], v[140:143], v[198:201], v[88:91]
	v_mfma_f32_16x16x32_bf16 v[124:127], v[132:135], v[206:209], v[124:127]
	v_mfma_f32_16x16x32_bf16 v[92:95], v[140:143], v[206:209], v[92:95]
	s_setprio 0
	s_setprio 1
	v_mfma_f32_16x16x32_bf16 v[96:99], v[144:147], v[178:181], v[96:99]
	v_mfma_f32_16x16x32_bf16 v[64:67], v[170:173], v[178:181], v[64:67]
	v_mfma_f32_16x16x32_bf16 v[100:103], v[144:147], v[186:189], v[100:103]
	v_mfma_f32_16x16x32_bf16 v[68:71], v[170:173], v[186:189], v[68:71]
	v_mfma_f32_16x16x32_bf16 v[104:107], v[144:147], v[194:197], v[104:107]
	v_mfma_f32_16x16x32_bf16 v[72:75], v[170:173], v[194:197], v[72:75]
	v_mfma_f32_16x16x32_bf16 v[108:111], v[144:147], v[202:205], v[108:111]
	v_mfma_f32_16x16x32_bf16 v[76:79], v[170:173], v[202:205], v[76:79]
	v_mfma_f32_16x16x32_bf16 v[96:99], v[148:151], v[182:185], v[96:99]
	v_mfma_f32_16x16x32_bf16 v[64:67], v[174:177], v[182:185], v[64:67]
	v_mfma_f32_16x16x32_bf16 v[100:103], v[148:151], v[190:193], v[100:103]
	v_mfma_f32_16x16x32_bf16 v[68:71], v[174:177], v[190:193], v[68:71]
	v_mfma_f32_16x16x32_bf16 v[104:107], v[148:151], v[198:201], v[104:107]
	v_mfma_f32_16x16x32_bf16 v[72:75], v[174:177], v[198:201], v[72:75]
	v_mfma_f32_16x16x32_bf16 v[108:111], v[148:151], v[206:209], v[108:111]
	v_mfma_f32_16x16x32_bf16 v[76:79], v[174:177], v[206:209], v[76:79]
	s_setprio 0
	s_barrier
; #define PG8_STAGE(bufoff, gbase, voff) do { _Pragma("unroll") for (int _i = 0; _i < 2; ++_i) \
;         __builtin_amdgcn_global_load_lds((const unsigned*)((const char*)(gbase) + (voff)[_i]), (PG8_LAS unsigned*)(lds + (bufoff) + ldsw + _i * 8192), 16, 0, 0); } while (0)
; #define PG8_LDA(dst, b, h) do { _Pragma("unroll") for (int m = 0; m < 4; ++m) _Pragma("unroll") for (int k = 0; k < 2; ++k) dst[m][k] = *(const PG8_LAS bf16x8*)(lds + PG8_SA(b, h) + aoff + m * 2048 + k * 1024); } while (0)
; #define PG8_MMA(ai, bj, At, Bt) do { __builtin_amdgcn_s_setprio(1); _Pragma("unroll") for (int m = 0; m < 4; ++m) _Pragma("unroll") for (int n = 0; n < 2; ++n) _Pragma("unroll") for (int k = 0; k < 2; ++k) \
;         acc[ai][bj][m][n] = __builtin_amdgcn_mfma_f32_16x16x32_bf16(Bt[n][k], At[m][k], acc[ai][bj][m][n], 0, 0, 0); __builtin_amdgcn_s_setprio(0); } while (0)
; #define PG8_WAIT_V(n) asm volatile("s_waitcnt vmcnt(" #n ")" ::: "memory")
; #define PG8_WAIT_L(n) asm volatile("s_waitcnt lgkmcnt(" #n ")" ::: "memory")
; #define PG8_BAR __builtin_amdgcn_s_barrier()
; #define PG8_SCHED __builtin_amdgcn_sched_barrier(0)
; template <class Epi, class Sched, bool ALIGN_EPI = false, bool SP2 = false>
; __device__ __forceinline__ void gemm_phase(PG8_LAS unsigned char* lds, const Gemm g, const Sched& S, const Epi& E) {
;     ...
;         for (int t = 0; t < nt; t += 2) {
;     ...
;             PG8_LDA(At, 1, 1); PG8_STAGE(PG8_SB(1, 0), b3, voffB); PG8_STAGE(PG8_SB(1, 1), b3 + hstep, voffB); PG8_STAGE(PG8_SA(1, 0), a3, voffA);
;             PG8_WAIT_V(8); PG8_WAIT_L(0); PG8_BAR; PG8_MMA(1, 0, At, B0); PG8_MMA(1, 1, At, B1); PG8_BAR; PG8_SCHED;
	s_add_i32 s58, s87, s62
	v_lshl_add_u64 v[152:153], v[152:153], 0, s[24:25]
	s_mov_b32 m0, s58
	ds_read_b128 v[178:181], v243 offset:49152
	ds_read_b128 v[182:185], v243 offset:50176
	ds_read_b128 v[186:189], v243 offset:51200
	ds_read_b128 v[190:193], v243 offset:52224
	ds_read_b128 v[194:197], v243 offset:53248
	ds_read_b128 v[198:201], v243 offset:54272
	ds_read_b128 v[202:205], v243 offset:55296
	ds_read_b128 v[206:209], v243 offset:56320
	global_load_lds_dwordx4 v[152:153], off
	s_add_i32 m0, s58, 0x2000
	s_add_u32 s56, s56, 0x80080
	v_lshl_add_u64 v[152:153], v[210:211], 0, s[24:25]
	s_addc_u32 s57, s57, 0
	s_add_i32 s58, s88, s62
	global_load_lds_dwordx4 v[152:153], off
	v_lshl_add_u64 v[152:153], s[56:57], 0, v[156:157]
	s_mov_b32 m0, s58
	s_nop 0
	global_load_lds_dwordx4 v[152:153], off
	v_lshl_add_u64 v[152:153], s[56:57], 0, v[160:161]
	s_add_i32 m0, s58, 0x2000
	s_nop 0
	global_load_lds_dwordx4 v[152:153], off
	v_lshl_add_u64 v[152:153], v[212:213], 0, s[24:25]
	s_mov_b32 m0, s75
	s_nop 0
	global_load_lds_dwordx4 v[152:153], off
	v_lshl_add_u64 v[152:153], v[214:215], 0, s[24:25]
	s_mov_b32 m0, s76
	s_nop 0
	global_load_lds_dwordx4 v[152:153], off
	s_waitcnt vmcnt(8)
	s_waitcnt lgkmcnt(0)
	s_barrier
	s_setprio 1
	s_waitcnt lgkmcnt(0)
	v_mfma_f32_16x16x32_bf16 v[48:51], v[128:131], v[178:181], v[48:51]
	v_mfma_f32_16x16x32_bf16 v[16:19], v[136:139], v[178:181], v[16:19]
	v_mfma_f32_16x16x32_bf16 v[52:55], v[128:131], v[186:189], v[52:55]
	v_mfma_f32_16x16x32_bf16 v[20:23], v[136:139], v[186:189], v[20:23]
	v_mfma_f32_16x16x32_bf16 v[56:59], v[128:131], v[194:197], v[56:59]
	v_mfma_f32_16x16x32_bf16 v[24:27], v[136:139], v[194:197], v[24:27]
	v_mfma_f32_16x16x32_bf16 v[60:63], v[128:131], v[202:205], v[60:63]
	v_mfma_f32_16x16x32_bf16 v[28:31], v[136:139], v[202:205], v[28:31]
	v_mfma_f32_16x16x32_bf16 v[48:51], v[132:135], v[182:185], v[48:51]
	v_mfma_f32_16x16x32_bf16 v[16:19], v[140:143], v[182:185], v[16:19]
	v_mfma_f32_16x16x32_bf16 v[52:55], v[132:135], v[190:193], v[52:55]
	v_mfma_f32_16x16x32_bf16 v[20:23], v[140:143], v[190:193], v[20:23]
	v_mfma_f32_16x16x32_bf16 v[56:59], v[132:135], v[198:201], v[56:59]
	v_mfma_f32_16x16x32_bf16 v[24:27], v[140:143], v[198:201], v[24:27]
	v_mfma_f32_16x16x32_bf16 v[60:63], v[132:135], v[206:209], v[60:63]
	v_mfma_f32_16x16x32_bf16 v[28:31], v[140:143], v[206:209], v[28:31]
	s_setprio 0
	s_setprio 1
	v_mfma_f32_16x16x32_bf16 v[32:35], v[144:147], v[178:181], v[32:35]
	v_mfma_f32_16x16x32_bf16 v[0:3], v[170:173], v[178:181], v[0:3]
	v_mfma_f32_16x16x32_bf16 v[36:39], v[144:147], v[186:189], v[36:39]
	v_mfma_f32_16x16x32_bf16 v[4:7], v[170:173], v[186:189], v[4:7]
	v_mfma_f32_16x16x32_bf16 v[40:43], v[144:147], v[194:197], v[40:43]
	v_mfma_f32_16x16x32_bf16 v[8:11], v[170:173], v[194:197], v[8:11]
	v_mfma_f32_16x16x32_bf16 v[44:47], v[144:147], v[202:205], v[44:47]
	v_mfma_f32_16x16x32_bf16 v[12:15], v[170:173], v[202:205], v[12:15]
	v_mfma_f32_16x16x32_bf16 v[32:35], v[148:151], v[182:185], v[32:35]
	v_mfma_f32_16x16x32_bf16 v[0:3], v[174:177], v[182:185], v[0:3]
	v_mfma_f32_16x16x32_bf16 v[36:39], v[148:151], v[190:193], v[36:39]
	v_mfma_f32_16x16x32_bf16 v[4:7], v[174:177], v[190:193], v[4:7]
	v_mfma_f32_16x16x32_bf16 v[40:43], v[148:151], v[198:201], v[40:43]
	v_mfma_f32_16x16x32_bf16 v[8:11], v[174:177], v[198:201], v[8:11]
	v_mfma_f32_16x16x32_bf16 v[44:47], v[148:151], v[206:209], v[44:47]
	v_mfma_f32_16x16x32_bf16 v[12:15], v[174:177], v[206:209], v[12:15]
	s_setprio 0
	s_barrier
	s_add_i32 s86, s86, 2
	s_add_u32 s54, s54, 0x100
	s_addc_u32 s55, s55, 0
	s_add_u32 s84, s84, 0x100
	s_addc_u32 s85, s85, 0
	s_cmp_gt_u32 s86, 29
	s_cbranch_scc0 .LBB0_2077
	s_branch .Lpeel_exit_9

; #define PG8_BAR __builtin_amdgcn_s_barrier()
; template <class Epi, class Sched, bool ALIGN_EPI = false, bool SP2 = false>
; __device__ __forceinline__ void gemm_phase(PG8_LAS unsigned char* lds, const Gemm g, const Sched& S, const Epi& E) {
;     ...
;         if constexpr (ALIGN_EPI) { if (wr == 0) PG8_BAR; }
.Lpeel_exit_9:
	s_and_b64 vcc, exec, s[26:27]
	s_cbranch_vccz .LBB0_2080
	s_barrier

; #define PG8_STAGE(bufoff, gbase, voff) do { _Pragma("unroll") for (int _i = 0; _i < 2; ++_i) \
;         __builtin_amdgcn_global_load_lds((const unsigned*)((const char*)(gbase) + (voff)[_i]), (PG8_LAS unsigned*)(lds + (bufoff) + ldsw + _i * 8192), 16, 0, 0); } while (0)
; #define PG8_LDA(dst, b, h) do { _Pragma("unroll") for (int m = 0; m < 4; ++m) _Pragma("unroll") for (int k = 0; k < 2; ++k) dst[m][k] = *(const PG8_LAS bf16x8*)(lds + PG8_SA(b, h) + aoff + m * 2048 + k * 1024); } while (0)
; #define PG8_LDB(dst, b, h) do { _Pragma("unroll") for (int n = 0; n < 2; ++n) _Pragma("unroll") for (int k = 0; k < 2; ++k) dst[n][k] = *(const PG8_LAS bf16x8*)(lds + PG8_SB(b, h) + boff + n * 2048 + k * 1024); } while (0)
; #define PG8_MMA(ai, bj, At, Bt) do { __builtin_amdgcn_s_setprio(1); _Pragma("unroll") for (int m = 0; m < 4; ++m) _Pragma("unroll") for (int n = 0; n < 2; ++n) _Pragma("unroll") for (int k = 0; k < 2; ++k) \
;         acc[ai][bj][m][n] = __builtin_amdgcn_mfma_f32_16x16x32_bf16(Bt[n][k], At[m][k], acc[ai][bj][m][n], 0, 0, 0); __builtin_amdgcn_s_setprio(0); } while (0)
; #define PG8_BAR __builtin_amdgcn_s_barrier()
; template <class Epi, class Sched, bool ALIGN_EPI = false, bool SP2 = false>
; __device__ __forceinline__ void gemm_phase(PG8_LAS unsigned char* lds, const Gemm g, const Sched& S, const Epi& E) {
;     ...
;         const bool has_next = S.next(ui + 1, nxt);
;         const char* nA = has_next ? (const char*)g.A + (size_t)nxt.pm * tstep : cA; const char* nB = has_next ? (const char*)g.Bt + (size_t)nxt.pn * tstep : cB;
;         for (int t = 0; t < nt; t += 2) {
;             const bool last = (t == nt - 2);
;             const char* a1 = cA + (size_t)(t + 1) * kstep;
;             const char* a2 = last ? nA : cA + (size_t)(t + 2) * kstep; const char* b2 = last ? nB : cB + (size_t)(t + 2) * kstep;
;             const char* a3 = a2 + kstep; const char* b3 = b2 + kstep;
;             if (last && has_next) S.a_ready(nxt);
;             if constexpr (SP2) {
;             PG8_LDB(B0, 0, 0); PG8_LDB(B1, 0, 1); PG8_SCHED; PG8_LDA(At, 0, 0); PG8_STAGE(PG8_SA(1, 1), a1 + hstep, voffA);
;             PG8_WAIT_V(8); PG8_WAIT_L(0); PG8_BAR; PG8_MMA(0, 0, At, B0); PG8_MMA(0, 1, At, B1); PG8_BAR; PG8_SCHED;
;             PG8_LDA(At, 0, 1); PG8_STAGE(PG8_SB(0, 0), b2, voffB); PG8_STAGE(PG8_SB(0, 1), b2 + hstep, voffB); PG8_STAGE(PG8_SA(0, 0), a2, voffA);
.LBB0_2240:
	s_add_u32 s59, s30, 0x100
	s_addc_u32 s60, s31, 0
	s_mov_b32 s61, -2
	s_waitcnt lgkmcnt(0)
	ds_read_b128 v[100:103], v225
	ds_read_b128 v[108:111], v225 offset:1024
	ds_read_b128 v[124:127], v225 offset:2048
	ds_read_b128 v[132:135], v225 offset:3072
	ds_read_b128 v[144:147], v226
	ds_read_b128 v[148:151], v226 offset:1024
	ds_read_b128 v[152:155], v226 offset:2048
	ds_read_b128 v[156:159], v226 offset:3072
	s_add_u32 s30, s28, 0x100
	s_addc_u32 s31, s29, 0
	s_cmpk_eq_i32 s61, 0x54
	s_cselect_b32 s37, s13, s31
	s_cselect_b32 s36, s12, s30
	s_cselect_b32 s35, s27, s60
	s_cselect_b32 s34, s26, s59
	v_lshl_add_u64 v[208:209], s[28:29], 0, v[192:193]
	s_add_i32 m0, s42, 0xc000
	ds_read_b128 v[160:163], v227
	ds_read_b128 v[164:167], v227 offset:1024
	ds_read_b128 v[168:171], v227 offset:2048
	ds_read_b128 v[172:175], v227 offset:3072
	ds_read_b128 v[176:179], v227 offset:4096
	ds_read_b128 v[180:183], v227 offset:5120
	ds_read_b128 v[200:203], v227 offset:6144
	ds_read_b128 v[204:207], v227 offset:7168
	global_load_lds_dwordx4 v[208:209], off
	v_lshl_add_u64 v[208:209], s[28:29], 0, v[194:195]
	s_add_i32 m0, s42, 0xe000
	s_nop 0
	global_load_lds_dwordx4 v[208:209], off
	s_waitcnt vmcnt(8)
	s_waitcnt lgkmcnt(0)
	s_barrier
	s_setprio 1
	s_waitcnt lgkmcnt(0)
	v_mfma_f32_16x16x32_bf16 v[140:143], v[100:103], v[160:163], 0
	v_mfma_f32_16x16x32_bf16 v[136:139], v[124:127], v[160:163], 0
	v_mfma_f32_16x16x32_bf16 v[116:119], v[100:103], v[168:171], 0
	v_mfma_f32_16x16x32_bf16 v[112:115], v[124:127], v[168:171], 0
	v_mfma_f32_16x16x32_bf16 v[92:95], v[100:103], v[176:179], 0
	v_mfma_f32_16x16x32_bf16 v[88:91], v[124:127], v[176:179], 0
	v_mfma_f32_16x16x32_bf16 v[76:79], v[100:103], v[200:203], 0
	v_mfma_f32_16x16x32_bf16 v[72:75], v[124:127], v[200:203], 0
	v_mfma_f32_16x16x32_bf16 v[140:143], v[108:111], v[164:167], v[140:143]
	v_mfma_f32_16x16x32_bf16 v[136:139], v[132:135], v[164:167], v[136:139]
	v_mfma_f32_16x16x32_bf16 v[116:119], v[108:111], v[172:175], v[116:119]
	v_mfma_f32_16x16x32_bf16 v[112:115], v[132:135], v[172:175], v[112:115]
	v_mfma_f32_16x16x32_bf16 v[92:95], v[108:111], v[180:183], v[92:95]
	v_mfma_f32_16x16x32_bf16 v[88:91], v[132:135], v[180:183], v[88:91]
	v_mfma_f32_16x16x32_bf16 v[76:79], v[108:111], v[204:207], v[76:79]
	v_mfma_f32_16x16x32_bf16 v[72:75], v[132:135], v[204:207], v[72:75]
	s_setprio 0
	s_setprio 1
	v_mfma_f32_16x16x32_bf16 v[128:131], v[144:147], v[160:163], 0
	v_mfma_f32_16x16x32_bf16 v[120:123], v[152:155], v[160:163], 0
	v_mfma_f32_16x16x32_bf16 v[104:107], v[144:147], v[168:171], 0
	v_mfma_f32_16x16x32_bf16 v[96:99], v[152:155], v[168:171], 0
	v_mfma_f32_16x16x32_bf16 v[84:87], v[144:147], v[176:179], 0
	v_mfma_f32_16x16x32_bf16 v[80:83], v[152:155], v[176:179], 0
	v_mfma_f32_16x16x32_bf16 v[68:71], v[144:147], v[200:203], 0
	v_mfma_f32_16x16x32_bf16 v[64:67], v[152:155], v[200:203], 0
	v_mfma_f32_16x16x32_bf16 v[128:131], v[148:151], v[164:167], v[128:131]
	v_mfma_f32_16x16x32_bf16 v[120:123], v[156:159], v[164:167], v[120:123]
	v_mfma_f32_16x16x32_bf16 v[104:107], v[148:151], v[172:175], v[104:107]
	v_mfma_f32_16x16x32_bf16 v[96:99], v[156:159], v[172:175], v[96:99]
	v_mfma_f32_16x16x32_bf16 v[84:87], v[148:151], v[180:183], v[84:87]
	v_mfma_f32_16x16x32_bf16 v[80:83], v[156:159], v[180:183], v[80:83]
	v_mfma_f32_16x16x32_bf16 v[68:71], v[148:151], v[204:207], v[68:71]
	v_mfma_f32_16x16x32_bf16 v[64:67], v[156:159], v[204:207], v[64:67]
	s_setprio 0
	s_barrier
	s_add_i32 s28, s53, s41
	v_lshl_add_u64 v[208:209], s[34:35], 0, v[186:187]
	s_mov_b32 m0, s28
	ds_read_b128 v[160:163], v227 offset:16384
	ds_read_b128 v[164:167], v227 offset:17408
	ds_read_b128 v[168:171], v227 offset:18432
	ds_read_b128 v[172:175], v227 offset:19456
	ds_read_b128 v[176:179], v227 offset:20480
	ds_read_b128 v[180:183], v227 offset:21504
	ds_read_b128 v[200:203], v227 offset:22528
	ds_read_b128 v[204:207], v227 offset:23552
	global_load_lds_dwordx4 v[208:209], off
	s_add_i32 m0, s28, 0x2000
	s_add_u32 s28, s34, 0x160000
	v_lshl_add_u64 v[210:211], s[34:35], 0, v[190:191]
	s_addc_u32 s29, s35, 0
	s_add_i32 s62, s54, s41
	global_load_lds_dwordx4 v[210:211], off
	v_lshl_add_u64 v[212:213], s[28:29], 0, v[186:187]
	s_mov_b32 m0, s62
	v_lshl_add_u64 v[214:215], s[36:37], 0, v[188:189]
	global_load_lds_dwordx4 v[212:213], off
	v_lshl_add_u64 v[212:213], s[28:29], 0, v[190:191]
	s_add_i32 m0, s62, 0x2000
	s_nop 0
	global_load_lds_dwordx4 v[212:213], off
	v_lshl_add_u64 v[212:213], s[36:37], 0, v[184:185]
	s_mov_b32 m0, s42
	s_nop 0
	global_load_lds_dwordx4 v[212:213], off
	s_mov_b32 m0, s43
	s_nop 0
	global_load_lds_dwordx4 v[214:215], off
	s_waitcnt vmcnt(8)
	s_waitcnt lgkmcnt(0)
	s_barrier
; #define PG8_STAGE(bufoff, gbase, voff) do { _Pragma("unroll") for (int _i = 0; _i < 2; ++_i) \
;         __builtin_amdgcn_global_load_lds((const unsigned*)((const char*)(gbase) + (voff)[_i]), (PG8_LAS unsigned*)(lds + (bufoff) + ldsw + _i * 8192), 16, 0, 0); } while (0)
; #define PG8_LDA(dst, b, h) do { _Pragma("unroll") for (int m = 0; m < 4; ++m) _Pragma("unroll") for (int k = 0; k < 2; ++k) dst[m][k] = *(const PG8_LAS bf16x8*)(lds + PG8_SA(b, h) + aoff + m * 2048 + k * 1024); } while (0)
; #define PG8_LDB(dst, b, h) do { _Pragma("unroll") for (int n = 0; n < 2; ++n) _Pragma("unroll") for (int k = 0; k < 2; ++k) dst[n][k] = *(const PG8_LAS bf16x8*)(lds + PG8_SB(b, h) + boff + n * 2048 + k * 1024); } while (0)
; #define PG8_MMA(ai, bj, At, Bt) do { __builtin_amdgcn_s_setprio(1); _Pragma("unroll") for (int m = 0; m < 4; ++m) _Pragma("unroll") for (int n = 0; n < 2; ++n) _Pragma("unroll") for (int k = 0; k < 2; ++k) \
;         acc[ai][bj][m][n] = __builtin_amdgcn_mfma_f32_16x16x32_bf16(Bt[n][k], At[m][k], acc[ai][bj][m][n], 0, 0, 0); __builtin_amdgcn_s_setprio(0); } while (0)
; #define PG8_WAIT_V(n) asm volatile("s_waitcnt vmcnt(" #n ")" ::: "memory")
; #define PG8_WAIT_L(n) asm volatile("s_waitcnt lgkmcnt(" #n ")" ::: "memory")
; #define PG8_BAR __builtin_amdgcn_s_barrier()
; #define PG8_SCHED __builtin_amdgcn_sched_barrier(0)
; template <class Epi, class Sched, bool ALIGN_EPI = false, bool SP2 = false>
; __device__ __forceinline__ void gemm_phase(PG8_LAS unsigned char* lds, const Gemm g, const Sched& S, const Epi& E) {
;     ...
;             PG8_WAIT_V(8); PG8_WAIT_L(0); PG8_BAR; PG8_MMA(1, 0, At, B0); PG8_MMA(1, 1, At, B1); PG8_BAR; PG8_SCHED;
;             PG8_LDB(B0, 1, 0); PG8_LDB(B1, 1, 1); PG8_SCHED; PG8_LDA(At, 1, 0); PG8_STAGE(PG8_SA(0, 1), a2 + hstep, voffA);
;             PG8_WAIT_V(8); PG8_WAIT_L(0); PG8_BAR; PG8_MMA(0, 0, At, B0); PG8_MMA(0, 1, At, B1); PG8_BAR; PG8_SCHED;
	s_setprio 1
	s_waitcnt lgkmcnt(0)
	v_mfma_f32_16x16x32_bf16 v[60:63], v[100:103], v[160:163], 0
	v_mfma_f32_16x16x32_bf16 v[56:59], v[124:127], v[160:163], 0
	v_mfma_f32_16x16x32_bf16 v[44:47], v[100:103], v[168:171], 0
	v_mfma_f32_16x16x32_bf16 v[40:43], v[124:127], v[168:171], 0
	v_mfma_f32_16x16x32_bf16 v[28:31], v[100:103], v[176:179], 0
	v_mfma_f32_16x16x32_bf16 v[24:27], v[124:127], v[176:179], 0
	v_mfma_f32_16x16x32_bf16 v[12:15], v[100:103], v[200:203], 0
	v_mfma_f32_16x16x32_bf16 v[8:11], v[124:127], v[200:203], 0
	v_mfma_f32_16x16x32_bf16 v[60:63], v[108:111], v[164:167], v[60:63]
	v_mfma_f32_16x16x32_bf16 v[56:59], v[132:135], v[164:167], v[56:59]
	v_mfma_f32_16x16x32_bf16 v[44:47], v[108:111], v[172:175], v[44:47]
	v_mfma_f32_16x16x32_bf16 v[40:43], v[132:135], v[172:175], v[40:43]
	v_mfma_f32_16x16x32_bf16 v[28:31], v[108:111], v[180:183], v[28:31]
	v_mfma_f32_16x16x32_bf16 v[24:27], v[132:135], v[180:183], v[24:27]
	v_mfma_f32_16x16x32_bf16 v[12:15], v[108:111], v[204:207], v[12:15]
	v_mfma_f32_16x16x32_bf16 v[8:11], v[132:135], v[204:207], v[8:11]
	s_setprio 0
	s_setprio 1
	v_mfma_f32_16x16x32_bf16 v[52:55], v[144:147], v[160:163], 0
	v_mfma_f32_16x16x32_bf16 v[48:51], v[152:155], v[160:163], 0
	v_mfma_f32_16x16x32_bf16 v[36:39], v[144:147], v[168:171], 0
	v_mfma_f32_16x16x32_bf16 v[32:35], v[152:155], v[168:171], 0
	v_mfma_f32_16x16x32_bf16 v[20:23], v[144:147], v[176:179], 0
	v_mfma_f32_16x16x32_bf16 v[16:19], v[152:155], v[176:179], 0
	v_mfma_f32_16x16x32_bf16 v[4:7], v[144:147], v[200:203], 0
	v_mfma_f32_16x16x32_bf16 v[0:3], v[152:155], v[200:203], 0
	v_mfma_f32_16x16x32_bf16 v[52:55], v[148:151], v[164:167], v[52:55]
	v_mfma_f32_16x16x32_bf16 v[48:51], v[156:159], v[164:167], v[48:51]
	v_mfma_f32_16x16x32_bf16 v[36:39], v[148:151], v[172:175], v[36:39]
	v_mfma_f32_16x16x32_bf16 v[32:35], v[156:159], v[172:175], v[32:35]
	v_mfma_f32_16x16x32_bf16 v[20:23], v[148:151], v[180:183], v[20:23]
	v_mfma_f32_16x16x32_bf16 v[16:19], v[156:159], v[180:183], v[16:19]
	v_mfma_f32_16x16x32_bf16 v[4:7], v[148:151], v[204:207], v[4:7]
	v_mfma_f32_16x16x32_bf16 v[0:3], v[156:159], v[204:207], v[0:3]
	s_setprio 0
	s_barrier
	s_add_i32 s62, 0, 0x18000
	s_add_i32 s63, 0, 0x1c000
	v_add_u32_e32 v132, s62, v223
	v_add_u32_e32 v156, s63, v223
	ds_read_b128 v[100:103], v132
	ds_read_b128 v[108:111], v132 offset:1024
	ds_read_b128 v[124:127], v132 offset:2048
	ds_read_b128 v[132:135], v132 offset:3072
	ds_read_b128 v[144:147], v156
	ds_read_b128 v[148:151], v156 offset:1024
	ds_read_b128 v[152:155], v156 offset:2048
	ds_read_b128 v[156:159], v156 offset:3072
	s_add_u32 s28, s36, 0x160000
	s_addc_u32 s29, s37, 0
	s_mov_b32 m0, s48
	v_lshl_add_u64 v[216:217], s[28:29], 0, v[184:185]
	ds_read_b128 v[160:163], v227 offset:32768
	ds_read_b128 v[164:167], v227 offset:33792
	ds_read_b128 v[168:171], v227 offset:34816
	ds_read_b128 v[172:175], v227 offset:35840
	ds_read_b128 v[176:179], v227 offset:36864
	ds_read_b128 v[180:183], v227 offset:37888
	ds_read_b128 v[200:203], v227 offset:38912
	ds_read_b128 v[204:207], v227 offset:39936
	global_load_lds_dwordx4 v[216:217], off
	v_lshl_add_u64 v[216:217], s[28:29], 0, v[188:189]
	s_mov_b32 m0, s49
	s_nop 0
	global_load_lds_dwordx4 v[216:217], off
	s_waitcnt vmcnt(8)
	s_waitcnt lgkmcnt(0)
	s_barrier
	s_setprio 1
	s_waitcnt lgkmcnt(0)
	v_mfma_f32_16x16x32_bf16 v[140:143], v[100:103], v[160:163], v[140:143]
	v_mfma_f32_16x16x32_bf16 v[136:139], v[124:127], v[160:163], v[136:139]
	v_mfma_f32_16x16x32_bf16 v[116:119], v[100:103], v[168:171], v[116:119]
	v_mfma_f32_16x16x32_bf16 v[112:115], v[124:127], v[168:171], v[112:115]
	v_mfma_f32_16x16x32_bf16 v[92:95], v[100:103], v[176:179], v[92:95]
	v_mfma_f32_16x16x32_bf16 v[88:91], v[124:127], v[176:179], v[88:91]
	v_mfma_f32_16x16x32_bf16 v[76:79], v[100:103], v[200:203], v[76:79]
	v_mfma_f32_16x16x32_bf16 v[72:75], v[124:127], v[200:203], v[72:75]
	v_mfma_f32_16x16x32_bf16 v[140:143], v[108:111], v[164:167], v[140:143]
	v_mfma_f32_16x16x32_bf16 v[136:139], v[132:135], v[164:167], v[136:139]
	v_mfma_f32_16x16x32_bf16 v[116:119], v[108:111], v[172:175], v[116:119]
	v_mfma_f32_16x16x32_bf16 v[112:115], v[132:135], v[172:175], v[112:115]
	v_mfma_f32_16x16x32_bf16 v[92:95], v[108:111], v[180:183], v[92:95]
	v_mfma_f32_16x16x32_bf16 v[88:91], v[132:135], v[180:183], v[88:91]
	v_mfma_f32_16x16x32_bf16 v[76:79], v[108:111], v[204:207], v[76:79]
	v_mfma_f32_16x16x32_bf16 v[72:75], v[132:135], v[204:207], v[72:75]
	s_setprio 0
	s_setprio 1
	v_mfma_f32_16x16x32_bf16 v[128:131], v[144:147], v[160:163], v[128:131]
	v_mfma_f32_16x16x32_bf16 v[120:123], v[152:155], v[160:163], v[120:123]
	v_mfma_f32_16x16x32_bf16 v[104:107], v[144:147], v[168:171], v[104:107]
	v_mfma_f32_16x16x32_bf16 v[96:99], v[152:155], v[168:171], v[96:99]
	v_mfma_f32_16x16x32_bf16 v[84:87], v[144:147], v[176:179], v[84:87]
	v_mfma_f32_16x16x32_bf16 v[80:83], v[152:155], v[176:179], v[80:83]
	v_mfma_f32_16x16x32_bf16 v[68:71], v[144:147], v[200:203], v[68:71]
	v_mfma_f32_16x16x32_bf16 v[64:67], v[152:155], v[200:203], v[64:67]
	v_mfma_f32_16x16x32_bf16 v[128:131], v[148:151], v[164:167], v[128:131]
	v_mfma_f32_16x16x32_bf16 v[120:123], v[156:159], v[164:167], v[120:123]
	v_mfma_f32_16x16x32_bf16 v[104:107], v[148:151], v[172:175], v[104:107]
	v_mfma_f32_16x16x32_bf16 v[96:99], v[156:159], v[172:175], v[96:99]
	v_mfma_f32_16x16x32_bf16 v[84:87], v[148:151], v[180:183], v[84:87]
	v_mfma_f32_16x16x32_bf16 v[80:83], v[156:159], v[180:183], v[80:83]
	v_mfma_f32_16x16x32_bf16 v[68:71], v[148:151], v[204:207], v[68:71]
	v_mfma_f32_16x16x32_bf16 v[64:67], v[156:159], v[204:207], v[64:67]
	s_setprio 0
	s_barrier
; #define PG8_STAGE(bufoff, gbase, voff) do { _Pragma("unroll") for (int _i = 0; _i < 2; ++_i) \
;         __builtin_amdgcn_global_load_lds((const unsigned*)((const char*)(gbase) + (voff)[_i]), (PG8_LAS unsigned*)(lds + (bufoff) + ldsw + _i * 8192), 16, 0, 0); } while (0)
; #define PG8_LDA(dst, b, h) do { _Pragma("unroll") for (int m = 0; m < 4; ++m) _Pragma("unroll") for (int k = 0; k < 2; ++k) dst[m][k] = *(const PG8_LAS bf16x8*)(lds + PG8_SA(b, h) + aoff + m * 2048 + k * 1024); } while (0)
; #define PG8_MMA(ai, bj, At, Bt) do { __builtin_amdgcn_s_setprio(1); _Pragma("unroll") for (int m = 0; m < 4; ++m) _Pragma("unroll") for (int n = 0; n < 2; ++n) _Pragma("unroll") for (int k = 0; k < 2; ++k) \
;         acc[ai][bj][m][n] = __builtin_amdgcn_mfma_f32_16x16x32_bf16(Bt[n][k], At[m][k], acc[ai][bj][m][n], 0, 0, 0); __builtin_amdgcn_s_setprio(0); } while (0)
; #define PG8_WAIT_V(n) asm volatile("s_waitcnt vmcnt(" #n ")" ::: "memory")
; #define PG8_WAIT_L(n) asm volatile("s_waitcnt lgkmcnt(" #n ")" ::: "memory")
; #define PG8_BAR __builtin_amdgcn_s_barrier()
; #define PG8_SCHED __builtin_amdgcn_sched_barrier(0)
; template <class Epi, class Sched, bool ALIGN_EPI = false, bool SP2 = false>
; __device__ __forceinline__ void gemm_phase(PG8_LAS unsigned char* lds, const Gemm g, const Sched& S, const Epi& E) {
;     ...
;         for (int t = 0; t < nt; t += 2) {
;     ...
;             PG8_LDA(At, 1, 1); PG8_STAGE(PG8_SB(1, 0), b3, voffB); PG8_STAGE(PG8_SB(1, 1), b3 + hstep, voffB); PG8_STAGE(PG8_SA(1, 0), a3, voffA);
;             PG8_WAIT_V(8); PG8_WAIT_L(0); PG8_BAR; PG8_MMA(1, 0, At, B0); PG8_MMA(1, 1, At, B1); PG8_BAR; PG8_SCHED;
	s_add_i32 s28, s62, s41
	v_lshl_add_u64 v[208:209], v[208:209], 0, s[22:23]
	s_mov_b32 m0, s28
	ds_read_b128 v[160:163], v227 offset:49152
	ds_read_b128 v[164:167], v227 offset:50176
	ds_read_b128 v[168:171], v227 offset:51200
	ds_read_b128 v[172:175], v227 offset:52224
	ds_read_b128 v[176:179], v227 offset:53248
	ds_read_b128 v[180:183], v227 offset:54272
	ds_read_b128 v[200:203], v227 offset:55296
	ds_read_b128 v[204:207], v227 offset:56320
	global_load_lds_dwordx4 v[208:209], off
	s_add_i32 m0, s28, 0x2000
	s_add_u32 s28, s34, 0x160080
	v_lshl_add_u64 v[208:209], v[210:211], 0, s[22:23]
	s_addc_u32 s29, s35, 0
	s_add_i32 s34, s63, s41
	global_load_lds_dwordx4 v[208:209], off
	v_lshl_add_u64 v[208:209], s[28:29], 0, v[186:187]
	s_mov_b32 m0, s34
	s_nop 0
	global_load_lds_dwordx4 v[208:209], off
	v_lshl_add_u64 v[208:209], s[28:29], 0, v[190:191]
	s_add_i32 m0, s34, 0x2000
	s_nop 0
	global_load_lds_dwordx4 v[208:209], off
	v_lshl_add_u64 v[208:209], v[212:213], 0, s[22:23]
	s_mov_b32 m0, s51
	s_nop 0
	global_load_lds_dwordx4 v[208:209], off
	v_lshl_add_u64 v[208:209], v[214:215], 0, s[22:23]
	s_mov_b32 m0, s52
	s_nop 0
	global_load_lds_dwordx4 v[208:209], off
	s_waitcnt vmcnt(8)
	s_waitcnt lgkmcnt(0)
	s_barrier
	s_setprio 1
	s_waitcnt lgkmcnt(0)
	v_mfma_f32_16x16x32_bf16 v[60:63], v[100:103], v[160:163], v[60:63]
	v_mfma_f32_16x16x32_bf16 v[56:59], v[124:127], v[160:163], v[56:59]
	v_mfma_f32_16x16x32_bf16 v[44:47], v[100:103], v[168:171], v[44:47]
	v_mfma_f32_16x16x32_bf16 v[40:43], v[124:127], v[168:171], v[40:43]
	v_mfma_f32_16x16x32_bf16 v[28:31], v[100:103], v[176:179], v[28:31]
	v_mfma_f32_16x16x32_bf16 v[24:27], v[124:127], v[176:179], v[24:27]
	v_mfma_f32_16x16x32_bf16 v[12:15], v[100:103], v[200:203], v[12:15]
	v_mfma_f32_16x16x32_bf16 v[8:11], v[124:127], v[200:203], v[8:11]
	v_mfma_f32_16x16x32_bf16 v[60:63], v[108:111], v[164:167], v[60:63]
	v_mfma_f32_16x16x32_bf16 v[56:59], v[132:135], v[164:167], v[56:59]
	v_mfma_f32_16x16x32_bf16 v[44:47], v[108:111], v[172:175], v[44:47]
	v_mfma_f32_16x16x32_bf16 v[40:43], v[132:135], v[172:175], v[40:43]
	v_mfma_f32_16x16x32_bf16 v[28:31], v[108:111], v[180:183], v[28:31]
	v_mfma_f32_16x16x32_bf16 v[24:27], v[132:135], v[180:183], v[24:27]
	v_mfma_f32_16x16x32_bf16 v[12:15], v[108:111], v[204:207], v[12:15]
	v_mfma_f32_16x16x32_bf16 v[8:11], v[132:135], v[204:207], v[8:11]
	s_setprio 0
	s_setprio 1
	v_mfma_f32_16x16x32_bf16 v[52:55], v[144:147], v[160:163], v[52:55]
	v_mfma_f32_16x16x32_bf16 v[48:51], v[152:155], v[160:163], v[48:51]
	v_mfma_f32_16x16x32_bf16 v[36:39], v[144:147], v[168:171], v[36:39]
	v_mfma_f32_16x16x32_bf16 v[32:35], v[152:155], v[168:171], v[32:35]
	v_mfma_f32_16x16x32_bf16 v[20:23], v[144:147], v[176:179], v[20:23]
	v_mfma_f32_16x16x32_bf16 v[16:19], v[152:155], v[176:179], v[16:19]
	v_mfma_f32_16x16x32_bf16 v[4:7], v[144:147], v[200:203], v[4:7]
	v_mfma_f32_16x16x32_bf16 v[0:3], v[152:155], v[200:203], v[0:3]
	v_mfma_f32_16x16x32_bf16 v[52:55], v[148:151], v[164:167], v[52:55]
	v_mfma_f32_16x16x32_bf16 v[48:51], v[156:159], v[164:167], v[48:51]
	v_mfma_f32_16x16x32_bf16 v[36:39], v[148:151], v[172:175], v[36:39]
	v_mfma_f32_16x16x32_bf16 v[32:35], v[156:159], v[172:175], v[32:35]
	v_mfma_f32_16x16x32_bf16 v[20:23], v[148:151], v[180:183], v[20:23]
	v_mfma_f32_16x16x32_bf16 v[16:19], v[156:159], v[180:183], v[16:19]
	v_mfma_f32_16x16x32_bf16 v[4:7], v[148:151], v[204:207], v[4:7]
	v_mfma_f32_16x16x32_bf16 v[0:3], v[156:159], v[204:207], v[0:3]
	s_setprio 0
	s_barrier
	s_add_i32 s61, s61, 2
	s_add_u32 s59, s59, 0x100
	s_addc_u32 s60, s60, 0
	s_cmpk_gt_u32 s61, 0x55
	s_mov_b64 s[28:29], s[30:31]
	s_cbranch_scc0 .LBB0_2241
	s_branch .Lpeel_exit_10

; #define PG8_STAGE(bufoff, gbase, voff) do { _Pragma("unroll") for (int _i = 0; _i < 2; ++_i) \
;         __builtin_amdgcn_global_load_lds((const unsigned*)((const char*)(gbase) + (voff)[_i]), (PG8_LAS unsigned*)(lds + (bufoff) + ldsw + _i * 8192), 16, 0, 0); } while (0)
; #define PG8_LDA(dst, b, h) do { _Pragma("unroll") for (int m = 0; m < 4; ++m) _Pragma("unroll") for (int k = 0; k < 2; ++k) dst[m][k] = *(const PG8_LAS bf16x8*)(lds + PG8_SA(b, h) + aoff + m * 2048 + k * 1024); } while (0)
; #define PG8_LDB(dst, b, h) do { _Pragma("unroll") for (int n = 0; n < 2; ++n) _Pragma("unroll") for (int k = 0; k < 2; ++k) dst[n][k] = *(const PG8_LAS bf16x8*)(lds + PG8_SB(b, h) + boff + n * 2048 + k * 1024); } while (0)
; #define PG8_MMA(ai, bj, At, Bt) do { __builtin_amdgcn_s_setprio(1); _Pragma("unroll") for (int m = 0; m < 4; ++m) _Pragma("unroll") for (int n = 0; n < 2; ++n) _Pragma("unroll") for (int k = 0; k < 2; ++k) \
;         acc[ai][bj][m][n] = __builtin_amdgcn_mfma_f32_16x16x32_bf16(Bt[n][k], At[m][k], acc[ai][bj][m][n], 0, 0, 0); __builtin_amdgcn_s_setprio(0); } while (0)
; #define PG8_BAR __builtin_amdgcn_s_barrier()
; template <class Epi, class Sched, bool ALIGN_EPI = false, bool SP2 = false>
; __device__ __forceinline__ void gemm_phase(PG8_LAS unsigned char* lds, const Gemm g, const Sched& S, const Epi& E) {
;     ...
;         const bool has_next = S.next(ui + 1, nxt);
;         const char* nA = has_next ? (const char*)g.A + (size_t)nxt.pm * tstep : cA; const char* nB = has_next ? (const char*)g.Bt + (size_t)nxt.pn * tstep : cB;
;         for (int t = 0; t < nt; t += 2) {
;             const bool last = (t == nt - 2);
;             const char* a1 = cA + (size_t)(t + 1) * kstep;
;             const char* a2 = last ? nA : cA + (size_t)(t + 2) * kstep; const char* b2 = last ? nB : cB + (size_t)(t + 2) * kstep;
;             const char* a3 = a2 + kstep; const char* b3 = b2 + kstep;
;             if (last && has_next) S.a_ready(nxt);
;             if constexpr (SP2) {
;             PG8_LDB(B0, 0, 0); PG8_LDB(B1, 0, 1); PG8_SCHED; PG8_LDA(At, 0, 0); PG8_STAGE(PG8_SA(1, 1), a1 + hstep, voffA);
;             PG8_WAIT_V(8); PG8_WAIT_L(0); PG8_BAR; PG8_MMA(0, 0, At, B0); PG8_MMA(0, 1, At, B1); PG8_BAR; PG8_SCHED;
;             PG8_LDA(At, 0, 1); PG8_STAGE(PG8_SB(0, 0), b2, voffB); PG8_STAGE(PG8_SB(0, 1), b2 + hstep, voffB); PG8_STAGE(PG8_SA(0, 0), a2, voffA);
.LBB0_2355:
	s_ashr_i32 s29, s28, 31
	s_lshl_b64 s[30:31], s[28:29], 20
	s_add_u32 s30, s51, s30
	s_addc_u32 s31, s52, s31
	s_and_b64 s[34:35], s[8:9], exec
	s_cselect_b32 s29, s31, s39
	s_cselect_b32 s70, s30, s38
	s_ashr_i32 s27, s26, 31
	s_lshl_b64 s[34:35], s[26:27], 20
	s_add_u32 s34, s53, s34
	s_addc_u32 s35, s54, s35
	s_and_b64 s[42:43], s[8:9], exec
	s_cselect_b32 s27, s35, s41
	s_cselect_b32 s71, s34, s40
	s_add_u32 s38, s38, 0x80080
	s_addc_u32 s39, s39, 0
	s_add_u32 s72, s40, 0x100
	s_addc_u32 s73, s41, 0
	s_mov_b32 s74, -2
	ds_read_b128 v[144:147], v154
	ds_read_b128 v[158:161], v154 offset:1024
	ds_read_b128 v[162:165], v154 offset:2048
	ds_read_b128 v[166:169], v154 offset:3072
	ds_read_b128 v[170:173], v155
	ds_read_b128 v[174:177], v155 offset:1024
	ds_read_b128 v[178:181], v155 offset:2048
	ds_read_b128 v[182:185], v155 offset:3072
	s_add_u32 s40, s38, 0xfff80080
	s_addc_u32 s41, s39, -1
	s_cmp_eq_u32 s74, 28
	s_cselect_b32 s43, s29, s41
	s_cselect_b32 s42, s70, s40
	s_cselect_b32 s41, s27, s73
	s_cselect_b32 s40, s71, s72
	v_lshl_add_u64 v[148:149], s[38:39], 0, v[136:137]
	s_add_i32 m0, s37, 0xc000
	ds_read_b128 v[186:189], v156
	ds_read_b128 v[190:193], v156 offset:1024
	ds_read_b128 v[194:197], v156 offset:2048
	ds_read_b128 v[198:201], v156 offset:3072
	ds_read_b128 v[202:205], v156 offset:4096
	ds_read_b128 v[206:209], v156 offset:5120
	ds_read_b128 v[210:213], v156 offset:6144
	ds_read_b128 v[214:217], v156 offset:7168
	global_load_lds_dwordx4 v[148:149], off
	v_lshl_add_u64 v[148:149], s[38:39], 0, v[138:139]
	s_add_i32 m0, s37, 0xe000
	s_nop 0
	global_load_lds_dwordx4 v[148:149], off
	s_waitcnt vmcnt(8)
	s_waitcnt lgkmcnt(0)
	s_barrier
	s_setprio 1
	s_waitcnt lgkmcnt(0)
	v_mfma_f32_16x16x32_bf16 v[124:127], v[144:147], v[186:189], 0
	v_mfma_f32_16x16x32_bf16 v[120:123], v[162:165], v[186:189], 0
	v_mfma_f32_16x16x32_bf16 v[108:111], v[144:147], v[194:197], 0
	v_mfma_f32_16x16x32_bf16 v[104:107], v[162:165], v[194:197], 0
	v_mfma_f32_16x16x32_bf16 v[92:95], v[144:147], v[202:205], 0
	v_mfma_f32_16x16x32_bf16 v[88:91], v[162:165], v[202:205], 0
	v_mfma_f32_16x16x32_bf16 v[76:79], v[144:147], v[210:213], 0
	v_mfma_f32_16x16x32_bf16 v[72:75], v[162:165], v[210:213], 0
	v_mfma_f32_16x16x32_bf16 v[124:127], v[158:161], v[190:193], v[124:127]
	v_mfma_f32_16x16x32_bf16 v[120:123], v[166:169], v[190:193], v[120:123]
	v_mfma_f32_16x16x32_bf16 v[108:111], v[158:161], v[198:201], v[108:111]
	v_mfma_f32_16x16x32_bf16 v[104:107], v[166:169], v[198:201], v[104:107]
	v_mfma_f32_16x16x32_bf16 v[92:95], v[158:161], v[206:209], v[92:95]
	v_mfma_f32_16x16x32_bf16 v[88:91], v[166:169], v[206:209], v[88:91]
	v_mfma_f32_16x16x32_bf16 v[76:79], v[158:161], v[214:217], v[76:79]
	v_mfma_f32_16x16x32_bf16 v[72:75], v[166:169], v[214:217], v[72:75]
	s_setprio 0
	s_setprio 1
	v_mfma_f32_16x16x32_bf16 v[116:119], v[170:173], v[186:189], 0
	v_mfma_f32_16x16x32_bf16 v[112:115], v[178:181], v[186:189], 0
	v_mfma_f32_16x16x32_bf16 v[100:103], v[170:173], v[194:197], 0
	v_mfma_f32_16x16x32_bf16 v[96:99], v[178:181], v[194:197], 0
	v_mfma_f32_16x16x32_bf16 v[84:87], v[170:173], v[202:205], 0
	v_mfma_f32_16x16x32_bf16 v[80:83], v[178:181], v[202:205], 0
	v_mfma_f32_16x16x32_bf16 v[68:71], v[170:173], v[210:213], 0
	v_mfma_f32_16x16x32_bf16 v[64:67], v[178:181], v[210:213], 0
	v_mfma_f32_16x16x32_bf16 v[116:119], v[174:177], v[190:193], v[116:119]
	v_mfma_f32_16x16x32_bf16 v[112:115], v[182:185], v[190:193], v[112:115]
	v_mfma_f32_16x16x32_bf16 v[100:103], v[174:177], v[198:201], v[100:103]
	v_mfma_f32_16x16x32_bf16 v[96:99], v[182:185], v[198:201], v[96:99]
	v_mfma_f32_16x16x32_bf16 v[84:87], v[174:177], v[206:209], v[84:87]
	v_mfma_f32_16x16x32_bf16 v[80:83], v[182:185], v[206:209], v[80:83]
	v_mfma_f32_16x16x32_bf16 v[68:71], v[174:177], v[214:217], v[68:71]
	v_mfma_f32_16x16x32_bf16 v[64:67], v[182:185], v[214:217], v[64:67]
	s_setprio 0
	s_barrier
	s_add_i32 s75, s61, s50
	v_lshl_add_u64 v[148:149], s[40:41], 0, v[130:131]
	s_mov_b32 m0, s75
	ds_read_b128 v[186:189], v156 offset:16384
	ds_read_b128 v[190:193], v156 offset:17408
	ds_read_b128 v[194:197], v156 offset:18432
	ds_read_b128 v[198:201], v156 offset:19456
	ds_read_b128 v[202:205], v156 offset:20480
	ds_read_b128 v[206:209], v156 offset:21504
	ds_read_b128 v[210:213], v156 offset:22528
	ds_read_b128 v[214:217], v156 offset:23552
	global_load_lds_dwordx4 v[148:149], off
	s_add_i32 m0, s75, 0x2000
	s_add_u32 s76, s40, 0x80000
	v_lshl_add_u64 v[218:219], s[40:41], 0, v[134:135]
	s_addc_u32 s77, s41, 0
	s_add_i32 s75, s62, s50
	global_load_lds_dwordx4 v[218:219], off
	v_lshl_add_u64 v[220:221], s[76:77], 0, v[130:131]
	s_mov_b32 m0, s75
	v_lshl_add_u64 v[222:223], s[42:43], 0, v[132:133]
	global_load_lds_dwordx4 v[220:221], off
	v_lshl_add_u64 v[220:221], s[76:77], 0, v[134:135]
	s_add_i32 m0, s75, 0x2000
	s_nop 0
	global_load_lds_dwordx4 v[220:221], off
	v_lshl_add_u64 v[220:221], s[42:43], 0, v[128:129]
	s_mov_b32 m0, s37
	s_nop 0
	global_load_lds_dwordx4 v[220:221], off
	s_mov_b32 m0, s55
	s_nop 0
	global_load_lds_dwordx4 v[222:223], off
	s_waitcnt vmcnt(8)
	s_waitcnt lgkmcnt(0)
	s_barrier
; #define PG8_STAGE(bufoff, gbase, voff) do { _Pragma("unroll") for (int _i = 0; _i < 2; ++_i) \
;         __builtin_amdgcn_global_load_lds((const unsigned*)((const char*)(gbase) + (voff)[_i]), (PG8_LAS unsigned*)(lds + (bufoff) + ldsw + _i * 8192), 16, 0, 0); } while (0)
; #define PG8_LDA(dst, b, h) do { _Pragma("unroll") for (int m = 0; m < 4; ++m) _Pragma("unroll") for (int k = 0; k < 2; ++k) dst[m][k] = *(const PG8_LAS bf16x8*)(lds + PG8_SA(b, h) + aoff + m * 2048 + k * 1024); } while (0)
; #define PG8_LDB(dst, b, h) do { _Pragma("unroll") for (int n = 0; n < 2; ++n) _Pragma("unroll") for (int k = 0; k < 2; ++k) dst[n][k] = *(const PG8_LAS bf16x8*)(lds + PG8_SB(b, h) + boff + n * 2048 + k * 1024); } while (0)
; #define PG8_MMA(ai, bj, At, Bt) do { __builtin_amdgcn_s_setprio(1); _Pragma("unroll") for (int m = 0; m < 4; ++m) _Pragma("unroll") for (int n = 0; n < 2; ++n) _Pragma("unroll") for (int k = 0; k < 2; ++k) \
;         acc[ai][bj][m][n] = __builtin_amdgcn_mfma_f32_16x16x32_bf16(Bt[n][k], At[m][k], acc[ai][bj][m][n], 0, 0, 0); __builtin_amdgcn_s_setprio(0); } while (0)
; #define PG8_WAIT_V(n) asm volatile("s_waitcnt vmcnt(" #n ")" ::: "memory")
; #define PG8_WAIT_L(n) asm volatile("s_waitcnt lgkmcnt(" #n ")" ::: "memory")
; #define PG8_BAR __builtin_amdgcn_s_barrier()
; #define PG8_SCHED __builtin_amdgcn_sched_barrier(0)
; template <class Epi, class Sched, bool ALIGN_EPI = false, bool SP2 = false>
; __device__ __forceinline__ void gemm_phase(PG8_LAS unsigned char* lds, const Gemm g, const Sched& S, const Epi& E) {
;     ...
;             PG8_WAIT_V(8); PG8_WAIT_L(0); PG8_BAR; PG8_MMA(1, 0, At, B0); PG8_MMA(1, 1, At, B1); PG8_BAR; PG8_SCHED;
;             PG8_LDB(B0, 1, 0); PG8_LDB(B1, 1, 1); PG8_SCHED; PG8_LDA(At, 1, 0); PG8_STAGE(PG8_SA(0, 1), a2 + hstep, voffA);
;             PG8_WAIT_V(8); PG8_WAIT_L(0); PG8_BAR; PG8_MMA(0, 0, At, B0); PG8_MMA(0, 1, At, B1); PG8_BAR; PG8_SCHED;
	s_setprio 1
	s_waitcnt lgkmcnt(0)
	v_mfma_f32_16x16x32_bf16 v[60:63], v[144:147], v[186:189], 0
	v_mfma_f32_16x16x32_bf16 v[56:59], v[162:165], v[186:189], 0
	v_mfma_f32_16x16x32_bf16 v[44:47], v[144:147], v[194:197], 0
	v_mfma_f32_16x16x32_bf16 v[40:43], v[162:165], v[194:197], 0
	v_mfma_f32_16x16x32_bf16 v[28:31], v[144:147], v[202:205], 0
	v_mfma_f32_16x16x32_bf16 v[24:27], v[162:165], v[202:205], 0
	v_mfma_f32_16x16x32_bf16 v[12:15], v[144:147], v[210:213], 0
	v_mfma_f32_16x16x32_bf16 v[8:11], v[162:165], v[210:213], 0
	v_mfma_f32_16x16x32_bf16 v[60:63], v[158:161], v[190:193], v[60:63]
	v_mfma_f32_16x16x32_bf16 v[56:59], v[166:169], v[190:193], v[56:59]
	v_mfma_f32_16x16x32_bf16 v[44:47], v[158:161], v[198:201], v[44:47]
	v_mfma_f32_16x16x32_bf16 v[40:43], v[166:169], v[198:201], v[40:43]
	v_mfma_f32_16x16x32_bf16 v[28:31], v[158:161], v[206:209], v[28:31]
	v_mfma_f32_16x16x32_bf16 v[24:27], v[166:169], v[206:209], v[24:27]
	v_mfma_f32_16x16x32_bf16 v[12:15], v[158:161], v[214:217], v[12:15]
	v_mfma_f32_16x16x32_bf16 v[8:11], v[166:169], v[214:217], v[8:11]
	s_setprio 0
	s_setprio 1
	v_mfma_f32_16x16x32_bf16 v[52:55], v[170:173], v[186:189], 0
	v_mfma_f32_16x16x32_bf16 v[48:51], v[178:181], v[186:189], 0
	v_mfma_f32_16x16x32_bf16 v[36:39], v[170:173], v[194:197], 0
	v_mfma_f32_16x16x32_bf16 v[32:35], v[178:181], v[194:197], 0
	v_mfma_f32_16x16x32_bf16 v[20:23], v[170:173], v[202:205], 0
	v_mfma_f32_16x16x32_bf16 v[16:19], v[178:181], v[202:205], 0
	v_mfma_f32_16x16x32_bf16 v[4:7], v[170:173], v[210:213], 0
	v_mfma_f32_16x16x32_bf16 v[0:3], v[178:181], v[210:213], 0
	v_mfma_f32_16x16x32_bf16 v[52:55], v[174:177], v[190:193], v[52:55]
	v_mfma_f32_16x16x32_bf16 v[48:51], v[182:185], v[190:193], v[48:51]
	v_mfma_f32_16x16x32_bf16 v[36:39], v[174:177], v[198:201], v[36:39]
	v_mfma_f32_16x16x32_bf16 v[32:35], v[182:185], v[198:201], v[32:35]
	v_mfma_f32_16x16x32_bf16 v[20:23], v[174:177], v[206:209], v[20:23]
	v_mfma_f32_16x16x32_bf16 v[16:19], v[182:185], v[206:209], v[16:19]
	v_mfma_f32_16x16x32_bf16 v[4:7], v[174:177], v[214:217], v[4:7]
	v_mfma_f32_16x16x32_bf16 v[0:3], v[182:185], v[214:217], v[0:3]
	s_setprio 0
	s_barrier
	s_add_i32 s75, 0, 0x18000
	v_add_u32_e32 v157, s75, v151
	s_add_i32 s76, 0, 0x1c000
	ds_read_b128 v[144:147], v157
	ds_read_b128 v[158:161], v157 offset:1024
	ds_read_b128 v[162:165], v157 offset:2048
	ds_read_b128 v[166:169], v157 offset:3072
	v_add_u32_e32 v157, s76, v151
	ds_read_b128 v[170:173], v157
	ds_read_b128 v[174:177], v157 offset:1024
	ds_read_b128 v[178:181], v157 offset:2048
	ds_read_b128 v[182:185], v157 offset:3072
	s_add_u32 s42, s42, 0x80000
	s_addc_u32 s43, s43, 0
	s_mov_b32 m0, s56
	v_lshl_add_u64 v[224:225], s[42:43], 0, v[128:129]
	ds_read_b128 v[186:189], v156 offset:32768
	ds_read_b128 v[190:193], v156 offset:33792
	ds_read_b128 v[194:197], v156 offset:34816
	ds_read_b128 v[198:201], v156 offset:35840
	ds_read_b128 v[202:205], v156 offset:36864
	ds_read_b128 v[206:209], v156 offset:37888
	ds_read_b128 v[210:213], v156 offset:38912
	ds_read_b128 v[214:217], v156 offset:39936
	global_load_lds_dwordx4 v[224:225], off
	v_lshl_add_u64 v[224:225], s[42:43], 0, v[132:133]
	s_mov_b32 m0, s57
	s_nop 0
	global_load_lds_dwordx4 v[224:225], off
	s_waitcnt vmcnt(8)
	s_waitcnt lgkmcnt(0)
	s_barrier
	s_setprio 1
	s_waitcnt lgkmcnt(0)
	v_mfma_f32_16x16x32_bf16 v[124:127], v[144:147], v[186:189], v[124:127]
	v_mfma_f32_16x16x32_bf16 v[120:123], v[162:165], v[186:189], v[120:123]
	v_mfma_f32_16x16x32_bf16 v[108:111], v[144:147], v[194:197], v[108:111]
	v_mfma_f32_16x16x32_bf16 v[104:107], v[162:165], v[194:197], v[104:107]
	v_mfma_f32_16x16x32_bf16 v[92:95], v[144:147], v[202:205], v[92:95]
	v_mfma_f32_16x16x32_bf16 v[88:91], v[162:165], v[202:205], v[88:91]
	v_mfma_f32_16x16x32_bf16 v[76:79], v[144:147], v[210:213], v[76:79]
	v_mfma_f32_16x16x32_bf16 v[72:75], v[162:165], v[210:213], v[72:75]
	v_mfma_f32_16x16x32_bf16 v[124:127], v[158:161], v[190:193], v[124:127]
	v_mfma_f32_16x16x32_bf16 v[120:123], v[166:169], v[190:193], v[120:123]
	v_mfma_f32_16x16x32_bf16 v[108:111], v[158:161], v[198:201], v[108:111]
	v_mfma_f32_16x16x32_bf16 v[104:107], v[166:169], v[198:201], v[104:107]
	v_mfma_f32_16x16x32_bf16 v[92:95], v[158:161], v[206:209], v[92:95]
	v_mfma_f32_16x16x32_bf16 v[88:91], v[166:169], v[206:209], v[88:91]
	v_mfma_f32_16x16x32_bf16 v[76:79], v[158:161], v[214:217], v[76:79]
	v_mfma_f32_16x16x32_bf16 v[72:75], v[166:169], v[214:217], v[72:75]
	s_setprio 0
	s_setprio 1
	v_mfma_f32_16x16x32_bf16 v[116:119], v[170:173], v[186:189], v[116:119]
	v_mfma_f32_16x16x32_bf16 v[112:115], v[178:181], v[186:189], v[112:115]
	v_mfma_f32_16x16x32_bf16 v[100:103], v[170:173], v[194:197], v[100:103]
	v_mfma_f32_16x16x32_bf16 v[96:99], v[178:181], v[194:197], v[96:99]
	v_mfma_f32_16x16x32_bf16 v[84:87], v[170:173], v[202:205], v[84:87]
	v_mfma_f32_16x16x32_bf16 v[80:83], v[178:181], v[202:205], v[80:83]
	v_mfma_f32_16x16x32_bf16 v[68:71], v[170:173], v[210:213], v[68:71]
	v_mfma_f32_16x16x32_bf16 v[64:67], v[178:181], v[210:213], v[64:67]
	v_mfma_f32_16x16x32_bf16 v[116:119], v[174:177], v[190:193], v[116:119]
	v_mfma_f32_16x16x32_bf16 v[112:115], v[182:185], v[190:193], v[112:115]
	v_mfma_f32_16x16x32_bf16 v[100:103], v[174:177], v[198:201], v[100:103]
	v_mfma_f32_16x16x32_bf16 v[96:99], v[182:185], v[198:201], v[96:99]
	v_mfma_f32_16x16x32_bf16 v[84:87], v[174:177], v[206:209], v[84:87]
	v_mfma_f32_16x16x32_bf16 v[80:83], v[182:185], v[206:209], v[80:83]
	v_mfma_f32_16x16x32_bf16 v[68:71], v[174:177], v[214:217], v[68:71]
	v_mfma_f32_16x16x32_bf16 v[64:67], v[182:185], v[214:217], v[64:67]
	s_setprio 0
	s_barrier
; #define PG8_STAGE(bufoff, gbase, voff) do { _Pragma("unroll") for (int _i = 0; _i < 2; ++_i) \
;         __builtin_amdgcn_global_load_lds((const unsigned*)((const char*)(gbase) + (voff)[_i]), (PG8_LAS unsigned*)(lds + (bufoff) + ldsw + _i * 8192), 16, 0, 0); } while (0)
; #define PG8_LDA(dst, b, h) do { _Pragma("unroll") for (int m = 0; m < 4; ++m) _Pragma("unroll") for (int k = 0; k < 2; ++k) dst[m][k] = *(const PG8_LAS bf16x8*)(lds + PG8_SA(b, h) + aoff + m * 2048 + k * 1024); } while (0)
; #define PG8_MMA(ai, bj, At, Bt) do { __builtin_amdgcn_s_setprio(1); _Pragma("unroll") for (int m = 0; m < 4; ++m) _Pragma("unroll") for (int n = 0; n < 2; ++n) _Pragma("unroll") for (int k = 0; k < 2; ++k) \
;         acc[ai][bj][m][n] = __builtin_amdgcn_mfma_f32_16x16x32_bf16(Bt[n][k], At[m][k], acc[ai][bj][m][n], 0, 0, 0); __builtin_amdgcn_s_setprio(0); } while (0)
; #define PG8_WAIT_V(n) asm volatile("s_waitcnt vmcnt(" #n ")" ::: "memory")
; #define PG8_WAIT_L(n) asm volatile("s_waitcnt lgkmcnt(" #n ")" ::: "memory")
; #define PG8_BAR __builtin_amdgcn_s_barrier()
; #define PG8_SCHED __builtin_amdgcn_sched_barrier(0)
; template <class Epi, class Sched, bool ALIGN_EPI = false, bool SP2 = false>
; __device__ __forceinline__ void gemm_phase(PG8_LAS unsigned char* lds, const Gemm g, const Sched& S, const Epi& E) {
;     ...
;         for (int t = 0; t < nt; t += 2) {
;     ...
;             PG8_LDA(At, 1, 1); PG8_STAGE(PG8_SB(1, 0), b3, voffB); PG8_STAGE(PG8_SB(1, 1), b3 + hstep, voffB); PG8_STAGE(PG8_SA(1, 0), a3, voffA);
;             PG8_WAIT_V(8); PG8_WAIT_L(0); PG8_BAR; PG8_MMA(1, 0, At, B0); PG8_MMA(1, 1, At, B1); PG8_BAR; PG8_SCHED;
	s_add_i32 s42, s75, s50
	v_lshl_add_u64 v[148:149], v[148:149], 0, s[16:17]
	s_mov_b32 m0, s42
	ds_read_b128 v[186:189], v156 offset:49152
	ds_read_b128 v[190:193], v156 offset:50176
	ds_read_b128 v[194:197], v156 offset:51200
	ds_read_b128 v[198:201], v156 offset:52224
	ds_read_b128 v[202:205], v156 offset:53248
	ds_read_b128 v[206:209], v156 offset:54272
	ds_read_b128 v[210:213], v156 offset:55296
	ds_read_b128 v[214:217], v156 offset:56320
	global_load_lds_dwordx4 v[148:149], off
	s_add_i32 m0, s42, 0x2000
	s_add_u32 s40, s40, 0x80080
	v_lshl_add_u64 v[148:149], v[218:219], 0, s[16:17]
	s_addc_u32 s41, s41, 0
	s_add_i32 s42, s76, s50
	global_load_lds_dwordx4 v[148:149], off
	v_lshl_add_u64 v[148:149], s[40:41], 0, v[130:131]
	s_mov_b32 m0, s42
	s_nop 0
	global_load_lds_dwordx4 v[148:149], off
	v_lshl_add_u64 v[148:149], s[40:41], 0, v[134:135]
	s_add_i32 m0, s42, 0x2000
	s_nop 0
	global_load_lds_dwordx4 v[148:149], off
	v_lshl_add_u64 v[148:149], v[220:221], 0, s[16:17]
	s_mov_b32 m0, s59
	s_nop 0
	global_load_lds_dwordx4 v[148:149], off
	v_lshl_add_u64 v[148:149], v[222:223], 0, s[16:17]
	s_mov_b32 m0, s60
	s_nop 0
	global_load_lds_dwordx4 v[148:149], off
	s_waitcnt vmcnt(8)
	s_waitcnt lgkmcnt(0)
	s_barrier
	s_setprio 1
	s_waitcnt lgkmcnt(0)
	v_mfma_f32_16x16x32_bf16 v[60:63], v[144:147], v[186:189], v[60:63]
	v_mfma_f32_16x16x32_bf16 v[56:59], v[162:165], v[186:189], v[56:59]
	v_mfma_f32_16x16x32_bf16 v[44:47], v[144:147], v[194:197], v[44:47]
	v_mfma_f32_16x16x32_bf16 v[40:43], v[162:165], v[194:197], v[40:43]
	v_mfma_f32_16x16x32_bf16 v[28:31], v[144:147], v[202:205], v[28:31]
	v_mfma_f32_16x16x32_bf16 v[24:27], v[162:165], v[202:205], v[24:27]
	v_mfma_f32_16x16x32_bf16 v[12:15], v[144:147], v[210:213], v[12:15]
	v_mfma_f32_16x16x32_bf16 v[8:11], v[162:165], v[210:213], v[8:11]
	v_mfma_f32_16x16x32_bf16 v[60:63], v[158:161], v[190:193], v[60:63]
	v_mfma_f32_16x16x32_bf16 v[56:59], v[166:169], v[190:193], v[56:59]
	v_mfma_f32_16x16x32_bf16 v[44:47], v[158:161], v[198:201], v[44:47]
	v_mfma_f32_16x16x32_bf16 v[40:43], v[166:169], v[198:201], v[40:43]
	v_mfma_f32_16x16x32_bf16 v[28:31], v[158:161], v[206:209], v[28:31]
	v_mfma_f32_16x16x32_bf16 v[24:27], v[166:169], v[206:209], v[24:27]
	v_mfma_f32_16x16x32_bf16 v[12:15], v[158:161], v[214:217], v[12:15]
	v_mfma_f32_16x16x32_bf16 v[8:11], v[166:169], v[214:217], v[8:11]
	s_setprio 0
	s_setprio 1
	v_mfma_f32_16x16x32_bf16 v[52:55], v[170:173], v[186:189], v[52:55]
	v_mfma_f32_16x16x32_bf16 v[48:51], v[178:181], v[186:189], v[48:51]
	v_mfma_f32_16x16x32_bf16 v[36:39], v[170:173], v[194:197], v[36:39]
	v_mfma_f32_16x16x32_bf16 v[32:35], v[178:181], v[194:197], v[32:35]
	v_mfma_f32_16x16x32_bf16 v[20:23], v[170:173], v[202:205], v[20:23]
	v_mfma_f32_16x16x32_bf16 v[16:19], v[178:181], v[202:205], v[16:19]
	v_mfma_f32_16x16x32_bf16 v[4:7], v[170:173], v[210:213], v[4:7]
	v_mfma_f32_16x16x32_bf16 v[0:3], v[178:181], v[210:213], v[0:3]
	v_mfma_f32_16x16x32_bf16 v[52:55], v[174:177], v[190:193], v[52:55]
	v_mfma_f32_16x16x32_bf16 v[48:51], v[182:185], v[190:193], v[48:51]
	v_mfma_f32_16x16x32_bf16 v[36:39], v[174:177], v[198:201], v[36:39]
	v_mfma_f32_16x16x32_bf16 v[32:35], v[182:185], v[198:201], v[32:35]
	v_mfma_f32_16x16x32_bf16 v[20:23], v[174:177], v[206:209], v[20:23]
	v_mfma_f32_16x16x32_bf16 v[16:19], v[182:185], v[206:209], v[16:19]
	v_mfma_f32_16x16x32_bf16 v[4:7], v[174:177], v[214:217], v[4:7]
	v_mfma_f32_16x16x32_bf16 v[0:3], v[182:185], v[214:217], v[0:3]
	s_setprio 0
	s_barrier
	s_add_i32 s74, s74, 2
	s_add_u32 s38, s38, 0x100
	s_addc_u32 s39, s39, 0
	s_add_u32 s72, s72, 0x100
	s_addc_u32 s73, s73, 0
	s_cmp_gt_u32 s74, 29
	s_cbranch_scc0 .LBB0_2356
	s_branch .Lpeel_exit_11

; #define PG8_STAGE(bufoff, gbase, voff) do { _Pragma("unroll") for (int _i = 0; _i < 2; ++_i) \
;         __builtin_amdgcn_global_load_lds((const unsigned*)((const char*)(gbase) + (voff)[_i]), (PG8_LAS unsigned*)(lds + (bufoff) + ldsw + _i * 8192), 16, 0, 0); } while (0)
; #define PG8_LDA(dst, b, h) do { _Pragma("unroll") for (int m = 0; m < 4; ++m) _Pragma("unroll") for (int k = 0; k < 2; ++k) dst[m][k] = *(const PG8_LAS bf16x8*)(lds + PG8_SA(b, h) + aoff + m * 2048 + k * 1024); } while (0)
; #define PG8_LDB(dst, b, h) do { _Pragma("unroll") for (int n = 0; n < 2; ++n) _Pragma("unroll") for (int k = 0; k < 2; ++k) dst[n][k] = *(const PG8_LAS bf16x8*)(lds + PG8_SB(b, h) + boff + n * 2048 + k * 1024); } while (0)
; #define PG8_WAIT_V(n) asm volatile("s_waitcnt vmcnt(" #n ")" ::: "memory")
; #define PG8_WAIT_L(n) asm volatile("s_waitcnt lgkmcnt(" #n ")" ::: "memory")
; #define PG8_BAR __builtin_amdgcn_s_barrier()
; #define PG8_SCHED __builtin_amdgcn_sched_barrier(0)
; template <class Epi, class Sched, bool ALIGN_EPI = false, bool SP2 = false>
; __device__ __forceinline__ void gemm_phase(PG8_LAS unsigned char* lds, const Gemm g, const Sched& S, const Epi& E) {
;     ...
;         for (int t = 0; t < nt; t += 2) {
;             const bool last = (t == nt - 2);
;             const char* a1 = cA + (size_t)(t + 1) * kstep;
;             const char* a2 = last ? nA : cA + (size_t)(t + 2) * kstep; const char* b2 = last ? nB : cB + (size_t)(t + 2) * kstep;
;             const char* a3 = a2 + kstep; const char* b3 = b2 + kstep;
;             if (last && has_next) S.a_ready(nxt);
;             if constexpr (SP2) {
;             PG8_LDB(B0, 0, 0); PG8_LDB(B1, 0, 1); PG8_SCHED; PG8_LDA(At, 0, 0); PG8_STAGE(PG8_SA(1, 1), a1 + hstep, voffA);
;             PG8_WAIT_V(8); PG8_WAIT_L(0); PG8_BAR; PG8_MMA(0, 0, At, B0); PG8_MMA(0, 1, At, B1); PG8_BAR; PG8_SCHED;
;             PG8_LDA(At, 0, 1); PG8_STAGE(PG8_SB(0, 0), b2, voffB); PG8_STAGE(PG8_SB(0, 1), b2 + hstep, voffB); PG8_STAGE(PG8_SA(0, 0), a2, voffA);
;     ...
;         for (int a = 0; a < 2; ++a)
; #pragma unroll
;             for (int b = 0; b < 2; ++b)
; #pragma unroll
;                 for (int m = 0; m < 4; ++m)
; #pragma unroll
;                     for (int n = 0; n < 2; ++n) acc[a][b][m][n] = (f32x4){0.f, 0.f, 0.f, 0.f};
.LBB0_2383:
	v_mov_b32_e32 v123, 0
	s_andn2_b64 vcc, exec, s[26:27]
	v_mov_b32_e32 v122, v123
	v_mov_b32_e32 v121, v123
	v_mov_b32_e32 v120, v123
	v_mov_b32_e32 v127, v123
	v_mov_b32_e32 v126, v123
	v_mov_b32_e32 v125, v123
	v_mov_b32_e32 v124, v123
	v_mov_b32_e32 v111, v123
	v_mov_b32_e32 v110, v123
	v_mov_b32_e32 v109, v123
	v_mov_b32_e32 v108, v123
	v_mov_b32_e32 v107, v123
	v_mov_b32_e32 v106, v123
	v_mov_b32_e32 v105, v123
	v_mov_b32_e32 v104, v123
	v_mov_b32_e32 v95, v123
	v_mov_b32_e32 v94, v123
	v_mov_b32_e32 v93, v123
	v_mov_b32_e32 v92, v123
	v_mov_b32_e32 v91, v123
	v_mov_b32_e32 v90, v123
	v_mov_b32_e32 v89, v123
	v_mov_b32_e32 v88, v123
	v_mov_b32_e32 v79, v123
	v_mov_b32_e32 v78, v123
	v_mov_b32_e32 v77, v123
	v_mov_b32_e32 v76, v123
	v_mov_b32_e32 v75, v123
	v_mov_b32_e32 v74, v123
	v_mov_b32_e32 v73, v123
	v_mov_b32_e32 v72, v123
	v_mov_b32_e32 v119, v123
	v_mov_b32_e32 v118, v123
	v_mov_b32_e32 v117, v123
	v_mov_b32_e32 v116, v123
	v_mov_b32_e32 v115, v123
	v_mov_b32_e32 v114, v123
	v_mov_b32_e32 v113, v123
	v_mov_b32_e32 v112, v123
	v_mov_b32_e32 v103, v123
	v_mov_b32_e32 v102, v123
	v_mov_b32_e32 v101, v123
	v_mov_b32_e32 v100, v123
	v_mov_b32_e32 v99, v123
	v_mov_b32_e32 v98, v123
	v_mov_b32_e32 v97, v123
	v_mov_b32_e32 v96, v123
	v_mov_b32_e32 v87, v123
	v_mov_b32_e32 v86, v123
	v_mov_b32_e32 v85, v123
	v_mov_b32_e32 v84, v123
	v_mov_b32_e32 v83, v123
	v_mov_b32_e32 v82, v123
	v_mov_b32_e32 v81, v123
	v_mov_b32_e32 v80, v123
	v_mov_b32_e32 v71, v123
	v_mov_b32_e32 v70, v123
	v_mov_b32_e32 v69, v123
	v_mov_b32_e32 v68, v123
	v_mov_b32_e32 v67, v123
	v_mov_b32_e32 v66, v123
	v_mov_b32_e32 v65, v123
	v_mov_b32_e32 v64, v123
	v_mov_b32_e32 v63, v123
	v_mov_b32_e32 v62, v123
	v_mov_b32_e32 v61, v123
	v_mov_b32_e32 v60, v123
	v_mov_b32_e32 v59, v123
	v_mov_b32_e32 v58, v123
	v_mov_b32_e32 v57, v123
	v_mov_b32_e32 v56, v123
	v_mov_b32_e32 v47, v123
	v_mov_b32_e32 v46, v123
	v_mov_b32_e32 v45, v123
	v_mov_b32_e32 v44, v123
	v_mov_b32_e32 v43, v123
	v_mov_b32_e32 v42, v123
	v_mov_b32_e32 v41, v123
	v_mov_b32_e32 v40, v123
	v_mov_b32_e32 v31, v123
	v_mov_b32_e32 v30, v123
	v_mov_b32_e32 v29, v123
	v_mov_b32_e32 v28, v123
	v_mov_b32_e32 v27, v123
	v_mov_b32_e32 v26, v123
	v_mov_b32_e32 v25, v123
	v_mov_b32_e32 v24, v123
	v_mov_b32_e32 v15, v123
	v_mov_b32_e32 v14, v123
	v_mov_b32_e32 v13, v123
	v_mov_b32_e32 v12, v123
	v_mov_b32_e32 v11, v123
	v_mov_b32_e32 v10, v123
	v_mov_b32_e32 v9, v123
	v_mov_b32_e32 v8, v123
	v_mov_b32_e32 v55, v123
	v_mov_b32_e32 v54, v123
	v_mov_b32_e32 v53, v123
	v_mov_b32_e32 v52, v123
	v_mov_b32_e32 v51, v123
	v_mov_b32_e32 v50, v123
	v_mov_b32_e32 v49, v123
	v_mov_b32_e32 v48, v123
	v_mov_b32_e32 v39, v123
	v_mov_b32_e32 v38, v123
	v_mov_b32_e32 v37, v123
	v_mov_b32_e32 v36, v123
	v_mov_b32_e32 v35, v123
	v_mov_b32_e32 v34, v123
	v_mov_b32_e32 v33, v123
	v_mov_b32_e32 v32, v123
	v_mov_b32_e32 v23, v123
	v_mov_b32_e32 v22, v123
	v_mov_b32_e32 v21, v123
	v_mov_b32_e32 v20, v123
	v_mov_b32_e32 v19, v123
	v_mov_b32_e32 v18, v123
	v_mov_b32_e32 v17, v123
	v_mov_b32_e32 v16, v123
	v_mov_b32_e32 v7, v123
	v_mov_b32_e32 v6, v123
	v_mov_b32_e32 v5, v123
	v_mov_b32_e32 v4, v123
	v_mov_b32_e32 v3, v123
	v_mov_b32_e32 v2, v123
	v_mov_b32_e32 v1, v123
	v_mov_b32_e32 v0, v123
	s_cbranch_vccnz .LBB0_2386
	s_add_u32 s34, s34, 0x80
	s_addc_u32 s35, s35, 0
	s_add_u32 s60, s36, 0x100
	s_addc_u32 s61, s37, 0
	s_mov_b32 s36, 0
	ds_read_b128 v[128:131], v183
	ds_read_b128 v[132:135], v183 offset:1024
	ds_read_b128 v[136:139], v183 offset:2048
	ds_read_b128 v[140:143], v183 offset:3072
	ds_read_b128 v[144:147], v184
	ds_read_b128 v[148:151], v184 offset:1024
	ds_read_b128 v[168:171], v184 offset:2048
	ds_read_b128 v[172:175], v184 offset:3072
	s_add_i32 s62, s36, 2
	s_add_u32 s63, s34, 0x80
	s_addc_u32 s37, s35, 0
	s_cmp_eq_u32 s53, s36
	s_cselect_b32 s36, s8, s63
	s_cselect_b32 s37, s9, s37
	s_cselect_b32 s65, s31, s61
	s_cselect_b32 s64, s30, s60
	v_lshl_add_u64 v[214:215], s[34:35], 0, v[160:161]
	s_add_i32 m0, s41, 0xc000
	ds_read_b128 v[176:179], v185
	ds_read_b128 v[186:189], v185 offset:1024
	ds_read_b128 v[190:193], v185 offset:2048
	ds_read_b128 v[194:197], v185 offset:3072
	ds_read_b128 v[198:201], v185 offset:4096
	ds_read_b128 v[202:205], v185 offset:5120
	ds_read_b128 v[206:209], v185 offset:6144
	ds_read_b128 v[210:213], v185 offset:7168
	global_load_lds_dwordx4 v[214:215], off
	v_lshl_add_u64 v[214:215], s[34:35], 0, v[162:163]
	s_add_i32 m0, s41, 0xe000
	s_nop 0
	global_load_lds_dwordx4 v[214:215], off
	s_waitcnt vmcnt(8)
	s_waitcnt lgkmcnt(0)
	s_barrier
; #define PG8_STAGE(bufoff, gbase, voff) do { _Pragma("unroll") for (int _i = 0; _i < 2; ++_i) \
;         __builtin_amdgcn_global_load_lds((const unsigned*)((const char*)(gbase) + (voff)[_i]), (PG8_LAS unsigned*)(lds + (bufoff) + ldsw + _i * 8192), 16, 0, 0); } while (0)
; #define PG8_LDA(dst, b, h) do { _Pragma("unroll") for (int m = 0; m < 4; ++m) _Pragma("unroll") for (int k = 0; k < 2; ++k) dst[m][k] = *(const PG8_LAS bf16x8*)(lds + PG8_SA(b, h) + aoff + m * 2048 + k * 1024); } while (0)
; #define PG8_LDB(dst, b, h) do { _Pragma("unroll") for (int n = 0; n < 2; ++n) _Pragma("unroll") for (int k = 0; k < 2; ++k) dst[n][k] = *(const PG8_LAS bf16x8*)(lds + PG8_SB(b, h) + boff + n * 2048 + k * 1024); } while (0)
; #define PG8_MMA(ai, bj, At, Bt) do { __builtin_amdgcn_s_setprio(1); _Pragma("unroll") for (int m = 0; m < 4; ++m) _Pragma("unroll") for (int n = 0; n < 2; ++n) _Pragma("unroll") for (int k = 0; k < 2; ++k) \
;         acc[ai][bj][m][n] = __builtin_amdgcn_mfma_f32_16x16x32_bf16(Bt[n][k], At[m][k], acc[ai][bj][m][n], 0, 0, 0); __builtin_amdgcn_s_setprio(0); } while (0)
; #define PG8_WAIT_V(n) asm volatile("s_waitcnt vmcnt(" #n ")" ::: "memory")
; #define PG8_WAIT_L(n) asm volatile("s_waitcnt lgkmcnt(" #n ")" ::: "memory")
; #define PG8_BAR __builtin_amdgcn_s_barrier()
; #define PG8_SCHED __builtin_amdgcn_sched_barrier(0)
; template <class Epi, class Sched, bool ALIGN_EPI = false, bool SP2 = false>
; __device__ __forceinline__ void gemm_phase(PG8_LAS unsigned char* lds, const Gemm g, const Sched& S, const Epi& E) {
;     ...
;             PG8_WAIT_V(8); PG8_WAIT_L(0); PG8_BAR; PG8_MMA(0, 0, At, B0); PG8_MMA(0, 1, At, B1); PG8_BAR; PG8_SCHED;
;             PG8_LDA(At, 0, 1); PG8_STAGE(PG8_SB(0, 0), b2, voffB); PG8_STAGE(PG8_SB(0, 1), b2 + hstep, voffB); PG8_STAGE(PG8_SA(0, 0), a2, voffA);
;             PG8_WAIT_V(8); PG8_WAIT_L(0); PG8_BAR; PG8_MMA(1, 0, At, B0); PG8_MMA(1, 1, At, B1); PG8_BAR; PG8_SCHED;
;             PG8_LDB(B0, 1, 0); PG8_LDB(B1, 1, 1); PG8_SCHED; PG8_LDA(At, 1, 0); PG8_STAGE(PG8_SA(0, 1), a2 + hstep, voffA);
;             PG8_WAIT_V(8); PG8_WAIT_L(0); PG8_BAR; PG8_MMA(0, 0, At, B0); PG8_MMA(0, 1, At, B1); PG8_BAR; PG8_SCHED;
	s_setprio 1
	s_waitcnt lgkmcnt(0)
	v_mfma_f32_16x16x32_bf16 v[120:123], v[128:131], v[176:179], 0
	v_mfma_f32_16x16x32_bf16 v[124:127], v[136:139], v[176:179], 0
	v_mfma_f32_16x16x32_bf16 v[108:111], v[128:131], v[190:193], 0
	v_mfma_f32_16x16x32_bf16 v[104:107], v[136:139], v[190:193], 0
	v_mfma_f32_16x16x32_bf16 v[92:95], v[128:131], v[198:201], 0
	v_mfma_f32_16x16x32_bf16 v[88:91], v[136:139], v[198:201], 0
	v_mfma_f32_16x16x32_bf16 v[76:79], v[128:131], v[206:209], 0
	v_mfma_f32_16x16x32_bf16 v[72:75], v[136:139], v[206:209], 0
	v_mfma_f32_16x16x32_bf16 v[120:123], v[132:135], v[186:189], v[120:123]
	v_mfma_f32_16x16x32_bf16 v[124:127], v[140:143], v[186:189], v[124:127]
	v_mfma_f32_16x16x32_bf16 v[108:111], v[132:135], v[194:197], v[108:111]
	v_mfma_f32_16x16x32_bf16 v[104:107], v[140:143], v[194:197], v[104:107]
	v_mfma_f32_16x16x32_bf16 v[92:95], v[132:135], v[202:205], v[92:95]
	v_mfma_f32_16x16x32_bf16 v[88:91], v[140:143], v[202:205], v[88:91]
	v_mfma_f32_16x16x32_bf16 v[76:79], v[132:135], v[210:213], v[76:79]
	v_mfma_f32_16x16x32_bf16 v[72:75], v[140:143], v[210:213], v[72:75]
	s_setprio 0
	s_setprio 1
	v_mfma_f32_16x16x32_bf16 v[116:119], v[144:147], v[176:179], 0
	v_mfma_f32_16x16x32_bf16 v[112:115], v[168:171], v[176:179], 0
	v_mfma_f32_16x16x32_bf16 v[100:103], v[144:147], v[190:193], 0
	v_mfma_f32_16x16x32_bf16 v[96:99], v[168:171], v[190:193], 0
	v_mfma_f32_16x16x32_bf16 v[84:87], v[144:147], v[198:201], 0
	v_mfma_f32_16x16x32_bf16 v[80:83], v[168:171], v[198:201], 0
	v_mfma_f32_16x16x32_bf16 v[68:71], v[144:147], v[206:209], 0
	v_mfma_f32_16x16x32_bf16 v[64:67], v[168:171], v[206:209], 0
	v_mfma_f32_16x16x32_bf16 v[116:119], v[148:151], v[186:189], v[116:119]
	v_mfma_f32_16x16x32_bf16 v[112:115], v[172:175], v[186:189], v[112:115]
	v_mfma_f32_16x16x32_bf16 v[100:103], v[148:151], v[194:197], v[100:103]
	v_mfma_f32_16x16x32_bf16 v[96:99], v[172:175], v[194:197], v[96:99]
	v_mfma_f32_16x16x32_bf16 v[84:87], v[148:151], v[202:205], v[84:87]
	v_mfma_f32_16x16x32_bf16 v[80:83], v[172:175], v[202:205], v[80:83]
	v_mfma_f32_16x16x32_bf16 v[68:71], v[148:151], v[210:213], v[68:71]
	v_mfma_f32_16x16x32_bf16 v[64:67], v[172:175], v[210:213], v[64:67]
	s_setprio 0
	s_barrier
	s_add_i32 s63, s54, s40
	v_lshl_add_u64 v[214:215], s[64:65], 0, v[154:155]
	s_mov_b32 m0, s63
	ds_read_b128 v[176:179], v185 offset:16384
	ds_read_b128 v[186:189], v185 offset:17408
	ds_read_b128 v[190:193], v185 offset:18432
	ds_read_b128 v[194:197], v185 offset:19456
	ds_read_b128 v[198:201], v185 offset:20480
	ds_read_b128 v[202:205], v185 offset:21504
	ds_read_b128 v[206:209], v185 offset:22528
	ds_read_b128 v[210:213], v185 offset:23552
	global_load_lds_dwordx4 v[214:215], off
	s_add_i32 m0, s63, 0x2000
	v_lshl_add_u64 v[216:217], s[64:65], 0, v[158:159]
	s_add_u32 s64, s64, s14
	s_addc_u32 s65, s65, s15
	s_add_i32 s63, s55, s40
	global_load_lds_dwordx4 v[216:217], off
	v_lshl_add_u64 v[218:219], s[64:65], 0, v[154:155]
	s_mov_b32 m0, s63
	v_lshl_add_u64 v[220:221], s[64:65], 0, v[158:159]
	global_load_lds_dwordx4 v[218:219], off
	s_add_i32 m0, s63, 0x2000
	v_lshl_add_u64 v[222:223], s[36:37], 0, v[152:153]
	global_load_lds_dwordx4 v[220:221], off
	s_mov_b32 m0, s41
	v_lshl_add_u64 v[224:225], s[36:37], 0, v[156:157]
	global_load_lds_dwordx4 v[222:223], off
	s_mov_b32 m0, s42
	s_nop 0
	global_load_lds_dwordx4 v[224:225], off
	s_waitcnt vmcnt(8)
	s_waitcnt lgkmcnt(0)
	s_barrier
	s_setprio 1
	s_waitcnt lgkmcnt(0)
	v_mfma_f32_16x16x32_bf16 v[60:63], v[128:131], v[176:179], 0
	v_mfma_f32_16x16x32_bf16 v[56:59], v[136:139], v[176:179], 0
	v_mfma_f32_16x16x32_bf16 v[44:47], v[128:131], v[190:193], 0
	v_mfma_f32_16x16x32_bf16 v[40:43], v[136:139], v[190:193], 0
	v_mfma_f32_16x16x32_bf16 v[28:31], v[128:131], v[198:201], 0
	v_mfma_f32_16x16x32_bf16 v[24:27], v[136:139], v[198:201], 0
	v_mfma_f32_16x16x32_bf16 v[12:15], v[128:131], v[206:209], 0
	v_mfma_f32_16x16x32_bf16 v[8:11], v[136:139], v[206:209], 0
	v_mfma_f32_16x16x32_bf16 v[60:63], v[132:135], v[186:189], v[60:63]
	v_mfma_f32_16x16x32_bf16 v[56:59], v[140:143], v[186:189], v[56:59]
	v_mfma_f32_16x16x32_bf16 v[44:47], v[132:135], v[194:197], v[44:47]
	v_mfma_f32_16x16x32_bf16 v[40:43], v[140:143], v[194:197], v[40:43]
	v_mfma_f32_16x16x32_bf16 v[28:31], v[132:135], v[202:205], v[28:31]
	v_mfma_f32_16x16x32_bf16 v[24:27], v[140:143], v[202:205], v[24:27]
	v_mfma_f32_16x16x32_bf16 v[12:15], v[132:135], v[210:213], v[12:15]
	v_mfma_f32_16x16x32_bf16 v[8:11], v[140:143], v[210:213], v[8:11]
	s_setprio 0
	s_setprio 1
	v_mfma_f32_16x16x32_bf16 v[52:55], v[144:147], v[176:179], 0
	v_mfma_f32_16x16x32_bf16 v[48:51], v[168:171], v[176:179], 0
	v_mfma_f32_16x16x32_bf16 v[36:39], v[144:147], v[190:193], 0
	v_mfma_f32_16x16x32_bf16 v[32:35], v[168:171], v[190:193], 0
	v_mfma_f32_16x16x32_bf16 v[20:23], v[144:147], v[198:201], 0
	v_mfma_f32_16x16x32_bf16 v[16:19], v[168:171], v[198:201], 0
	v_mfma_f32_16x16x32_bf16 v[4:7], v[144:147], v[206:209], 0
	v_mfma_f32_16x16x32_bf16 v[0:3], v[168:171], v[206:209], 0
	v_mfma_f32_16x16x32_bf16 v[52:55], v[148:151], v[186:189], v[52:55]
	v_mfma_f32_16x16x32_bf16 v[48:51], v[172:175], v[186:189], v[48:51]
	v_mfma_f32_16x16x32_bf16 v[36:39], v[148:151], v[194:197], v[36:39]
	v_mfma_f32_16x16x32_bf16 v[32:35], v[172:175], v[194:197], v[32:35]
	v_mfma_f32_16x16x32_bf16 v[20:23], v[148:151], v[202:205], v[20:23]
	v_mfma_f32_16x16x32_bf16 v[16:19], v[172:175], v[202:205], v[16:19]
	v_mfma_f32_16x16x32_bf16 v[4:7], v[148:151], v[210:213], v[4:7]
	v_mfma_f32_16x16x32_bf16 v[0:3], v[172:175], v[210:213], v[0:3]
	s_setprio 0
	s_barrier
; #define PG8_STAGE(bufoff, gbase, voff) do { _Pragma("unroll") for (int _i = 0; _i < 2; ++_i) \
;         __builtin_amdgcn_global_load_lds((const unsigned*)((const char*)(gbase) + (voff)[_i]), (PG8_LAS unsigned*)(lds + (bufoff) + ldsw + _i * 8192), 16, 0, 0); } while (0)
; #define PG8_LDA(dst, b, h) do { _Pragma("unroll") for (int m = 0; m < 4; ++m) _Pragma("unroll") for (int k = 0; k < 2; ++k) dst[m][k] = *(const PG8_LAS bf16x8*)(lds + PG8_SA(b, h) + aoff + m * 2048 + k * 1024); } while (0)
; #define PG8_LDB(dst, b, h) do { _Pragma("unroll") for (int n = 0; n < 2; ++n) _Pragma("unroll") for (int k = 0; k < 2; ++k) dst[n][k] = *(const PG8_LAS bf16x8*)(lds + PG8_SB(b, h) + boff + n * 2048 + k * 1024); } while (0)
; #define PG8_MMA(ai, bj, At, Bt) do { __builtin_amdgcn_s_setprio(1); _Pragma("unroll") for (int m = 0; m < 4; ++m) _Pragma("unroll") for (int n = 0; n < 2; ++n) _Pragma("unroll") for (int k = 0; k < 2; ++k) \
;         acc[ai][bj][m][n] = __builtin_amdgcn_mfma_f32_16x16x32_bf16(Bt[n][k], At[m][k], acc[ai][bj][m][n], 0, 0, 0); __builtin_amdgcn_s_setprio(0); } while (0)
; #define PG8_WAIT_V(n) asm volatile("s_waitcnt vmcnt(" #n ")" ::: "memory")
; #define PG8_WAIT_L(n) asm volatile("s_waitcnt lgkmcnt(" #n ")" ::: "memory")
; #define PG8_BAR __builtin_amdgcn_s_barrier()
; #define PG8_SCHED __builtin_amdgcn_sched_barrier(0)
; template <class Epi, class Sched, bool ALIGN_EPI = false, bool SP2 = false>
; __device__ __forceinline__ void gemm_phase(PG8_LAS unsigned char* lds, const Gemm g, const Sched& S, const Epi& E) {
;     ...
;             PG8_LDB(B0, 1, 0); PG8_LDB(B1, 1, 1); PG8_SCHED; PG8_LDA(At, 1, 0); PG8_STAGE(PG8_SA(0, 1), a2 + hstep, voffA);
;             PG8_WAIT_V(8); PG8_WAIT_L(0); PG8_BAR; PG8_MMA(0, 0, At, B0); PG8_MMA(0, 1, At, B1); PG8_BAR; PG8_SCHED;
	s_add_i32 s63, 0, 0x18000
	s_add_i32 s64, 0, 0x1c000
	v_add_u32_e32 v140, s63, v181
	v_add_u32_e32 v172, s64, v181
	ds_read_b128 v[128:131], v140
	ds_read_b128 v[132:135], v140 offset:1024
	ds_read_b128 v[136:139], v140 offset:2048
	ds_read_b128 v[140:143], v140 offset:3072
	ds_read_b128 v[144:147], v172
	ds_read_b128 v[148:151], v172 offset:1024
	ds_read_b128 v[168:171], v172 offset:2048
	ds_read_b128 v[172:175], v172 offset:3072
	s_add_u32 s36, s36, s14
	s_addc_u32 s37, s37, s15
	s_mov_b32 m0, s43
	v_lshl_add_u64 v[226:227], s[36:37], 0, v[152:153]
	ds_read_b128 v[176:179], v185 offset:32768
	ds_read_b128 v[186:189], v185 offset:33792
	ds_read_b128 v[190:193], v185 offset:34816
	ds_read_b128 v[194:197], v185 offset:35840
	ds_read_b128 v[198:201], v185 offset:36864
	ds_read_b128 v[202:205], v185 offset:37888
	ds_read_b128 v[206:209], v185 offset:38912
	ds_read_b128 v[210:213], v185 offset:39936
	global_load_lds_dwordx4 v[226:227], off
	v_lshl_add_u64 v[226:227], s[36:37], 0, v[156:157]
	s_mov_b32 m0, s48
	s_nop 0
	global_load_lds_dwordx4 v[226:227], off
	s_waitcnt vmcnt(8)
	s_waitcnt lgkmcnt(0)
	s_barrier
	s_setprio 1
	s_waitcnt lgkmcnt(0)
	v_mfma_f32_16x16x32_bf16 v[120:123], v[128:131], v[176:179], v[120:123]
	v_mfma_f32_16x16x32_bf16 v[124:127], v[136:139], v[176:179], v[124:127]
	v_mfma_f32_16x16x32_bf16 v[108:111], v[128:131], v[190:193], v[108:111]
	v_mfma_f32_16x16x32_bf16 v[104:107], v[136:139], v[190:193], v[104:107]
	v_mfma_f32_16x16x32_bf16 v[92:95], v[128:131], v[198:201], v[92:95]
	v_mfma_f32_16x16x32_bf16 v[88:91], v[136:139], v[198:201], v[88:91]
	v_mfma_f32_16x16x32_bf16 v[76:79], v[128:131], v[206:209], v[76:79]
	v_mfma_f32_16x16x32_bf16 v[72:75], v[136:139], v[206:209], v[72:75]
	v_mfma_f32_16x16x32_bf16 v[120:123], v[132:135], v[186:189], v[120:123]
	v_mfma_f32_16x16x32_bf16 v[124:127], v[140:143], v[186:189], v[124:127]
	v_mfma_f32_16x16x32_bf16 v[108:111], v[132:135], v[194:197], v[108:111]
	v_mfma_f32_16x16x32_bf16 v[104:107], v[140:143], v[194:197], v[104:107]
	v_mfma_f32_16x16x32_bf16 v[92:95], v[132:135], v[202:205], v[92:95]
	v_mfma_f32_16x16x32_bf16 v[88:91], v[140:143], v[202:205], v[88:91]
	v_mfma_f32_16x16x32_bf16 v[76:79], v[132:135], v[210:213], v[76:79]
	v_mfma_f32_16x16x32_bf16 v[72:75], v[140:143], v[210:213], v[72:75]
	s_setprio 0
	s_setprio 1
	v_mfma_f32_16x16x32_bf16 v[116:119], v[144:147], v[176:179], v[116:119]
	v_mfma_f32_16x16x32_bf16 v[112:115], v[168:171], v[176:179], v[112:115]
	v_mfma_f32_16x16x32_bf16 v[100:103], v[144:147], v[190:193], v[100:103]
	v_mfma_f32_16x16x32_bf16 v[96:99], v[168:171], v[190:193], v[96:99]
	v_mfma_f32_16x16x32_bf16 v[84:87], v[144:147], v[198:201], v[84:87]
	v_mfma_f32_16x16x32_bf16 v[80:83], v[168:171], v[198:201], v[80:83]
	v_mfma_f32_16x16x32_bf16 v[68:71], v[144:147], v[206:209], v[68:71]
	v_mfma_f32_16x16x32_bf16 v[64:67], v[168:171], v[206:209], v[64:67]
	v_mfma_f32_16x16x32_bf16 v[116:119], v[148:151], v[186:189], v[116:119]
	v_mfma_f32_16x16x32_bf16 v[112:115], v[172:175], v[186:189], v[112:115]
	v_mfma_f32_16x16x32_bf16 v[100:103], v[148:151], v[194:197], v[100:103]
	v_mfma_f32_16x16x32_bf16 v[96:99], v[172:175], v[194:197], v[96:99]
	v_mfma_f32_16x16x32_bf16 v[84:87], v[148:151], v[202:205], v[84:87]
	v_mfma_f32_16x16x32_bf16 v[80:83], v[172:175], v[202:205], v[80:83]
	v_mfma_f32_16x16x32_bf16 v[68:71], v[148:151], v[210:213], v[68:71]
	v_mfma_f32_16x16x32_bf16 v[64:67], v[172:175], v[210:213], v[64:67]
	s_setprio 0
	s_barrier
; #define PG8_STAGE(bufoff, gbase, voff) do { _Pragma("unroll") for (int _i = 0; _i < 2; ++_i) \
;         __builtin_amdgcn_global_load_lds((const unsigned*)((const char*)(gbase) + (voff)[_i]), (PG8_LAS unsigned*)(lds + (bufoff) + ldsw + _i * 8192), 16, 0, 0); } while (0)
; #define PG8_LDA(dst, b, h) do { _Pragma("unroll") for (int m = 0; m < 4; ++m) _Pragma("unroll") for (int k = 0; k < 2; ++k) dst[m][k] = *(const PG8_LAS bf16x8*)(lds + PG8_SA(b, h) + aoff + m * 2048 + k * 1024); } while (0)
; #define PG8_MMA(ai, bj, At, Bt) do { __builtin_amdgcn_s_setprio(1); _Pragma("unroll") for (int m = 0; m < 4; ++m) _Pragma("unroll") for (int n = 0; n < 2; ++n) _Pragma("unroll") for (int k = 0; k < 2; ++k) \
;         acc[ai][bj][m][n] = __builtin_amdgcn_mfma_f32_16x16x32_bf16(Bt[n][k], At[m][k], acc[ai][bj][m][n], 0, 0, 0); __builtin_amdgcn_s_setprio(0); } while (0)
; #define PG8_WAIT_V(n) asm volatile("s_waitcnt vmcnt(" #n ")" ::: "memory")
; #define PG8_WAIT_L(n) asm volatile("s_waitcnt lgkmcnt(" #n ")" ::: "memory")
; #define PG8_BAR __builtin_amdgcn_s_barrier()
; #define PG8_SCHED __builtin_amdgcn_sched_barrier(0)
; template <class Epi, class Sched, bool ALIGN_EPI = false, bool SP2 = false>
; __device__ __forceinline__ void gemm_phase(PG8_LAS unsigned char* lds, const Gemm g, const Sched& S, const Epi& E) {
;     ...
;         for (int t = 0; t < nt; t += 2) {
;     ...
;             PG8_LDA(At, 1, 1); PG8_STAGE(PG8_SB(1, 0), b3, voffB); PG8_STAGE(PG8_SB(1, 1), b3 + hstep, voffB); PG8_STAGE(PG8_SA(1, 0), a3, voffA);
;             PG8_WAIT_V(8); PG8_WAIT_L(0); PG8_BAR; PG8_MMA(1, 0, At, B0); PG8_MMA(1, 1, At, B1); PG8_BAR; PG8_SCHED;
	s_add_i32 s36, s63, s40
	v_lshl_add_u64 v[214:215], v[214:215], 0, s[24:25]
	s_mov_b32 m0, s36
	ds_read_b128 v[176:179], v185 offset:49152
	ds_read_b128 v[186:189], v185 offset:50176
	ds_read_b128 v[190:193], v185 offset:51200
	ds_read_b128 v[194:197], v185 offset:52224
	ds_read_b128 v[198:201], v185 offset:53248
	ds_read_b128 v[202:205], v185 offset:54272
	ds_read_b128 v[206:209], v185 offset:55296
	ds_read_b128 v[210:213], v185 offset:56320
	global_load_lds_dwordx4 v[214:215], off
	v_lshl_add_u64 v[214:215], v[216:217], 0, s[24:25]
	s_add_i32 m0, s36, 0x2000
	s_add_i32 s36, s64, s40
	global_load_lds_dwordx4 v[214:215], off
	v_lshl_add_u64 v[214:215], v[218:219], 0, s[24:25]
	s_mov_b32 m0, s36
	s_nop 0
	global_load_lds_dwordx4 v[214:215], off
	v_lshl_add_u64 v[214:215], v[220:221], 0, s[24:25]
	s_add_i32 m0, s36, 0x2000
	s_nop 0
	global_load_lds_dwordx4 v[214:215], off
	v_lshl_add_u64 v[214:215], v[222:223], 0, s[24:25]
	s_mov_b32 m0, s50
	s_nop 0
	global_load_lds_dwordx4 v[214:215], off
	v_lshl_add_u64 v[214:215], v[224:225], 0, s[24:25]
	s_mov_b32 m0, s51
	s_nop 0
	global_load_lds_dwordx4 v[214:215], off
	s_waitcnt vmcnt(8)
	s_waitcnt lgkmcnt(0)
	s_barrier
	s_setprio 1
	s_waitcnt lgkmcnt(0)
	v_mfma_f32_16x16x32_bf16 v[60:63], v[128:131], v[176:179], v[60:63]
	v_mfma_f32_16x16x32_bf16 v[56:59], v[136:139], v[176:179], v[56:59]
	v_mfma_f32_16x16x32_bf16 v[44:47], v[128:131], v[190:193], v[44:47]
	v_mfma_f32_16x16x32_bf16 v[40:43], v[136:139], v[190:193], v[40:43]
	v_mfma_f32_16x16x32_bf16 v[28:31], v[128:131], v[198:201], v[28:31]
	v_mfma_f32_16x16x32_bf16 v[24:27], v[136:139], v[198:201], v[24:27]
	v_mfma_f32_16x16x32_bf16 v[12:15], v[128:131], v[206:209], v[12:15]
	v_mfma_f32_16x16x32_bf16 v[8:11], v[136:139], v[206:209], v[8:11]
	v_mfma_f32_16x16x32_bf16 v[60:63], v[132:135], v[186:189], v[60:63]
	v_mfma_f32_16x16x32_bf16 v[56:59], v[140:143], v[186:189], v[56:59]
	v_mfma_f32_16x16x32_bf16 v[44:47], v[132:135], v[194:197], v[44:47]
	v_mfma_f32_16x16x32_bf16 v[40:43], v[140:143], v[194:197], v[40:43]
	v_mfma_f32_16x16x32_bf16 v[28:31], v[132:135], v[202:205], v[28:31]
	v_mfma_f32_16x16x32_bf16 v[24:27], v[140:143], v[202:205], v[24:27]
	v_mfma_f32_16x16x32_bf16 v[12:15], v[132:135], v[210:213], v[12:15]
	v_mfma_f32_16x16x32_bf16 v[8:11], v[140:143], v[210:213], v[8:11]
	s_setprio 0
	s_setprio 1
	v_mfma_f32_16x16x32_bf16 v[52:55], v[144:147], v[176:179], v[52:55]
	v_mfma_f32_16x16x32_bf16 v[48:51], v[168:171], v[176:179], v[48:51]
	v_mfma_f32_16x16x32_bf16 v[36:39], v[144:147], v[190:193], v[36:39]
	v_mfma_f32_16x16x32_bf16 v[32:35], v[168:171], v[190:193], v[32:35]
	v_mfma_f32_16x16x32_bf16 v[20:23], v[144:147], v[198:201], v[20:23]
	v_mfma_f32_16x16x32_bf16 v[16:19], v[168:171], v[198:201], v[16:19]
	v_mfma_f32_16x16x32_bf16 v[4:7], v[144:147], v[206:209], v[4:7]
	v_mfma_f32_16x16x32_bf16 v[0:3], v[168:171], v[206:209], v[0:3]
	v_mfma_f32_16x16x32_bf16 v[52:55], v[148:151], v[186:189], v[52:55]
	v_mfma_f32_16x16x32_bf16 v[48:51], v[172:175], v[186:189], v[48:51]
	v_mfma_f32_16x16x32_bf16 v[36:39], v[148:151], v[194:197], v[36:39]
	v_mfma_f32_16x16x32_bf16 v[32:35], v[172:175], v[194:197], v[32:35]
	v_mfma_f32_16x16x32_bf16 v[20:23], v[148:151], v[202:205], v[20:23]
	v_mfma_f32_16x16x32_bf16 v[16:19], v[172:175], v[202:205], v[16:19]
	v_mfma_f32_16x16x32_bf16 v[4:7], v[148:151], v[210:213], v[4:7]
	v_mfma_f32_16x16x32_bf16 v[0:3], v[172:175], v[210:213], v[0:3]
	s_setprio 0
	s_barrier
	s_add_u32 s34, s34, 0x100
	s_addc_u32 s35, s35, 0
	s_add_u32 s60, s60, 0x100
	s_addc_u32 s61, s61, 0
	s_cmp_ge_i32 s62, s52
	s_mov_b32 s36, s62
	s_cbranch_scc0 .LBB0_2385
	s_branch .Lpeel_exit_12

; #define PG8_BAR __builtin_amdgcn_s_barrier()
; template <class Epi, class Sched, bool ALIGN_EPI = false, bool SP2 = false>
; __device__ __forceinline__ void gemm_phase(PG8_LAS unsigned char* lds, const Gemm g, const Sched& S, const Epi& E) {
;     ...
;         if constexpr (ALIGN_EPI) { if (wr == 0) PG8_BAR; }
.Lpeel_exit_12:
.LBB0_2386:
	s_and_b64 vcc, exec, s[28:29]
	s_cbranch_vccz .LBB0_2388
	s_barrier
